# GEMM K-loops: one counted vmcnt(10) per phase instead of two vmcnt(6) per iteration (5-phase DMA latency budget)
# baseline (speedup 1.0000x reference)
.LBB0_155:
	ds_read_b128 v[154:157], v150
	ds_read_b128 v[158:161], v150 offset:1024
	ds_read_b128 v[162:165], v150 offset:2048
	ds_read_b128 v[166:169], v150 offset:3072
	s_add_u32 s26, s20, 0xfffc0080
	s_addc_u32 s27, s21, -1
	s_cmp_eq_u32 s86, 12
	s_cselect_b32 s29, s15, s27
	s_cselect_b32 s28, s82, s26
	s_cselect_b32 s27, s13, s85
	s_cselect_b32 s26, s83, s84
	v_lshl_add_u64 v[202:203], s[20:21], 0, v[138:139]
	s_add_i32 m0, s11, 0xc000
	ds_read_b128 v[170:173], v151
	ds_read_b128 v[174:177], v151 offset:1024
	ds_read_b128 v[178:181], v151 offset:2048
	ds_read_b128 v[182:185], v151 offset:3072
	ds_read_b128 v[186:189], v151 offset:4096
	ds_read_b128 v[190:193], v151 offset:5120
	ds_read_b128 v[194:197], v151 offset:6144
	ds_read_b128 v[198:201], v151 offset:7168
	global_load_lds_dwordx4 v[202:203], off
	v_lshl_add_u64 v[202:203], s[20:21], 0, v[140:141]
	s_add_i32 m0, s11, 0xe000
	s_nop 0
	global_load_lds_dwordx4 v[202:203], off
	s_waitcnt lgkmcnt(8)
	s_waitcnt vmcnt(10)
	s_barrier
	s_waitcnt lgkmcnt(0)
	s_waitcnt lgkmcnt(0)
	v_mfma_f32_16x16x32_bf16 v[124:127], v[154:157], v[170:173], v[124:127]
	v_mfma_f32_16x16x32_bf16 v[120:123], v[162:165], v[170:173], v[120:123]
	v_mfma_f32_16x16x32_bf16 v[116:119], v[154:157], v[178:181], v[116:119]
	v_mfma_f32_16x16x32_bf16 v[112:115], v[162:165], v[178:181], v[112:115]
	v_mfma_f32_16x16x32_bf16 v[100:103], v[154:157], v[186:189], v[100:103]
	v_mfma_f32_16x16x32_bf16 v[96:99], v[162:165], v[186:189], v[96:99]
	v_mfma_f32_16x16x32_bf16 v[84:87], v[154:157], v[194:197], v[84:87]
	v_mfma_f32_16x16x32_bf16 v[80:83], v[162:165], v[194:197], v[80:83]
	v_mfma_f32_16x16x32_bf16 v[124:127], v[158:161], v[174:177], v[124:127]
	v_mfma_f32_16x16x32_bf16 v[120:123], v[166:169], v[174:177], v[120:123]
	v_mfma_f32_16x16x32_bf16 v[116:119], v[158:161], v[182:185], v[116:119]
	v_mfma_f32_16x16x32_bf16 v[112:115], v[166:169], v[182:185], v[112:115]
	v_mfma_f32_16x16x32_bf16 v[100:103], v[158:161], v[190:193], v[100:103]
	v_mfma_f32_16x16x32_bf16 v[96:99], v[166:169], v[190:193], v[96:99]
	v_mfma_f32_16x16x32_bf16 v[84:87], v[158:161], v[198:201], v[84:87]
	v_mfma_f32_16x16x32_bf16 v[80:83], v[166:169], v[198:201], v[80:83]
	s_barrier
	s_add_i32 s87, s72, s34
	v_lshl_add_u64 v[218:219], s[26:27], 0, v[134:135]
	s_mov_b32 m0, s87
	ds_read_b128 v[202:205], v152
	ds_read_b128 v[206:209], v152 offset:1024
	ds_read_b128 v[210:213], v152 offset:2048
	ds_read_b128 v[214:217], v152 offset:3072
	global_load_lds_dwordx4 v[218:219], off
	v_lshl_add_u64 v[220:221], s[26:27], 0, v[130:131]
	s_add_i32 m0, s87, 0x2000
	s_nop 0
	global_load_lds_dwordx4 v[220:221], off
	s_waitcnt vmcnt(10)
	s_barrier
	s_waitcnt lgkmcnt(0)
	s_waitcnt lgkmcnt(0)
	v_mfma_f32_16x16x32_bf16 v[108:111], v[202:205], v[170:173], v[108:111]
	v_mfma_f32_16x16x32_bf16 v[104:107], v[210:213], v[170:173], v[104:107]
	v_mfma_f32_16x16x32_bf16 v[92:95], v[202:205], v[178:181], v[92:95]
	v_mfma_f32_16x16x32_bf16 v[88:91], v[210:213], v[178:181], v[88:91]
	v_mfma_f32_16x16x32_bf16 v[76:79], v[202:205], v[186:189], v[76:79]
	v_mfma_f32_16x16x32_bf16 v[72:75], v[210:213], v[186:189], v[72:75]
	v_mfma_f32_16x16x32_bf16 v[68:71], v[202:205], v[194:197], v[68:71]
	v_mfma_f32_16x16x32_bf16 v[64:67], v[210:213], v[194:197], v[64:67]
	v_mfma_f32_16x16x32_bf16 v[108:111], v[206:209], v[174:177], v[108:111]
	v_mfma_f32_16x16x32_bf16 v[104:107], v[214:217], v[174:177], v[104:107]
	v_mfma_f32_16x16x32_bf16 v[92:95], v[206:209], v[182:185], v[92:95]
	v_mfma_f32_16x16x32_bf16 v[88:91], v[214:217], v[182:185], v[88:91]
	v_mfma_f32_16x16x32_bf16 v[76:79], v[206:209], v[190:193], v[76:79]
	v_mfma_f32_16x16x32_bf16 v[72:75], v[214:217], v[190:193], v[72:75]
	v_mfma_f32_16x16x32_bf16 v[68:71], v[206:209], v[198:201], v[68:71]
	v_mfma_f32_16x16x32_bf16 v[64:67], v[214:217], v[198:201], v[64:67]
	s_mov_b32 m0, s11
	v_lshl_add_u64 v[222:223], s[28:29], 0, v[136:137]
	s_barrier
	ds_read_b128 v[170:173], v151 offset:16384
	ds_read_b128 v[174:177], v151 offset:17408
	ds_read_b128 v[178:181], v151 offset:18432
	ds_read_b128 v[182:185], v151 offset:19456
	ds_read_b128 v[186:189], v151 offset:20480
	ds_read_b128 v[190:193], v151 offset:21504
	ds_read_b128 v[194:197], v151 offset:22528
	ds_read_b128 v[198:201], v151 offset:23552
	global_load_lds_dwordx4 v[222:223], off
	v_lshl_add_u64 v[224:225], s[28:29], 0, v[132:133]
	s_mov_b32 m0, s35
	s_nop 0
	global_load_lds_dwordx4 v[224:225], off
	s_waitcnt vmcnt(10)
	s_barrier
	s_waitcnt lgkmcnt(0)
	s_waitcnt lgkmcnt(0)
	v_mfma_f32_16x16x32_bf16 v[60:63], v[154:157], v[170:173], v[60:63]
	v_mfma_f32_16x16x32_bf16 v[56:59], v[162:165], v[170:173], v[56:59]
	v_mfma_f32_16x16x32_bf16 v[52:55], v[154:157], v[178:181], v[52:55]
	v_mfma_f32_16x16x32_bf16 v[48:51], v[162:165], v[178:181], v[48:51]
	v_mfma_f32_16x16x32_bf16 v[36:39], v[154:157], v[186:189], v[36:39]
	v_mfma_f32_16x16x32_bf16 v[32:35], v[162:165], v[186:189], v[32:35]
	v_mfma_f32_16x16x32_bf16 v[20:23], v[154:157], v[194:197], v[20:23]
	v_mfma_f32_16x16x32_bf16 v[16:19], v[162:165], v[194:197], v[16:19]
	v_mfma_f32_16x16x32_bf16 v[60:63], v[158:161], v[174:177], v[60:63]
	v_mfma_f32_16x16x32_bf16 v[56:59], v[166:169], v[174:177], v[56:59]
	v_mfma_f32_16x16x32_bf16 v[52:55], v[158:161], v[182:185], v[52:55]
	v_mfma_f32_16x16x32_bf16 v[48:51], v[166:169], v[182:185], v[48:51]
	v_mfma_f32_16x16x32_bf16 v[36:39], v[158:161], v[190:193], v[36:39]
	v_mfma_f32_16x16x32_bf16 v[32:35], v[166:169], v[190:193], v[32:35]
	v_mfma_f32_16x16x32_bf16 v[20:23], v[158:161], v[198:201], v[20:23]
	v_mfma_f32_16x16x32_bf16 v[16:19], v[166:169], v[198:201], v[16:19]
	s_barrier
	s_add_u32 s88, s26, 0x40000
	s_addc_u32 s89, s27, 0
	s_add_i32 s87, s73, s34
	v_lshl_add_u64 v[154:155], s[88:89], 0, v[134:135]
	s_mov_b32 m0, s87
	s_nop 0
	global_load_lds_dwordx4 v[154:155], off
	v_lshl_add_u64 v[154:155], s[88:89], 0, v[130:131]
	s_add_i32 m0, s87, 0x2000
	s_nop 0
	global_load_lds_dwordx4 v[154:155], off
	s_waitcnt vmcnt(10)
	s_barrier
	v_mfma_f32_16x16x32_bf16 v[44:47], v[202:205], v[170:173], v[44:47]
	v_mfma_f32_16x16x32_bf16 v[40:43], v[210:213], v[170:173], v[40:43]
	v_mfma_f32_16x16x32_bf16 v[28:31], v[202:205], v[178:181], v[28:31]
	v_mfma_f32_16x16x32_bf16 v[24:27], v[210:213], v[178:181], v[24:27]
	v_mfma_f32_16x16x32_bf16 v[12:15], v[202:205], v[186:189], v[12:15]
	v_mfma_f32_16x16x32_bf16 v[8:11], v[210:213], v[186:189], v[8:11]
	v_mfma_f32_16x16x32_bf16 v[4:7], v[202:205], v[194:197], v[4:7]
	v_mfma_f32_16x16x32_bf16 v[0:3], v[210:213], v[194:197], v[0:3]
	v_mfma_f32_16x16x32_bf16 v[44:47], v[206:209], v[174:177], v[44:47]
	v_mfma_f32_16x16x32_bf16 v[40:43], v[214:217], v[174:177], v[40:43]
	v_mfma_f32_16x16x32_bf16 v[28:31], v[206:209], v[182:185], v[28:31]
	v_mfma_f32_16x16x32_bf16 v[24:27], v[214:217], v[182:185], v[24:27]
	v_mfma_f32_16x16x32_bf16 v[12:15], v[206:209], v[190:193], v[12:15]
	v_mfma_f32_16x16x32_bf16 v[8:11], v[214:217], v[190:193], v[8:11]
	v_mfma_f32_16x16x32_bf16 v[4:7], v[206:209], v[198:201], v[4:7]
	v_mfma_f32_16x16x32_bf16 v[0:3], v[214:217], v[198:201], v[0:3]
	s_add_i32 s87, 0, 0x18000
	v_add_u32_e32 v153, s87, v148
	s_barrier
	ds_read_b128 v[154:157], v153
	ds_read_b128 v[158:161], v153 offset:1024
	ds_read_b128 v[162:165], v153 offset:2048
	ds_read_b128 v[166:169], v153 offset:3072
	s_add_u32 s28, s28, 0x40000
	s_addc_u32 s29, s29, 0
	s_mov_b32 m0, s54
	v_lshl_add_u64 v[202:203], s[28:29], 0, v[136:137]
	ds_read_b128 v[170:173], v151 offset:32768
	ds_read_b128 v[174:177], v151 offset:33792
	ds_read_b128 v[178:181], v151 offset:34816
	ds_read_b128 v[182:185], v151 offset:35840
	ds_read_b128 v[186:189], v151 offset:36864
	ds_read_b128 v[190:193], v151 offset:37888
	ds_read_b128 v[194:197], v151 offset:38912
	ds_read_b128 v[198:201], v151 offset:39936
	global_load_lds_dwordx4 v[202:203], off
	v_lshl_add_u64 v[202:203], s[28:29], 0, v[132:133]
	s_mov_b32 m0, s55
	s_nop 0
	global_load_lds_dwordx4 v[202:203], off
	s_waitcnt lgkmcnt(8)
	s_waitcnt vmcnt(10)
	s_barrier
	s_waitcnt lgkmcnt(0)
	s_waitcnt lgkmcnt(0)
	v_mfma_f32_16x16x32_bf16 v[124:127], v[154:157], v[170:173], v[124:127]
	v_mfma_f32_16x16x32_bf16 v[120:123], v[162:165], v[170:173], v[120:123]
	v_mfma_f32_16x16x32_bf16 v[116:119], v[154:157], v[178:181], v[116:119]
	v_mfma_f32_16x16x32_bf16 v[112:115], v[162:165], v[178:181], v[112:115]
	v_mfma_f32_16x16x32_bf16 v[100:103], v[154:157], v[186:189], v[100:103]
	v_mfma_f32_16x16x32_bf16 v[96:99], v[162:165], v[186:189], v[96:99]
	v_mfma_f32_16x16x32_bf16 v[84:87], v[154:157], v[194:197], v[84:87]
	v_mfma_f32_16x16x32_bf16 v[80:83], v[162:165], v[194:197], v[80:83]
	v_mfma_f32_16x16x32_bf16 v[124:127], v[158:161], v[174:177], v[124:127]
	v_mfma_f32_16x16x32_bf16 v[120:123], v[166:169], v[174:177], v[120:123]
	v_mfma_f32_16x16x32_bf16 v[116:119], v[158:161], v[182:185], v[116:119]
	v_mfma_f32_16x16x32_bf16 v[112:115], v[166:169], v[182:185], v[112:115]
	v_mfma_f32_16x16x32_bf16 v[100:103], v[158:161], v[190:193], v[100:103]
	v_mfma_f32_16x16x32_bf16 v[96:99], v[166:169], v[190:193], v[96:99]
	v_mfma_f32_16x16x32_bf16 v[84:87], v[158:161], v[198:201], v[84:87]
	v_mfma_f32_16x16x32_bf16 v[80:83], v[166:169], v[198:201], v[80:83]
	s_barrier
	s_add_i32 s28, 0, 0x1c000
	s_add_i32 s29, s87, s34
	v_add_u32_e32 v153, s28, v148
	v_lshl_add_u64 v[218:219], v[218:219], 0, s[8:9]
	s_mov_b32 m0, s29
	ds_read_b128 v[202:205], v153
	ds_read_b128 v[206:209], v153 offset:1024
	ds_read_b128 v[210:213], v153 offset:2048
	ds_read_b128 v[214:217], v153 offset:3072
	global_load_lds_dwordx4 v[218:219], off
	v_lshl_add_u64 v[218:219], v[220:221], 0, s[8:9]
	s_add_i32 m0, s29, 0x2000
	s_nop 0
	global_load_lds_dwordx4 v[218:219], off
	s_waitcnt vmcnt(10)
	s_barrier
	s_waitcnt lgkmcnt(0)
	s_waitcnt lgkmcnt(0)
	v_mfma_f32_16x16x32_bf16 v[108:111], v[202:205], v[170:173], v[108:111]
	v_mfma_f32_16x16x32_bf16 v[104:107], v[210:213], v[170:173], v[104:107]
	v_mfma_f32_16x16x32_bf16 v[92:95], v[202:205], v[178:181], v[92:95]
	v_mfma_f32_16x16x32_bf16 v[88:91], v[210:213], v[178:181], v[88:91]
	v_mfma_f32_16x16x32_bf16 v[76:79], v[202:205], v[186:189], v[76:79]
	v_mfma_f32_16x16x32_bf16 v[72:75], v[210:213], v[186:189], v[72:75]
	v_mfma_f32_16x16x32_bf16 v[68:71], v[202:205], v[194:197], v[68:71]
	v_mfma_f32_16x16x32_bf16 v[64:67], v[210:213], v[194:197], v[64:67]
	v_mfma_f32_16x16x32_bf16 v[108:111], v[206:209], v[174:177], v[108:111]
	v_mfma_f32_16x16x32_bf16 v[104:107], v[214:217], v[174:177], v[104:107]
	v_mfma_f32_16x16x32_bf16 v[92:95], v[206:209], v[182:185], v[92:95]
	v_mfma_f32_16x16x32_bf16 v[88:91], v[214:217], v[182:185], v[88:91]
	v_mfma_f32_16x16x32_bf16 v[76:79], v[206:209], v[190:193], v[76:79]
	v_mfma_f32_16x16x32_bf16 v[72:75], v[214:217], v[190:193], v[72:75]
	v_mfma_f32_16x16x32_bf16 v[68:71], v[206:209], v[198:201], v[68:71]
	v_mfma_f32_16x16x32_bf16 v[64:67], v[214:217], v[198:201], v[64:67]
	s_mov_b32 m0, s57
	v_lshl_add_u64 v[218:219], v[222:223], 0, s[8:9]
	s_barrier
	ds_read_b128 v[170:173], v151 offset:49152
	ds_read_b128 v[174:177], v151 offset:50176
	ds_read_b128 v[178:181], v151 offset:51200
	ds_read_b128 v[182:185], v151 offset:52224
	ds_read_b128 v[186:189], v151 offset:53248
	ds_read_b128 v[190:193], v151 offset:54272
	ds_read_b128 v[194:197], v151 offset:55296
	ds_read_b128 v[198:201], v151 offset:56320
	global_load_lds_dwordx4 v[218:219], off
	v_lshl_add_u64 v[218:219], v[224:225], 0, s[8:9]
	s_mov_b32 m0, s70
	s_nop 0
	global_load_lds_dwordx4 v[218:219], off
	s_waitcnt vmcnt(10)
	s_barrier
	s_waitcnt lgkmcnt(0)
	s_waitcnt lgkmcnt(0)
	v_mfma_f32_16x16x32_bf16 v[60:63], v[154:157], v[170:173], v[60:63]
	v_mfma_f32_16x16x32_bf16 v[56:59], v[162:165], v[170:173], v[56:59]
	v_mfma_f32_16x16x32_bf16 v[52:55], v[154:157], v[178:181], v[52:55]
	v_mfma_f32_16x16x32_bf16 v[48:51], v[162:165], v[178:181], v[48:51]
	v_mfma_f32_16x16x32_bf16 v[36:39], v[154:157], v[186:189], v[36:39]
	v_mfma_f32_16x16x32_bf16 v[32:35], v[162:165], v[186:189], v[32:35]
	v_mfma_f32_16x16x32_bf16 v[20:23], v[154:157], v[194:197], v[20:23]
	v_mfma_f32_16x16x32_bf16 v[16:19], v[162:165], v[194:197], v[16:19]
	v_mfma_f32_16x16x32_bf16 v[60:63], v[158:161], v[174:177], v[60:63]
	v_mfma_f32_16x16x32_bf16 v[56:59], v[166:169], v[174:177], v[56:59]
	v_mfma_f32_16x16x32_bf16 v[52:55], v[158:161], v[182:185], v[52:55]
	v_mfma_f32_16x16x32_bf16 v[48:51], v[166:169], v[182:185], v[48:51]
	v_mfma_f32_16x16x32_bf16 v[36:39], v[158:161], v[190:193], v[36:39]
	v_mfma_f32_16x16x32_bf16 v[32:35], v[166:169], v[190:193], v[32:35]
	v_mfma_f32_16x16x32_bf16 v[20:23], v[158:161], v[198:201], v[20:23]
	v_mfma_f32_16x16x32_bf16 v[16:19], v[166:169], v[198:201], v[16:19]
	s_barrier
	s_add_u32 s26, s26, 0x40080
	s_addc_u32 s27, s27, 0
	s_add_i32 s28, s28, s34
	v_lshl_add_u64 v[154:155], s[26:27], 0, v[134:135]
	s_mov_b32 m0, s28
	s_nop 0
	global_load_lds_dwordx4 v[154:155], off
	v_lshl_add_u64 v[154:155], s[26:27], 0, v[130:131]
	s_add_i32 m0, s28, 0x2000
	s_nop 0
	global_load_lds_dwordx4 v[154:155], off
	s_waitcnt vmcnt(10)
	s_barrier
	v_mfma_f32_16x16x32_bf16 v[44:47], v[202:205], v[170:173], v[44:47]
	v_mfma_f32_16x16x32_bf16 v[40:43], v[210:213], v[170:173], v[40:43]
	v_mfma_f32_16x16x32_bf16 v[28:31], v[202:205], v[178:181], v[28:31]
	v_mfma_f32_16x16x32_bf16 v[24:27], v[210:213], v[178:181], v[24:27]
	v_mfma_f32_16x16x32_bf16 v[12:15], v[202:205], v[186:189], v[12:15]
	v_mfma_f32_16x16x32_bf16 v[8:11], v[210:213], v[186:189], v[8:11]
	v_mfma_f32_16x16x32_bf16 v[4:7], v[202:205], v[194:197], v[4:7]
	v_mfma_f32_16x16x32_bf16 v[0:3], v[210:213], v[194:197], v[0:3]
	v_mfma_f32_16x16x32_bf16 v[44:47], v[206:209], v[174:177], v[44:47]
	v_mfma_f32_16x16x32_bf16 v[40:43], v[214:217], v[174:177], v[40:43]
	v_mfma_f32_16x16x32_bf16 v[28:31], v[206:209], v[182:185], v[28:31]
	v_mfma_f32_16x16x32_bf16 v[24:27], v[214:217], v[182:185], v[24:27]
	v_mfma_f32_16x16x32_bf16 v[12:15], v[206:209], v[190:193], v[12:15]
	v_mfma_f32_16x16x32_bf16 v[8:11], v[214:217], v[190:193], v[8:11]
	v_mfma_f32_16x16x32_bf16 v[4:7], v[206:209], v[198:201], v[4:7]
	v_mfma_f32_16x16x32_bf16 v[0:3], v[214:217], v[198:201], v[0:3]
	s_add_i32 s86, s86, 2
	s_add_u32 s20, s20, 0x100
	s_addc_u32 s21, s21, 0
	s_add_u32 s84, s84, 0x100
	s_addc_u32 s85, s85, 0
	s_cmp_gt_u32 s86, 13
	s_barrier
	s_cbranch_scc0 .LBB0_155
	v_lshl_add_u32 v153, s10, 8, v147
	v_lshl_or_b32 v154, s75, 8, v149
	v_mov_b64_e32 v[156:157], s[46:47]
	v_ashrrev_i32_e32 v155, 31, v154
	v_cvt_pk_bf16_f32 v68, v68, v69
	v_cvt_pk_bf16_f32 v69, v70, v71
	v_cvt_pk_bf16_f32 v70, v64, v65
	v_add_u32_e32 v64, 0x80, v153
	v_mad_i64_i32 v[158:159], s[20:21], v153, s74, v[156:157]
	v_cvt_pk_bf16_f32 v124, v124, v125
	v_cvt_pk_bf16_f32 v125, v126, v127
	v_cvt_pk_bf16_f32 v126, v120, v121
	v_lshlrev_b64 v[120:121], 1, v[154:155]
	v_mad_i64_i32 v[64:65], s[20:21], v64, s74, v[156:157]
	v_cvt_pk_bf16_f32 v127, v122, v123
	v_lshl_add_u64 v[122:123], v[158:159], 0, v[120:121]
	v_cvt_pk_bf16_f32 v108, v108, v109
	v_cvt_pk_bf16_f32 v109, v110, v111
	v_cvt_pk_bf16_f32 v110, v104, v105
	v_cvt_pk_bf16_f32 v111, v106, v107
	v_or_b32_e32 v104, 16, v153
	v_cvt_pk_bf16_f32 v60, v60, v61
	v_cvt_pk_bf16_f32 v61, v62, v63
	v_cvt_pk_bf16_f32 v62, v56, v57
	v_lshl_add_u64 v[56:57], v[64:65], 0, v[120:121]
	v_cvt_pk_bf16_f32 v44, v44, v45
	v_cvt_pk_bf16_f32 v45, v46, v47
	v_cvt_pk_bf16_f32 v46, v40, v41
	v_cvt_pk_bf16_f32 v47, v42, v43
	v_add_u32_e32 v40, 0x90, v153
	global_store_dwordx4 v[122:123], v[108:111], off offset:256
	global_store_dwordx4 v[56:57], v[44:47], off offset:256
	v_cvt_pk_bf16_f32 v92, v92, v93
	v_mad_i64_i32 v[108:109], s[20:21], v104, s74, v[156:157]
	v_mad_i64_i32 v[44:45], s[20:21], v40, s74, v[156:157]
	v_lshl_add_u64 v[108:109], v[108:109], 0, v[120:121]
	v_cvt_pk_bf16_f32 v93, v94, v95
	v_cvt_pk_bf16_f32 v94, v88, v89
	v_cvt_pk_bf16_f32 v95, v90, v91
	v_or_b32_e32 v88, 32, v153
	v_lshl_add_u64 v[44:45], v[44:45], 0, v[120:121]
	v_cvt_pk_bf16_f32 v28, v28, v29
	v_cvt_pk_bf16_f32 v29, v30, v31
	v_cvt_pk_bf16_f32 v30, v24, v25
	v_cvt_pk_bf16_f32 v31, v26, v27
	v_add_u32_e32 v24, 0xa0, v153
	global_store_dwordx4 v[108:109], v[92:95], off offset:256
	global_store_dwordx4 v[44:45], v[28:31], off offset:256
	v_cvt_pk_bf16_f32 v76, v76, v77
	v_mad_i64_i32 v[92:93], s[20:21], v88, s74, v[156:157]
	v_mad_i64_i32 v[28:29], s[20:21], v24, s74, v[156:157]
	v_lshl_add_u64 v[92:93], v[92:93], 0, v[120:121]
	v_cvt_pk_bf16_f32 v77, v78, v79
	v_cvt_pk_bf16_f32 v78, v72, v73
	v_cvt_pk_bf16_f32 v79, v74, v75
	v_or_b32_e32 v72, 48, v153
	v_lshl_add_u64 v[28:29], v[28:29], 0, v[120:121]
	v_cvt_pk_bf16_f32 v12, v12, v13
	v_cvt_pk_bf16_f32 v13, v14, v15
	v_cvt_pk_bf16_f32 v14, v8, v9
	v_cvt_pk_bf16_f32 v15, v10, v11
	v_add_u32_e32 v8, 0xb0, v153
	global_store_dwordx4 v[92:93], v[76:79], off offset:256
	global_store_dwordx4 v[28:29], v[12:15], off offset:256
	v_cvt_pk_bf16_f32 v104, v116, v117
	v_mad_i64_i32 v[76:77], s[20:21], v72, s74, v[156:157]
	v_mad_i64_i32 v[12:13], s[20:21], v8, s74, v[156:157]
	v_cvt_pk_bf16_f32 v105, v118, v119
	v_cvt_pk_bf16_f32 v106, v112, v113
	v_cvt_pk_bf16_f32 v107, v114, v115
	v_cvt_pk_bf16_f32 v88, v100, v101
	v_cvt_pk_bf16_f32 v89, v102, v103
	v_cvt_pk_bf16_f32 v90, v96, v97
	v_cvt_pk_bf16_f32 v91, v98, v99
	v_cvt_pk_bf16_f32 v72, v84, v85
	v_cvt_pk_bf16_f32 v73, v86, v87
	v_cvt_pk_bf16_f32 v74, v80, v81
	v_cvt_pk_bf16_f32 v75, v82, v83
	v_lshl_add_u64 v[76:77], v[76:77], 0, v[120:121]
	v_cvt_pk_bf16_f32 v71, v66, v67
	v_cvt_pk_bf16_f32 v63, v58, v59
	v_cvt_pk_bf16_f32 v40, v52, v53
	v_cvt_pk_bf16_f32 v41, v54, v55
	v_cvt_pk_bf16_f32 v42, v48, v49
	v_cvt_pk_bf16_f32 v43, v50, v51
	v_cvt_pk_bf16_f32 v24, v36, v37
	v_cvt_pk_bf16_f32 v25, v38, v39
	v_cvt_pk_bf16_f32 v26, v32, v33
	v_cvt_pk_bf16_f32 v27, v34, v35
	v_cvt_pk_bf16_f32 v8, v20, v21
	v_cvt_pk_bf16_f32 v9, v22, v23
	v_cvt_pk_bf16_f32 v10, v16, v17
	v_cvt_pk_bf16_f32 v11, v18, v19
	v_lshl_add_u64 v[12:13], v[12:13], 0, v[120:121]
	v_cvt_pk_bf16_f32 v4, v4, v5
	v_cvt_pk_bf16_f32 v5, v6, v7
	v_cvt_pk_bf16_f32 v6, v0, v1
	v_cvt_pk_bf16_f32 v7, v2, v3
	s_and_b64 vcc, exec, s[4:5]
	s_mov_b32 s75, s12
	s_mov_b32 s10, s14
	s_mov_b64 s[26:27], s[18:19]
	s_mov_b64 s[20:21], s[16:17]
	global_store_dwordx4 v[122:123], v[124:127], off
	global_store_dwordx4 v[108:109], v[104:107], off
	global_store_dwordx4 v[92:93], v[88:91], off
	global_store_dwordx4 v[76:77], v[72:75], off
	global_store_dwordx4 v[76:77], v[68:71], off offset:256
	global_store_dwordx4 v[56:57], v[60:63], off
	global_store_dwordx4 v[44:45], v[40:43], off
	global_store_dwordx4 v[28:29], v[24:27], off
	global_store_dwordx4 v[12:13], v[8:11], off
	global_store_dwordx4 v[12:13], v[4:7], off offset:256
	s_cbranch_vccz .LBB0_152
	s_waitcnt vmcnt(16)
	s_cmpk_gt_u32 s30, 0xff
	s_cbranch_scc1 .LBB0_159
	s_barrier

.LBB0_486:
	ds_read_b128 v[154:157], v151
	ds_read_b128 v[158:161], v151 offset:1024
	ds_read_b128 v[162:165], v151 offset:2048
	ds_read_b128 v[166:169], v151 offset:3072
	s_add_u32 s30, s28, 0xfffc0080
	s_addc_u32 s31, s29, -1
	s_cmp_eq_u32 s84, 12
	s_cselect_b32 s35, s19, s31
	s_cselect_b32 s34, s80, s30
	s_cselect_b32 s31, s17, s83
	s_cselect_b32 s30, s81, s82
	v_lshl_add_u64 v[202:203], s[28:29], 0, v[138:139]
	s_add_i32 m0, s15, 0xc000
	ds_read_b128 v[170:173], v152
	ds_read_b128 v[174:177], v152 offset:1024
	ds_read_b128 v[178:181], v152 offset:2048
	ds_read_b128 v[182:185], v152 offset:3072
	ds_read_b128 v[186:189], v152 offset:4096
	ds_read_b128 v[190:193], v152 offset:5120
	ds_read_b128 v[194:197], v152 offset:6144
	ds_read_b128 v[198:201], v152 offset:7168
	global_load_lds_dwordx4 v[202:203], off
	v_lshl_add_u64 v[202:203], s[28:29], 0, v[140:141]
	s_add_i32 m0, s15, 0xe000
	s_nop 0
	global_load_lds_dwordx4 v[202:203], off
	s_waitcnt lgkmcnt(8)
	s_waitcnt vmcnt(10)
	s_barrier
	s_waitcnt lgkmcnt(0)
	s_waitcnt lgkmcnt(0)
	v_mfma_f32_16x16x32_bf16 v[124:127], v[154:157], v[170:173], v[124:127]
	v_mfma_f32_16x16x32_bf16 v[120:123], v[162:165], v[170:173], v[120:123]
	v_mfma_f32_16x16x32_bf16 v[116:119], v[154:157], v[178:181], v[116:119]
	v_mfma_f32_16x16x32_bf16 v[112:115], v[162:165], v[178:181], v[112:115]
	v_mfma_f32_16x16x32_bf16 v[100:103], v[154:157], v[186:189], v[100:103]
	v_mfma_f32_16x16x32_bf16 v[96:99], v[162:165], v[186:189], v[96:99]
	v_mfma_f32_16x16x32_bf16 v[84:87], v[154:157], v[194:197], v[84:87]
	v_mfma_f32_16x16x32_bf16 v[80:83], v[162:165], v[194:197], v[80:83]
	v_mfma_f32_16x16x32_bf16 v[124:127], v[158:161], v[174:177], v[124:127]
	v_mfma_f32_16x16x32_bf16 v[120:123], v[166:169], v[174:177], v[120:123]
	v_mfma_f32_16x16x32_bf16 v[116:119], v[158:161], v[182:185], v[116:119]
	v_mfma_f32_16x16x32_bf16 v[112:115], v[166:169], v[182:185], v[112:115]
	v_mfma_f32_16x16x32_bf16 v[100:103], v[158:161], v[190:193], v[100:103]
	v_mfma_f32_16x16x32_bf16 v[96:99], v[166:169], v[190:193], v[96:99]
	v_mfma_f32_16x16x32_bf16 v[84:87], v[158:161], v[198:201], v[84:87]
	v_mfma_f32_16x16x32_bf16 v[80:83], v[166:169], v[198:201], v[80:83]
	s_barrier
	s_add_i32 s85, s74, s55
	v_lshl_add_u64 v[218:219], s[30:31], 0, v[134:135]
	s_mov_b32 m0, s85
	ds_read_b128 v[202:205], v153
	ds_read_b128 v[206:209], v153 offset:1024
	ds_read_b128 v[210:213], v153 offset:2048
	ds_read_b128 v[214:217], v153 offset:3072
	global_load_lds_dwordx4 v[218:219], off
	v_lshl_add_u64 v[220:221], s[30:31], 0, v[130:131]
	s_add_i32 m0, s85, 0x2000
	s_nop 0
	global_load_lds_dwordx4 v[220:221], off
	s_waitcnt vmcnt(10)
	s_barrier
	s_waitcnt lgkmcnt(0)
	s_waitcnt lgkmcnt(0)
	v_mfma_f32_16x16x32_bf16 v[108:111], v[202:205], v[170:173], v[108:111]
	v_mfma_f32_16x16x32_bf16 v[104:107], v[210:213], v[170:173], v[104:107]
	v_mfma_f32_16x16x32_bf16 v[92:95], v[202:205], v[178:181], v[92:95]
	v_mfma_f32_16x16x32_bf16 v[88:91], v[210:213], v[178:181], v[88:91]
	v_mfma_f32_16x16x32_bf16 v[76:79], v[202:205], v[186:189], v[76:79]
	v_mfma_f32_16x16x32_bf16 v[72:75], v[210:213], v[186:189], v[72:75]
	v_mfma_f32_16x16x32_bf16 v[68:71], v[202:205], v[194:197], v[68:71]
	v_mfma_f32_16x16x32_bf16 v[64:67], v[210:213], v[194:197], v[64:67]
	v_mfma_f32_16x16x32_bf16 v[108:111], v[206:209], v[174:177], v[108:111]
	v_mfma_f32_16x16x32_bf16 v[104:107], v[214:217], v[174:177], v[104:107]
	v_mfma_f32_16x16x32_bf16 v[92:95], v[206:209], v[182:185], v[92:95]
	v_mfma_f32_16x16x32_bf16 v[88:91], v[214:217], v[182:185], v[88:91]
	v_mfma_f32_16x16x32_bf16 v[76:79], v[206:209], v[190:193], v[76:79]
	v_mfma_f32_16x16x32_bf16 v[72:75], v[214:217], v[190:193], v[72:75]
	v_mfma_f32_16x16x32_bf16 v[68:71], v[206:209], v[198:201], v[68:71]
	v_mfma_f32_16x16x32_bf16 v[64:67], v[214:217], v[198:201], v[64:67]
	s_mov_b32 m0, s15
	v_lshl_add_u64 v[222:223], s[34:35], 0, v[136:137]
	s_barrier
	ds_read_b128 v[170:173], v152 offset:16384
	ds_read_b128 v[174:177], v152 offset:17408
	ds_read_b128 v[178:181], v152 offset:18432
	ds_read_b128 v[182:185], v152 offset:19456
	ds_read_b128 v[186:189], v152 offset:20480
	ds_read_b128 v[190:193], v152 offset:21504
	ds_read_b128 v[194:197], v152 offset:22528
	ds_read_b128 v[198:201], v152 offset:23552
	global_load_lds_dwordx4 v[222:223], off
	v_lshl_add_u64 v[224:225], s[34:35], 0, v[132:133]
	s_mov_b32 m0, s57
	s_nop 0
	global_load_lds_dwordx4 v[224:225], off
	s_waitcnt vmcnt(10)
	s_barrier
	s_waitcnt lgkmcnt(0)
	s_waitcnt lgkmcnt(0)
	v_mfma_f32_16x16x32_bf16 v[60:63], v[154:157], v[170:173], v[60:63]
	v_mfma_f32_16x16x32_bf16 v[56:59], v[162:165], v[170:173], v[56:59]
	v_mfma_f32_16x16x32_bf16 v[52:55], v[154:157], v[178:181], v[52:55]
	v_mfma_f32_16x16x32_bf16 v[48:51], v[162:165], v[178:181], v[48:51]
	v_mfma_f32_16x16x32_bf16 v[36:39], v[154:157], v[186:189], v[36:39]
	v_mfma_f32_16x16x32_bf16 v[32:35], v[162:165], v[186:189], v[32:35]
	v_mfma_f32_16x16x32_bf16 v[20:23], v[154:157], v[194:197], v[20:23]
	v_mfma_f32_16x16x32_bf16 v[16:19], v[162:165], v[194:197], v[16:19]
	v_mfma_f32_16x16x32_bf16 v[60:63], v[158:161], v[174:177], v[60:63]
	v_mfma_f32_16x16x32_bf16 v[56:59], v[166:169], v[174:177], v[56:59]
	v_mfma_f32_16x16x32_bf16 v[52:55], v[158:161], v[182:185], v[52:55]
	v_mfma_f32_16x16x32_bf16 v[48:51], v[166:169], v[182:185], v[48:51]
	v_mfma_f32_16x16x32_bf16 v[36:39], v[158:161], v[190:193], v[36:39]
	v_mfma_f32_16x16x32_bf16 v[32:35], v[166:169], v[190:193], v[32:35]
	v_mfma_f32_16x16x32_bf16 v[20:23], v[158:161], v[198:201], v[20:23]
	v_mfma_f32_16x16x32_bf16 v[16:19], v[166:169], v[198:201], v[16:19]
	s_barrier
	s_add_u32 s86, s30, 0x40000
	s_addc_u32 s87, s31, 0
	s_add_i32 s85, s75, s55
	v_lshl_add_u64 v[154:155], s[86:87], 0, v[134:135]
	s_mov_b32 m0, s85
	s_nop 0
	global_load_lds_dwordx4 v[154:155], off
	v_lshl_add_u64 v[154:155], s[86:87], 0, v[130:131]
	s_add_i32 m0, s85, 0x2000
	s_nop 0
	global_load_lds_dwordx4 v[154:155], off
	s_waitcnt vmcnt(10)
	s_barrier
	v_mfma_f32_16x16x32_bf16 v[44:47], v[202:205], v[170:173], v[44:47]
	v_mfma_f32_16x16x32_bf16 v[40:43], v[210:213], v[170:173], v[40:43]
	v_mfma_f32_16x16x32_bf16 v[28:31], v[202:205], v[178:181], v[28:31]
	v_mfma_f32_16x16x32_bf16 v[24:27], v[210:213], v[178:181], v[24:27]
	v_mfma_f32_16x16x32_bf16 v[12:15], v[202:205], v[186:189], v[12:15]
	v_mfma_f32_16x16x32_bf16 v[8:11], v[210:213], v[186:189], v[8:11]
	v_mfma_f32_16x16x32_bf16 v[4:7], v[202:205], v[194:197], v[4:7]
	v_mfma_f32_16x16x32_bf16 v[0:3], v[210:213], v[194:197], v[0:3]
	v_mfma_f32_16x16x32_bf16 v[44:47], v[206:209], v[174:177], v[44:47]
	v_mfma_f32_16x16x32_bf16 v[40:43], v[214:217], v[174:177], v[40:43]
	v_mfma_f32_16x16x32_bf16 v[28:31], v[206:209], v[182:185], v[28:31]
	v_mfma_f32_16x16x32_bf16 v[24:27], v[214:217], v[182:185], v[24:27]
	v_mfma_f32_16x16x32_bf16 v[12:15], v[206:209], v[190:193], v[12:15]
	v_mfma_f32_16x16x32_bf16 v[8:11], v[214:217], v[190:193], v[8:11]
	v_mfma_f32_16x16x32_bf16 v[4:7], v[206:209], v[198:201], v[4:7]
	v_mfma_f32_16x16x32_bf16 v[0:3], v[214:217], v[198:201], v[0:3]
	s_add_i32 s85, 0, 0x18000
	v_add_u32_e32 v166, s85, v149
	s_barrier
	ds_read_b128 v[154:157], v166
	ds_read_b128 v[158:161], v166 offset:1024
	ds_read_b128 v[162:165], v166 offset:2048
	ds_read_b128 v[166:169], v166 offset:3072
	s_add_u32 s34, s34, 0x40000
	s_addc_u32 s35, s35, 0
	s_mov_b32 m0, s60
	v_lshl_add_u64 v[202:203], s[34:35], 0, v[136:137]
	ds_read_b128 v[170:173], v152 offset:32768
	ds_read_b128 v[174:177], v152 offset:33792
	ds_read_b128 v[178:181], v152 offset:34816
	ds_read_b128 v[182:185], v152 offset:35840
	ds_read_b128 v[186:189], v152 offset:36864
	ds_read_b128 v[190:193], v152 offset:37888
	ds_read_b128 v[194:197], v152 offset:38912
	ds_read_b128 v[198:201], v152 offset:39936
	global_load_lds_dwordx4 v[202:203], off
	v_lshl_add_u64 v[202:203], s[34:35], 0, v[132:133]
	s_mov_b32 m0, s61
	s_nop 0
	global_load_lds_dwordx4 v[202:203], off
	s_waitcnt lgkmcnt(8)
	s_waitcnt vmcnt(10)
	s_barrier
	s_waitcnt lgkmcnt(0)
	s_waitcnt lgkmcnt(0)
	v_mfma_f32_16x16x32_bf16 v[124:127], v[154:157], v[170:173], v[124:127]
	v_mfma_f32_16x16x32_bf16 v[120:123], v[162:165], v[170:173], v[120:123]
	v_mfma_f32_16x16x32_bf16 v[116:119], v[154:157], v[178:181], v[116:119]
	v_mfma_f32_16x16x32_bf16 v[112:115], v[162:165], v[178:181], v[112:115]
	v_mfma_f32_16x16x32_bf16 v[100:103], v[154:157], v[186:189], v[100:103]
	v_mfma_f32_16x16x32_bf16 v[96:99], v[162:165], v[186:189], v[96:99]
	v_mfma_f32_16x16x32_bf16 v[84:87], v[154:157], v[194:197], v[84:87]
	v_mfma_f32_16x16x32_bf16 v[80:83], v[162:165], v[194:197], v[80:83]
	v_mfma_f32_16x16x32_bf16 v[124:127], v[158:161], v[174:177], v[124:127]
	v_mfma_f32_16x16x32_bf16 v[120:123], v[166:169], v[174:177], v[120:123]
	v_mfma_f32_16x16x32_bf16 v[116:119], v[158:161], v[182:185], v[116:119]
	v_mfma_f32_16x16x32_bf16 v[112:115], v[166:169], v[182:185], v[112:115]
	v_mfma_f32_16x16x32_bf16 v[100:103], v[158:161], v[190:193], v[100:103]
	v_mfma_f32_16x16x32_bf16 v[96:99], v[166:169], v[190:193], v[96:99]
	v_mfma_f32_16x16x32_bf16 v[84:87], v[158:161], v[198:201], v[84:87]
	v_mfma_f32_16x16x32_bf16 v[80:83], v[166:169], v[198:201], v[80:83]
	s_barrier
	s_add_i32 s34, 0, 0x1c000
	s_add_i32 s35, s85, s55
	v_add_u32_e32 v214, s34, v149
	v_lshl_add_u64 v[218:219], v[218:219], 0, s[8:9]
	s_mov_b32 m0, s35
	ds_read_b128 v[202:205], v214
	ds_read_b128 v[206:209], v214 offset:1024
	ds_read_b128 v[210:213], v214 offset:2048
	ds_read_b128 v[214:217], v214 offset:3072
	global_load_lds_dwordx4 v[218:219], off
	v_lshl_add_u64 v[218:219], v[220:221], 0, s[8:9]
	s_add_i32 m0, s35, 0x2000
	s_nop 0
	global_load_lds_dwordx4 v[218:219], off
	s_waitcnt vmcnt(10)
	s_barrier
	s_waitcnt lgkmcnt(0)
	s_waitcnt lgkmcnt(0)
	v_mfma_f32_16x16x32_bf16 v[108:111], v[202:205], v[170:173], v[108:111]
	v_mfma_f32_16x16x32_bf16 v[104:107], v[210:213], v[170:173], v[104:107]
	v_mfma_f32_16x16x32_bf16 v[92:95], v[202:205], v[178:181], v[92:95]
	v_mfma_f32_16x16x32_bf16 v[88:91], v[210:213], v[178:181], v[88:91]
	v_mfma_f32_16x16x32_bf16 v[76:79], v[202:205], v[186:189], v[76:79]
	v_mfma_f32_16x16x32_bf16 v[72:75], v[210:213], v[186:189], v[72:75]
	v_mfma_f32_16x16x32_bf16 v[68:71], v[202:205], v[194:197], v[68:71]
	v_mfma_f32_16x16x32_bf16 v[64:67], v[210:213], v[194:197], v[64:67]
	v_mfma_f32_16x16x32_bf16 v[108:111], v[206:209], v[174:177], v[108:111]
	v_mfma_f32_16x16x32_bf16 v[104:107], v[214:217], v[174:177], v[104:107]
	v_mfma_f32_16x16x32_bf16 v[92:95], v[206:209], v[182:185], v[92:95]
	v_mfma_f32_16x16x32_bf16 v[88:91], v[214:217], v[182:185], v[88:91]
	v_mfma_f32_16x16x32_bf16 v[76:79], v[206:209], v[190:193], v[76:79]
	v_mfma_f32_16x16x32_bf16 v[72:75], v[214:217], v[190:193], v[72:75]
	v_mfma_f32_16x16x32_bf16 v[68:71], v[206:209], v[198:201], v[68:71]
	v_mfma_f32_16x16x32_bf16 v[64:67], v[214:217], v[198:201], v[64:67]
	s_mov_b32 m0, s71
	v_lshl_add_u64 v[218:219], v[222:223], 0, s[8:9]
	s_barrier
	ds_read_b128 v[170:173], v152 offset:49152
	ds_read_b128 v[174:177], v152 offset:50176
	ds_read_b128 v[178:181], v152 offset:51200
	ds_read_b128 v[182:185], v152 offset:52224
	ds_read_b128 v[186:189], v152 offset:53248
	ds_read_b128 v[190:193], v152 offset:54272
	ds_read_b128 v[194:197], v152 offset:55296
	ds_read_b128 v[198:201], v152 offset:56320
	global_load_lds_dwordx4 v[218:219], off
	v_lshl_add_u64 v[218:219], v[224:225], 0, s[8:9]
	s_mov_b32 m0, s72
	s_nop 0
	global_load_lds_dwordx4 v[218:219], off
	s_waitcnt vmcnt(10)
	s_barrier
	s_waitcnt lgkmcnt(0)
	s_waitcnt lgkmcnt(0)
	v_mfma_f32_16x16x32_bf16 v[60:63], v[154:157], v[170:173], v[60:63]
	v_mfma_f32_16x16x32_bf16 v[56:59], v[162:165], v[170:173], v[56:59]
	v_mfma_f32_16x16x32_bf16 v[52:55], v[154:157], v[178:181], v[52:55]
	v_mfma_f32_16x16x32_bf16 v[48:51], v[162:165], v[178:181], v[48:51]
	v_mfma_f32_16x16x32_bf16 v[36:39], v[154:157], v[186:189], v[36:39]
	v_mfma_f32_16x16x32_bf16 v[32:35], v[162:165], v[186:189], v[32:35]
	v_mfma_f32_16x16x32_bf16 v[20:23], v[154:157], v[194:197], v[20:23]
	v_mfma_f32_16x16x32_bf16 v[16:19], v[162:165], v[194:197], v[16:19]
	v_mfma_f32_16x16x32_bf16 v[60:63], v[158:161], v[174:177], v[60:63]
	v_mfma_f32_16x16x32_bf16 v[56:59], v[166:169], v[174:177], v[56:59]
	v_mfma_f32_16x16x32_bf16 v[52:55], v[158:161], v[182:185], v[52:55]
	v_mfma_f32_16x16x32_bf16 v[48:51], v[166:169], v[182:185], v[48:51]
	v_mfma_f32_16x16x32_bf16 v[36:39], v[158:161], v[190:193], v[36:39]
	v_mfma_f32_16x16x32_bf16 v[32:35], v[166:169], v[190:193], v[32:35]
	v_mfma_f32_16x16x32_bf16 v[20:23], v[158:161], v[198:201], v[20:23]
	v_mfma_f32_16x16x32_bf16 v[16:19], v[166:169], v[198:201], v[16:19]
	s_barrier
	s_add_u32 s30, s30, 0x40080
	s_addc_u32 s31, s31, 0
	s_add_i32 s34, s34, s55
	v_lshl_add_u64 v[154:155], s[30:31], 0, v[134:135]
	s_mov_b32 m0, s34
	s_nop 0
	global_load_lds_dwordx4 v[154:155], off
	v_lshl_add_u64 v[154:155], s[30:31], 0, v[130:131]
	s_add_i32 m0, s34, 0x2000
	s_nop 0
	global_load_lds_dwordx4 v[154:155], off
	s_waitcnt vmcnt(10)
	s_barrier
	v_mfma_f32_16x16x32_bf16 v[44:47], v[202:205], v[170:173], v[44:47]
	v_mfma_f32_16x16x32_bf16 v[40:43], v[210:213], v[170:173], v[40:43]
	v_mfma_f32_16x16x32_bf16 v[28:31], v[202:205], v[178:181], v[28:31]
	v_mfma_f32_16x16x32_bf16 v[24:27], v[210:213], v[178:181], v[24:27]
	v_mfma_f32_16x16x32_bf16 v[12:15], v[202:205], v[186:189], v[12:15]
	v_mfma_f32_16x16x32_bf16 v[8:11], v[210:213], v[186:189], v[8:11]
	v_mfma_f32_16x16x32_bf16 v[4:7], v[202:205], v[194:197], v[4:7]
	v_mfma_f32_16x16x32_bf16 v[0:3], v[210:213], v[194:197], v[0:3]
	v_mfma_f32_16x16x32_bf16 v[44:47], v[206:209], v[174:177], v[44:47]
	v_mfma_f32_16x16x32_bf16 v[40:43], v[214:217], v[174:177], v[40:43]
	v_mfma_f32_16x16x32_bf16 v[28:31], v[206:209], v[182:185], v[28:31]
	v_mfma_f32_16x16x32_bf16 v[24:27], v[214:217], v[182:185], v[24:27]
	v_mfma_f32_16x16x32_bf16 v[12:15], v[206:209], v[190:193], v[12:15]
	v_mfma_f32_16x16x32_bf16 v[8:11], v[214:217], v[190:193], v[8:11]
	v_mfma_f32_16x16x32_bf16 v[4:7], v[206:209], v[198:201], v[4:7]
	v_mfma_f32_16x16x32_bf16 v[0:3], v[214:217], v[198:201], v[0:3]
	s_add_i32 s84, s84, 2
	s_add_u32 s28, s28, 0x100
	s_addc_u32 s29, s29, 0
	s_add_u32 s82, s82, 0x100
	s_addc_u32 s83, s83, 0
	s_cmp_gt_u32 s84, 13
	s_barrier
	s_cbranch_scc0 .LBB0_486
	v_lshl_add_u32 v154, s14, 8, v148
	v_lshl_or_b32 v156, s79, 8, v150
	v_ashrrev_i32_e32 v155, 31, v154
	v_lshlrev_b64 v[158:159], 11, v[154:155]
	v_ashrrev_i32_e32 v157, 31, v156
	v_lshl_add_u64 v[158:159], s[46:47], 0, v[158:159]
	v_cvt_pk_bf16_f32 v124, v124, v125
	v_cvt_pk_bf16_f32 v125, v126, v127
	v_cvt_pk_bf16_f32 v126, v120, v121
	v_lshlrev_b64 v[120:121], 1, v[156:157]
	v_cvt_pk_bf16_f32 v127, v122, v123
	v_lshl_add_u64 v[122:123], v[158:159], 0, v[120:121]
	s_mov_b32 s14, 0x40000
	v_cvt_pk_bf16_f32 v108, v108, v109
	v_cvt_pk_bf16_f32 v109, v110, v111
	v_cvt_pk_bf16_f32 v110, v104, v105
	v_or_b32_e32 v104, 16, v154
	v_cvt_pk_bf16_f32 v60, v60, v61
	v_cvt_pk_bf16_f32 v61, v62, v63
	v_cvt_pk_bf16_f32 v63, v58, v59
	s_mov_b64 s[28:29], 0x40000
	v_add_co_u32_e32 v58, vcc, s14, v122
	v_ashrrev_i32_e32 v105, 31, v104
	v_cvt_pk_bf16_f32 v62, v56, v57
	v_lshl_add_u64 v[56:57], v[122:123], 0, s[28:29]
	v_addc_co_u32_e32 v59, vcc, 0, v123, vcc
	v_cvt_pk_bf16_f32 v44, v44, v45
	v_cvt_pk_bf16_f32 v45, v46, v47
	v_cvt_pk_bf16_f32 v46, v40, v41
	v_cvt_pk_bf16_f32 v47, v42, v43
	v_cvt_pk_bf16_f32 v111, v106, v107
	v_lshlrev_b64 v[104:105], 11, v[104:105]
	v_cvt_pk_bf16_f32 v92, v92, v93
	v_cvt_pk_bf16_f32 v93, v94, v95
	v_cvt_pk_bf16_f32 v94, v88, v89
	v_or_b32_e32 v88, 32, v154
	global_store_dwordx4 v[56:57], v[44:47], off offset:256
	s_mov_b64 s[28:29], 0x48000
	global_store_dwordx4 v[122:123], v[108:111], off offset:256
	v_add_co_u32_e32 v46, vcc, s76, v122
	s_nop 0
	v_lshl_add_u64 v[108:109], s[46:47], 0, v[104:105]
	v_ashrrev_i32_e32 v89, 31, v88
	v_lshl_add_u64 v[44:45], v[122:123], 0, s[28:29]
	v_addc_co_u32_e32 v47, vcc, 0, v123, vcc
	v_cvt_pk_bf16_f32 v28, v28, v29
	v_cvt_pk_bf16_f32 v29, v30, v31
	v_cvt_pk_bf16_f32 v30, v24, v25
	v_cvt_pk_bf16_f32 v31, v26, v27
	v_lshl_add_u64 v[108:109], v[108:109], 0, v[120:121]
	v_cvt_pk_bf16_f32 v95, v90, v91
	v_lshlrev_b64 v[88:89], 11, v[88:89]
	v_cvt_pk_bf16_f32 v76, v76, v77
	v_cvt_pk_bf16_f32 v77, v78, v79
	v_cvt_pk_bf16_f32 v78, v72, v73
	v_or_b32_e32 v72, 48, v154
	global_store_dwordx4 v[44:45], v[28:31], off offset:256
	global_store_dwordx4 v[108:109], v[92:95], off offset:256
	v_ashrrev_i32_e32 v73, 31, v72
	v_add_co_u32_e32 v30, vcc, s77, v122
	v_lshl_add_u64 v[92:93], s[46:47], 0, v[88:89]
	v_lshl_add_u64 v[28:29], v[122:123], 0, s[10:11]
	v_addc_co_u32_e32 v31, vcc, 0, v123, vcc
	v_cvt_pk_bf16_f32 v12, v12, v13
	v_cvt_pk_bf16_f32 v13, v14, v15
	v_cvt_pk_bf16_f32 v14, v8, v9
	v_cvt_pk_bf16_f32 v15, v10, v11
	v_lshl_add_u64 v[92:93], v[92:93], 0, v[120:121]
	v_cvt_pk_bf16_f32 v79, v74, v75
	v_lshlrev_b64 v[72:73], 11, v[72:73]
	global_store_dwordx4 v[28:29], v[12:15], off offset:256
	global_store_dwordx4 v[92:93], v[76:79], off offset:256
	v_cvt_pk_bf16_f32 v104, v116, v117
	v_add_co_u32_e32 v14, vcc, s78, v122
	v_lshl_add_u64 v[76:77], s[46:47], 0, v[72:73]
	s_nop 0
	v_addc_co_u32_e32 v15, vcc, 0, v123, vcc
	v_cvt_pk_bf16_f32 v105, v118, v119
	v_cvt_pk_bf16_f32 v106, v112, v113
	v_cvt_pk_bf16_f32 v107, v114, v115
	v_cvt_pk_bf16_f32 v88, v100, v101
	v_cvt_pk_bf16_f32 v89, v102, v103
	v_cvt_pk_bf16_f32 v90, v96, v97
	v_cvt_pk_bf16_f32 v91, v98, v99
	v_cvt_pk_bf16_f32 v72, v84, v85
	v_cvt_pk_bf16_f32 v73, v86, v87
	v_cvt_pk_bf16_f32 v74, v80, v81
	v_cvt_pk_bf16_f32 v75, v82, v83
	v_lshl_add_u64 v[76:77], v[76:77], 0, v[120:121]
	v_cvt_pk_bf16_f32 v68, v68, v69
	v_cvt_pk_bf16_f32 v69, v70, v71
	v_cvt_pk_bf16_f32 v70, v64, v65
	v_cvt_pk_bf16_f32 v71, v66, v67
	v_cvt_pk_bf16_f32 v40, v52, v53
	v_cvt_pk_bf16_f32 v41, v54, v55
	v_cvt_pk_bf16_f32 v42, v48, v49
	v_cvt_pk_bf16_f32 v43, v50, v51
	v_cvt_pk_bf16_f32 v24, v36, v37
	v_cvt_pk_bf16_f32 v25, v38, v39
	v_cvt_pk_bf16_f32 v26, v32, v33
	v_cvt_pk_bf16_f32 v27, v34, v35
	v_cvt_pk_bf16_f32 v8, v20, v21
	v_cvt_pk_bf16_f32 v9, v22, v23
	v_cvt_pk_bf16_f32 v10, v16, v17
	v_cvt_pk_bf16_f32 v11, v18, v19
	v_lshl_add_u64 v[12:13], v[122:123], 0, s[12:13]
	v_cvt_pk_bf16_f32 v4, v4, v5
	v_cvt_pk_bf16_f32 v5, v6, v7
	v_cvt_pk_bf16_f32 v6, v0, v1
	v_cvt_pk_bf16_f32 v7, v2, v3
	s_and_b64 vcc, exec, s[4:5]
	s_mov_b32 s79, s16
	s_mov_b32 s14, s18
	s_mov_b64 s[30:31], s[26:27]
	s_mov_b64 s[28:29], s[20:21]
	global_store_dwordx4 v[122:123], v[124:127], off
	global_store_dwordx4 v[108:109], v[104:107], off
	global_store_dwordx4 v[92:93], v[88:91], off
	global_store_dwordx4 v[76:77], v[72:75], off
	global_store_dwordx4 v[76:77], v[68:71], off offset:256
	global_store_dwordx4 v[58:59], v[60:63], off
	global_store_dwordx4 v[46:47], v[40:43], off
	global_store_dwordx4 v[30:31], v[24:27], off
	global_store_dwordx4 v[14:15], v[8:11], off
	global_store_dwordx4 v[12:13], v[4:7], off offset:256
	s_cbranch_vccz .LBB0_483
	s_waitcnt vmcnt(16)
	s_cmpk_gt_u32 s54, 0xff
	s_cbranch_scc1 .LBB0_490
	s_barrier

.LBB0_683:
	ds_read_b128 v[154:157], v151
	ds_read_b128 v[158:161], v151 offset:1024
	ds_read_b128 v[162:165], v151 offset:2048
	ds_read_b128 v[166:169], v151 offset:3072
	s_add_u32 s34, s30, 0xfffc0080
	s_addc_u32 s35, s31, -1
	s_cmp_eq_u32 s85, 12
	s_cselect_b32 s55, s19, s35
	s_cselect_b32 s54, s81, s34
	s_cselect_b32 s35, s17, s84
	s_cselect_b32 s34, s82, s83
	v_lshl_add_u64 v[202:203], s[30:31], 0, v[138:139]
	s_add_i32 m0, s29, 0xc000
	ds_read_b128 v[170:173], v152
	ds_read_b128 v[174:177], v152 offset:1024
	ds_read_b128 v[178:181], v152 offset:2048
	ds_read_b128 v[182:185], v152 offset:3072
	ds_read_b128 v[186:189], v152 offset:4096
	ds_read_b128 v[190:193], v152 offset:5120
	ds_read_b128 v[194:197], v152 offset:6144
	ds_read_b128 v[198:201], v152 offset:7168
	global_load_lds_dwordx4 v[202:203], off
	v_lshl_add_u64 v[202:203], s[30:31], 0, v[140:141]
	s_add_i32 m0, s29, 0xe000
	s_nop 0
	global_load_lds_dwordx4 v[202:203], off
	s_waitcnt lgkmcnt(8)
	s_waitcnt vmcnt(10)
	s_barrier
	s_waitcnt lgkmcnt(0)
	s_waitcnt lgkmcnt(0)
	v_mfma_f32_16x16x32_bf16 v[124:127], v[154:157], v[170:173], v[124:127]
	v_mfma_f32_16x16x32_bf16 v[120:123], v[162:165], v[170:173], v[120:123]
	v_mfma_f32_16x16x32_bf16 v[108:111], v[154:157], v[178:181], v[108:111]
	v_mfma_f32_16x16x32_bf16 v[104:107], v[162:165], v[178:181], v[104:107]
	v_mfma_f32_16x16x32_bf16 v[92:95], v[154:157], v[186:189], v[92:95]
	v_mfma_f32_16x16x32_bf16 v[88:91], v[162:165], v[186:189], v[88:91]
	v_mfma_f32_16x16x32_bf16 v[76:79], v[154:157], v[194:197], v[76:79]
	v_mfma_f32_16x16x32_bf16 v[72:75], v[162:165], v[194:197], v[72:75]
	v_mfma_f32_16x16x32_bf16 v[124:127], v[158:161], v[174:177], v[124:127]
	v_mfma_f32_16x16x32_bf16 v[120:123], v[166:169], v[174:177], v[120:123]
	v_mfma_f32_16x16x32_bf16 v[108:111], v[158:161], v[182:185], v[108:111]
	v_mfma_f32_16x16x32_bf16 v[104:107], v[166:169], v[182:185], v[104:107]
	v_mfma_f32_16x16x32_bf16 v[92:95], v[158:161], v[190:193], v[92:95]
	v_mfma_f32_16x16x32_bf16 v[88:91], v[166:169], v[190:193], v[88:91]
	v_mfma_f32_16x16x32_bf16 v[76:79], v[158:161], v[198:201], v[76:79]
	v_mfma_f32_16x16x32_bf16 v[72:75], v[166:169], v[198:201], v[72:75]
	s_barrier
	s_add_i32 s86, s74, s60
	v_lshl_add_u64 v[218:219], s[34:35], 0, v[132:133]
	s_mov_b32 m0, s86
	ds_read_b128 v[202:205], v153
	ds_read_b128 v[206:209], v153 offset:1024
	ds_read_b128 v[210:213], v153 offset:2048
	ds_read_b128 v[214:217], v153 offset:3072
	global_load_lds_dwordx4 v[218:219], off
	v_lshl_add_u64 v[220:221], s[34:35], 0, v[136:137]
	s_add_i32 m0, s86, 0x2000
	s_nop 0
	global_load_lds_dwordx4 v[220:221], off
	s_waitcnt vmcnt(10)
	s_barrier
	s_waitcnt lgkmcnt(0)
	s_waitcnt lgkmcnt(0)
	v_mfma_f32_16x16x32_bf16 v[116:119], v[202:205], v[170:173], v[116:119]
	v_mfma_f32_16x16x32_bf16 v[112:115], v[210:213], v[170:173], v[112:115]
	v_mfma_f32_16x16x32_bf16 v[100:103], v[202:205], v[178:181], v[100:103]
	v_mfma_f32_16x16x32_bf16 v[96:99], v[210:213], v[178:181], v[96:99]
	v_mfma_f32_16x16x32_bf16 v[84:87], v[202:205], v[186:189], v[84:87]
	v_mfma_f32_16x16x32_bf16 v[80:83], v[210:213], v[186:189], v[80:83]
	v_mfma_f32_16x16x32_bf16 v[68:71], v[202:205], v[194:197], v[68:71]
	v_mfma_f32_16x16x32_bf16 v[64:67], v[210:213], v[194:197], v[64:67]
	v_mfma_f32_16x16x32_bf16 v[116:119], v[206:209], v[174:177], v[116:119]
	v_mfma_f32_16x16x32_bf16 v[112:115], v[214:217], v[174:177], v[112:115]
	v_mfma_f32_16x16x32_bf16 v[100:103], v[206:209], v[182:185], v[100:103]
	v_mfma_f32_16x16x32_bf16 v[96:99], v[214:217], v[182:185], v[96:99]
	v_mfma_f32_16x16x32_bf16 v[84:87], v[206:209], v[190:193], v[84:87]
	v_mfma_f32_16x16x32_bf16 v[80:83], v[214:217], v[190:193], v[80:83]
	v_mfma_f32_16x16x32_bf16 v[68:71], v[206:209], v[198:201], v[68:71]
	v_mfma_f32_16x16x32_bf16 v[64:67], v[214:217], v[198:201], v[64:67]
	s_mov_b32 m0, s29
	v_lshl_add_u64 v[222:223], s[54:55], 0, v[130:131]
	s_barrier
	ds_read_b128 v[170:173], v152 offset:16384
	ds_read_b128 v[174:177], v152 offset:17408
	ds_read_b128 v[178:181], v152 offset:18432
	ds_read_b128 v[182:185], v152 offset:19456
	ds_read_b128 v[186:189], v152 offset:20480
	ds_read_b128 v[190:193], v152 offset:21504
	ds_read_b128 v[194:197], v152 offset:22528
	ds_read_b128 v[198:201], v152 offset:23552
	global_load_lds_dwordx4 v[222:223], off
	v_lshl_add_u64 v[224:225], s[54:55], 0, v[134:135]
	s_mov_b32 m0, s61
	s_nop 0
	global_load_lds_dwordx4 v[224:225], off
	s_waitcnt vmcnt(10)
	s_barrier
	s_waitcnt lgkmcnt(0)
	s_waitcnt lgkmcnt(0)
	v_mfma_f32_16x16x32_bf16 v[60:63], v[154:157], v[170:173], v[60:63]
	v_mfma_f32_16x16x32_bf16 v[56:59], v[162:165], v[170:173], v[56:59]
	v_mfma_f32_16x16x32_bf16 v[44:47], v[154:157], v[178:181], v[44:47]
	v_mfma_f32_16x16x32_bf16 v[40:43], v[162:165], v[178:181], v[40:43]
	v_mfma_f32_16x16x32_bf16 v[28:31], v[154:157], v[186:189], v[28:31]
	v_mfma_f32_16x16x32_bf16 v[24:27], v[162:165], v[186:189], v[24:27]
	v_mfma_f32_16x16x32_bf16 v[12:15], v[154:157], v[194:197], v[12:15]
	v_mfma_f32_16x16x32_bf16 v[8:11], v[162:165], v[194:197], v[8:11]
	v_mfma_f32_16x16x32_bf16 v[60:63], v[158:161], v[174:177], v[60:63]
	v_mfma_f32_16x16x32_bf16 v[56:59], v[166:169], v[174:177], v[56:59]
	v_mfma_f32_16x16x32_bf16 v[44:47], v[158:161], v[182:185], v[44:47]
	v_mfma_f32_16x16x32_bf16 v[40:43], v[166:169], v[182:185], v[40:43]
	v_mfma_f32_16x16x32_bf16 v[28:31], v[158:161], v[190:193], v[28:31]
	v_mfma_f32_16x16x32_bf16 v[24:27], v[166:169], v[190:193], v[24:27]
	v_mfma_f32_16x16x32_bf16 v[12:15], v[158:161], v[198:201], v[12:15]
	v_mfma_f32_16x16x32_bf16 v[8:11], v[166:169], v[198:201], v[8:11]
	s_barrier
	s_add_u32 s86, s34, 0x40000
	s_addc_u32 s87, s35, 0
	s_add_i32 s88, s75, s60
	v_lshl_add_u64 v[154:155], s[86:87], 0, v[132:133]
	s_mov_b32 m0, s88
	s_nop 0
	global_load_lds_dwordx4 v[154:155], off
	v_lshl_add_u64 v[154:155], s[86:87], 0, v[136:137]
	s_add_i32 m0, s88, 0x2000
	s_nop 0
	global_load_lds_dwordx4 v[154:155], off
	s_waitcnt vmcnt(10)
	s_barrier
	v_mfma_f32_16x16x32_bf16 v[52:55], v[202:205], v[170:173], v[52:55]
	v_mfma_f32_16x16x32_bf16 v[48:51], v[210:213], v[170:173], v[48:51]
	v_mfma_f32_16x16x32_bf16 v[36:39], v[202:205], v[178:181], v[36:39]
	v_mfma_f32_16x16x32_bf16 v[32:35], v[210:213], v[178:181], v[32:35]
	v_mfma_f32_16x16x32_bf16 v[20:23], v[202:205], v[186:189], v[20:23]
	v_mfma_f32_16x16x32_bf16 v[16:19], v[210:213], v[186:189], v[16:19]
	v_mfma_f32_16x16x32_bf16 v[4:7], v[202:205], v[194:197], v[4:7]
	v_mfma_f32_16x16x32_bf16 v[0:3], v[210:213], v[194:197], v[0:3]
	v_mfma_f32_16x16x32_bf16 v[52:55], v[206:209], v[174:177], v[52:55]
	v_mfma_f32_16x16x32_bf16 v[48:51], v[214:217], v[174:177], v[48:51]
	v_mfma_f32_16x16x32_bf16 v[36:39], v[206:209], v[182:185], v[36:39]
	v_mfma_f32_16x16x32_bf16 v[32:35], v[214:217], v[182:185], v[32:35]
	v_mfma_f32_16x16x32_bf16 v[20:23], v[206:209], v[190:193], v[20:23]
	v_mfma_f32_16x16x32_bf16 v[16:19], v[214:217], v[190:193], v[16:19]
	v_mfma_f32_16x16x32_bf16 v[4:7], v[206:209], v[198:201], v[4:7]
	v_mfma_f32_16x16x32_bf16 v[0:3], v[214:217], v[198:201], v[0:3]
	s_add_i32 s86, 0, 0x18000
	v_add_u32_e32 v166, s86, v149
	s_barrier
	ds_read_b128 v[154:157], v166
	ds_read_b128 v[158:161], v166 offset:1024
	ds_read_b128 v[162:165], v166 offset:2048
	ds_read_b128 v[166:169], v166 offset:3072
	s_add_u32 s54, s54, 0x40000
	s_addc_u32 s55, s55, 0
	s_mov_b32 m0, s62
	v_lshl_add_u64 v[202:203], s[54:55], 0, v[130:131]
	ds_read_b128 v[170:173], v152 offset:32768
	ds_read_b128 v[174:177], v152 offset:33792
	ds_read_b128 v[178:181], v152 offset:34816
	ds_read_b128 v[182:185], v152 offset:35840
	ds_read_b128 v[186:189], v152 offset:36864
	ds_read_b128 v[190:193], v152 offset:37888
	ds_read_b128 v[194:197], v152 offset:38912
	ds_read_b128 v[198:201], v152 offset:39936
	global_load_lds_dwordx4 v[202:203], off
	v_lshl_add_u64 v[202:203], s[54:55], 0, v[134:135]
	s_mov_b32 m0, s63
	s_nop 0
	global_load_lds_dwordx4 v[202:203], off
	s_waitcnt lgkmcnt(8)
	s_waitcnt vmcnt(10)
	s_barrier
	s_waitcnt lgkmcnt(0)
	s_waitcnt lgkmcnt(0)
	v_mfma_f32_16x16x32_bf16 v[124:127], v[154:157], v[170:173], v[124:127]
	v_mfma_f32_16x16x32_bf16 v[120:123], v[162:165], v[170:173], v[120:123]
	v_mfma_f32_16x16x32_bf16 v[108:111], v[154:157], v[178:181], v[108:111]
	v_mfma_f32_16x16x32_bf16 v[104:107], v[162:165], v[178:181], v[104:107]
	v_mfma_f32_16x16x32_bf16 v[92:95], v[154:157], v[186:189], v[92:95]
	v_mfma_f32_16x16x32_bf16 v[88:91], v[162:165], v[186:189], v[88:91]
	v_mfma_f32_16x16x32_bf16 v[76:79], v[154:157], v[194:197], v[76:79]
	v_mfma_f32_16x16x32_bf16 v[72:75], v[162:165], v[194:197], v[72:75]
	v_mfma_f32_16x16x32_bf16 v[124:127], v[158:161], v[174:177], v[124:127]
	v_mfma_f32_16x16x32_bf16 v[120:123], v[166:169], v[174:177], v[120:123]
	v_mfma_f32_16x16x32_bf16 v[108:111], v[158:161], v[182:185], v[108:111]
	v_mfma_f32_16x16x32_bf16 v[104:107], v[166:169], v[182:185], v[104:107]
	v_mfma_f32_16x16x32_bf16 v[92:95], v[158:161], v[190:193], v[92:95]
	v_mfma_f32_16x16x32_bf16 v[88:91], v[166:169], v[190:193], v[88:91]
	v_mfma_f32_16x16x32_bf16 v[76:79], v[158:161], v[198:201], v[76:79]
	v_mfma_f32_16x16x32_bf16 v[72:75], v[166:169], v[198:201], v[72:75]
	s_barrier
	s_add_i32 s54, 0, 0x1c000
	s_add_i32 s55, s86, s60
	v_add_u32_e32 v214, s54, v149
	v_lshl_add_u64 v[218:219], v[218:219], 0, s[8:9]
	s_mov_b32 m0, s55
	ds_read_b128 v[202:205], v214
	ds_read_b128 v[206:209], v214 offset:1024
	ds_read_b128 v[210:213], v214 offset:2048
	ds_read_b128 v[214:217], v214 offset:3072
	global_load_lds_dwordx4 v[218:219], off
	v_lshl_add_u64 v[218:219], v[220:221], 0, s[8:9]
	s_add_i32 m0, s55, 0x2000
	s_nop 0
	global_load_lds_dwordx4 v[218:219], off
	s_waitcnt vmcnt(10)
	s_barrier
	s_waitcnt lgkmcnt(0)
	s_waitcnt lgkmcnt(0)
	v_mfma_f32_16x16x32_bf16 v[116:119], v[202:205], v[170:173], v[116:119]
	v_mfma_f32_16x16x32_bf16 v[112:115], v[210:213], v[170:173], v[112:115]
	v_mfma_f32_16x16x32_bf16 v[100:103], v[202:205], v[178:181], v[100:103]
	v_mfma_f32_16x16x32_bf16 v[96:99], v[210:213], v[178:181], v[96:99]
	v_mfma_f32_16x16x32_bf16 v[84:87], v[202:205], v[186:189], v[84:87]
	v_mfma_f32_16x16x32_bf16 v[80:83], v[210:213], v[186:189], v[80:83]
	v_mfma_f32_16x16x32_bf16 v[68:71], v[202:205], v[194:197], v[68:71]
	v_mfma_f32_16x16x32_bf16 v[64:67], v[210:213], v[194:197], v[64:67]
	v_mfma_f32_16x16x32_bf16 v[116:119], v[206:209], v[174:177], v[116:119]
	v_mfma_f32_16x16x32_bf16 v[112:115], v[214:217], v[174:177], v[112:115]
	v_mfma_f32_16x16x32_bf16 v[100:103], v[206:209], v[182:185], v[100:103]
	v_mfma_f32_16x16x32_bf16 v[96:99], v[214:217], v[182:185], v[96:99]
	v_mfma_f32_16x16x32_bf16 v[84:87], v[206:209], v[190:193], v[84:87]
	v_mfma_f32_16x16x32_bf16 v[80:83], v[214:217], v[190:193], v[80:83]
	v_mfma_f32_16x16x32_bf16 v[68:71], v[206:209], v[198:201], v[68:71]
	v_mfma_f32_16x16x32_bf16 v[64:67], v[214:217], v[198:201], v[64:67]
	s_mov_b32 m0, s71
	v_lshl_add_u64 v[218:219], v[222:223], 0, s[8:9]
	s_barrier
	ds_read_b128 v[170:173], v152 offset:49152
	ds_read_b128 v[174:177], v152 offset:50176
	ds_read_b128 v[178:181], v152 offset:51200
	ds_read_b128 v[182:185], v152 offset:52224
	ds_read_b128 v[186:189], v152 offset:53248
	ds_read_b128 v[190:193], v152 offset:54272
	ds_read_b128 v[194:197], v152 offset:55296
	ds_read_b128 v[198:201], v152 offset:56320
	global_load_lds_dwordx4 v[218:219], off
	v_lshl_add_u64 v[218:219], v[224:225], 0, s[8:9]
	s_mov_b32 m0, s72
	s_nop 0
	global_load_lds_dwordx4 v[218:219], off
	s_waitcnt vmcnt(10)
	s_barrier
	s_waitcnt lgkmcnt(0)
	s_waitcnt lgkmcnt(0)
	v_mfma_f32_16x16x32_bf16 v[60:63], v[154:157], v[170:173], v[60:63]
	v_mfma_f32_16x16x32_bf16 v[56:59], v[162:165], v[170:173], v[56:59]
	v_mfma_f32_16x16x32_bf16 v[44:47], v[154:157], v[178:181], v[44:47]
	v_mfma_f32_16x16x32_bf16 v[40:43], v[162:165], v[178:181], v[40:43]
	v_mfma_f32_16x16x32_bf16 v[28:31], v[154:157], v[186:189], v[28:31]
	v_mfma_f32_16x16x32_bf16 v[24:27], v[162:165], v[186:189], v[24:27]
	v_mfma_f32_16x16x32_bf16 v[12:15], v[154:157], v[194:197], v[12:15]
	v_mfma_f32_16x16x32_bf16 v[8:11], v[162:165], v[194:197], v[8:11]
	v_mfma_f32_16x16x32_bf16 v[60:63], v[158:161], v[174:177], v[60:63]
	v_mfma_f32_16x16x32_bf16 v[56:59], v[166:169], v[174:177], v[56:59]
	v_mfma_f32_16x16x32_bf16 v[44:47], v[158:161], v[182:185], v[44:47]
	v_mfma_f32_16x16x32_bf16 v[40:43], v[166:169], v[182:185], v[40:43]
	v_mfma_f32_16x16x32_bf16 v[28:31], v[158:161], v[190:193], v[28:31]
	v_mfma_f32_16x16x32_bf16 v[24:27], v[166:169], v[190:193], v[24:27]
	v_mfma_f32_16x16x32_bf16 v[12:15], v[158:161], v[198:201], v[12:15]
	v_mfma_f32_16x16x32_bf16 v[8:11], v[166:169], v[198:201], v[8:11]
	s_barrier
	s_add_u32 s34, s34, 0x40080
	s_addc_u32 s35, s35, 0
	s_add_i32 s54, s54, s60
	v_lshl_add_u64 v[154:155], s[34:35], 0, v[132:133]
	s_mov_b32 m0, s54
	s_nop 0
	global_load_lds_dwordx4 v[154:155], off
	v_lshl_add_u64 v[154:155], s[34:35], 0, v[136:137]
	s_add_i32 m0, s54, 0x2000
	s_nop 0
	global_load_lds_dwordx4 v[154:155], off
	s_waitcnt vmcnt(10)
	s_barrier
	v_mfma_f32_16x16x32_bf16 v[52:55], v[202:205], v[170:173], v[52:55]
	v_mfma_f32_16x16x32_bf16 v[48:51], v[210:213], v[170:173], v[48:51]
	v_mfma_f32_16x16x32_bf16 v[36:39], v[202:205], v[178:181], v[36:39]
	v_mfma_f32_16x16x32_bf16 v[32:35], v[210:213], v[178:181], v[32:35]
	v_mfma_f32_16x16x32_bf16 v[20:23], v[202:205], v[186:189], v[20:23]
	v_mfma_f32_16x16x32_bf16 v[16:19], v[210:213], v[186:189], v[16:19]
	v_mfma_f32_16x16x32_bf16 v[4:7], v[202:205], v[194:197], v[4:7]
	v_mfma_f32_16x16x32_bf16 v[0:3], v[210:213], v[194:197], v[0:3]
	v_mfma_f32_16x16x32_bf16 v[52:55], v[206:209], v[174:177], v[52:55]
	v_mfma_f32_16x16x32_bf16 v[48:51], v[214:217], v[174:177], v[48:51]
	v_mfma_f32_16x16x32_bf16 v[36:39], v[206:209], v[182:185], v[36:39]
	v_mfma_f32_16x16x32_bf16 v[32:35], v[214:217], v[182:185], v[32:35]
	v_mfma_f32_16x16x32_bf16 v[20:23], v[206:209], v[190:193], v[20:23]
	v_mfma_f32_16x16x32_bf16 v[16:19], v[214:217], v[190:193], v[16:19]
	v_mfma_f32_16x16x32_bf16 v[4:7], v[206:209], v[198:201], v[4:7]
	v_mfma_f32_16x16x32_bf16 v[0:3], v[214:217], v[198:201], v[0:3]
	s_add_i32 s85, s85, 2
	s_add_u32 s30, s30, 0x100
	s_addc_u32 s31, s31, 0
	s_add_u32 s83, s83, 0x100
	s_addc_u32 s84, s84, 0
	s_cmp_gt_u32 s85, 13
	s_barrier
	s_cbranch_scc0 .LBB0_683
	v_lshl_add_u32 v154, s28, 8, v148
	v_max_f32_e32 v126, v126, v126
	v_max_f32_e32 v127, v127, v127
	v_lshl_or_b32 v156, s80, 8, v150
	v_ashrrev_i32_e32 v155, 31, v154
	v_max_f32_e32 v124, v124, v124
	v_max_f32_e32 v120, v120, v120
	v_max_f32_e32 v125, v125, v125
	v_max_f32_e32 v121, v121, v121
	v_max_f32_e32 v126, 0, v126
	v_max_f32_e32 v122, v122, v122
	v_max_f32_e32 v127, 0, v127
	v_max_f32_e32 v123, v123, v123
	v_lshlrev_b64 v[158:159], 13, v[154:155]
	v_max_f32_e32 v124, 0, v124
	v_max_f32_e32 v120, 0, v120
	v_max_f32_e32 v125, 0, v125
	v_max_f32_e32 v121, 0, v121
	v_max_f32_e32 v122, 0, v122
	v_max_f32_e32 v123, 0, v123
	v_pk_mul_f32 v[126:127], v[126:127], v[126:127]
	v_ashrrev_i32_e32 v157, 31, v156
	v_lshl_add_u64 v[158:159], s[46:47], 0, v[158:159]
	v_pk_mul_f32 v[124:125], v[124:125], v[124:125]
	v_pk_mul_f32 v[120:121], v[120:121], v[120:121]
	v_pk_mul_f32 v[160:161], v[122:123], v[122:123]
	v_cvt_pk_bf16_f32 v123, v126, v127
	v_lshlrev_b64 v[126:127], 1, v[156:157]
	v_max_f32_e32 v112, v112, v112
	v_max_f32_e32 v113, v113, v113
	v_cvt_pk_bf16_f32 v122, v124, v125
	v_cvt_pk_bf16_f32 v124, v120, v121
	v_cvt_pk_bf16_f32 v125, v160, v161
	v_lshl_add_u64 v[120:121], v[158:159], 0, v[126:127]
	v_max_f32_e32 v112, 0, v112
	v_max_f32_e32 v113, 0, v113
	global_store_dwordx4 v[120:121], v[122:125], off
	v_max_f32_e32 v116, v116, v116
	v_max_f32_e32 v117, v117, v117
	v_pk_mul_f32 v[122:123], v[112:113], v[112:113]
	v_max_f32_e32 v113, v114, v114
	v_max_f32_e32 v112, v118, v118
	v_max_f32_e32 v114, 0, v113
	v_max_f32_e32 v113, v119, v119
	v_max_f32_e32 v115, v115, v115
	v_max_f32_e32 v116, 0, v116
	v_max_f32_e32 v117, 0, v117
	v_max_f32_e32 v112, 0, v112
	v_max_f32_e32 v113, 0, v113
	v_max_f32_e32 v115, 0, v115
	v_pk_mul_f32 v[116:117], v[116:117], v[116:117]
	v_pk_mul_f32 v[118:119], v[112:113], v[112:113]
	v_pk_mul_f32 v[124:125], v[114:115], v[114:115]
	v_max_f32_e32 v104, v104, v104
	v_max_f32_e32 v105, v105, v105
	v_cvt_pk_bf16_f32 v112, v116, v117
	v_cvt_pk_bf16_f32 v113, v118, v119
	v_cvt_pk_bf16_f32 v114, v122, v123
	v_cvt_pk_bf16_f32 v115, v124, v125
	v_max_f32_e32 v104, 0, v104
	v_max_f32_e32 v105, 0, v105
	global_store_dwordx4 v[120:121], v[112:115], off offset:256
	v_max_f32_e32 v108, v108, v108
	v_max_f32_e32 v109, v109, v109
	v_or_b32_e32 v112, 16, v154
	v_pk_mul_f32 v[114:115], v[104:105], v[104:105]
	v_max_f32_e32 v105, v106, v106
	v_ashrrev_i32_e32 v113, 31, v112
	v_max_f32_e32 v104, v110, v110
	v_max_f32_e32 v106, 0, v105
	v_max_f32_e32 v105, v111, v111
	v_max_f32_e32 v107, v107, v107
	v_lshlrev_b64 v[112:113], 13, v[112:113]
	v_max_f32_e32 v108, 0, v108
	v_max_f32_e32 v109, 0, v109
	v_max_f32_e32 v104, 0, v104
	v_max_f32_e32 v105, 0, v105
	v_max_f32_e32 v107, 0, v107
	v_lshl_add_u64 v[112:113], s[46:47], 0, v[112:113]
	v_pk_mul_f32 v[108:109], v[108:109], v[108:109]
	v_pk_mul_f32 v[110:111], v[104:105], v[104:105]
	v_pk_mul_f32 v[116:117], v[106:107], v[106:107]
	v_max_f32_e32 v96, v96, v96
	v_max_f32_e32 v97, v97, v97
	v_cvt_pk_bf16_f32 v104, v108, v109
	v_cvt_pk_bf16_f32 v105, v110, v111
	v_cvt_pk_bf16_f32 v106, v114, v115
	v_cvt_pk_bf16_f32 v107, v116, v117
	v_lshl_add_u64 v[108:109], v[112:113], 0, v[126:127]
	v_max_f32_e32 v96, 0, v96
	v_max_f32_e32 v97, 0, v97
	global_store_dwordx4 v[108:109], v[104:107], off
	v_max_f32_e32 v100, v100, v100
	v_max_f32_e32 v101, v101, v101
	v_pk_mul_f32 v[104:105], v[96:97], v[96:97]
	v_max_f32_e32 v97, v98, v98
	v_max_f32_e32 v96, v102, v102
	v_max_f32_e32 v98, 0, v97
	v_max_f32_e32 v97, v103, v103
	v_max_f32_e32 v99, v99, v99
	v_max_f32_e32 v100, 0, v100
	v_max_f32_e32 v101, 0, v101
	v_max_f32_e32 v96, 0, v96
	v_max_f32_e32 v97, 0, v97
	v_max_f32_e32 v99, 0, v99
	v_pk_mul_f32 v[100:101], v[100:101], v[100:101]
	v_pk_mul_f32 v[102:103], v[96:97], v[96:97]
	v_pk_mul_f32 v[106:107], v[98:99], v[98:99]
	v_max_f32_e32 v88, v88, v88
	v_max_f32_e32 v89, v89, v89
	v_cvt_pk_bf16_f32 v96, v100, v101
	v_cvt_pk_bf16_f32 v97, v102, v103
	v_cvt_pk_bf16_f32 v98, v104, v105
	v_cvt_pk_bf16_f32 v99, v106, v107
	v_max_f32_e32 v88, 0, v88
	v_max_f32_e32 v89, 0, v89
	global_store_dwordx4 v[108:109], v[96:99], off offset:256
	v_max_f32_e32 v92, v92, v92
	v_max_f32_e32 v93, v93, v93
	v_or_b32_e32 v96, 32, v154
	v_pk_mul_f32 v[98:99], v[88:89], v[88:89]
	v_max_f32_e32 v89, v90, v90
	v_ashrrev_i32_e32 v97, 31, v96
	v_max_f32_e32 v88, v94, v94
	v_max_f32_e32 v90, 0, v89
	v_max_f32_e32 v89, v95, v95
	v_max_f32_e32 v91, v91, v91
	v_lshlrev_b64 v[96:97], 13, v[96:97]
	v_max_f32_e32 v92, 0, v92
	v_max_f32_e32 v93, 0, v93
	v_max_f32_e32 v88, 0, v88
	v_max_f32_e32 v89, 0, v89
	v_max_f32_e32 v91, 0, v91
	v_lshl_add_u64 v[96:97], s[46:47], 0, v[96:97]
	v_pk_mul_f32 v[92:93], v[92:93], v[92:93]
	v_pk_mul_f32 v[94:95], v[88:89], v[88:89]
	v_pk_mul_f32 v[100:101], v[90:91], v[90:91]
	v_max_f32_e32 v80, v80, v80
	v_max_f32_e32 v81, v81, v81
	v_cvt_pk_bf16_f32 v88, v92, v93
	v_cvt_pk_bf16_f32 v89, v94, v95
	v_cvt_pk_bf16_f32 v90, v98, v99
	v_cvt_pk_bf16_f32 v91, v100, v101
	v_lshl_add_u64 v[92:93], v[96:97], 0, v[126:127]
	v_max_f32_e32 v80, 0, v80
	v_max_f32_e32 v81, 0, v81
	global_store_dwordx4 v[92:93], v[88:91], off
	v_max_f32_e32 v84, v84, v84
	v_max_f32_e32 v85, v85, v85
	v_pk_mul_f32 v[88:89], v[80:81], v[80:81]
	v_max_f32_e32 v81, v82, v82
	v_max_f32_e32 v80, v86, v86
	v_max_f32_e32 v82, 0, v81
	v_max_f32_e32 v81, v87, v87
	v_max_f32_e32 v83, v83, v83
	v_max_f32_e32 v84, 0, v84
	v_max_f32_e32 v85, 0, v85
	v_max_f32_e32 v80, 0, v80
	v_max_f32_e32 v81, 0, v81
	v_max_f32_e32 v83, 0, v83
	v_pk_mul_f32 v[84:85], v[84:85], v[84:85]
	v_pk_mul_f32 v[86:87], v[80:81], v[80:81]
	v_pk_mul_f32 v[90:91], v[82:83], v[82:83]
	v_max_f32_e32 v72, v72, v72
	v_max_f32_e32 v73, v73, v73
	v_cvt_pk_bf16_f32 v80, v84, v85
	v_cvt_pk_bf16_f32 v81, v86, v87
	v_cvt_pk_bf16_f32 v82, v88, v89
	v_cvt_pk_bf16_f32 v83, v90, v91
	v_max_f32_e32 v72, 0, v72
	v_max_f32_e32 v73, 0, v73
	global_store_dwordx4 v[92:93], v[80:83], off offset:256
	v_max_f32_e32 v76, v76, v76
	v_max_f32_e32 v77, v77, v77
	v_or_b32_e32 v80, 48, v154
	v_pk_mul_f32 v[82:83], v[72:73], v[72:73]
	v_max_f32_e32 v73, v74, v74
	v_ashrrev_i32_e32 v81, 31, v80
	v_max_f32_e32 v72, v78, v78
	v_max_f32_e32 v74, 0, v73
	v_max_f32_e32 v73, v79, v79
	v_max_f32_e32 v75, v75, v75
	v_lshlrev_b64 v[80:81], 13, v[80:81]
	v_max_f32_e32 v76, 0, v76
	v_max_f32_e32 v77, 0, v77
	v_max_f32_e32 v72, 0, v72
	v_max_f32_e32 v73, 0, v73
	v_max_f32_e32 v75, 0, v75
	v_lshl_add_u64 v[80:81], s[46:47], 0, v[80:81]
	v_pk_mul_f32 v[76:77], v[76:77], v[76:77]
	v_pk_mul_f32 v[78:79], v[72:73], v[72:73]
	v_pk_mul_f32 v[84:85], v[74:75], v[74:75]
	v_max_f32_e32 v64, v64, v64
	v_max_f32_e32 v65, v65, v65
	v_cvt_pk_bf16_f32 v72, v76, v77
	v_cvt_pk_bf16_f32 v73, v78, v79
	v_cvt_pk_bf16_f32 v74, v82, v83
	v_cvt_pk_bf16_f32 v75, v84, v85
	v_lshl_add_u64 v[76:77], v[80:81], 0, v[126:127]
	v_max_f32_e32 v64, 0, v64
	v_max_f32_e32 v65, 0, v65
	global_store_dwordx4 v[76:77], v[72:75], off
	v_max_f32_e32 v68, v68, v68
	v_max_f32_e32 v69, v69, v69
	v_pk_mul_f32 v[72:73], v[64:65], v[64:65]
	v_max_f32_e32 v65, v66, v66
	v_max_f32_e32 v64, v70, v70
	v_max_f32_e32 v66, 0, v65
	v_max_f32_e32 v65, v71, v71
	v_max_f32_e32 v67, v67, v67
	v_max_f32_e32 v68, 0, v68
	v_max_f32_e32 v69, 0, v69
	v_max_f32_e32 v64, 0, v64
	v_max_f32_e32 v65, 0, v65
	v_max_f32_e32 v67, 0, v67
	v_pk_mul_f32 v[68:69], v[68:69], v[68:69]
	v_pk_mul_f32 v[70:71], v[64:65], v[64:65]
	v_pk_mul_f32 v[74:75], v[66:67], v[66:67]
	v_max_f32_e32 v56, v56, v56
	v_max_f32_e32 v57, v57, v57
	v_cvt_pk_bf16_f32 v64, v68, v69
	v_cvt_pk_bf16_f32 v65, v70, v71
	v_cvt_pk_bf16_f32 v66, v72, v73
	v_cvt_pk_bf16_f32 v67, v74, v75
	v_max_f32_e32 v56, 0, v56
	v_max_f32_e32 v57, 0, v57
	global_store_dwordx4 v[76:77], v[64:67], off offset:256
	v_max_f32_e32 v60, v60, v60
	v_max_f32_e32 v61, v61, v61
	v_pk_mul_f32 v[64:65], v[56:57], v[56:57]
	v_max_f32_e32 v57, v58, v58
	v_max_f32_e32 v56, v62, v62
	v_max_f32_e32 v58, 0, v57
	v_max_f32_e32 v57, v63, v63
	v_max_f32_e32 v56, 0, v56
	v_max_f32_e32 v57, 0, v57
	v_max_f32_e32 v59, v59, v59
	v_max_f32_e32 v60, 0, v60
	v_max_f32_e32 v61, 0, v61
	v_max_f32_e32 v59, 0, v59
	v_pk_mul_f32 v[62:63], v[56:57], v[56:57]
	v_pk_mul_f32 v[60:61], v[60:61], v[60:61]
	v_pk_mul_f32 v[66:67], v[58:59], v[58:59]
	v_cvt_pk_bf16_f32 v57, v62, v63
	v_add_co_u32_e32 v62, vcc, s76, v120
	v_max_f32_e32 v48, v48, v48
	v_max_f32_e32 v49, v49, v49
	v_cvt_pk_bf16_f32 v56, v60, v61
	v_cvt_pk_bf16_f32 v58, v64, v65
	v_cvt_pk_bf16_f32 v59, v66, v67
	v_addc_co_u32_e32 v63, vcc, 0, v121, vcc
	v_max_f32_e32 v48, 0, v48
	v_max_f32_e32 v49, 0, v49
	global_store_dwordx4 v[62:63], v[56:59], off
	v_max_f32_e32 v52, v52, v52
	v_max_f32_e32 v53, v53, v53
	v_pk_mul_f32 v[56:57], v[48:49], v[48:49]
	v_max_f32_e32 v49, v50, v50
	v_max_f32_e32 v48, v54, v54
	v_max_f32_e32 v50, 0, v49
	v_max_f32_e32 v49, v55, v55
	v_max_f32_e32 v51, v51, v51
	v_max_f32_e32 v52, 0, v52
	v_max_f32_e32 v53, 0, v53
	v_max_f32_e32 v48, 0, v48
	v_max_f32_e32 v49, 0, v49
	v_max_f32_e32 v51, 0, v51
	s_mov_b64 s[30:31], 0x100000
	v_pk_mul_f32 v[52:53], v[52:53], v[52:53]
	v_pk_mul_f32 v[54:55], v[48:49], v[48:49]
	v_pk_mul_f32 v[58:59], v[50:51], v[50:51]
	v_max_f32_e32 v40, v40, v40
	v_max_f32_e32 v41, v41, v41
	v_lshl_add_u64 v[60:61], v[120:121], 0, s[30:31]
	v_cvt_pk_bf16_f32 v48, v52, v53
	v_cvt_pk_bf16_f32 v49, v54, v55
	v_cvt_pk_bf16_f32 v50, v56, v57
	v_cvt_pk_bf16_f32 v51, v58, v59
	v_max_f32_e32 v40, 0, v40
	v_max_f32_e32 v41, 0, v41
	global_store_dwordx4 v[60:61], v[48:51], off offset:256
	v_max_f32_e32 v44, v44, v44
	v_max_f32_e32 v45, v45, v45
	v_pk_mul_f32 v[48:49], v[40:41], v[40:41]
	v_max_f32_e32 v41, v42, v42
	v_max_f32_e32 v40, v46, v46
	v_max_f32_e32 v42, 0, v41
	v_max_f32_e32 v41, v47, v47
	v_max_f32_e32 v40, 0, v40
	v_max_f32_e32 v41, 0, v41
	v_max_f32_e32 v43, v43, v43
	v_max_f32_e32 v44, 0, v44
	v_max_f32_e32 v45, 0, v45
	v_max_f32_e32 v43, 0, v43
	v_pk_mul_f32 v[46:47], v[40:41], v[40:41]
	v_pk_mul_f32 v[44:45], v[44:45], v[44:45]
	v_pk_mul_f32 v[50:51], v[42:43], v[42:43]
	v_cvt_pk_bf16_f32 v41, v46, v47
	v_add_co_u32_e32 v46, vcc, s77, v120
	v_max_f32_e32 v32, v32, v32
	v_max_f32_e32 v33, v33, v33
	v_cvt_pk_bf16_f32 v40, v44, v45
	v_cvt_pk_bf16_f32 v42, v48, v49
	v_cvt_pk_bf16_f32 v43, v50, v51
	v_addc_co_u32_e32 v47, vcc, 0, v121, vcc
	v_max_f32_e32 v32, 0, v32
	v_max_f32_e32 v33, 0, v33
	global_store_dwordx4 v[46:47], v[40:43], off
	v_max_f32_e32 v36, v36, v36
	v_max_f32_e32 v37, v37, v37
	v_pk_mul_f32 v[40:41], v[32:33], v[32:33]
	v_max_f32_e32 v33, v34, v34
	v_max_f32_e32 v32, v38, v38
	v_max_f32_e32 v34, 0, v33
	v_max_f32_e32 v33, v39, v39
	v_max_f32_e32 v35, v35, v35
	v_max_f32_e32 v36, 0, v36
	v_max_f32_e32 v37, 0, v37
	v_max_f32_e32 v32, 0, v32
	v_max_f32_e32 v33, 0, v33
	v_max_f32_e32 v35, 0, v35
	v_pk_mul_f32 v[36:37], v[36:37], v[36:37]
	v_pk_mul_f32 v[38:39], v[32:33], v[32:33]
	v_pk_mul_f32 v[42:43], v[34:35], v[34:35]
	v_max_f32_e32 v24, v24, v24
	v_max_f32_e32 v25, v25, v25
	v_lshl_add_u64 v[44:45], v[120:121], 0, s[10:11]
	v_cvt_pk_bf16_f32 v32, v36, v37
	v_cvt_pk_bf16_f32 v33, v38, v39
	v_cvt_pk_bf16_f32 v34, v40, v41
	v_cvt_pk_bf16_f32 v35, v42, v43
	v_max_f32_e32 v24, 0, v24
	v_max_f32_e32 v25, 0, v25
	global_store_dwordx4 v[44:45], v[32:35], off offset:256
	v_max_f32_e32 v28, v28, v28
	v_max_f32_e32 v29, v29, v29
	v_pk_mul_f32 v[32:33], v[24:25], v[24:25]
	v_max_f32_e32 v25, v26, v26
	v_max_f32_e32 v24, v30, v30
	v_max_f32_e32 v26, 0, v25
	v_max_f32_e32 v25, v31, v31
	v_max_f32_e32 v24, 0, v24
	v_max_f32_e32 v25, 0, v25
	v_max_f32_e32 v27, v27, v27
	v_max_f32_e32 v28, 0, v28
	v_max_f32_e32 v29, 0, v29
	v_max_f32_e32 v27, 0, v27
	v_pk_mul_f32 v[30:31], v[24:25], v[24:25]
	v_pk_mul_f32 v[28:29], v[28:29], v[28:29]
	v_pk_mul_f32 v[34:35], v[26:27], v[26:27]
	v_cvt_pk_bf16_f32 v25, v30, v31
	v_add_co_u32_e32 v30, vcc, s78, v120
	v_max_f32_e32 v16, v16, v16
	v_max_f32_e32 v17, v17, v17
	v_cvt_pk_bf16_f32 v24, v28, v29
	v_cvt_pk_bf16_f32 v26, v32, v33
	v_cvt_pk_bf16_f32 v27, v34, v35
	v_addc_co_u32_e32 v31, vcc, 0, v121, vcc
	v_max_f32_e32 v16, 0, v16
	v_max_f32_e32 v17, 0, v17
	global_store_dwordx4 v[30:31], v[24:27], off
	v_max_f32_e32 v20, v20, v20
	v_max_f32_e32 v21, v21, v21
	v_pk_mul_f32 v[24:25], v[16:17], v[16:17]
	v_max_f32_e32 v17, v18, v18
	v_max_f32_e32 v16, v22, v22
	v_max_f32_e32 v18, 0, v17
	v_max_f32_e32 v17, v23, v23
	v_max_f32_e32 v19, v19, v19
	v_max_f32_e32 v20, 0, v20
	v_max_f32_e32 v21, 0, v21
	v_max_f32_e32 v16, 0, v16
	v_max_f32_e32 v17, 0, v17
	v_max_f32_e32 v19, 0, v19
	v_pk_mul_f32 v[20:21], v[20:21], v[20:21]
	v_pk_mul_f32 v[22:23], v[16:17], v[16:17]
	v_pk_mul_f32 v[26:27], v[18:19], v[18:19]
	v_max_f32_e32 v8, v8, v8
	v_max_f32_e32 v9, v9, v9
	v_lshl_add_u64 v[28:29], v[120:121], 0, s[12:13]
	v_cvt_pk_bf16_f32 v16, v20, v21
	v_cvt_pk_bf16_f32 v17, v22, v23
	v_cvt_pk_bf16_f32 v18, v24, v25
	v_cvt_pk_bf16_f32 v19, v26, v27
	v_max_f32_e32 v8, 0, v8
	v_max_f32_e32 v9, 0, v9
	global_store_dwordx4 v[28:29], v[16:19], off offset:256
	v_max_f32_e32 v12, v12, v12
	v_max_f32_e32 v13, v13, v13
	v_pk_mul_f32 v[16:17], v[8:9], v[8:9]
	v_max_f32_e32 v9, v10, v10
	v_max_f32_e32 v8, v14, v14
	v_max_f32_e32 v10, 0, v9
	v_max_f32_e32 v9, v15, v15
	v_max_f32_e32 v8, 0, v8
	v_max_f32_e32 v9, 0, v9
	v_max_f32_e32 v11, v11, v11
	v_max_f32_e32 v12, 0, v12
	v_max_f32_e32 v13, 0, v13
	v_max_f32_e32 v11, 0, v11
	v_pk_mul_f32 v[14:15], v[8:9], v[8:9]
	v_pk_mul_f32 v[12:13], v[12:13], v[12:13]
	v_pk_mul_f32 v[18:19], v[10:11], v[10:11]
	v_cvt_pk_bf16_f32 v9, v14, v15
	v_add_co_u32_e32 v14, vcc, s79, v120
	v_max_f32_e32 v0, v0, v0
	v_max_f32_e32 v1, v1, v1
	v_cvt_pk_bf16_f32 v8, v12, v13
	v_cvt_pk_bf16_f32 v10, v16, v17
	v_cvt_pk_bf16_f32 v11, v18, v19
	v_addc_co_u32_e32 v15, vcc, 0, v121, vcc
	v_max_f32_e32 v0, 0, v0
	v_max_f32_e32 v1, 0, v1
	global_store_dwordx4 v[14:15], v[8:11], off
	v_max_f32_e32 v4, v4, v4
	v_max_f32_e32 v5, v5, v5
	v_pk_mul_f32 v[8:9], v[0:1], v[0:1]
	v_max_f32_e32 v1, v2, v2
	v_max_f32_e32 v0, v6, v6
	v_max_f32_e32 v2, 0, v1
	v_max_f32_e32 v1, v7, v7
	v_max_f32_e32 v3, v3, v3
	v_max_f32_e32 v4, 0, v4
	v_max_f32_e32 v5, 0, v5
	v_max_f32_e32 v0, 0, v0
	v_max_f32_e32 v1, 0, v1
	v_max_f32_e32 v3, 0, v3
	v_pk_mul_f32 v[4:5], v[4:5], v[4:5]
	v_pk_mul_f32 v[6:7], v[0:1], v[0:1]
	v_pk_mul_f32 v[10:11], v[2:3], v[2:3]
	v_lshl_add_u64 v[12:13], v[120:121], 0, s[14:15]
	v_cvt_pk_bf16_f32 v0, v4, v5
	v_cvt_pk_bf16_f32 v1, v6, v7
	v_cvt_pk_bf16_f32 v2, v8, v9
	v_cvt_pk_bf16_f32 v3, v10, v11
	s_and_b64 vcc, exec, s[4:5]
	s_mov_b32 s80, s16
	s_mov_b32 s28, s18
	s_mov_b64 s[34:35], s[26:27]
	s_mov_b64 s[30:31], s[20:21]
	global_store_dwordx4 v[12:13], v[0:3], off offset:256
	s_cbranch_vccz .LBB0_676
	s_waitcnt vmcnt(16)
	s_cmpk_gt_u32 s56, 0xff
	s_cbranch_scc1 .LBB0_687
	s_barrier

.LBB0_776:
	ds_read_b128 v[156:159], v152
	ds_read_b128 v[160:163], v152 offset:1024
	ds_read_b128 v[164:167], v152 offset:2048
	ds_read_b128 v[168:171], v152 offset:3072
	s_add_u32 s34, s30, 0xfff00080
	s_addc_u32 s35, s31, -1
	s_cmp_eq_u32 s85, 60
	s_cselect_b32 s55, s21, s35
	s_cselect_b32 s54, s81, s34
	s_cselect_b32 s35, s19, s84
	s_cselect_b32 s34, s82, s83
	v_lshl_add_u64 v[204:205], s[30:31], 0, v[138:139]
	s_add_i32 m0, s17, 0xc000
	ds_read_b128 v[172:175], v153
	ds_read_b128 v[176:179], v153 offset:1024
	ds_read_b128 v[180:183], v153 offset:2048
	ds_read_b128 v[184:187], v153 offset:3072
	ds_read_b128 v[188:191], v153 offset:4096
	ds_read_b128 v[192:195], v153 offset:5120
	ds_read_b128 v[196:199], v153 offset:6144
	ds_read_b128 v[200:203], v153 offset:7168
	global_load_lds_dwordx4 v[204:205], off
	v_lshl_add_u64 v[204:205], s[30:31], 0, v[140:141]
	s_add_i32 m0, s17, 0xe000
	s_nop 0
	global_load_lds_dwordx4 v[204:205], off
	s_waitcnt lgkmcnt(8)
	s_waitcnt vmcnt(10)
	s_barrier
	s_waitcnt lgkmcnt(0)
	s_waitcnt lgkmcnt(0)
	v_mfma_f32_16x16x32_bf16 v[124:127], v[156:159], v[172:175], v[124:127]
	v_mfma_f32_16x16x32_bf16 v[120:123], v[164:167], v[172:175], v[120:123]
	v_mfma_f32_16x16x32_bf16 v[116:119], v[156:159], v[180:183], v[116:119]
	v_mfma_f32_16x16x32_bf16 v[112:115], v[164:167], v[180:183], v[112:115]
	v_mfma_f32_16x16x32_bf16 v[100:103], v[156:159], v[188:191], v[100:103]
	v_mfma_f32_16x16x32_bf16 v[96:99], v[164:167], v[188:191], v[96:99]
	v_mfma_f32_16x16x32_bf16 v[84:87], v[156:159], v[196:199], v[84:87]
	v_mfma_f32_16x16x32_bf16 v[80:83], v[164:167], v[196:199], v[80:83]
	v_mfma_f32_16x16x32_bf16 v[124:127], v[160:163], v[176:179], v[124:127]
	v_mfma_f32_16x16x32_bf16 v[120:123], v[168:171], v[176:179], v[120:123]
	v_mfma_f32_16x16x32_bf16 v[116:119], v[160:163], v[184:187], v[116:119]
	v_mfma_f32_16x16x32_bf16 v[112:115], v[168:171], v[184:187], v[112:115]
	v_mfma_f32_16x16x32_bf16 v[100:103], v[160:163], v[192:195], v[100:103]
	v_mfma_f32_16x16x32_bf16 v[96:99], v[168:171], v[192:195], v[96:99]
	v_mfma_f32_16x16x32_bf16 v[84:87], v[160:163], v[200:203], v[84:87]
	v_mfma_f32_16x16x32_bf16 v[80:83], v[168:171], v[200:203], v[80:83]
	s_barrier
	s_add_i32 s86, s74, s57
	v_lshl_add_u64 v[220:221], s[34:35], 0, v[134:135]
	s_mov_b32 m0, s86
	ds_read_b128 v[204:207], v154
	ds_read_b128 v[208:211], v154 offset:1024
	ds_read_b128 v[212:215], v154 offset:2048
	ds_read_b128 v[216:219], v154 offset:3072
	global_load_lds_dwordx4 v[220:221], off
	v_lshl_add_u64 v[222:223], s[34:35], 0, v[130:131]
	s_add_i32 m0, s86, 0x2000
	s_nop 0
	global_load_lds_dwordx4 v[222:223], off
	s_waitcnt vmcnt(10)
	s_barrier
	s_waitcnt lgkmcnt(0)
	s_waitcnt lgkmcnt(0)
	v_mfma_f32_16x16x32_bf16 v[108:111], v[204:207], v[172:175], v[108:111]
	v_mfma_f32_16x16x32_bf16 v[104:107], v[212:215], v[172:175], v[104:107]
	v_mfma_f32_16x16x32_bf16 v[92:95], v[204:207], v[180:183], v[92:95]
	v_mfma_f32_16x16x32_bf16 v[88:91], v[212:215], v[180:183], v[88:91]
	v_mfma_f32_16x16x32_bf16 v[76:79], v[204:207], v[188:191], v[76:79]
	v_mfma_f32_16x16x32_bf16 v[72:75], v[212:215], v[188:191], v[72:75]
	v_mfma_f32_16x16x32_bf16 v[68:71], v[204:207], v[196:199], v[68:71]
	v_mfma_f32_16x16x32_bf16 v[64:67], v[212:215], v[196:199], v[64:67]
	v_mfma_f32_16x16x32_bf16 v[108:111], v[208:211], v[176:179], v[108:111]
	v_mfma_f32_16x16x32_bf16 v[104:107], v[216:219], v[176:179], v[104:107]
	v_mfma_f32_16x16x32_bf16 v[92:95], v[208:211], v[184:187], v[92:95]
	v_mfma_f32_16x16x32_bf16 v[88:91], v[216:219], v[184:187], v[88:91]
	v_mfma_f32_16x16x32_bf16 v[76:79], v[208:211], v[192:195], v[76:79]
	v_mfma_f32_16x16x32_bf16 v[72:75], v[216:219], v[192:195], v[72:75]
	v_mfma_f32_16x16x32_bf16 v[68:71], v[208:211], v[200:203], v[68:71]
	v_mfma_f32_16x16x32_bf16 v[64:67], v[216:219], v[200:203], v[64:67]
	s_mov_b32 m0, s17
	v_lshl_add_u64 v[224:225], s[54:55], 0, v[136:137]
	s_barrier
	ds_read_b128 v[172:175], v153 offset:16384
	ds_read_b128 v[176:179], v153 offset:17408
	ds_read_b128 v[180:183], v153 offset:18432
	ds_read_b128 v[184:187], v153 offset:19456
	ds_read_b128 v[188:191], v153 offset:20480
	ds_read_b128 v[192:195], v153 offset:21504
	ds_read_b128 v[196:199], v153 offset:22528
	ds_read_b128 v[200:203], v153 offset:23552
	global_load_lds_dwordx4 v[224:225], off
	v_lshl_add_u64 v[226:227], s[54:55], 0, v[132:133]
	s_mov_b32 m0, s61
	s_nop 0
	global_load_lds_dwordx4 v[226:227], off
	s_waitcnt vmcnt(10)
	s_barrier
	s_waitcnt lgkmcnt(0)
	s_waitcnt lgkmcnt(0)
	v_mfma_f32_16x16x32_bf16 v[60:63], v[156:159], v[172:175], v[60:63]
	v_mfma_f32_16x16x32_bf16 v[56:59], v[164:167], v[172:175], v[56:59]
	v_mfma_f32_16x16x32_bf16 v[52:55], v[156:159], v[180:183], v[52:55]
	v_mfma_f32_16x16x32_bf16 v[48:51], v[164:167], v[180:183], v[48:51]
	v_mfma_f32_16x16x32_bf16 v[36:39], v[156:159], v[188:191], v[36:39]
	v_mfma_f32_16x16x32_bf16 v[32:35], v[164:167], v[188:191], v[32:35]
	v_mfma_f32_16x16x32_bf16 v[20:23], v[156:159], v[196:199], v[20:23]
	v_mfma_f32_16x16x32_bf16 v[16:19], v[164:167], v[196:199], v[16:19]
	v_mfma_f32_16x16x32_bf16 v[60:63], v[160:163], v[176:179], v[60:63]
	v_mfma_f32_16x16x32_bf16 v[56:59], v[168:171], v[176:179], v[56:59]
	v_mfma_f32_16x16x32_bf16 v[52:55], v[160:163], v[184:187], v[52:55]
	v_mfma_f32_16x16x32_bf16 v[48:51], v[168:171], v[184:187], v[48:51]
	v_mfma_f32_16x16x32_bf16 v[36:39], v[160:163], v[192:195], v[36:39]
	v_mfma_f32_16x16x32_bf16 v[32:35], v[168:171], v[192:195], v[32:35]
	v_mfma_f32_16x16x32_bf16 v[20:23], v[160:163], v[200:203], v[20:23]
	v_mfma_f32_16x16x32_bf16 v[16:19], v[168:171], v[200:203], v[16:19]
	s_barrier
	s_add_u32 s86, s34, 0x100000
	s_addc_u32 s87, s35, 0
	s_add_i32 s88, s75, s57
	v_lshl_add_u64 v[156:157], s[86:87], 0, v[134:135]
	s_mov_b32 m0, s88
	s_nop 0
	global_load_lds_dwordx4 v[156:157], off
	v_lshl_add_u64 v[156:157], s[86:87], 0, v[130:131]
	s_add_i32 m0, s88, 0x2000
	s_nop 0
	global_load_lds_dwordx4 v[156:157], off
	s_waitcnt vmcnt(10)
	s_barrier
	v_mfma_f32_16x16x32_bf16 v[44:47], v[204:207], v[172:175], v[44:47]
	v_mfma_f32_16x16x32_bf16 v[40:43], v[212:215], v[172:175], v[40:43]
	v_mfma_f32_16x16x32_bf16 v[28:31], v[204:207], v[180:183], v[28:31]
	v_mfma_f32_16x16x32_bf16 v[24:27], v[212:215], v[180:183], v[24:27]
	v_mfma_f32_16x16x32_bf16 v[12:15], v[204:207], v[188:191], v[12:15]
	v_mfma_f32_16x16x32_bf16 v[8:11], v[212:215], v[188:191], v[8:11]
	v_mfma_f32_16x16x32_bf16 v[4:7], v[204:207], v[196:199], v[4:7]
	v_mfma_f32_16x16x32_bf16 v[0:3], v[212:215], v[196:199], v[0:3]
	v_mfma_f32_16x16x32_bf16 v[44:47], v[208:211], v[176:179], v[44:47]
	v_mfma_f32_16x16x32_bf16 v[40:43], v[216:219], v[176:179], v[40:43]
	v_mfma_f32_16x16x32_bf16 v[28:31], v[208:211], v[184:187], v[28:31]
	v_mfma_f32_16x16x32_bf16 v[24:27], v[216:219], v[184:187], v[24:27]
	v_mfma_f32_16x16x32_bf16 v[12:15], v[208:211], v[192:195], v[12:15]
	v_mfma_f32_16x16x32_bf16 v[8:11], v[216:219], v[192:195], v[8:11]
	v_mfma_f32_16x16x32_bf16 v[4:7], v[208:211], v[200:203], v[4:7]
	v_mfma_f32_16x16x32_bf16 v[0:3], v[216:219], v[200:203], v[0:3]
	s_add_i32 s86, 0, 0x18000
	v_add_u32_e32 v155, s86, v150
	s_barrier
	ds_read_b128 v[156:159], v155
	ds_read_b128 v[160:163], v155 offset:1024
	ds_read_b128 v[164:167], v155 offset:2048
	ds_read_b128 v[168:171], v155 offset:3072
	s_add_u32 s54, s54, 0x100000
	s_addc_u32 s55, s55, 0
	s_mov_b32 m0, s62
	v_lshl_add_u64 v[204:205], s[54:55], 0, v[136:137]
	ds_read_b128 v[172:175], v153 offset:32768
	ds_read_b128 v[176:179], v153 offset:33792
	ds_read_b128 v[180:183], v153 offset:34816
	ds_read_b128 v[184:187], v153 offset:35840
	ds_read_b128 v[188:191], v153 offset:36864
	ds_read_b128 v[192:195], v153 offset:37888
	ds_read_b128 v[196:199], v153 offset:38912
	ds_read_b128 v[200:203], v153 offset:39936
	global_load_lds_dwordx4 v[204:205], off
	v_lshl_add_u64 v[204:205], s[54:55], 0, v[132:133]
	s_mov_b32 m0, s63
	s_nop 0
	global_load_lds_dwordx4 v[204:205], off
	s_waitcnt lgkmcnt(8)
	s_waitcnt vmcnt(10)
	s_barrier
	s_waitcnt lgkmcnt(0)
	s_waitcnt lgkmcnt(0)
	v_mfma_f32_16x16x32_bf16 v[124:127], v[156:159], v[172:175], v[124:127]
	v_mfma_f32_16x16x32_bf16 v[120:123], v[164:167], v[172:175], v[120:123]
	v_mfma_f32_16x16x32_bf16 v[116:119], v[156:159], v[180:183], v[116:119]
	v_mfma_f32_16x16x32_bf16 v[112:115], v[164:167], v[180:183], v[112:115]
	v_mfma_f32_16x16x32_bf16 v[100:103], v[156:159], v[188:191], v[100:103]
	v_mfma_f32_16x16x32_bf16 v[96:99], v[164:167], v[188:191], v[96:99]
	v_mfma_f32_16x16x32_bf16 v[84:87], v[156:159], v[196:199], v[84:87]
	v_mfma_f32_16x16x32_bf16 v[80:83], v[164:167], v[196:199], v[80:83]
	v_mfma_f32_16x16x32_bf16 v[124:127], v[160:163], v[176:179], v[124:127]
	v_mfma_f32_16x16x32_bf16 v[120:123], v[168:171], v[176:179], v[120:123]
	v_mfma_f32_16x16x32_bf16 v[116:119], v[160:163], v[184:187], v[116:119]
	v_mfma_f32_16x16x32_bf16 v[112:115], v[168:171], v[184:187], v[112:115]
	v_mfma_f32_16x16x32_bf16 v[100:103], v[160:163], v[192:195], v[100:103]
	v_mfma_f32_16x16x32_bf16 v[96:99], v[168:171], v[192:195], v[96:99]
	v_mfma_f32_16x16x32_bf16 v[84:87], v[160:163], v[200:203], v[84:87]
	v_mfma_f32_16x16x32_bf16 v[80:83], v[168:171], v[200:203], v[80:83]
	s_barrier
	s_add_i32 s54, 0, 0x1c000
	s_add_i32 s55, s86, s57
	v_add_u32_e32 v155, s54, v150
	v_lshl_add_u64 v[220:221], v[220:221], 0, s[8:9]
	s_mov_b32 m0, s55
	ds_read_b128 v[204:207], v155
	ds_read_b128 v[208:211], v155 offset:1024
	ds_read_b128 v[212:215], v155 offset:2048
	ds_read_b128 v[216:219], v155 offset:3072
	global_load_lds_dwordx4 v[220:221], off
	v_lshl_add_u64 v[220:221], v[222:223], 0, s[8:9]
	s_add_i32 m0, s55, 0x2000
	s_nop 0
	global_load_lds_dwordx4 v[220:221], off
	s_waitcnt vmcnt(10)
	s_barrier
	s_waitcnt lgkmcnt(0)
	s_waitcnt lgkmcnt(0)
	v_mfma_f32_16x16x32_bf16 v[108:111], v[204:207], v[172:175], v[108:111]
	v_mfma_f32_16x16x32_bf16 v[104:107], v[212:215], v[172:175], v[104:107]
	v_mfma_f32_16x16x32_bf16 v[92:95], v[204:207], v[180:183], v[92:95]
	v_mfma_f32_16x16x32_bf16 v[88:91], v[212:215], v[180:183], v[88:91]
	v_mfma_f32_16x16x32_bf16 v[76:79], v[204:207], v[188:191], v[76:79]
	v_mfma_f32_16x16x32_bf16 v[72:75], v[212:215], v[188:191], v[72:75]
	v_mfma_f32_16x16x32_bf16 v[68:71], v[204:207], v[196:199], v[68:71]
	v_mfma_f32_16x16x32_bf16 v[64:67], v[212:215], v[196:199], v[64:67]
	v_mfma_f32_16x16x32_bf16 v[108:111], v[208:211], v[176:179], v[108:111]
	v_mfma_f32_16x16x32_bf16 v[104:107], v[216:219], v[176:179], v[104:107]
	v_mfma_f32_16x16x32_bf16 v[92:95], v[208:211], v[184:187], v[92:95]
	v_mfma_f32_16x16x32_bf16 v[88:91], v[216:219], v[184:187], v[88:91]
	v_mfma_f32_16x16x32_bf16 v[76:79], v[208:211], v[192:195], v[76:79]
	v_mfma_f32_16x16x32_bf16 v[72:75], v[216:219], v[192:195], v[72:75]
	v_mfma_f32_16x16x32_bf16 v[68:71], v[208:211], v[200:203], v[68:71]
	v_mfma_f32_16x16x32_bf16 v[64:67], v[216:219], v[200:203], v[64:67]
	s_mov_b32 m0, s71
	v_lshl_add_u64 v[220:221], v[224:225], 0, s[8:9]
	s_barrier
	ds_read_b128 v[172:175], v153 offset:49152
	ds_read_b128 v[176:179], v153 offset:50176
	ds_read_b128 v[180:183], v153 offset:51200
	ds_read_b128 v[184:187], v153 offset:52224
	ds_read_b128 v[188:191], v153 offset:53248
	ds_read_b128 v[192:195], v153 offset:54272
	ds_read_b128 v[196:199], v153 offset:55296
	ds_read_b128 v[200:203], v153 offset:56320
	global_load_lds_dwordx4 v[220:221], off
	v_lshl_add_u64 v[220:221], v[226:227], 0, s[8:9]
	s_mov_b32 m0, s72
	s_nop 0
	global_load_lds_dwordx4 v[220:221], off
	s_waitcnt vmcnt(10)
	s_barrier
	s_waitcnt lgkmcnt(0)
	s_waitcnt lgkmcnt(0)
	v_mfma_f32_16x16x32_bf16 v[60:63], v[156:159], v[172:175], v[60:63]
	v_mfma_f32_16x16x32_bf16 v[56:59], v[164:167], v[172:175], v[56:59]
	v_mfma_f32_16x16x32_bf16 v[52:55], v[156:159], v[180:183], v[52:55]
	v_mfma_f32_16x16x32_bf16 v[48:51], v[164:167], v[180:183], v[48:51]
	v_mfma_f32_16x16x32_bf16 v[36:39], v[156:159], v[188:191], v[36:39]
	v_mfma_f32_16x16x32_bf16 v[32:35], v[164:167], v[188:191], v[32:35]
	v_mfma_f32_16x16x32_bf16 v[20:23], v[156:159], v[196:199], v[20:23]
	v_mfma_f32_16x16x32_bf16 v[16:19], v[164:167], v[196:199], v[16:19]
	v_mfma_f32_16x16x32_bf16 v[60:63], v[160:163], v[176:179], v[60:63]
	v_mfma_f32_16x16x32_bf16 v[56:59], v[168:171], v[176:179], v[56:59]
	v_mfma_f32_16x16x32_bf16 v[52:55], v[160:163], v[184:187], v[52:55]
	v_mfma_f32_16x16x32_bf16 v[48:51], v[168:171], v[184:187], v[48:51]
	v_mfma_f32_16x16x32_bf16 v[36:39], v[160:163], v[192:195], v[36:39]
	v_mfma_f32_16x16x32_bf16 v[32:35], v[168:171], v[192:195], v[32:35]
	v_mfma_f32_16x16x32_bf16 v[20:23], v[160:163], v[200:203], v[20:23]
	v_mfma_f32_16x16x32_bf16 v[16:19], v[168:171], v[200:203], v[16:19]
	s_barrier
	s_add_u32 s34, s34, 0x100080
	s_addc_u32 s35, s35, 0
	s_add_i32 s54, s54, s57
	v_lshl_add_u64 v[156:157], s[34:35], 0, v[134:135]
	s_mov_b32 m0, s54
	s_nop 0
	global_load_lds_dwordx4 v[156:157], off
	v_lshl_add_u64 v[156:157], s[34:35], 0, v[130:131]
	s_add_i32 m0, s54, 0x2000
	s_nop 0
	global_load_lds_dwordx4 v[156:157], off
	s_waitcnt vmcnt(10)
	s_barrier
	v_mfma_f32_16x16x32_bf16 v[44:47], v[204:207], v[172:175], v[44:47]
	v_mfma_f32_16x16x32_bf16 v[40:43], v[212:215], v[172:175], v[40:43]
	v_mfma_f32_16x16x32_bf16 v[28:31], v[204:207], v[180:183], v[28:31]
	v_mfma_f32_16x16x32_bf16 v[24:27], v[212:215], v[180:183], v[24:27]
	v_mfma_f32_16x16x32_bf16 v[12:15], v[204:207], v[188:191], v[12:15]
	v_mfma_f32_16x16x32_bf16 v[8:11], v[212:215], v[188:191], v[8:11]
	v_mfma_f32_16x16x32_bf16 v[4:7], v[204:207], v[196:199], v[4:7]
	v_mfma_f32_16x16x32_bf16 v[0:3], v[212:215], v[196:199], v[0:3]
	v_mfma_f32_16x16x32_bf16 v[44:47], v[208:211], v[176:179], v[44:47]
	v_mfma_f32_16x16x32_bf16 v[40:43], v[216:219], v[176:179], v[40:43]
	v_mfma_f32_16x16x32_bf16 v[28:31], v[208:211], v[184:187], v[28:31]
	v_mfma_f32_16x16x32_bf16 v[24:27], v[216:219], v[184:187], v[24:27]
	v_mfma_f32_16x16x32_bf16 v[12:15], v[208:211], v[192:195], v[12:15]
	v_mfma_f32_16x16x32_bf16 v[8:11], v[216:219], v[192:195], v[8:11]
	v_mfma_f32_16x16x32_bf16 v[4:7], v[208:211], v[200:203], v[4:7]
	v_mfma_f32_16x16x32_bf16 v[0:3], v[216:219], v[200:203], v[0:3]
	s_add_i32 s85, s85, 2
	s_add_u32 s30, s30, 0x100
	s_addc_u32 s31, s31, 0
	s_add_u32 s83, s83, 0x100
	s_addc_u32 s84, s84, 0
	s_cmp_gt_u32 s85, 61
	s_barrier
	s_cbranch_scc0 .LBB0_776
	v_lshl_add_u32 v156, s16, 8, v149
	v_lshl_or_b32 v158, s80, 8, v151
	v_ashrrev_i32_e32 v157, 31, v156
	v_lshlrev_b64 v[160:161], 11, v[156:157]
	v_ashrrev_i32_e32 v159, 31, v158
	v_lshl_add_u64 v[160:161], s[44:45], 0, v[160:161]
	v_cvt_pk_bf16_f32 v124, v124, v125
	v_cvt_pk_bf16_f32 v125, v126, v127
	v_cvt_pk_bf16_f32 v126, v120, v121
	v_lshlrev_b64 v[120:121], 1, v[158:159]
	v_cvt_pk_bf16_f32 v127, v122, v123
	v_lshl_add_u64 v[122:123], v[160:161], 0, v[120:121]
	v_cvt_pk_bf16_f32 v108, v108, v109
	v_cvt_pk_bf16_f32 v109, v110, v111
	v_cvt_pk_bf16_f32 v110, v104, v105
	v_or_b32_e32 v104, 16, v156
	v_cvt_pk_bf16_f32 v60, v60, v61
	v_cvt_pk_bf16_f32 v61, v62, v63
	v_cvt_pk_bf16_f32 v63, v58, v59
	s_mov_b64 s[30:31], 0x40000
	v_add_co_u32_e32 v58, vcc, s76, v122
	v_ashrrev_i32_e32 v105, 31, v104
	v_cvt_pk_bf16_f32 v62, v56, v57
	v_lshl_add_u64 v[56:57], v[122:123], 0, s[30:31]
	v_addc_co_u32_e32 v59, vcc, 0, v123, vcc
	v_cvt_pk_bf16_f32 v44, v44, v45
	v_cvt_pk_bf16_f32 v45, v46, v47
	v_cvt_pk_bf16_f32 v46, v40, v41
	v_cvt_pk_bf16_f32 v47, v42, v43
	v_cvt_pk_bf16_f32 v111, v106, v107
	v_lshlrev_b64 v[104:105], 11, v[104:105]
	v_cvt_pk_bf16_f32 v92, v92, v93
	v_cvt_pk_bf16_f32 v93, v94, v95
	v_cvt_pk_bf16_f32 v94, v88, v89
	v_or_b32_e32 v88, 32, v156
	global_store_dwordx4 v[56:57], v[44:47], off offset:256
	global_store_dwordx4 v[122:123], v[108:111], off offset:256
	v_ashrrev_i32_e32 v89, 31, v88
	v_add_co_u32_e32 v46, vcc, s77, v122
	v_lshl_add_u64 v[108:109], s[44:45], 0, v[104:105]
	v_lshl_add_u64 v[44:45], v[122:123], 0, s[10:11]
	v_addc_co_u32_e32 v47, vcc, 0, v123, vcc
	v_cvt_pk_bf16_f32 v28, v28, v29
	v_cvt_pk_bf16_f32 v29, v30, v31
	v_cvt_pk_bf16_f32 v30, v24, v25
	v_cvt_pk_bf16_f32 v31, v26, v27
	v_lshl_add_u64 v[108:109], v[108:109], 0, v[120:121]
	v_cvt_pk_bf16_f32 v95, v90, v91
	v_lshlrev_b64 v[88:89], 11, v[88:89]
	v_cvt_pk_bf16_f32 v76, v76, v77
	v_cvt_pk_bf16_f32 v77, v78, v79
	v_cvt_pk_bf16_f32 v78, v72, v73
	v_or_b32_e32 v72, 48, v156
	global_store_dwordx4 v[44:45], v[28:31], off offset:256
	global_store_dwordx4 v[108:109], v[92:95], off offset:256
	v_ashrrev_i32_e32 v73, 31, v72
	v_add_co_u32_e32 v30, vcc, s78, v122
	v_lshl_add_u64 v[92:93], s[44:45], 0, v[88:89]
	v_lshl_add_u64 v[28:29], v[122:123], 0, s[12:13]
	v_addc_co_u32_e32 v31, vcc, 0, v123, vcc
	v_cvt_pk_bf16_f32 v12, v12, v13
	v_cvt_pk_bf16_f32 v13, v14, v15
	v_cvt_pk_bf16_f32 v14, v8, v9
	v_cvt_pk_bf16_f32 v15, v10, v11
	v_lshl_add_u64 v[92:93], v[92:93], 0, v[120:121]
	v_cvt_pk_bf16_f32 v79, v74, v75
	v_lshlrev_b64 v[72:73], 11, v[72:73]
	global_store_dwordx4 v[28:29], v[12:15], off offset:256
	global_store_dwordx4 v[92:93], v[76:79], off offset:256
	v_cvt_pk_bf16_f32 v104, v116, v117
	v_add_co_u32_e32 v14, vcc, s79, v122
	v_lshl_add_u64 v[76:77], s[44:45], 0, v[72:73]
	s_nop 0
	v_addc_co_u32_e32 v15, vcc, 0, v123, vcc
	v_cvt_pk_bf16_f32 v105, v118, v119
	v_cvt_pk_bf16_f32 v106, v112, v113
	v_cvt_pk_bf16_f32 v107, v114, v115
	v_cvt_pk_bf16_f32 v88, v100, v101
	v_cvt_pk_bf16_f32 v89, v102, v103
	v_cvt_pk_bf16_f32 v90, v96, v97
	v_cvt_pk_bf16_f32 v91, v98, v99
	v_cvt_pk_bf16_f32 v72, v84, v85
	v_cvt_pk_bf16_f32 v73, v86, v87
	v_cvt_pk_bf16_f32 v74, v80, v81
	v_cvt_pk_bf16_f32 v75, v82, v83
	v_lshl_add_u64 v[76:77], v[76:77], 0, v[120:121]
	v_cvt_pk_bf16_f32 v68, v68, v69
	v_cvt_pk_bf16_f32 v69, v70, v71
	v_cvt_pk_bf16_f32 v70, v64, v65
	v_cvt_pk_bf16_f32 v71, v66, v67
	v_cvt_pk_bf16_f32 v40, v52, v53
	v_cvt_pk_bf16_f32 v41, v54, v55
	v_cvt_pk_bf16_f32 v42, v48, v49
	v_cvt_pk_bf16_f32 v43, v50, v51
	v_cvt_pk_bf16_f32 v24, v36, v37
	v_cvt_pk_bf16_f32 v25, v38, v39
	v_cvt_pk_bf16_f32 v26, v32, v33
	v_cvt_pk_bf16_f32 v27, v34, v35
	v_cvt_pk_bf16_f32 v8, v20, v21
	v_cvt_pk_bf16_f32 v9, v22, v23
	v_cvt_pk_bf16_f32 v10, v16, v17
	v_cvt_pk_bf16_f32 v11, v18, v19
	v_lshl_add_u64 v[12:13], v[122:123], 0, s[14:15]
	v_cvt_pk_bf16_f32 v4, v4, v5
	v_cvt_pk_bf16_f32 v5, v6, v7
	v_cvt_pk_bf16_f32 v6, v0, v1
	v_cvt_pk_bf16_f32 v7, v2, v3
	s_and_b64 vcc, exec, s[4:5]
	s_mov_b32 s80, s18
	s_mov_b32 s16, s20
	s_mov_b64 s[34:35], s[28:29]
	s_mov_b64 s[30:31], s[26:27]
	global_store_dwordx4 v[122:123], v[124:127], off
	global_store_dwordx4 v[108:109], v[104:107], off
	global_store_dwordx4 v[92:93], v[88:91], off
	global_store_dwordx4 v[76:77], v[72:75], off
	global_store_dwordx4 v[76:77], v[68:71], off offset:256
	global_store_dwordx4 v[58:59], v[60:63], off
	global_store_dwordx4 v[46:47], v[40:43], off
	global_store_dwordx4 v[30:31], v[24:27], off
	global_store_dwordx4 v[14:15], v[8:11], off
	global_store_dwordx4 v[12:13], v[4:7], off offset:256
	s_cbranch_vccz .LBB0_773
	s_waitcnt vmcnt(16)
	s_cmpk_gt_u32 s56, 0xff
	s_cbranch_scc1 .LBB0_780
	s_barrier

.LBB0_912:
	ds_read_b128 v[156:159], v152
	ds_read_b128 v[160:163], v152 offset:1024
	ds_read_b128 v[164:167], v152 offset:2048
	ds_read_b128 v[168:171], v152 offset:3072
	s_add_u32 s54, s34, 0xfffc0080
	s_addc_u32 s55, s35, -1
	s_cmp_eq_u32 s87, 12
	s_cselect_b32 s57, s27, s55
	s_cselect_b32 s56, s83, s54
	s_cselect_b32 s55, s21, s86
	s_cselect_b32 s54, s84, s85
	v_lshl_add_u64 v[204:205], s[34:35], 0, v[138:139]
	s_add_i32 m0, s19, 0xc000
	ds_read_b128 v[172:175], v153
	ds_read_b128 v[176:179], v153 offset:1024
	ds_read_b128 v[180:183], v153 offset:2048
	ds_read_b128 v[184:187], v153 offset:3072
	ds_read_b128 v[188:191], v153 offset:4096
	ds_read_b128 v[192:195], v153 offset:5120
	ds_read_b128 v[196:199], v153 offset:6144
	ds_read_b128 v[200:203], v153 offset:7168
	global_load_lds_dwordx4 v[204:205], off
	v_lshl_add_u64 v[204:205], s[34:35], 0, v[140:141]
	s_add_i32 m0, s19, 0xe000
	s_nop 0
	global_load_lds_dwordx4 v[204:205], off
	s_waitcnt lgkmcnt(8)
	s_waitcnt vmcnt(10)
	s_barrier
	s_waitcnt lgkmcnt(0)
	s_waitcnt lgkmcnt(0)
	v_mfma_f32_16x16x32_bf16 v[124:127], v[156:159], v[172:175], v[124:127]
	v_mfma_f32_16x16x32_bf16 v[120:123], v[164:167], v[172:175], v[120:123]
	v_mfma_f32_16x16x32_bf16 v[116:119], v[156:159], v[180:183], v[116:119]
	v_mfma_f32_16x16x32_bf16 v[112:115], v[164:167], v[180:183], v[112:115]
	v_mfma_f32_16x16x32_bf16 v[100:103], v[156:159], v[188:191], v[100:103]
	v_mfma_f32_16x16x32_bf16 v[96:99], v[164:167], v[188:191], v[96:99]
	v_mfma_f32_16x16x32_bf16 v[84:87], v[156:159], v[196:199], v[84:87]
	v_mfma_f32_16x16x32_bf16 v[80:83], v[164:167], v[196:199], v[80:83]
	v_mfma_f32_16x16x32_bf16 v[124:127], v[160:163], v[176:179], v[124:127]
	v_mfma_f32_16x16x32_bf16 v[120:123], v[168:171], v[176:179], v[120:123]
	v_mfma_f32_16x16x32_bf16 v[116:119], v[160:163], v[184:187], v[116:119]
	v_mfma_f32_16x16x32_bf16 v[112:115], v[168:171], v[184:187], v[112:115]
	v_mfma_f32_16x16x32_bf16 v[100:103], v[160:163], v[192:195], v[100:103]
	v_mfma_f32_16x16x32_bf16 v[96:99], v[168:171], v[192:195], v[96:99]
	v_mfma_f32_16x16x32_bf16 v[84:87], v[160:163], v[200:203], v[84:87]
	v_mfma_f32_16x16x32_bf16 v[80:83], v[168:171], v[200:203], v[80:83]
	s_barrier
	s_add_i32 s88, s76, s61
	v_lshl_add_u64 v[220:221], s[54:55], 0, v[134:135]
	s_mov_b32 m0, s88
	ds_read_b128 v[204:207], v154
	ds_read_b128 v[208:211], v154 offset:1024
	ds_read_b128 v[212:215], v154 offset:2048
	ds_read_b128 v[216:219], v154 offset:3072
	global_load_lds_dwordx4 v[220:221], off
	v_lshl_add_u64 v[222:223], s[54:55], 0, v[130:131]
	s_add_i32 m0, s88, 0x2000
	s_nop 0
	global_load_lds_dwordx4 v[222:223], off
	s_waitcnt vmcnt(10)
	s_barrier
	s_waitcnt lgkmcnt(0)
	s_waitcnt lgkmcnt(0)
	v_mfma_f32_16x16x32_bf16 v[108:111], v[204:207], v[172:175], v[108:111]
	v_mfma_f32_16x16x32_bf16 v[104:107], v[212:215], v[172:175], v[104:107]
	v_mfma_f32_16x16x32_bf16 v[92:95], v[204:207], v[180:183], v[92:95]
	v_mfma_f32_16x16x32_bf16 v[88:91], v[212:215], v[180:183], v[88:91]
	v_mfma_f32_16x16x32_bf16 v[76:79], v[204:207], v[188:191], v[76:79]
	v_mfma_f32_16x16x32_bf16 v[72:75], v[212:215], v[188:191], v[72:75]
	v_mfma_f32_16x16x32_bf16 v[68:71], v[204:207], v[196:199], v[68:71]
	v_mfma_f32_16x16x32_bf16 v[64:67], v[212:215], v[196:199], v[64:67]
	v_mfma_f32_16x16x32_bf16 v[108:111], v[208:211], v[176:179], v[108:111]
	v_mfma_f32_16x16x32_bf16 v[104:107], v[216:219], v[176:179], v[104:107]
	v_mfma_f32_16x16x32_bf16 v[92:95], v[208:211], v[184:187], v[92:95]
	v_mfma_f32_16x16x32_bf16 v[88:91], v[216:219], v[184:187], v[88:91]
	v_mfma_f32_16x16x32_bf16 v[76:79], v[208:211], v[192:195], v[76:79]
	v_mfma_f32_16x16x32_bf16 v[72:75], v[216:219], v[192:195], v[72:75]
	v_mfma_f32_16x16x32_bf16 v[68:71], v[208:211], v[200:203], v[68:71]
	v_mfma_f32_16x16x32_bf16 v[64:67], v[216:219], v[200:203], v[64:67]
	s_mov_b32 m0, s19
	v_lshl_add_u64 v[224:225], s[56:57], 0, v[136:137]
	s_barrier
	ds_read_b128 v[172:175], v153 offset:16384
	ds_read_b128 v[176:179], v153 offset:17408
	ds_read_b128 v[180:183], v153 offset:18432
	ds_read_b128 v[184:187], v153 offset:19456
	ds_read_b128 v[188:191], v153 offset:20480
	ds_read_b128 v[192:195], v153 offset:21504
	ds_read_b128 v[196:199], v153 offset:22528
	ds_read_b128 v[200:203], v153 offset:23552
	global_load_lds_dwordx4 v[224:225], off
	v_lshl_add_u64 v[226:227], s[56:57], 0, v[132:133]
	s_mov_b32 m0, s63
	s_nop 0
	global_load_lds_dwordx4 v[226:227], off
	s_waitcnt vmcnt(10)
	s_barrier
	s_waitcnt lgkmcnt(0)
	s_waitcnt lgkmcnt(0)
	v_mfma_f32_16x16x32_bf16 v[60:63], v[156:159], v[172:175], v[60:63]
	v_mfma_f32_16x16x32_bf16 v[56:59], v[164:167], v[172:175], v[56:59]
	v_mfma_f32_16x16x32_bf16 v[52:55], v[156:159], v[180:183], v[52:55]
	v_mfma_f32_16x16x32_bf16 v[48:51], v[164:167], v[180:183], v[48:51]
	v_mfma_f32_16x16x32_bf16 v[36:39], v[156:159], v[188:191], v[36:39]
	v_mfma_f32_16x16x32_bf16 v[32:35], v[164:167], v[188:191], v[32:35]
	v_mfma_f32_16x16x32_bf16 v[20:23], v[156:159], v[196:199], v[20:23]
	v_mfma_f32_16x16x32_bf16 v[16:19], v[164:167], v[196:199], v[16:19]
	v_mfma_f32_16x16x32_bf16 v[60:63], v[160:163], v[176:179], v[60:63]
	v_mfma_f32_16x16x32_bf16 v[56:59], v[168:171], v[176:179], v[56:59]
	v_mfma_f32_16x16x32_bf16 v[52:55], v[160:163], v[184:187], v[52:55]
	v_mfma_f32_16x16x32_bf16 v[48:51], v[168:171], v[184:187], v[48:51]
	v_mfma_f32_16x16x32_bf16 v[36:39], v[160:163], v[192:195], v[36:39]
	v_mfma_f32_16x16x32_bf16 v[32:35], v[168:171], v[192:195], v[32:35]
	v_mfma_f32_16x16x32_bf16 v[20:23], v[160:163], v[200:203], v[20:23]
	v_mfma_f32_16x16x32_bf16 v[16:19], v[168:171], v[200:203], v[16:19]
	s_barrier
	s_add_u32 s88, s54, 0x40000
	s_addc_u32 s89, s55, 0
	s_add_i32 s90, s77, s61
	v_lshl_add_u64 v[156:157], s[88:89], 0, v[134:135]
	s_mov_b32 m0, s90
	s_nop 0
	global_load_lds_dwordx4 v[156:157], off
	v_lshl_add_u64 v[156:157], s[88:89], 0, v[130:131]
	s_add_i32 m0, s90, 0x2000
	s_nop 0
	global_load_lds_dwordx4 v[156:157], off
	s_waitcnt vmcnt(10)
	s_barrier
	v_mfma_f32_16x16x32_bf16 v[44:47], v[204:207], v[172:175], v[44:47]
	v_mfma_f32_16x16x32_bf16 v[40:43], v[212:215], v[172:175], v[40:43]
	v_mfma_f32_16x16x32_bf16 v[28:31], v[204:207], v[180:183], v[28:31]
	v_mfma_f32_16x16x32_bf16 v[24:27], v[212:215], v[180:183], v[24:27]
	v_mfma_f32_16x16x32_bf16 v[12:15], v[204:207], v[188:191], v[12:15]
	v_mfma_f32_16x16x32_bf16 v[8:11], v[212:215], v[188:191], v[8:11]
	v_mfma_f32_16x16x32_bf16 v[4:7], v[204:207], v[196:199], v[4:7]
	v_mfma_f32_16x16x32_bf16 v[0:3], v[212:215], v[196:199], v[0:3]
	v_mfma_f32_16x16x32_bf16 v[44:47], v[208:211], v[176:179], v[44:47]
	v_mfma_f32_16x16x32_bf16 v[40:43], v[216:219], v[176:179], v[40:43]
	v_mfma_f32_16x16x32_bf16 v[28:31], v[208:211], v[184:187], v[28:31]
	v_mfma_f32_16x16x32_bf16 v[24:27], v[216:219], v[184:187], v[24:27]
	v_mfma_f32_16x16x32_bf16 v[12:15], v[208:211], v[192:195], v[12:15]
	v_mfma_f32_16x16x32_bf16 v[8:11], v[216:219], v[192:195], v[8:11]
	v_mfma_f32_16x16x32_bf16 v[4:7], v[208:211], v[200:203], v[4:7]
	v_mfma_f32_16x16x32_bf16 v[0:3], v[216:219], v[200:203], v[0:3]
	s_add_i32 s88, 0, 0x18000
	v_add_u32_e32 v155, s88, v150
	s_barrier
	ds_read_b128 v[156:159], v155
	ds_read_b128 v[160:163], v155 offset:1024
	ds_read_b128 v[164:167], v155 offset:2048
	ds_read_b128 v[168:171], v155 offset:3072
	s_add_u32 s56, s56, 0x40000
	s_addc_u32 s57, s57, 0
	s_mov_b32 m0, s70
	v_lshl_add_u64 v[204:205], s[56:57], 0, v[136:137]
	ds_read_b128 v[172:175], v153 offset:32768
	ds_read_b128 v[176:179], v153 offset:33792
	ds_read_b128 v[180:183], v153 offset:34816
	ds_read_b128 v[184:187], v153 offset:35840
	ds_read_b128 v[188:191], v153 offset:36864
	ds_read_b128 v[192:195], v153 offset:37888
	ds_read_b128 v[196:199], v153 offset:38912
	ds_read_b128 v[200:203], v153 offset:39936
	global_load_lds_dwordx4 v[204:205], off
	v_lshl_add_u64 v[204:205], s[56:57], 0, v[132:133]
	s_mov_b32 m0, s71
	s_nop 0
	global_load_lds_dwordx4 v[204:205], off
	s_waitcnt lgkmcnt(8)
	s_waitcnt vmcnt(10)
	s_barrier
	s_waitcnt lgkmcnt(0)
	s_waitcnt lgkmcnt(0)
	v_mfma_f32_16x16x32_bf16 v[124:127], v[156:159], v[172:175], v[124:127]
	v_mfma_f32_16x16x32_bf16 v[120:123], v[164:167], v[172:175], v[120:123]
	v_mfma_f32_16x16x32_bf16 v[116:119], v[156:159], v[180:183], v[116:119]
	v_mfma_f32_16x16x32_bf16 v[112:115], v[164:167], v[180:183], v[112:115]
	v_mfma_f32_16x16x32_bf16 v[100:103], v[156:159], v[188:191], v[100:103]
	v_mfma_f32_16x16x32_bf16 v[96:99], v[164:167], v[188:191], v[96:99]
	v_mfma_f32_16x16x32_bf16 v[84:87], v[156:159], v[196:199], v[84:87]
	v_mfma_f32_16x16x32_bf16 v[80:83], v[164:167], v[196:199], v[80:83]
	v_mfma_f32_16x16x32_bf16 v[124:127], v[160:163], v[176:179], v[124:127]
	v_mfma_f32_16x16x32_bf16 v[120:123], v[168:171], v[176:179], v[120:123]
	v_mfma_f32_16x16x32_bf16 v[116:119], v[160:163], v[184:187], v[116:119]
	v_mfma_f32_16x16x32_bf16 v[112:115], v[168:171], v[184:187], v[112:115]
	v_mfma_f32_16x16x32_bf16 v[100:103], v[160:163], v[192:195], v[100:103]
	v_mfma_f32_16x16x32_bf16 v[96:99], v[168:171], v[192:195], v[96:99]
	v_mfma_f32_16x16x32_bf16 v[84:87], v[160:163], v[200:203], v[84:87]
	v_mfma_f32_16x16x32_bf16 v[80:83], v[168:171], v[200:203], v[80:83]
	s_barrier
	s_add_i32 s56, 0, 0x1c000
	s_add_i32 s57, s88, s61
	v_add_u32_e32 v155, s56, v150
	v_lshl_add_u64 v[220:221], v[220:221], 0, s[10:11]
	s_mov_b32 m0, s57
	ds_read_b128 v[204:207], v155
	ds_read_b128 v[208:211], v155 offset:1024
	ds_read_b128 v[212:215], v155 offset:2048
	ds_read_b128 v[216:219], v155 offset:3072
	global_load_lds_dwordx4 v[220:221], off
	v_lshl_add_u64 v[220:221], v[222:223], 0, s[10:11]
	s_add_i32 m0, s57, 0x2000
	s_nop 0
	global_load_lds_dwordx4 v[220:221], off
	s_waitcnt vmcnt(10)
	s_barrier
	s_waitcnt lgkmcnt(0)
	s_waitcnt lgkmcnt(0)
	v_mfma_f32_16x16x32_bf16 v[108:111], v[204:207], v[172:175], v[108:111]
	v_mfma_f32_16x16x32_bf16 v[104:107], v[212:215], v[172:175], v[104:107]
	v_mfma_f32_16x16x32_bf16 v[92:95], v[204:207], v[180:183], v[92:95]
	v_mfma_f32_16x16x32_bf16 v[88:91], v[212:215], v[180:183], v[88:91]
	v_mfma_f32_16x16x32_bf16 v[76:79], v[204:207], v[188:191], v[76:79]
	v_mfma_f32_16x16x32_bf16 v[72:75], v[212:215], v[188:191], v[72:75]
	v_mfma_f32_16x16x32_bf16 v[68:71], v[204:207], v[196:199], v[68:71]
	v_mfma_f32_16x16x32_bf16 v[64:67], v[212:215], v[196:199], v[64:67]
	v_mfma_f32_16x16x32_bf16 v[108:111], v[208:211], v[176:179], v[108:111]
	v_mfma_f32_16x16x32_bf16 v[104:107], v[216:219], v[176:179], v[104:107]
	v_mfma_f32_16x16x32_bf16 v[92:95], v[208:211], v[184:187], v[92:95]
	v_mfma_f32_16x16x32_bf16 v[88:91], v[216:219], v[184:187], v[88:91]
	v_mfma_f32_16x16x32_bf16 v[76:79], v[208:211], v[192:195], v[76:79]
	v_mfma_f32_16x16x32_bf16 v[72:75], v[216:219], v[192:195], v[72:75]
	v_mfma_f32_16x16x32_bf16 v[68:71], v[208:211], v[200:203], v[68:71]
	v_mfma_f32_16x16x32_bf16 v[64:67], v[216:219], v[200:203], v[64:67]
	s_mov_b32 m0, s73
	v_lshl_add_u64 v[220:221], v[224:225], 0, s[10:11]
	s_barrier
	ds_read_b128 v[172:175], v153 offset:49152
	ds_read_b128 v[176:179], v153 offset:50176
	ds_read_b128 v[180:183], v153 offset:51200
	ds_read_b128 v[184:187], v153 offset:52224
	ds_read_b128 v[188:191], v153 offset:53248
	ds_read_b128 v[192:195], v153 offset:54272
	ds_read_b128 v[196:199], v153 offset:55296
	ds_read_b128 v[200:203], v153 offset:56320
	global_load_lds_dwordx4 v[220:221], off
	v_lshl_add_u64 v[220:221], v[226:227], 0, s[10:11]
	s_mov_b32 m0, s74
	s_nop 0
	global_load_lds_dwordx4 v[220:221], off
	s_waitcnt vmcnt(10)
	s_barrier
	s_waitcnt lgkmcnt(0)
	s_waitcnt lgkmcnt(0)
	v_mfma_f32_16x16x32_bf16 v[60:63], v[156:159], v[172:175], v[60:63]
	v_mfma_f32_16x16x32_bf16 v[56:59], v[164:167], v[172:175], v[56:59]
	v_mfma_f32_16x16x32_bf16 v[52:55], v[156:159], v[180:183], v[52:55]
	v_mfma_f32_16x16x32_bf16 v[48:51], v[164:167], v[180:183], v[48:51]
	v_mfma_f32_16x16x32_bf16 v[36:39], v[156:159], v[188:191], v[36:39]
	v_mfma_f32_16x16x32_bf16 v[32:35], v[164:167], v[188:191], v[32:35]
	v_mfma_f32_16x16x32_bf16 v[20:23], v[156:159], v[196:199], v[20:23]
	v_mfma_f32_16x16x32_bf16 v[16:19], v[164:167], v[196:199], v[16:19]
	v_mfma_f32_16x16x32_bf16 v[60:63], v[160:163], v[176:179], v[60:63]
	v_mfma_f32_16x16x32_bf16 v[56:59], v[168:171], v[176:179], v[56:59]
	v_mfma_f32_16x16x32_bf16 v[52:55], v[160:163], v[184:187], v[52:55]
	v_mfma_f32_16x16x32_bf16 v[48:51], v[168:171], v[184:187], v[48:51]
	v_mfma_f32_16x16x32_bf16 v[36:39], v[160:163], v[192:195], v[36:39]
	v_mfma_f32_16x16x32_bf16 v[32:35], v[168:171], v[192:195], v[32:35]
	v_mfma_f32_16x16x32_bf16 v[20:23], v[160:163], v[200:203], v[20:23]
	v_mfma_f32_16x16x32_bf16 v[16:19], v[168:171], v[200:203], v[16:19]
	s_barrier
	s_add_u32 s54, s54, 0x40080
	s_addc_u32 s55, s55, 0
	s_add_i32 s56, s56, s61
	v_lshl_add_u64 v[156:157], s[54:55], 0, v[134:135]
	s_mov_b32 m0, s56
	s_nop 0
	global_load_lds_dwordx4 v[156:157], off
	v_lshl_add_u64 v[156:157], s[54:55], 0, v[130:131]
	s_add_i32 m0, s56, 0x2000
	s_nop 0
	global_load_lds_dwordx4 v[156:157], off
	s_waitcnt vmcnt(10)
	s_barrier
	v_mfma_f32_16x16x32_bf16 v[44:47], v[204:207], v[172:175], v[44:47]
	v_mfma_f32_16x16x32_bf16 v[40:43], v[212:215], v[172:175], v[40:43]
	v_mfma_f32_16x16x32_bf16 v[28:31], v[204:207], v[180:183], v[28:31]
	v_mfma_f32_16x16x32_bf16 v[24:27], v[212:215], v[180:183], v[24:27]
	v_mfma_f32_16x16x32_bf16 v[12:15], v[204:207], v[188:191], v[12:15]
	v_mfma_f32_16x16x32_bf16 v[8:11], v[212:215], v[188:191], v[8:11]
	v_mfma_f32_16x16x32_bf16 v[4:7], v[204:207], v[196:199], v[4:7]
	v_mfma_f32_16x16x32_bf16 v[0:3], v[212:215], v[196:199], v[0:3]
	v_mfma_f32_16x16x32_bf16 v[44:47], v[208:211], v[176:179], v[44:47]
	v_mfma_f32_16x16x32_bf16 v[40:43], v[216:219], v[176:179], v[40:43]
	v_mfma_f32_16x16x32_bf16 v[28:31], v[208:211], v[184:187], v[28:31]
	v_mfma_f32_16x16x32_bf16 v[24:27], v[216:219], v[184:187], v[24:27]
	v_mfma_f32_16x16x32_bf16 v[12:15], v[208:211], v[192:195], v[12:15]
	v_mfma_f32_16x16x32_bf16 v[8:11], v[216:219], v[192:195], v[8:11]
	v_mfma_f32_16x16x32_bf16 v[4:7], v[208:211], v[200:203], v[4:7]
	v_mfma_f32_16x16x32_bf16 v[0:3], v[216:219], v[200:203], v[0:3]
	s_add_i32 s87, s87, 2
	s_add_u32 s34, s34, 0x100
	s_addc_u32 s35, s35, 0
	s_add_u32 s85, s85, 0x100
	s_addc_u32 s86, s86, 0
	s_cmp_gt_u32 s87, 13
	s_barrier
	s_cbranch_scc0 .LBB0_912
	v_lshl_add_u32 v156, s18, 8, v149
	v_lshl_or_b32 v158, s82, 8, v151
	v_ashrrev_i32_e32 v157, 31, v156
	v_lshlrev_b64 v[160:161], 11, v[156:157]
	v_ashrrev_i32_e32 v159, 31, v158
	v_lshl_add_u64 v[160:161], s[46:47], 0, v[160:161]
	v_cvt_pk_bf16_f32 v124, v124, v125
	v_cvt_pk_bf16_f32 v125, v126, v127
	v_cvt_pk_bf16_f32 v126, v120, v121
	v_lshlrev_b64 v[120:121], 1, v[158:159]
	v_cvt_pk_bf16_f32 v127, v122, v123
	v_lshl_add_u64 v[122:123], v[160:161], 0, v[120:121]
	v_cvt_pk_bf16_f32 v108, v108, v109
	v_cvt_pk_bf16_f32 v109, v110, v111
	v_cvt_pk_bf16_f32 v110, v104, v105
	v_or_b32_e32 v104, 16, v156
	v_cvt_pk_bf16_f32 v60, v60, v61
	v_cvt_pk_bf16_f32 v61, v62, v63
	v_cvt_pk_bf16_f32 v63, v58, v59
	v_add_co_u32_e32 v58, vcc, s78, v122
	v_ashrrev_i32_e32 v105, 31, v104
	v_cvt_pk_bf16_f32 v62, v56, v57
	v_lshl_add_u64 v[56:57], v[122:123], 0, s[8:9]
	v_addc_co_u32_e32 v59, vcc, 0, v123, vcc
	v_cvt_pk_bf16_f32 v44, v44, v45
	v_cvt_pk_bf16_f32 v45, v46, v47
	v_cvt_pk_bf16_f32 v46, v40, v41
	v_cvt_pk_bf16_f32 v47, v42, v43
	v_cvt_pk_bf16_f32 v111, v106, v107
	v_lshlrev_b64 v[104:105], 11, v[104:105]
	v_cvt_pk_bf16_f32 v92, v92, v93
	v_cvt_pk_bf16_f32 v93, v94, v95
	v_cvt_pk_bf16_f32 v94, v88, v89
	v_or_b32_e32 v88, 32, v156
	global_store_dwordx4 v[56:57], v[44:47], off offset:256
	global_store_dwordx4 v[122:123], v[108:111], off offset:256
	v_ashrrev_i32_e32 v89, 31, v88
	v_add_co_u32_e32 v46, vcc, s79, v122
	v_lshl_add_u64 v[108:109], s[46:47], 0, v[104:105]
	v_lshl_add_u64 v[44:45], v[122:123], 0, s[12:13]
	v_addc_co_u32_e32 v47, vcc, 0, v123, vcc
	v_cvt_pk_bf16_f32 v28, v28, v29
	v_cvt_pk_bf16_f32 v29, v30, v31
	v_cvt_pk_bf16_f32 v30, v24, v25
	v_cvt_pk_bf16_f32 v31, v26, v27
	v_lshl_add_u64 v[108:109], v[108:109], 0, v[120:121]
	v_cvt_pk_bf16_f32 v95, v90, v91
	v_lshlrev_b64 v[88:89], 11, v[88:89]
	v_cvt_pk_bf16_f32 v76, v76, v77
	v_cvt_pk_bf16_f32 v77, v78, v79
	v_cvt_pk_bf16_f32 v78, v72, v73
	v_or_b32_e32 v72, 48, v156
	global_store_dwordx4 v[44:45], v[28:31], off offset:256
	global_store_dwordx4 v[108:109], v[92:95], off offset:256
	v_ashrrev_i32_e32 v73, 31, v72
	v_add_co_u32_e32 v30, vcc, s80, v122
	v_lshl_add_u64 v[92:93], s[46:47], 0, v[88:89]
	v_lshl_add_u64 v[28:29], v[122:123], 0, s[14:15]
	v_addc_co_u32_e32 v31, vcc, 0, v123, vcc
	v_cvt_pk_bf16_f32 v12, v12, v13
	v_cvt_pk_bf16_f32 v13, v14, v15
	v_cvt_pk_bf16_f32 v14, v8, v9
	v_cvt_pk_bf16_f32 v15, v10, v11
	v_lshl_add_u64 v[92:93], v[92:93], 0, v[120:121]
	v_cvt_pk_bf16_f32 v79, v74, v75
	v_lshlrev_b64 v[72:73], 11, v[72:73]
	global_store_dwordx4 v[28:29], v[12:15], off offset:256
	global_store_dwordx4 v[92:93], v[76:79], off offset:256
	v_cvt_pk_bf16_f32 v104, v116, v117
	v_add_co_u32_e32 v14, vcc, s81, v122
	v_lshl_add_u64 v[76:77], s[46:47], 0, v[72:73]
	s_nop 0
	v_addc_co_u32_e32 v15, vcc, 0, v123, vcc
	v_cvt_pk_bf16_f32 v105, v118, v119
	v_cvt_pk_bf16_f32 v106, v112, v113
	v_cvt_pk_bf16_f32 v107, v114, v115
	v_cvt_pk_bf16_f32 v88, v100, v101
	v_cvt_pk_bf16_f32 v89, v102, v103
	v_cvt_pk_bf16_f32 v90, v96, v97
	v_cvt_pk_bf16_f32 v91, v98, v99
	v_cvt_pk_bf16_f32 v72, v84, v85
	v_cvt_pk_bf16_f32 v73, v86, v87
	v_cvt_pk_bf16_f32 v74, v80, v81
	v_cvt_pk_bf16_f32 v75, v82, v83
	v_lshl_add_u64 v[76:77], v[76:77], 0, v[120:121]
	v_cvt_pk_bf16_f32 v68, v68, v69
	v_cvt_pk_bf16_f32 v69, v70, v71
	v_cvt_pk_bf16_f32 v70, v64, v65
	v_cvt_pk_bf16_f32 v71, v66, v67
	v_cvt_pk_bf16_f32 v40, v52, v53
	v_cvt_pk_bf16_f32 v41, v54, v55
	v_cvt_pk_bf16_f32 v42, v48, v49
	v_cvt_pk_bf16_f32 v43, v50, v51
	v_cvt_pk_bf16_f32 v24, v36, v37
	v_cvt_pk_bf16_f32 v25, v38, v39
	v_cvt_pk_bf16_f32 v26, v32, v33
	v_cvt_pk_bf16_f32 v27, v34, v35
	v_cvt_pk_bf16_f32 v8, v20, v21
	v_cvt_pk_bf16_f32 v9, v22, v23
	v_cvt_pk_bf16_f32 v10, v16, v17
	v_cvt_pk_bf16_f32 v11, v18, v19
	v_lshl_add_u64 v[12:13], v[122:123], 0, s[16:17]
	v_cvt_pk_bf16_f32 v4, v4, v5
	v_cvt_pk_bf16_f32 v5, v6, v7
	v_cvt_pk_bf16_f32 v6, v0, v1
	v_cvt_pk_bf16_f32 v7, v2, v3
	s_and_b64 vcc, exec, s[4:5]
	s_mov_b32 s82, s20
	s_mov_b32 s18, s26
	s_mov_b64 s[54:55], s[30:31]
	s_mov_b64 s[34:35], s[28:29]
	global_store_dwordx4 v[122:123], v[124:127], off
	global_store_dwordx4 v[108:109], v[104:107], off
	global_store_dwordx4 v[92:93], v[88:91], off
	global_store_dwordx4 v[76:77], v[72:75], off
	global_store_dwordx4 v[76:77], v[68:71], off offset:256
	global_store_dwordx4 v[58:59], v[60:63], off
	global_store_dwordx4 v[46:47], v[40:43], off
	global_store_dwordx4 v[30:31], v[24:27], off
	global_store_dwordx4 v[14:15], v[8:11], off
	global_store_dwordx4 v[12:13], v[4:7], off offset:256
	s_cbranch_vccz .LBB0_909
	s_waitcnt vmcnt(16)
	s_cmpk_gt_u32 s60, 0xff
	s_cbranch_scc1 .LBB0_916
	s_barrier

.LBB0_1116:
	ds_read_b128 v[154:157], v150
	ds_read_b128 v[158:161], v150 offset:1024
	ds_read_b128 v[162:165], v150 offset:2048
	ds_read_b128 v[166:169], v150 offset:3072
	s_add_u32 s34, s30, 0xfffc0080
	s_addc_u32 s35, s31, -1
	s_cmp_eq_u32 s77, 12
	s_cselect_b32 s37, s19, s35
	s_cselect_b32 s36, s73, s34
	s_cselect_b32 s35, s17, s76
	s_cselect_b32 s34, s74, s75
	v_lshl_add_u64 v[202:203], s[30:31], 0, v[134:135]
	s_add_i32 m0, s29, 0xc000
	ds_read_b128 v[170:173], v151
	ds_read_b128 v[174:177], v151 offset:1024
	ds_read_b128 v[178:181], v151 offset:2048
	ds_read_b128 v[182:185], v151 offset:3072
	ds_read_b128 v[186:189], v151 offset:4096
	ds_read_b128 v[190:193], v151 offset:5120
	ds_read_b128 v[194:197], v151 offset:6144
	ds_read_b128 v[198:201], v151 offset:7168
	global_load_lds_dwordx4 v[202:203], off
	v_lshl_add_u64 v[202:203], s[30:31], 0, v[136:137]
	s_add_i32 m0, s29, 0xe000
	s_nop 0
	global_load_lds_dwordx4 v[202:203], off
	s_waitcnt lgkmcnt(8)
	s_waitcnt vmcnt(10)
	s_barrier
	s_waitcnt lgkmcnt(0)
	s_waitcnt lgkmcnt(0)
	v_mfma_f32_16x16x32_bf16 v[120:123], v[154:157], v[170:173], v[120:123]
	v_mfma_f32_16x16x32_bf16 v[124:127], v[162:165], v[170:173], v[124:127]
	v_mfma_f32_16x16x32_bf16 v[104:107], v[154:157], v[178:181], v[104:107]
	v_mfma_f32_16x16x32_bf16 v[108:111], v[162:165], v[178:181], v[108:111]
	v_mfma_f32_16x16x32_bf16 v[88:91], v[154:157], v[186:189], v[88:91]
	v_mfma_f32_16x16x32_bf16 v[92:95], v[162:165], v[186:189], v[92:95]
	v_mfma_f32_16x16x32_bf16 v[72:75], v[154:157], v[194:197], v[72:75]
	v_mfma_f32_16x16x32_bf16 v[76:79], v[162:165], v[194:197], v[76:79]
	v_mfma_f32_16x16x32_bf16 v[120:123], v[158:161], v[174:177], v[120:123]
	v_mfma_f32_16x16x32_bf16 v[124:127], v[166:169], v[174:177], v[124:127]
	v_mfma_f32_16x16x32_bf16 v[104:107], v[158:161], v[182:185], v[104:107]
	v_mfma_f32_16x16x32_bf16 v[108:111], v[166:169], v[182:185], v[108:111]
	v_mfma_f32_16x16x32_bf16 v[88:91], v[158:161], v[190:193], v[88:91]
	v_mfma_f32_16x16x32_bf16 v[92:95], v[166:169], v[190:193], v[92:95]
	v_mfma_f32_16x16x32_bf16 v[72:75], v[158:161], v[198:201], v[72:75]
	v_mfma_f32_16x16x32_bf16 v[76:79], v[166:169], v[198:201], v[76:79]
	s_barrier
	s_add_i32 s78, s60, s42
	v_lshl_add_u64 v[218:219], s[34:35], 0, v[130:131]
	s_mov_b32 m0, s78
	ds_read_b128 v[202:205], v152
	ds_read_b128 v[206:209], v152 offset:1024
	ds_read_b128 v[210:213], v152 offset:2048
	ds_read_b128 v[214:217], v152 offset:3072
	global_load_lds_dwordx4 v[218:219], off
	v_lshl_add_u64 v[220:221], s[34:35], 0, v[132:133]
	s_add_i32 m0, s78, 0x2000
	s_nop 0
	global_load_lds_dwordx4 v[220:221], off
	s_waitcnt vmcnt(10)
	s_barrier
	s_waitcnt lgkmcnt(0)
	s_waitcnt lgkmcnt(0)
	v_mfma_f32_16x16x32_bf16 v[112:115], v[202:205], v[170:173], v[112:115]
	v_mfma_f32_16x16x32_bf16 v[116:119], v[210:213], v[170:173], v[116:119]
	v_mfma_f32_16x16x32_bf16 v[96:99], v[202:205], v[178:181], v[96:99]
	v_mfma_f32_16x16x32_bf16 v[100:103], v[210:213], v[178:181], v[100:103]
	v_mfma_f32_16x16x32_bf16 v[80:83], v[202:205], v[186:189], v[80:83]
	v_mfma_f32_16x16x32_bf16 v[84:87], v[210:213], v[186:189], v[84:87]
	v_mfma_f32_16x16x32_bf16 v[64:67], v[202:205], v[194:197], v[64:67]
	v_mfma_f32_16x16x32_bf16 v[68:71], v[210:213], v[194:197], v[68:71]
	v_mfma_f32_16x16x32_bf16 v[112:115], v[206:209], v[174:177], v[112:115]
	v_mfma_f32_16x16x32_bf16 v[116:119], v[214:217], v[174:177], v[116:119]
	v_mfma_f32_16x16x32_bf16 v[96:99], v[206:209], v[182:185], v[96:99]
	v_mfma_f32_16x16x32_bf16 v[100:103], v[214:217], v[182:185], v[100:103]
	v_mfma_f32_16x16x32_bf16 v[80:83], v[206:209], v[190:193], v[80:83]
	v_mfma_f32_16x16x32_bf16 v[84:87], v[214:217], v[190:193], v[84:87]
	v_mfma_f32_16x16x32_bf16 v[64:67], v[206:209], v[198:201], v[64:67]
	v_mfma_f32_16x16x32_bf16 v[68:71], v[214:217], v[198:201], v[68:71]
	s_mov_b32 m0, s29
	v_lshl_add_u64 v[222:223], s[36:37], 0, v[130:131]
	s_barrier
	ds_read_b128 v[170:173], v151 offset:16384
	ds_read_b128 v[174:177], v151 offset:17408
	ds_read_b128 v[178:181], v151 offset:18432
	ds_read_b128 v[182:185], v151 offset:19456
	ds_read_b128 v[186:189], v151 offset:20480
	ds_read_b128 v[190:193], v151 offset:21504
	ds_read_b128 v[194:197], v151 offset:22528
	ds_read_b128 v[198:201], v151 offset:23552
	global_load_lds_dwordx4 v[222:223], off
	v_lshl_add_u64 v[224:225], s[36:37], 0, v[132:133]
	s_mov_b32 m0, s43
	s_nop 0
	global_load_lds_dwordx4 v[224:225], off
	s_waitcnt vmcnt(10)
	s_barrier
	s_waitcnt lgkmcnt(0)
	s_waitcnt lgkmcnt(0)
	v_mfma_f32_16x16x32_bf16 v[56:59], v[154:157], v[170:173], v[56:59]
	v_mfma_f32_16x16x32_bf16 v[60:63], v[162:165], v[170:173], v[60:63]
	v_mfma_f32_16x16x32_bf16 v[40:43], v[154:157], v[178:181], v[40:43]
	v_mfma_f32_16x16x32_bf16 v[44:47], v[162:165], v[178:181], v[44:47]
	v_mfma_f32_16x16x32_bf16 v[24:27], v[154:157], v[186:189], v[24:27]
	v_mfma_f32_16x16x32_bf16 v[28:31], v[162:165], v[186:189], v[28:31]
	v_mfma_f32_16x16x32_bf16 v[8:11], v[154:157], v[194:197], v[8:11]
	v_mfma_f32_16x16x32_bf16 v[12:15], v[162:165], v[194:197], v[12:15]
	v_mfma_f32_16x16x32_bf16 v[56:59], v[158:161], v[174:177], v[56:59]
	v_mfma_f32_16x16x32_bf16 v[60:63], v[166:169], v[174:177], v[60:63]
	v_mfma_f32_16x16x32_bf16 v[40:43], v[158:161], v[182:185], v[40:43]
	v_mfma_f32_16x16x32_bf16 v[44:47], v[166:169], v[182:185], v[44:47]
	v_mfma_f32_16x16x32_bf16 v[24:27], v[158:161], v[190:193], v[24:27]
	v_mfma_f32_16x16x32_bf16 v[28:31], v[166:169], v[190:193], v[28:31]
	v_mfma_f32_16x16x32_bf16 v[8:11], v[158:161], v[198:201], v[8:11]
	v_mfma_f32_16x16x32_bf16 v[12:15], v[166:169], v[198:201], v[12:15]
	s_barrier
	s_add_u32 s78, s34, 0x40000
	s_addc_u32 s79, s35, 0
	s_add_i32 s80, s61, s42
	v_lshl_add_u64 v[154:155], s[78:79], 0, v[130:131]
	s_mov_b32 m0, s80
	s_nop 0
	global_load_lds_dwordx4 v[154:155], off
	v_lshl_add_u64 v[154:155], s[78:79], 0, v[132:133]
	s_add_i32 m0, s80, 0x2000
	s_nop 0
	global_load_lds_dwordx4 v[154:155], off
	s_waitcnt vmcnt(10)
	s_barrier
	v_mfma_f32_16x16x32_bf16 v[48:51], v[202:205], v[170:173], v[48:51]
	v_mfma_f32_16x16x32_bf16 v[52:55], v[210:213], v[170:173], v[52:55]
	v_mfma_f32_16x16x32_bf16 v[32:35], v[202:205], v[178:181], v[32:35]
	v_mfma_f32_16x16x32_bf16 v[36:39], v[210:213], v[178:181], v[36:39]
	v_mfma_f32_16x16x32_bf16 v[16:19], v[202:205], v[186:189], v[16:19]
	v_mfma_f32_16x16x32_bf16 v[20:23], v[210:213], v[186:189], v[20:23]
	v_mfma_f32_16x16x32_bf16 v[0:3], v[202:205], v[194:197], v[0:3]
	v_mfma_f32_16x16x32_bf16 v[4:7], v[210:213], v[194:197], v[4:7]
	v_mfma_f32_16x16x32_bf16 v[48:51], v[206:209], v[174:177], v[48:51]
	v_mfma_f32_16x16x32_bf16 v[52:55], v[214:217], v[174:177], v[52:55]
	v_mfma_f32_16x16x32_bf16 v[32:35], v[206:209], v[182:185], v[32:35]
	v_mfma_f32_16x16x32_bf16 v[36:39], v[214:217], v[182:185], v[36:39]
	v_mfma_f32_16x16x32_bf16 v[16:19], v[206:209], v[190:193], v[16:19]
	v_mfma_f32_16x16x32_bf16 v[20:23], v[214:217], v[190:193], v[20:23]
	v_mfma_f32_16x16x32_bf16 v[0:3], v[206:209], v[198:201], v[0:3]
	v_mfma_f32_16x16x32_bf16 v[4:7], v[214:217], v[198:201], v[4:7]
	s_add_i32 s78, 0, 0x18000
	v_add_u32_e32 v153, s78, v148
	s_barrier
	ds_read_b128 v[154:157], v153
	ds_read_b128 v[158:161], v153 offset:1024
	ds_read_b128 v[162:165], v153 offset:2048
	ds_read_b128 v[166:169], v153 offset:3072
	s_add_u32 s36, s36, 0x40000
	s_addc_u32 s37, s37, 0
	s_mov_b32 m0, s52
	v_lshl_add_u64 v[202:203], s[36:37], 0, v[130:131]
	ds_read_b128 v[170:173], v151 offset:32768
	ds_read_b128 v[174:177], v151 offset:33792
	ds_read_b128 v[178:181], v151 offset:34816
	ds_read_b128 v[182:185], v151 offset:35840
	ds_read_b128 v[186:189], v151 offset:36864
	ds_read_b128 v[190:193], v151 offset:37888
	ds_read_b128 v[194:197], v151 offset:38912
	ds_read_b128 v[198:201], v151 offset:39936
	global_load_lds_dwordx4 v[202:203], off
	v_lshl_add_u64 v[202:203], s[36:37], 0, v[132:133]
	s_mov_b32 m0, s53
	s_nop 0
	global_load_lds_dwordx4 v[202:203], off
	s_waitcnt lgkmcnt(8)
	s_waitcnt vmcnt(10)
	s_barrier
	s_waitcnt lgkmcnt(0)
	s_waitcnt lgkmcnt(0)
	v_mfma_f32_16x16x32_bf16 v[120:123], v[154:157], v[170:173], v[120:123]
	v_mfma_f32_16x16x32_bf16 v[124:127], v[162:165], v[170:173], v[124:127]
	v_mfma_f32_16x16x32_bf16 v[104:107], v[154:157], v[178:181], v[104:107]
	v_mfma_f32_16x16x32_bf16 v[108:111], v[162:165], v[178:181], v[108:111]
	v_mfma_f32_16x16x32_bf16 v[88:91], v[154:157], v[186:189], v[88:91]
	v_mfma_f32_16x16x32_bf16 v[92:95], v[162:165], v[186:189], v[92:95]
	v_mfma_f32_16x16x32_bf16 v[72:75], v[154:157], v[194:197], v[72:75]
	v_mfma_f32_16x16x32_bf16 v[76:79], v[162:165], v[194:197], v[76:79]
	v_mfma_f32_16x16x32_bf16 v[120:123], v[158:161], v[174:177], v[120:123]
	v_mfma_f32_16x16x32_bf16 v[124:127], v[166:169], v[174:177], v[124:127]
	v_mfma_f32_16x16x32_bf16 v[104:107], v[158:161], v[182:185], v[104:107]
	v_mfma_f32_16x16x32_bf16 v[108:111], v[166:169], v[182:185], v[108:111]
	v_mfma_f32_16x16x32_bf16 v[88:91], v[158:161], v[190:193], v[88:91]
	v_mfma_f32_16x16x32_bf16 v[92:95], v[166:169], v[190:193], v[92:95]
	v_mfma_f32_16x16x32_bf16 v[72:75], v[158:161], v[198:201], v[72:75]
	v_mfma_f32_16x16x32_bf16 v[76:79], v[166:169], v[198:201], v[76:79]
	s_barrier
	s_add_i32 s36, 0, 0x1c000
	s_add_i32 s37, s78, s42
	v_add_u32_e32 v153, s36, v148
	v_lshl_add_u64 v[218:219], v[218:219], 0, s[8:9]
	s_mov_b32 m0, s37
	ds_read_b128 v[202:205], v153
	ds_read_b128 v[206:209], v153 offset:1024
	ds_read_b128 v[210:213], v153 offset:2048
	ds_read_b128 v[214:217], v153 offset:3072
	global_load_lds_dwordx4 v[218:219], off
	v_lshl_add_u64 v[218:219], v[220:221], 0, s[8:9]
	s_add_i32 m0, s37, 0x2000
	s_nop 0
	global_load_lds_dwordx4 v[218:219], off
	s_waitcnt vmcnt(10)
	s_barrier
	s_waitcnt lgkmcnt(0)
	s_waitcnt lgkmcnt(0)
	v_mfma_f32_16x16x32_bf16 v[112:115], v[202:205], v[170:173], v[112:115]
	v_mfma_f32_16x16x32_bf16 v[116:119], v[210:213], v[170:173], v[116:119]
	v_mfma_f32_16x16x32_bf16 v[96:99], v[202:205], v[178:181], v[96:99]
	v_mfma_f32_16x16x32_bf16 v[100:103], v[210:213], v[178:181], v[100:103]
	v_mfma_f32_16x16x32_bf16 v[80:83], v[202:205], v[186:189], v[80:83]
	v_mfma_f32_16x16x32_bf16 v[84:87], v[210:213], v[186:189], v[84:87]
	v_mfma_f32_16x16x32_bf16 v[64:67], v[202:205], v[194:197], v[64:67]
	v_mfma_f32_16x16x32_bf16 v[68:71], v[210:213], v[194:197], v[68:71]
	v_mfma_f32_16x16x32_bf16 v[112:115], v[206:209], v[174:177], v[112:115]
	v_mfma_f32_16x16x32_bf16 v[116:119], v[214:217], v[174:177], v[116:119]
	v_mfma_f32_16x16x32_bf16 v[96:99], v[206:209], v[182:185], v[96:99]
	v_mfma_f32_16x16x32_bf16 v[100:103], v[214:217], v[182:185], v[100:103]
	v_mfma_f32_16x16x32_bf16 v[80:83], v[206:209], v[190:193], v[80:83]
	v_mfma_f32_16x16x32_bf16 v[84:87], v[214:217], v[190:193], v[84:87]
	v_mfma_f32_16x16x32_bf16 v[64:67], v[206:209], v[198:201], v[64:67]
	v_mfma_f32_16x16x32_bf16 v[68:71], v[214:217], v[198:201], v[68:71]
	s_mov_b32 m0, s55
	v_lshl_add_u64 v[218:219], v[222:223], 0, s[8:9]
	s_barrier
	ds_read_b128 v[170:173], v151 offset:49152
	ds_read_b128 v[174:177], v151 offset:50176
	ds_read_b128 v[178:181], v151 offset:51200
	ds_read_b128 v[182:185], v151 offset:52224
	ds_read_b128 v[186:189], v151 offset:53248
	ds_read_b128 v[190:193], v151 offset:54272
	ds_read_b128 v[194:197], v151 offset:55296
	ds_read_b128 v[198:201], v151 offset:56320
	global_load_lds_dwordx4 v[218:219], off
	v_lshl_add_u64 v[218:219], v[224:225], 0, s[8:9]
	s_mov_b32 m0, s56
	s_nop 0
	global_load_lds_dwordx4 v[218:219], off
	s_waitcnt vmcnt(10)
	s_barrier
	s_waitcnt lgkmcnt(0)
	s_waitcnt lgkmcnt(0)
	v_mfma_f32_16x16x32_bf16 v[56:59], v[154:157], v[170:173], v[56:59]
	v_mfma_f32_16x16x32_bf16 v[60:63], v[162:165], v[170:173], v[60:63]
	v_mfma_f32_16x16x32_bf16 v[40:43], v[154:157], v[178:181], v[40:43]
	v_mfma_f32_16x16x32_bf16 v[44:47], v[162:165], v[178:181], v[44:47]
	v_mfma_f32_16x16x32_bf16 v[24:27], v[154:157], v[186:189], v[24:27]
	v_mfma_f32_16x16x32_bf16 v[28:31], v[162:165], v[186:189], v[28:31]
	v_mfma_f32_16x16x32_bf16 v[8:11], v[154:157], v[194:197], v[8:11]
	v_mfma_f32_16x16x32_bf16 v[12:15], v[162:165], v[194:197], v[12:15]
	v_mfma_f32_16x16x32_bf16 v[56:59], v[158:161], v[174:177], v[56:59]
	v_mfma_f32_16x16x32_bf16 v[60:63], v[166:169], v[174:177], v[60:63]
	v_mfma_f32_16x16x32_bf16 v[40:43], v[158:161], v[182:185], v[40:43]
	v_mfma_f32_16x16x32_bf16 v[44:47], v[166:169], v[182:185], v[44:47]
	v_mfma_f32_16x16x32_bf16 v[24:27], v[158:161], v[190:193], v[24:27]
	v_mfma_f32_16x16x32_bf16 v[28:31], v[166:169], v[190:193], v[28:31]
	v_mfma_f32_16x16x32_bf16 v[8:11], v[158:161], v[198:201], v[8:11]
	v_mfma_f32_16x16x32_bf16 v[12:15], v[166:169], v[198:201], v[12:15]
	s_barrier
	s_add_u32 s34, s34, 0x40080
	s_addc_u32 s35, s35, 0
	s_add_i32 s36, s36, s42
	v_lshl_add_u64 v[154:155], s[34:35], 0, v[130:131]
	s_mov_b32 m0, s36
	s_nop 0
	global_load_lds_dwordx4 v[154:155], off
	v_lshl_add_u64 v[154:155], s[34:35], 0, v[132:133]
	s_add_i32 m0, s36, 0x2000
	s_nop 0
	global_load_lds_dwordx4 v[154:155], off
	s_waitcnt vmcnt(10)
	s_barrier
	v_mfma_f32_16x16x32_bf16 v[48:51], v[202:205], v[170:173], v[48:51]
	v_mfma_f32_16x16x32_bf16 v[52:55], v[210:213], v[170:173], v[52:55]
	v_mfma_f32_16x16x32_bf16 v[32:35], v[202:205], v[178:181], v[32:35]
	v_mfma_f32_16x16x32_bf16 v[36:39], v[210:213], v[178:181], v[36:39]
	v_mfma_f32_16x16x32_bf16 v[16:19], v[202:205], v[186:189], v[16:19]
	v_mfma_f32_16x16x32_bf16 v[20:23], v[210:213], v[186:189], v[20:23]
	v_mfma_f32_16x16x32_bf16 v[0:3], v[202:205], v[194:197], v[0:3]
	v_mfma_f32_16x16x32_bf16 v[4:7], v[210:213], v[194:197], v[4:7]
	v_mfma_f32_16x16x32_bf16 v[48:51], v[206:209], v[174:177], v[48:51]
	v_mfma_f32_16x16x32_bf16 v[52:55], v[214:217], v[174:177], v[52:55]
	v_mfma_f32_16x16x32_bf16 v[32:35], v[206:209], v[182:185], v[32:35]
	v_mfma_f32_16x16x32_bf16 v[36:39], v[214:217], v[182:185], v[36:39]
	v_mfma_f32_16x16x32_bf16 v[16:19], v[206:209], v[190:193], v[16:19]
	v_mfma_f32_16x16x32_bf16 v[20:23], v[214:217], v[190:193], v[20:23]
	v_mfma_f32_16x16x32_bf16 v[0:3], v[206:209], v[198:201], v[0:3]
	v_mfma_f32_16x16x32_bf16 v[4:7], v[214:217], v[198:201], v[4:7]
	s_add_i32 s77, s77, 2
	s_add_u32 s30, s30, 0x100
	s_addc_u32 s31, s31, 0
	s_add_u32 s75, s75, 0x100
	s_addc_u32 s76, s76, 0
	s_cmp_gt_u32 s77, 13
	s_barrier
	s_cbranch_scc0 .LBB0_1116
	v_mul_f32_e32 v124, 0xbfb8aa3b, v124
	v_exp_f32_e32 v154, v124
	v_mul_f32_e32 v124, 0xbfb8aa3b, v125
	v_exp_f32_e32 v155, v124
	v_lshl_add_u32 v124, s28, 8, v145
	v_ashrrev_i32_e32 v125, 31, v124
	v_lshlrev_b64 v[158:159], 11, v[124:125]
	v_pk_add_f32 v[154:155], v[154:155], 1.0 op_sel_hi:[1,0]
	v_mul_f32_e32 v126, 0xbfb8aa3b, v126
	v_div_scale_f32 v153, s[30:31], v155, v155, v121
	v_rcp_f32_e32 v157, v153
	v_mul_f32_e32 v127, 0xbfb8aa3b, v127
	v_exp_f32_e32 v126, v126
	v_exp_f32_e32 v127, v127
	v_fma_f32 v125, -v153, v157, 1.0
	v_fmac_f32_e32 v157, v125, v157
	v_div_scale_f32 v125, vcc, v121, v155, v121
	v_mul_f32_e32 v160, v125, v157
	v_fma_f32 v161, -v153, v160, v125
	v_fmac_f32_e32 v160, v161, v157
	v_fma_f32 v125, -v153, v160, v125
	v_div_scale_f32 v153, s[30:31], v154, v154, v120
	v_rcp_f32_e32 v161, v153
	v_div_fmas_f32 v125, v125, v157, v160
	v_div_fixup_f32 v121, v125, v155, v121
	v_pk_add_f32 v[126:127], v[126:127], 1.0 op_sel_hi:[1,0]
	v_fma_f32 v125, -v153, v161, 1.0
	v_fmac_f32_e32 v161, v125, v161
	v_div_scale_f32 v125, vcc, v120, v154, v120
	v_mul_f32_e32 v155, v125, v161
	v_fma_f32 v157, -v153, v155, v125
	v_fmac_f32_e32 v155, v157, v161
	v_fma_f32 v125, -v153, v155, v125
	v_div_scale_f32 v153, s[30:31], v127, v127, v123
	v_rcp_f32_e32 v157, v153
	v_div_fmas_f32 v125, v125, v161, v155
	v_div_fixup_f32 v120, v125, v154, v120
	v_mul_f32_e32 v116, 0xbfb8aa3b, v116
	v_fma_f32 v125, -v153, v157, 1.0
	v_fmac_f32_e32 v157, v125, v157
	v_div_scale_f32 v125, vcc, v123, v127, v123
	v_mul_f32_e32 v154, v125, v157
	v_fma_f32 v155, -v153, v154, v125
	v_fmac_f32_e32 v154, v155, v157
	v_fma_f32 v125, -v153, v154, v125
	v_div_scale_f32 v153, s[30:31], v126, v126, v122
	v_rcp_f32_e32 v155, v153
	v_div_fmas_f32 v125, v125, v157, v154
	v_div_fixup_f32 v123, v125, v127, v123
	v_mul_f32_e32 v117, 0xbfb8aa3b, v117
	v_fma_f32 v125, -v153, v155, 1.0
	v_fmac_f32_e32 v155, v125, v155
	v_div_scale_f32 v125, vcc, v122, v126, v122
	v_mul_f32_e32 v127, v125, v155
	v_fma_f32 v154, -v153, v127, v125
	v_exp_f32_e32 v116, v116
	v_exp_f32_e32 v117, v117
	v_fmac_f32_e32 v127, v154, v155
	v_fma_f32 v125, -v153, v127, v125
	v_div_fmas_f32 v125, v125, v155, v127
	v_div_fixup_f32 v125, v125, v126, v122
	v_pk_add_f32 v[126:127], v[116:117], 1.0 op_sel_hi:[1,0]
	v_cvt_pk_bf16_f32 v123, v125, v123
	v_div_scale_f32 v125, s[30:31], v127, v127, v113
	v_lshl_or_b32 v156, s72, 7, v149
	v_rcp_f32_e32 v153, v125
	v_ashrrev_i32_e32 v157, 31, v156
	v_lshl_add_u64 v[158:159], s[46:47], 0, v[158:159]
	v_cvt_pk_bf16_f32 v122, v120, v121
	v_lshlrev_b64 v[120:121], 1, v[156:157]
	v_lshl_add_u64 v[116:117], v[158:159], 0, v[120:121]
	global_store_dwordx2 v[116:117], v[122:123], off
	v_fma_f32 v122, -v125, v153, 1.0
	v_fmac_f32_e32 v153, v122, v153
	v_div_scale_f32 v122, vcc, v113, v127, v113
	v_mul_f32_e32 v123, v122, v153
	v_fma_f32 v154, -v125, v123, v122
	v_fmac_f32_e32 v123, v154, v153
	v_fma_f32 v122, -v125, v123, v122
	v_div_scale_f32 v125, s[30:31], v126, v126, v112
	v_rcp_f32_e32 v154, v125
	v_div_fmas_f32 v122, v122, v153, v123
	v_mul_f32_e32 v118, 0xbfb8aa3b, v118
	v_mul_f32_e32 v119, 0xbfb8aa3b, v119
	v_div_fixup_f32 v113, v122, v127, v113
	v_fma_f32 v122, -v125, v154, 1.0
	v_exp_f32_e32 v118, v118
	v_exp_f32_e32 v119, v119
	v_fmac_f32_e32 v154, v122, v154
	v_div_scale_f32 v122, vcc, v112, v126, v112
	v_mul_f32_e32 v123, v122, v154
	v_fma_f32 v127, -v125, v123, v122
	v_fmac_f32_e32 v123, v127, v154
	v_pk_add_f32 v[118:119], v[118:119], 1.0 op_sel_hi:[1,0]
	v_fma_f32 v122, -v125, v123, v122
	v_div_scale_f32 v125, s[30:31], v119, v119, v115
	v_rcp_f32_e32 v127, v125
	v_div_fmas_f32 v122, v122, v154, v123
	v_div_fixup_f32 v112, v122, v126, v112
	v_mul_f32_e32 v108, 0xbfb8aa3b, v108
	v_fma_f32 v122, -v125, v127, 1.0
	v_fmac_f32_e32 v127, v122, v127
	v_div_scale_f32 v122, vcc, v115, v119, v115
	v_mul_f32_e32 v123, v122, v127
	v_fma_f32 v126, -v125, v123, v122
	v_fmac_f32_e32 v123, v126, v127
	v_fma_f32 v122, -v125, v123, v122
	v_div_scale_f32 v125, s[30:31], v118, v118, v114
	v_rcp_f32_e32 v126, v125
	v_div_fmas_f32 v122, v122, v127, v123
	v_div_fixup_f32 v115, v122, v119, v115
	v_mul_f32_e32 v109, 0xbfb8aa3b, v109
	v_fma_f32 v119, -v125, v126, 1.0
	v_fmac_f32_e32 v126, v119, v126
	v_div_scale_f32 v119, vcc, v114, v118, v114
	v_mul_f32_e32 v122, v119, v126
	v_fma_f32 v123, -v125, v122, v119
	v_exp_f32_e32 v108, v108
	v_exp_f32_e32 v109, v109
	v_fmac_f32_e32 v122, v123, v126
	v_fma_f32 v119, -v125, v122, v119
	v_div_fmas_f32 v119, v119, v126, v122
	v_div_fixup_f32 v114, v119, v118, v114
	v_pk_add_f32 v[108:109], v[108:109], 1.0 op_sel_hi:[1,0]
	v_cvt_pk_bf16_f32 v112, v112, v113
	v_cvt_pk_bf16_f32 v113, v114, v115
	v_div_scale_f32 v114, s[30:31], v109, v109, v105
	v_rcp_f32_e32 v115, v114
	v_mul_f32_e32 v110, 0xbfb8aa3b, v110
	v_mul_f32_e32 v111, 0xbfb8aa3b, v111
	v_exp_f32_e32 v110, v110
	v_fma_f32 v118, -v114, v115, 1.0
	v_fmac_f32_e32 v115, v118, v115
	v_div_scale_f32 v118, vcc, v105, v109, v105
	v_mul_f32_e32 v119, v118, v115
	v_fma_f32 v122, -v114, v119, v118
	v_fmac_f32_e32 v119, v122, v115
	v_fma_f32 v114, -v114, v119, v118
	v_div_scale_f32 v118, s[30:31], v108, v108, v104
	v_rcp_f32_e32 v122, v118
	v_div_fmas_f32 v114, v114, v115, v119
	v_exp_f32_e32 v111, v111
	v_div_fixup_f32 v105, v114, v109, v105
	v_fma_f32 v109, -v118, v122, 1.0
	v_fmac_f32_e32 v122, v109, v122
	v_div_scale_f32 v109, vcc, v104, v108, v104
	v_mul_f32_e32 v114, v109, v122
	v_fma_f32 v115, -v118, v114, v109
	v_pk_add_f32 v[110:111], v[110:111], 1.0 op_sel_hi:[1,0]
	v_fmac_f32_e32 v114, v115, v122
	v_div_scale_f32 v115, s[30:31], v111, v111, v107
	v_fma_f32 v109, -v118, v114, v109
	v_rcp_f32_e32 v118, v115
	v_div_fmas_f32 v109, v109, v122, v114
	v_div_fixup_f32 v104, v109, v108, v104
	v_mul_f32_e32 v100, 0xbfb8aa3b, v100
	v_fma_f32 v108, -v115, v118, 1.0
	v_fmac_f32_e32 v118, v108, v118
	v_div_scale_f32 v108, vcc, v107, v111, v107
	v_mul_f32_e32 v109, v108, v118
	v_fma_f32 v114, -v115, v109, v108
	v_fmac_f32_e32 v109, v114, v118
	v_div_scale_f32 v114, s[30:31], v110, v110, v106
	v_fma_f32 v108, -v115, v109, v108
	v_rcp_f32_e32 v115, v114
	v_div_fmas_f32 v108, v108, v118, v109
	v_div_fixup_f32 v107, v108, v111, v107
	v_mul_f32_e32 v101, 0xbfb8aa3b, v101
	v_fma_f32 v108, -v114, v115, 1.0
	v_fmac_f32_e32 v115, v108, v115
	v_div_scale_f32 v108, vcc, v106, v110, v106
	v_mul_f32_e32 v109, v108, v115
	v_exp_f32_e32 v100, v100
	v_exp_f32_e32 v101, v101
	v_fma_f32 v111, -v114, v109, v108
	v_fmac_f32_e32 v109, v111, v115
	v_fma_f32 v108, -v114, v109, v108
	v_div_fmas_f32 v108, v108, v115, v109
	v_pk_add_f32 v[100:101], v[100:101], 1.0 op_sel_hi:[1,0]
	global_store_dwordx2 v[116:117], v[112:113], off offset:128
	v_or_b32_e32 v112, 16, v124
	v_div_fixup_f32 v106, v108, v110, v106
	v_div_scale_f32 v108, s[30:31], v101, v101, v97
	v_ashrrev_i32_e32 v113, 31, v112
	v_rcp_f32_e32 v109, v108
	v_lshlrev_b64 v[112:113], 11, v[112:113]
	v_lshl_add_u64 v[112:113], s[46:47], 0, v[112:113]
	v_cvt_pk_bf16_f32 v104, v104, v105
	v_cvt_pk_bf16_f32 v105, v106, v107
	v_lshl_add_u64 v[106:107], v[112:113], 0, v[120:121]
	global_store_dwordx2 v[106:107], v[104:105], off
	v_fma_f32 v104, -v108, v109, 1.0
	v_fmac_f32_e32 v109, v104, v109
	v_div_scale_f32 v104, vcc, v97, v101, v97
	v_mul_f32_e32 v105, v104, v109
	v_fma_f32 v110, -v108, v105, v104
	v_fmac_f32_e32 v105, v110, v109
	v_fma_f32 v104, -v108, v105, v104
	v_div_scale_f32 v108, s[30:31], v100, v100, v96
	v_rcp_f32_e32 v110, v108
	v_mul_f32_e32 v102, 0xbfb8aa3b, v102
	v_mul_f32_e32 v103, 0xbfb8aa3b, v103
	v_div_fmas_f32 v104, v104, v109, v105
	v_exp_f32_e32 v102, v102
	v_exp_f32_e32 v103, v103
	v_div_fixup_f32 v97, v104, v101, v97
	v_fma_f32 v101, -v108, v110, 1.0
	v_fmac_f32_e32 v110, v101, v110
	v_div_scale_f32 v101, vcc, v96, v100, v96
	v_mul_f32_e32 v104, v101, v110
	v_fma_f32 v105, -v108, v104, v101
	v_pk_add_f32 v[102:103], v[102:103], 1.0 op_sel_hi:[1,0]
	v_fmac_f32_e32 v104, v105, v110
	v_div_scale_f32 v105, s[30:31], v103, v103, v99
	v_fma_f32 v101, -v108, v104, v101
	v_rcp_f32_e32 v108, v105
	v_div_fmas_f32 v101, v101, v110, v104
	v_div_fixup_f32 v96, v101, v100, v96
	v_mul_f32_e32 v92, 0xbfb8aa3b, v92
	v_fma_f32 v100, -v105, v108, 1.0
	v_fmac_f32_e32 v108, v100, v108
	v_div_scale_f32 v100, vcc, v99, v103, v99
	v_mul_f32_e32 v101, v100, v108
	v_fma_f32 v104, -v105, v101, v100
	v_fmac_f32_e32 v101, v104, v108
	v_div_scale_f32 v104, s[30:31], v102, v102, v98
	v_fma_f32 v100, -v105, v101, v100
	v_rcp_f32_e32 v105, v104
	v_div_fmas_f32 v100, v100, v108, v101
	v_div_fixup_f32 v99, v100, v103, v99
	v_mul_f32_e32 v93, 0xbfb8aa3b, v93
	v_fma_f32 v100, -v104, v105, 1.0
	v_fmac_f32_e32 v105, v100, v105
	v_div_scale_f32 v100, vcc, v98, v102, v98
	v_mul_f32_e32 v101, v100, v105
	v_fma_f32 v103, -v104, v101, v100
	v_exp_f32_e32 v92, v92
	v_exp_f32_e32 v93, v93
	v_fmac_f32_e32 v101, v103, v105
	v_fma_f32 v100, -v104, v101, v100
	v_div_fmas_f32 v100, v100, v105, v101
	v_div_fixup_f32 v98, v100, v102, v98
	v_pk_add_f32 v[92:93], v[92:93], 1.0 op_sel_hi:[1,0]
	v_cvt_pk_bf16_f32 v96, v96, v97
	v_cvt_pk_bf16_f32 v97, v98, v99
	v_div_scale_f32 v98, s[30:31], v93, v93, v89
	v_rcp_f32_e32 v99, v98
	v_mul_f32_e32 v94, 0xbfb8aa3b, v94
	v_mul_f32_e32 v95, 0xbfb8aa3b, v95
	v_exp_f32_e32 v94, v94
	v_fma_f32 v100, -v98, v99, 1.0
	v_fmac_f32_e32 v99, v100, v99
	v_div_scale_f32 v100, vcc, v89, v93, v89
	v_mul_f32_e32 v101, v100, v99
	v_fma_f32 v102, -v98, v101, v100
	v_fmac_f32_e32 v101, v102, v99
	v_fma_f32 v98, -v98, v101, v100
	v_div_scale_f32 v100, s[30:31], v92, v92, v88
	v_rcp_f32_e32 v102, v100
	v_div_fmas_f32 v98, v98, v99, v101
	v_exp_f32_e32 v95, v95
	v_div_fixup_f32 v89, v98, v93, v89
	v_fma_f32 v93, -v100, v102, 1.0
	v_fmac_f32_e32 v102, v93, v102
	v_div_scale_f32 v93, vcc, v88, v92, v88
	v_mul_f32_e32 v98, v93, v102
	v_fma_f32 v99, -v100, v98, v93
	v_pk_add_f32 v[94:95], v[94:95], 1.0 op_sel_hi:[1,0]
	v_fmac_f32_e32 v98, v99, v102
	v_div_scale_f32 v99, s[30:31], v95, v95, v91
	v_fma_f32 v93, -v100, v98, v93
	v_rcp_f32_e32 v100, v99
	v_div_fmas_f32 v93, v93, v102, v98
	v_div_fixup_f32 v88, v93, v92, v88
	v_mul_f32_e32 v84, 0xbfb8aa3b, v84
	v_fma_f32 v92, -v99, v100, 1.0
	v_fmac_f32_e32 v100, v92, v100
	v_div_scale_f32 v92, vcc, v91, v95, v91
	v_mul_f32_e32 v93, v92, v100
	v_fma_f32 v98, -v99, v93, v92
	v_fmac_f32_e32 v93, v98, v100
	v_div_scale_f32 v98, s[30:31], v94, v94, v90
	v_fma_f32 v92, -v99, v93, v92
	v_rcp_f32_e32 v99, v98
	v_div_fmas_f32 v92, v92, v100, v93
	v_div_fixup_f32 v91, v92, v95, v91
	v_mul_f32_e32 v85, 0xbfb8aa3b, v85
	v_fma_f32 v92, -v98, v99, 1.0
	v_fmac_f32_e32 v99, v92, v99
	v_div_scale_f32 v92, vcc, v90, v94, v90
	v_mul_f32_e32 v93, v92, v99
	v_exp_f32_e32 v84, v84
	v_exp_f32_e32 v85, v85
	v_fma_f32 v95, -v98, v93, v92
	v_fmac_f32_e32 v93, v95, v99
	v_fma_f32 v92, -v98, v93, v92
	v_div_fmas_f32 v92, v92, v99, v93
	v_pk_add_f32 v[84:85], v[84:85], 1.0 op_sel_hi:[1,0]
	global_store_dwordx2 v[106:107], v[96:97], off offset:128
	v_or_b32_e32 v96, 32, v124
	v_div_fixup_f32 v90, v92, v94, v90
	v_div_scale_f32 v92, s[30:31], v85, v85, v81
	v_ashrrev_i32_e32 v97, 31, v96
	v_rcp_f32_e32 v93, v92
	v_lshlrev_b64 v[96:97], 11, v[96:97]
	v_lshl_add_u64 v[96:97], s[46:47], 0, v[96:97]
	v_cvt_pk_bf16_f32 v88, v88, v89
	v_cvt_pk_bf16_f32 v89, v90, v91
	v_lshl_add_u64 v[90:91], v[96:97], 0, v[120:121]
	global_store_dwordx2 v[90:91], v[88:89], off
	v_fma_f32 v88, -v92, v93, 1.0
	v_fmac_f32_e32 v93, v88, v93
	v_div_scale_f32 v88, vcc, v81, v85, v81
	v_mul_f32_e32 v89, v88, v93
	v_fma_f32 v94, -v92, v89, v88
	v_fmac_f32_e32 v89, v94, v93
	v_fma_f32 v88, -v92, v89, v88
	v_div_scale_f32 v92, s[30:31], v84, v84, v80
	v_rcp_f32_e32 v94, v92
	v_mul_f32_e32 v86, 0xbfb8aa3b, v86
	v_mul_f32_e32 v87, 0xbfb8aa3b, v87
	v_div_fmas_f32 v88, v88, v93, v89
	v_exp_f32_e32 v86, v86
	v_exp_f32_e32 v87, v87
	v_div_fixup_f32 v81, v88, v85, v81
	v_fma_f32 v85, -v92, v94, 1.0
	v_fmac_f32_e32 v94, v85, v94
	v_div_scale_f32 v85, vcc, v80, v84, v80
	v_mul_f32_e32 v88, v85, v94
	v_fma_f32 v89, -v92, v88, v85
	v_pk_add_f32 v[86:87], v[86:87], 1.0 op_sel_hi:[1,0]
	v_fmac_f32_e32 v88, v89, v94
	v_div_scale_f32 v89, s[30:31], v87, v87, v83
	v_fma_f32 v85, -v92, v88, v85
	v_rcp_f32_e32 v92, v89
	v_div_fmas_f32 v85, v85, v94, v88
	v_div_fixup_f32 v80, v85, v84, v80
	v_mul_f32_e32 v76, 0xbfb8aa3b, v76
	v_fma_f32 v84, -v89, v92, 1.0
	v_fmac_f32_e32 v92, v84, v92
	v_div_scale_f32 v84, vcc, v83, v87, v83
	v_mul_f32_e32 v85, v84, v92
	v_fma_f32 v88, -v89, v85, v84
	v_fmac_f32_e32 v85, v88, v92
	v_div_scale_f32 v88, s[30:31], v86, v86, v82
	v_fma_f32 v84, -v89, v85, v84
	v_rcp_f32_e32 v89, v88
	v_div_fmas_f32 v84, v84, v92, v85
	v_div_fixup_f32 v83, v84, v87, v83
	v_mul_f32_e32 v77, 0xbfb8aa3b, v77
	v_fma_f32 v84, -v88, v89, 1.0
	v_fmac_f32_e32 v89, v84, v89
	v_div_scale_f32 v84, vcc, v82, v86, v82
	v_mul_f32_e32 v85, v84, v89
	v_fma_f32 v87, -v88, v85, v84
	v_exp_f32_e32 v76, v76
	v_exp_f32_e32 v77, v77
	v_fmac_f32_e32 v85, v87, v89
	v_fma_f32 v84, -v88, v85, v84
	v_div_fmas_f32 v84, v84, v89, v85
	v_div_fixup_f32 v82, v84, v86, v82
	v_pk_add_f32 v[76:77], v[76:77], 1.0 op_sel_hi:[1,0]
	v_cvt_pk_bf16_f32 v80, v80, v81
	v_cvt_pk_bf16_f32 v81, v82, v83
	v_div_scale_f32 v82, s[30:31], v77, v77, v73
	v_rcp_f32_e32 v83, v82
	v_mul_f32_e32 v78, 0xbfb8aa3b, v78
	v_mul_f32_e32 v79, 0xbfb8aa3b, v79
	v_exp_f32_e32 v78, v78
	v_fma_f32 v84, -v82, v83, 1.0
	v_fmac_f32_e32 v83, v84, v83
	v_div_scale_f32 v84, vcc, v73, v77, v73
	v_mul_f32_e32 v85, v84, v83
	v_fma_f32 v86, -v82, v85, v84
	v_fmac_f32_e32 v85, v86, v83
	v_fma_f32 v82, -v82, v85, v84
	v_div_scale_f32 v84, s[30:31], v76, v76, v72
	v_rcp_f32_e32 v86, v84
	v_div_fmas_f32 v82, v82, v83, v85
	v_exp_f32_e32 v79, v79
	v_div_fixup_f32 v73, v82, v77, v73
	v_fma_f32 v77, -v84, v86, 1.0
	v_fmac_f32_e32 v86, v77, v86
	v_div_scale_f32 v77, vcc, v72, v76, v72
	v_mul_f32_e32 v82, v77, v86
	v_fma_f32 v83, -v84, v82, v77
	v_pk_add_f32 v[78:79], v[78:79], 1.0 op_sel_hi:[1,0]
	v_fmac_f32_e32 v82, v83, v86
	v_div_scale_f32 v83, s[30:31], v79, v79, v75
	v_fma_f32 v77, -v84, v82, v77
	v_rcp_f32_e32 v84, v83
	v_div_fmas_f32 v77, v77, v86, v82
	v_div_fixup_f32 v72, v77, v76, v72
	v_mul_f32_e32 v68, 0xbfb8aa3b, v68
	v_fma_f32 v76, -v83, v84, 1.0
	v_fmac_f32_e32 v84, v76, v84
	v_div_scale_f32 v76, vcc, v75, v79, v75
	v_mul_f32_e32 v77, v76, v84
	v_fma_f32 v82, -v83, v77, v76
	v_fmac_f32_e32 v77, v82, v84
	v_div_scale_f32 v82, s[30:31], v78, v78, v74
	v_fma_f32 v76, -v83, v77, v76
	v_rcp_f32_e32 v83, v82
	v_div_fmas_f32 v76, v76, v84, v77
	v_div_fixup_f32 v75, v76, v79, v75
	v_mul_f32_e32 v69, 0xbfb8aa3b, v69
	v_fma_f32 v76, -v82, v83, 1.0
	v_fmac_f32_e32 v83, v76, v83
	v_div_scale_f32 v76, vcc, v74, v78, v74
	v_mul_f32_e32 v77, v76, v83
	v_exp_f32_e32 v68, v68
	v_exp_f32_e32 v69, v69
	v_fma_f32 v79, -v82, v77, v76
	v_fmac_f32_e32 v77, v79, v83
	v_fma_f32 v76, -v82, v77, v76
	v_div_fmas_f32 v76, v76, v83, v77
	v_pk_add_f32 v[68:69], v[68:69], 1.0 op_sel_hi:[1,0]
	global_store_dwordx2 v[90:91], v[80:81], off offset:128
	v_or_b32_e32 v80, 48, v124
	v_div_fixup_f32 v74, v76, v78, v74
	v_div_scale_f32 v76, s[30:31], v69, v69, v65
	v_ashrrev_i32_e32 v81, 31, v80
	v_rcp_f32_e32 v77, v76
	v_lshlrev_b64 v[80:81], 11, v[80:81]
	v_lshl_add_u64 v[80:81], s[46:47], 0, v[80:81]
	v_cvt_pk_bf16_f32 v72, v72, v73
	v_cvt_pk_bf16_f32 v73, v74, v75
	v_lshl_add_u64 v[74:75], v[80:81], 0, v[120:121]
	global_store_dwordx2 v[74:75], v[72:73], off
	v_fma_f32 v72, -v76, v77, 1.0
	v_fmac_f32_e32 v77, v72, v77
	v_div_scale_f32 v72, vcc, v65, v69, v65
	v_mul_f32_e32 v73, v72, v77
	v_fma_f32 v78, -v76, v73, v72
	v_fmac_f32_e32 v73, v78, v77
	v_fma_f32 v72, -v76, v73, v72
	v_div_scale_f32 v76, s[30:31], v68, v68, v64
	v_rcp_f32_e32 v78, v76
	v_mul_f32_e32 v70, 0xbfb8aa3b, v70
	v_mul_f32_e32 v71, 0xbfb8aa3b, v71
	v_div_fmas_f32 v72, v72, v77, v73
	v_exp_f32_e32 v70, v70
	v_exp_f32_e32 v71, v71
	v_div_fixup_f32 v65, v72, v69, v65
	v_fma_f32 v69, -v76, v78, 1.0
	v_fmac_f32_e32 v78, v69, v78
	v_div_scale_f32 v69, vcc, v64, v68, v64
	v_mul_f32_e32 v72, v69, v78
	v_fma_f32 v73, -v76, v72, v69
	v_pk_add_f32 v[70:71], v[70:71], 1.0 op_sel_hi:[1,0]
	v_fmac_f32_e32 v72, v73, v78
	v_div_scale_f32 v73, s[30:31], v71, v71, v67
	v_fma_f32 v69, -v76, v72, v69
	v_rcp_f32_e32 v76, v73
	v_div_fmas_f32 v69, v69, v78, v72
	v_div_fixup_f32 v64, v69, v68, v64
	v_mul_f32_e32 v60, 0xbfb8aa3b, v60
	v_fma_f32 v68, -v73, v76, 1.0
	v_fmac_f32_e32 v76, v68, v76
	v_div_scale_f32 v68, vcc, v67, v71, v67
	v_mul_f32_e32 v69, v68, v76
	v_fma_f32 v72, -v73, v69, v68
	v_fmac_f32_e32 v69, v72, v76
	v_div_scale_f32 v72, s[30:31], v70, v70, v66
	v_fma_f32 v68, -v73, v69, v68
	v_rcp_f32_e32 v73, v72
	v_div_fmas_f32 v68, v68, v76, v69
	v_div_fixup_f32 v67, v68, v71, v67
	v_mul_f32_e32 v61, 0xbfb8aa3b, v61
	v_fma_f32 v68, -v72, v73, 1.0
	v_fmac_f32_e32 v73, v68, v73
	v_div_scale_f32 v68, vcc, v66, v70, v66
	v_mul_f32_e32 v69, v68, v73
	v_exp_f32_e32 v60, v60
	v_exp_f32_e32 v61, v61
	v_fma_f32 v71, -v72, v69, v68
	v_fmac_f32_e32 v69, v71, v73
	v_fma_f32 v68, -v72, v69, v68
	v_div_fmas_f32 v68, v68, v73, v69
	v_pk_add_f32 v[60:61], v[60:61], 1.0 op_sel_hi:[1,0]
	v_div_fixup_f32 v66, v68, v70, v66
	v_div_scale_f32 v68, s[30:31], v61, v61, v57
	v_rcp_f32_e32 v69, v68
	v_cvt_pk_bf16_f32 v64, v64, v65
	v_cvt_pk_bf16_f32 v65, v66, v67
	global_store_dwordx2 v[74:75], v[64:65], off offset:128
	v_fma_f32 v64, -v68, v69, 1.0
	v_fmac_f32_e32 v69, v64, v69
	v_div_scale_f32 v64, vcc, v57, v61, v57
	v_mul_f32_e32 v65, v64, v69
	v_fma_f32 v66, -v68, v65, v64
	v_fmac_f32_e32 v65, v66, v69
	v_div_scale_f32 v66, s[30:31], v60, v60, v56
	v_rcp_f32_e32 v67, v66
	v_fma_f32 v64, -v68, v65, v64
	v_mul_f32_e32 v62, 0xbfb8aa3b, v62
	v_mul_f32_e32 v63, 0xbfb8aa3b, v63
	v_div_fmas_f32 v64, v64, v69, v65
	v_exp_f32_e32 v62, v62
	v_exp_f32_e32 v63, v63
	v_div_fixup_f32 v57, v64, v61, v57
	v_fma_f32 v61, -v66, v67, 1.0
	v_fmac_f32_e32 v67, v61, v67
	v_div_scale_f32 v61, vcc, v56, v60, v56
	v_mul_f32_e32 v64, v61, v67
	v_fma_f32 v65, -v66, v64, v61
	v_pk_add_f32 v[62:63], v[62:63], 1.0 op_sel_hi:[1,0]
	v_fmac_f32_e32 v64, v65, v67
	v_div_scale_f32 v65, s[30:31], v63, v63, v59
	v_fma_f32 v61, -v66, v64, v61
	v_rcp_f32_e32 v66, v65
	v_div_fmas_f32 v61, v61, v67, v64
	v_div_fixup_f32 v56, v61, v60, v56
	v_mul_f32_e32 v52, 0xbfb8aa3b, v52
	v_fma_f32 v60, -v65, v66, 1.0
	v_fmac_f32_e32 v66, v60, v66
	v_div_scale_f32 v60, vcc, v59, v63, v59
	v_mul_f32_e32 v61, v60, v66
	v_fma_f32 v64, -v65, v61, v60
	v_fmac_f32_e32 v61, v64, v66
	v_div_scale_f32 v64, s[30:31], v62, v62, v58
	v_fma_f32 v60, -v65, v61, v60
	v_rcp_f32_e32 v65, v64
	v_div_fmas_f32 v60, v60, v66, v61
	v_div_fixup_f32 v59, v60, v63, v59
	v_mul_f32_e32 v53, 0xbfb8aa3b, v53
	v_fma_f32 v60, -v64, v65, 1.0
	v_fmac_f32_e32 v65, v60, v65
	v_div_scale_f32 v60, vcc, v58, v62, v58
	v_mul_f32_e32 v61, v60, v65
	v_exp_f32_e32 v52, v52
	v_exp_f32_e32 v53, v53
	v_fma_f32 v63, -v64, v61, v60
	v_fmac_f32_e32 v61, v63, v65
	v_fma_f32 v60, -v64, v61, v60
	v_div_fmas_f32 v60, v60, v65, v61
	v_pk_add_f32 v[52:53], v[52:53], 1.0 op_sel_hi:[1,0]
	v_div_fixup_f32 v58, v60, v62, v58
	v_div_scale_f32 v62, s[30:31], v53, v53, v49
	v_rcp_f32_e32 v63, v62
	v_add_co_u32_e32 v60, vcc, s62, v116
	v_cvt_pk_bf16_f32 v56, v56, v57
	v_cvt_pk_bf16_f32 v57, v58, v59
	v_addc_co_u32_e32 v61, vcc, 0, v117, vcc
	global_store_dwordx2 v[60:61], v[56:57], off
	v_fma_f32 v56, -v62, v63, 1.0
	v_fmac_f32_e32 v63, v56, v63
	v_div_scale_f32 v56, vcc, v49, v53, v49
	v_mul_f32_e32 v57, v56, v63
	v_fma_f32 v60, -v62, v57, v56
	v_fmac_f32_e32 v57, v60, v63
	v_div_scale_f32 v60, s[30:31], v52, v52, v48
	v_rcp_f32_e32 v61, v60
	v_fma_f32 v56, -v62, v57, v56
	v_mul_f32_e32 v54, 0xbfb8aa3b, v54
	v_mul_f32_e32 v55, 0xbfb8aa3b, v55
	v_div_fmas_f32 v56, v56, v63, v57
	v_exp_f32_e32 v54, v54
	v_exp_f32_e32 v55, v55
	v_div_fixup_f32 v49, v56, v53, v49
	v_fma_f32 v53, -v60, v61, 1.0
	v_fmac_f32_e32 v61, v53, v61
	v_div_scale_f32 v53, vcc, v48, v52, v48
	v_mul_f32_e32 v56, v53, v61
	v_fma_f32 v57, -v60, v56, v53
	v_pk_add_f32 v[54:55], v[54:55], 1.0 op_sel_hi:[1,0]
	v_fmac_f32_e32 v56, v57, v61
	v_div_scale_f32 v57, s[30:31], v55, v55, v51
	v_fma_f32 v53, -v60, v56, v53
	v_rcp_f32_e32 v60, v57
	v_div_fmas_f32 v53, v53, v61, v56
	v_div_fixup_f32 v48, v53, v52, v48
	v_mul_f32_e32 v44, 0xbfb8aa3b, v44
	v_fma_f32 v52, -v57, v60, 1.0
	v_fmac_f32_e32 v60, v52, v60
	v_div_scale_f32 v52, vcc, v51, v55, v51
	v_mul_f32_e32 v53, v52, v60
	v_fma_f32 v56, -v57, v53, v52
	v_fmac_f32_e32 v53, v56, v60
	v_div_scale_f32 v56, s[30:31], v54, v54, v50
	v_fma_f32 v52, -v57, v53, v52
	v_rcp_f32_e32 v57, v56
	v_div_fmas_f32 v52, v52, v60, v53
	v_div_fixup_f32 v51, v52, v55, v51
	v_mul_f32_e32 v45, 0xbfb8aa3b, v45
	v_fma_f32 v52, -v56, v57, 1.0
	v_fmac_f32_e32 v57, v52, v57
	v_div_scale_f32 v52, vcc, v50, v54, v50
	v_mul_f32_e32 v53, v52, v57
	v_exp_f32_e32 v44, v44
	v_exp_f32_e32 v45, v45
	v_fma_f32 v55, -v56, v53, v52
	v_fmac_f32_e32 v53, v55, v57
	v_fma_f32 v52, -v56, v53, v52
	v_div_fmas_f32 v52, v52, v57, v53
	v_pk_add_f32 v[44:45], v[44:45], 1.0 op_sel_hi:[1,0]
	v_div_fixup_f32 v50, v52, v54, v50
	v_div_scale_f32 v52, s[30:31], v45, v45, v41
	v_rcp_f32_e32 v53, v52
	v_lshl_add_u64 v[58:59], v[116:117], 0, s[6:7]
	v_cvt_pk_bf16_f32 v48, v48, v49
	v_cvt_pk_bf16_f32 v49, v50, v51
	global_store_dwordx2 v[58:59], v[48:49], off offset:128
	v_fma_f32 v48, -v52, v53, 1.0
	v_fmac_f32_e32 v53, v48, v53
	v_div_scale_f32 v48, vcc, v41, v45, v41
	v_mul_f32_e32 v49, v48, v53
	v_fma_f32 v50, -v52, v49, v48
	v_fmac_f32_e32 v49, v50, v53
	v_div_scale_f32 v50, s[30:31], v44, v44, v40
	v_rcp_f32_e32 v51, v50
	v_fma_f32 v48, -v52, v49, v48
	v_mul_f32_e32 v46, 0xbfb8aa3b, v46
	v_mul_f32_e32 v47, 0xbfb8aa3b, v47
	v_div_fmas_f32 v48, v48, v53, v49
	v_exp_f32_e32 v46, v46
	v_exp_f32_e32 v47, v47
	v_div_fixup_f32 v41, v48, v45, v41
	v_fma_f32 v45, -v50, v51, 1.0
	v_fmac_f32_e32 v51, v45, v51
	v_div_scale_f32 v45, vcc, v40, v44, v40
	v_mul_f32_e32 v48, v45, v51
	v_fma_f32 v49, -v50, v48, v45
	v_pk_add_f32 v[46:47], v[46:47], 1.0 op_sel_hi:[1,0]
	v_fmac_f32_e32 v48, v49, v51
	v_div_scale_f32 v49, s[30:31], v47, v47, v43
	v_fma_f32 v45, -v50, v48, v45
	v_rcp_f32_e32 v50, v49
	v_div_fmas_f32 v45, v45, v51, v48
	v_div_fixup_f32 v40, v45, v44, v40
	v_mul_f32_e32 v36, 0xbfb8aa3b, v36
	v_fma_f32 v44, -v49, v50, 1.0
	v_fmac_f32_e32 v50, v44, v50
	v_div_scale_f32 v44, vcc, v43, v47, v43
	v_mul_f32_e32 v45, v44, v50
	v_fma_f32 v48, -v49, v45, v44
	v_fmac_f32_e32 v45, v48, v50
	v_div_scale_f32 v48, s[30:31], v46, v46, v42
	v_fma_f32 v44, -v49, v45, v44
	v_rcp_f32_e32 v49, v48
	v_div_fmas_f32 v44, v44, v50, v45
	v_div_fixup_f32 v43, v44, v47, v43
	v_mul_f32_e32 v37, 0xbfb8aa3b, v37
	v_fma_f32 v44, -v48, v49, 1.0
	v_fmac_f32_e32 v49, v44, v49
	v_div_scale_f32 v44, vcc, v42, v46, v42
	v_mul_f32_e32 v45, v44, v49
	v_exp_f32_e32 v36, v36
	v_exp_f32_e32 v37, v37
	v_fma_f32 v47, -v48, v45, v44
	v_fmac_f32_e32 v45, v47, v49
	v_fma_f32 v44, -v48, v45, v44
	v_div_fmas_f32 v44, v44, v49, v45
	v_pk_add_f32 v[36:37], v[36:37], 1.0 op_sel_hi:[1,0]
	v_div_fixup_f32 v42, v44, v46, v42
	v_div_scale_f32 v46, s[30:31], v37, v37, v33
	v_rcp_f32_e32 v47, v46
	v_add_co_u32_e32 v44, vcc, s63, v116
	v_cvt_pk_bf16_f32 v40, v40, v41
	v_cvt_pk_bf16_f32 v41, v42, v43
	v_addc_co_u32_e32 v45, vcc, 0, v117, vcc
	global_store_dwordx2 v[44:45], v[40:41], off
	v_fma_f32 v40, -v46, v47, 1.0
	v_fmac_f32_e32 v47, v40, v47
	v_div_scale_f32 v40, vcc, v33, v37, v33
	v_mul_f32_e32 v41, v40, v47
	v_fma_f32 v44, -v46, v41, v40
	v_fmac_f32_e32 v41, v44, v47
	v_div_scale_f32 v44, s[30:31], v36, v36, v32
	v_rcp_f32_e32 v45, v44
	v_fma_f32 v40, -v46, v41, v40
	v_mul_f32_e32 v38, 0xbfb8aa3b, v38
	v_mul_f32_e32 v39, 0xbfb8aa3b, v39
	v_div_fmas_f32 v40, v40, v47, v41
	v_exp_f32_e32 v38, v38
	v_exp_f32_e32 v39, v39
	v_div_fixup_f32 v33, v40, v37, v33
	v_fma_f32 v37, -v44, v45, 1.0
	v_fmac_f32_e32 v45, v37, v45
	v_div_scale_f32 v37, vcc, v32, v36, v32
	v_mul_f32_e32 v40, v37, v45
	v_fma_f32 v41, -v44, v40, v37
	v_pk_add_f32 v[38:39], v[38:39], 1.0 op_sel_hi:[1,0]
	v_fmac_f32_e32 v40, v41, v45
	v_div_scale_f32 v41, s[30:31], v39, v39, v35
	v_fma_f32 v37, -v44, v40, v37
	v_rcp_f32_e32 v44, v41
	v_div_fmas_f32 v37, v37, v45, v40
	v_div_fixup_f32 v32, v37, v36, v32
	v_mul_f32_e32 v28, 0xbfb8aa3b, v28
	v_fma_f32 v36, -v41, v44, 1.0
	v_fmac_f32_e32 v44, v36, v44
	v_div_scale_f32 v36, vcc, v35, v39, v35
	v_mul_f32_e32 v37, v36, v44
	v_fma_f32 v40, -v41, v37, v36
	v_fmac_f32_e32 v37, v40, v44
	v_div_scale_f32 v40, s[30:31], v38, v38, v34
	v_fma_f32 v36, -v41, v37, v36
	v_rcp_f32_e32 v41, v40
	v_div_fmas_f32 v36, v36, v44, v37
	v_div_fixup_f32 v35, v36, v39, v35
	v_mul_f32_e32 v29, 0xbfb8aa3b, v29
	v_fma_f32 v36, -v40, v41, 1.0
	v_fmac_f32_e32 v41, v36, v41
	v_div_scale_f32 v36, vcc, v34, v38, v34
	v_mul_f32_e32 v37, v36, v41
	v_exp_f32_e32 v28, v28
	v_exp_f32_e32 v29, v29
	v_fma_f32 v39, -v40, v37, v36
	v_fmac_f32_e32 v37, v39, v41
	v_fma_f32 v36, -v40, v37, v36
	v_div_fmas_f32 v36, v36, v41, v37
	v_pk_add_f32 v[28:29], v[28:29], 1.0 op_sel_hi:[1,0]
	v_div_fixup_f32 v34, v36, v38, v34
	v_div_scale_f32 v36, s[30:31], v29, v29, v25
	v_rcp_f32_e32 v37, v36
	v_lshl_add_u64 v[42:43], v[116:117], 0, s[10:11]
	v_cvt_pk_bf16_f32 v32, v32, v33
	v_cvt_pk_bf16_f32 v33, v34, v35
	global_store_dwordx2 v[42:43], v[32:33], off offset:128
	v_fma_f32 v32, -v36, v37, 1.0
	v_fmac_f32_e32 v37, v32, v37
	v_div_scale_f32 v32, vcc, v25, v29, v25
	v_mul_f32_e32 v33, v32, v37
	v_fma_f32 v34, -v36, v33, v32
	v_fmac_f32_e32 v33, v34, v37
	v_div_scale_f32 v34, s[30:31], v28, v28, v24
	v_rcp_f32_e32 v35, v34
	v_fma_f32 v32, -v36, v33, v32
	v_mul_f32_e32 v30, 0xbfb8aa3b, v30
	v_mul_f32_e32 v31, 0xbfb8aa3b, v31
	v_div_fmas_f32 v32, v32, v37, v33
	v_exp_f32_e32 v30, v30
	v_exp_f32_e32 v31, v31
	v_div_fixup_f32 v25, v32, v29, v25
	v_fma_f32 v29, -v34, v35, 1.0
	v_fmac_f32_e32 v35, v29, v35
	v_div_scale_f32 v29, vcc, v24, v28, v24
	v_mul_f32_e32 v32, v29, v35
	v_fma_f32 v33, -v34, v32, v29
	v_pk_add_f32 v[30:31], v[30:31], 1.0 op_sel_hi:[1,0]
	v_fmac_f32_e32 v32, v33, v35
	v_div_scale_f32 v33, s[30:31], v31, v31, v27
	v_fma_f32 v29, -v34, v32, v29
	v_rcp_f32_e32 v34, v33
	v_div_fmas_f32 v29, v29, v35, v32
	v_div_fixup_f32 v24, v29, v28, v24
	v_mul_f32_e32 v20, 0xbfb8aa3b, v20
	v_fma_f32 v28, -v33, v34, 1.0
	v_fmac_f32_e32 v34, v28, v34
	v_div_scale_f32 v28, vcc, v27, v31, v27
	v_mul_f32_e32 v29, v28, v34
	v_fma_f32 v32, -v33, v29, v28
	v_fmac_f32_e32 v29, v32, v34
	v_div_scale_f32 v32, s[30:31], v30, v30, v26
	v_fma_f32 v28, -v33, v29, v28
	v_rcp_f32_e32 v33, v32
	v_div_fmas_f32 v28, v28, v34, v29
	v_div_fixup_f32 v27, v28, v31, v27
	v_mul_f32_e32 v21, 0xbfb8aa3b, v21
	v_fma_f32 v28, -v32, v33, 1.0
	v_fmac_f32_e32 v33, v28, v33
	v_div_scale_f32 v28, vcc, v26, v30, v26
	v_mul_f32_e32 v29, v28, v33
	v_exp_f32_e32 v20, v20
	v_exp_f32_e32 v21, v21
	v_fma_f32 v31, -v32, v29, v28
	v_fmac_f32_e32 v29, v31, v33
	v_fma_f32 v28, -v32, v29, v28
	v_div_fmas_f32 v28, v28, v33, v29
	v_pk_add_f32 v[20:21], v[20:21], 1.0 op_sel_hi:[1,0]
	v_div_fixup_f32 v26, v28, v30, v26
	v_div_scale_f32 v30, s[30:31], v21, v21, v17
	v_rcp_f32_e32 v31, v30
	v_add_co_u32_e32 v28, vcc, s70, v116
	v_cvt_pk_bf16_f32 v24, v24, v25
	v_cvt_pk_bf16_f32 v25, v26, v27
	v_addc_co_u32_e32 v29, vcc, 0, v117, vcc
	global_store_dwordx2 v[28:29], v[24:25], off
	v_fma_f32 v24, -v30, v31, 1.0
	v_fmac_f32_e32 v31, v24, v31
	v_div_scale_f32 v24, vcc, v17, v21, v17
	v_mul_f32_e32 v25, v24, v31
	v_fma_f32 v28, -v30, v25, v24
	v_fmac_f32_e32 v25, v28, v31
	v_div_scale_f32 v28, s[30:31], v20, v20, v16
	v_rcp_f32_e32 v29, v28
	v_fma_f32 v24, -v30, v25, v24
	v_mul_f32_e32 v22, 0xbfb8aa3b, v22
	v_mul_f32_e32 v23, 0xbfb8aa3b, v23
	v_div_fmas_f32 v24, v24, v31, v25
	v_exp_f32_e32 v22, v22
	v_exp_f32_e32 v23, v23
	v_div_fixup_f32 v17, v24, v21, v17
	v_fma_f32 v21, -v28, v29, 1.0
	v_fmac_f32_e32 v29, v21, v29
	v_div_scale_f32 v21, vcc, v16, v20, v16
	v_mul_f32_e32 v24, v21, v29
	v_fma_f32 v25, -v28, v24, v21
	v_pk_add_f32 v[22:23], v[22:23], 1.0 op_sel_hi:[1,0]
	v_fmac_f32_e32 v24, v25, v29
	v_div_scale_f32 v25, s[30:31], v23, v23, v19
	v_fma_f32 v21, -v28, v24, v21
	v_rcp_f32_e32 v28, v25
	v_div_fmas_f32 v21, v21, v29, v24
	v_div_fixup_f32 v16, v21, v20, v16
	v_mul_f32_e32 v12, 0xbfb8aa3b, v12
	v_fma_f32 v20, -v25, v28, 1.0
	v_fmac_f32_e32 v28, v20, v28
	v_div_scale_f32 v20, vcc, v19, v23, v19
	v_mul_f32_e32 v21, v20, v28
	v_fma_f32 v24, -v25, v21, v20
	v_fmac_f32_e32 v21, v24, v28
	v_div_scale_f32 v24, s[30:31], v22, v22, v18
	v_fma_f32 v20, -v25, v21, v20
	v_rcp_f32_e32 v25, v24
	v_div_fmas_f32 v20, v20, v28, v21
	v_div_fixup_f32 v19, v20, v23, v19
	v_mul_f32_e32 v13, 0xbfb8aa3b, v13
	v_fma_f32 v20, -v24, v25, 1.0
	v_fmac_f32_e32 v25, v20, v25
	v_div_scale_f32 v20, vcc, v18, v22, v18
	v_mul_f32_e32 v21, v20, v25
	v_exp_f32_e32 v12, v12
	v_exp_f32_e32 v13, v13
	v_fma_f32 v23, -v24, v21, v20
	v_fmac_f32_e32 v21, v23, v25
	v_fma_f32 v20, -v24, v21, v20
	v_div_fmas_f32 v20, v20, v25, v21
	v_pk_add_f32 v[12:13], v[12:13], 1.0 op_sel_hi:[1,0]
	v_div_fixup_f32 v18, v20, v22, v18
	v_div_scale_f32 v20, s[30:31], v13, v13, v9
	v_rcp_f32_e32 v21, v20
	v_lshl_add_u64 v[26:27], v[116:117], 0, s[12:13]
	v_cvt_pk_bf16_f32 v16, v16, v17
	v_cvt_pk_bf16_f32 v17, v18, v19
	global_store_dwordx2 v[26:27], v[16:17], off offset:128
	v_fma_f32 v16, -v20, v21, 1.0
	v_fmac_f32_e32 v21, v16, v21
	v_div_scale_f32 v16, vcc, v9, v13, v9
	v_mul_f32_e32 v17, v16, v21
	v_fma_f32 v18, -v20, v17, v16
	v_fmac_f32_e32 v17, v18, v21
	v_div_scale_f32 v18, s[30:31], v12, v12, v8
	v_rcp_f32_e32 v19, v18
	v_fma_f32 v16, -v20, v17, v16
	v_mul_f32_e32 v14, 0xbfb8aa3b, v14
	v_mul_f32_e32 v15, 0xbfb8aa3b, v15
	v_div_fmas_f32 v16, v16, v21, v17
	v_exp_f32_e32 v14, v14
	v_exp_f32_e32 v15, v15
	v_div_fixup_f32 v9, v16, v13, v9
	v_fma_f32 v13, -v18, v19, 1.0
	v_fmac_f32_e32 v19, v13, v19
	v_div_scale_f32 v13, vcc, v8, v12, v8
	v_mul_f32_e32 v16, v13, v19
	v_fma_f32 v17, -v18, v16, v13
	v_pk_add_f32 v[14:15], v[14:15], 1.0 op_sel_hi:[1,0]
	v_fmac_f32_e32 v16, v17, v19
	v_div_scale_f32 v17, s[30:31], v15, v15, v11
	v_fma_f32 v13, -v18, v16, v13
	v_rcp_f32_e32 v18, v17
	v_div_fmas_f32 v13, v13, v19, v16
	v_div_fixup_f32 v8, v13, v12, v8
	v_mul_f32_e32 v4, 0xbfb8aa3b, v4
	v_fma_f32 v12, -v17, v18, 1.0
	v_fmac_f32_e32 v18, v12, v18
	v_div_scale_f32 v12, vcc, v11, v15, v11
	v_mul_f32_e32 v13, v12, v18
	v_fma_f32 v16, -v17, v13, v12
	v_fmac_f32_e32 v13, v16, v18
	v_div_scale_f32 v16, s[30:31], v14, v14, v10
	v_fma_f32 v12, -v17, v13, v12
	v_rcp_f32_e32 v17, v16
	v_div_fmas_f32 v12, v12, v18, v13
	v_div_fixup_f32 v11, v12, v15, v11
	v_mul_f32_e32 v5, 0xbfb8aa3b, v5
	v_fma_f32 v12, -v16, v17, 1.0
	v_fmac_f32_e32 v17, v12, v17
	v_div_scale_f32 v12, vcc, v10, v14, v10
	v_mul_f32_e32 v13, v12, v17
	v_exp_f32_e32 v4, v4
	v_exp_f32_e32 v5, v5
	v_fma_f32 v15, -v16, v13, v12
	v_fmac_f32_e32 v13, v15, v17
	v_fma_f32 v12, -v16, v13, v12
	v_div_fmas_f32 v12, v12, v17, v13
	v_pk_add_f32 v[4:5], v[4:5], 1.0 op_sel_hi:[1,0]
	v_div_fixup_f32 v10, v12, v14, v10
	v_div_scale_f32 v14, s[30:31], v5, v5, v1
	v_rcp_f32_e32 v15, v14
	v_add_co_u32_e32 v12, vcc, s71, v116
	v_cvt_pk_bf16_f32 v8, v8, v9
	v_cvt_pk_bf16_f32 v9, v10, v11
	v_addc_co_u32_e32 v13, vcc, 0, v117, vcc
	global_store_dwordx2 v[12:13], v[8:9], off
	v_fma_f32 v8, -v14, v15, 1.0
	v_fmac_f32_e32 v15, v8, v15
	v_div_scale_f32 v8, vcc, v1, v5, v1
	v_mul_f32_e32 v9, v8, v15
	v_fma_f32 v12, -v14, v9, v8
	v_fmac_f32_e32 v9, v12, v15
	v_div_scale_f32 v12, s[30:31], v4, v4, v0
	v_rcp_f32_e32 v13, v12
	v_fma_f32 v8, -v14, v9, v8
	v_mul_f32_e32 v6, 0xbfb8aa3b, v6
	v_mul_f32_e32 v7, 0xbfb8aa3b, v7
	v_div_fmas_f32 v8, v8, v15, v9
	v_exp_f32_e32 v6, v6
	v_exp_f32_e32 v7, v7
	v_div_fixup_f32 v1, v8, v5, v1
	v_fma_f32 v5, -v12, v13, 1.0
	v_fmac_f32_e32 v13, v5, v13
	v_div_scale_f32 v5, vcc, v0, v4, v0
	v_mul_f32_e32 v8, v5, v13
	v_fma_f32 v9, -v12, v8, v5
	v_pk_add_f32 v[6:7], v[6:7], 1.0 op_sel_hi:[1,0]
	v_fmac_f32_e32 v8, v9, v13
	v_div_scale_f32 v9, s[30:31], v7, v7, v3
	v_fma_f32 v5, -v12, v8, v5
	v_rcp_f32_e32 v12, v9
	v_div_fmas_f32 v5, v5, v13, v8
	v_div_fixup_f32 v0, v5, v4, v0
	v_lshl_add_u64 v[10:11], v[116:117], 0, s[14:15]
	v_fma_f32 v4, -v9, v12, 1.0
	v_fmac_f32_e32 v12, v4, v12
	v_div_scale_f32 v4, vcc, v3, v7, v3
	v_mul_f32_e32 v5, v4, v12
	v_fma_f32 v8, -v9, v5, v4
	v_fmac_f32_e32 v5, v8, v12
	v_div_scale_f32 v8, s[30:31], v6, v6, v2
	v_fma_f32 v4, -v9, v5, v4
	v_rcp_f32_e32 v9, v8
	v_div_fmas_f32 v4, v4, v12, v5
	v_div_fixup_f32 v3, v4, v7, v3
	v_cvt_pk_bf16_f32 v0, v0, v1
	v_fma_f32 v4, -v8, v9, 1.0
	v_fmac_f32_e32 v9, v4, v9
	v_div_scale_f32 v4, vcc, v2, v6, v2
	v_mul_f32_e32 v5, v4, v9
	v_fma_f32 v7, -v8, v5, v4
	v_fmac_f32_e32 v5, v7, v9
	v_fma_f32 v4, -v8, v5, v4
	v_div_fmas_f32 v4, v4, v9, v5
	v_div_fixup_f32 v2, v4, v6, v2
	v_cvt_pk_bf16_f32 v1, v2, v3
	s_and_b64 vcc, exec, s[4:5]
	s_mov_b32 s72, s16
	s_mov_b32 s28, s18
	s_mov_b64 s[34:35], s[26:27]
	s_mov_b64 s[30:31], s[20:21]
	global_store_dwordx2 v[10:11], v[0:1], off offset:128
	s_cbranch_vccz .LBB0_1109
	s_waitcnt vmcnt(16)
	s_cmpk_gt_u32 s40, 0xff
	s_cbranch_scc1 .LBB0_1120
	s_barrier

.LBB0_1141:
	ds_read_b128 v[150:153], v145
	ds_read_b128 v[154:157], v145 offset:1024
	ds_read_b128 v[158:161], v145 offset:2048
	ds_read_b128 v[162:165], v145 offset:3072
	s_add_u32 s34, s30, 0xfffc0080
	s_addc_u32 s35, s31, -1
	s_cmp_eq_u32 s77, 12
	s_cselect_b32 s37, s19, s35
	s_cselect_b32 s36, s73, s34
	s_cselect_b32 s35, s17, s76
	s_cselect_b32 s34, s74, s75
	v_lshl_add_u64 v[198:199], s[30:31], 0, v[134:135]
	s_add_i32 m0, s29, 0xc000
	ds_read_b128 v[166:169], v148
	ds_read_b128 v[170:173], v148 offset:1024
	ds_read_b128 v[174:177], v148 offset:2048
	ds_read_b128 v[178:181], v148 offset:3072
	ds_read_b128 v[182:185], v148 offset:4096
	ds_read_b128 v[186:189], v148 offset:5120
	ds_read_b128 v[190:193], v148 offset:6144
	ds_read_b128 v[194:197], v148 offset:7168
	global_load_lds_dwordx4 v[198:199], off
	v_lshl_add_u64 v[198:199], s[30:31], 0, v[136:137]
	s_add_i32 m0, s29, 0xe000
	s_nop 0
	global_load_lds_dwordx4 v[198:199], off
	s_waitcnt lgkmcnt(8)
	s_waitcnt vmcnt(10)
	s_barrier
	s_waitcnt lgkmcnt(0)
	s_waitcnt lgkmcnt(0)
	v_mfma_f32_16x16x32_bf16 v[120:123], v[150:153], v[166:169], v[120:123]
	v_mfma_f32_16x16x32_bf16 v[124:127], v[158:161], v[166:169], v[124:127]
	v_mfma_f32_16x16x32_bf16 v[104:107], v[150:153], v[174:177], v[104:107]
	v_mfma_f32_16x16x32_bf16 v[108:111], v[158:161], v[174:177], v[108:111]
	v_mfma_f32_16x16x32_bf16 v[88:91], v[150:153], v[182:185], v[88:91]
	v_mfma_f32_16x16x32_bf16 v[92:95], v[158:161], v[182:185], v[92:95]
	v_mfma_f32_16x16x32_bf16 v[72:75], v[150:153], v[190:193], v[72:75]
	v_mfma_f32_16x16x32_bf16 v[76:79], v[158:161], v[190:193], v[76:79]
	v_mfma_f32_16x16x32_bf16 v[120:123], v[154:157], v[170:173], v[120:123]
	v_mfma_f32_16x16x32_bf16 v[124:127], v[162:165], v[170:173], v[124:127]
	v_mfma_f32_16x16x32_bf16 v[104:107], v[154:157], v[178:181], v[104:107]
	v_mfma_f32_16x16x32_bf16 v[108:111], v[162:165], v[178:181], v[108:111]
	v_mfma_f32_16x16x32_bf16 v[88:91], v[154:157], v[186:189], v[88:91]
	v_mfma_f32_16x16x32_bf16 v[92:95], v[162:165], v[186:189], v[92:95]
	v_mfma_f32_16x16x32_bf16 v[72:75], v[154:157], v[194:197], v[72:75]
	v_mfma_f32_16x16x32_bf16 v[76:79], v[162:165], v[194:197], v[76:79]
	s_barrier
	s_add_i32 s78, s60, s42
	v_lshl_add_u64 v[214:215], s[34:35], 0, v[130:131]
	s_mov_b32 m0, s78
	ds_read_b128 v[198:201], v149
	ds_read_b128 v[202:205], v149 offset:1024
	ds_read_b128 v[206:209], v149 offset:2048
	ds_read_b128 v[210:213], v149 offset:3072
	global_load_lds_dwordx4 v[214:215], off
	v_lshl_add_u64 v[216:217], s[34:35], 0, v[132:133]
	s_add_i32 m0, s78, 0x2000
	s_nop 0
	global_load_lds_dwordx4 v[216:217], off
	s_waitcnt vmcnt(10)
	s_barrier
	s_waitcnt lgkmcnt(0)
	s_waitcnt lgkmcnt(0)
	v_mfma_f32_16x16x32_bf16 v[112:115], v[198:201], v[166:169], v[112:115]
	v_mfma_f32_16x16x32_bf16 v[116:119], v[206:209], v[166:169], v[116:119]
	v_mfma_f32_16x16x32_bf16 v[96:99], v[198:201], v[174:177], v[96:99]
	v_mfma_f32_16x16x32_bf16 v[100:103], v[206:209], v[174:177], v[100:103]
	v_mfma_f32_16x16x32_bf16 v[80:83], v[198:201], v[182:185], v[80:83]
	v_mfma_f32_16x16x32_bf16 v[84:87], v[206:209], v[182:185], v[84:87]
	v_mfma_f32_16x16x32_bf16 v[64:67], v[198:201], v[190:193], v[64:67]
	v_mfma_f32_16x16x32_bf16 v[68:71], v[206:209], v[190:193], v[68:71]
	v_mfma_f32_16x16x32_bf16 v[112:115], v[202:205], v[170:173], v[112:115]
	v_mfma_f32_16x16x32_bf16 v[116:119], v[210:213], v[170:173], v[116:119]
	v_mfma_f32_16x16x32_bf16 v[96:99], v[202:205], v[178:181], v[96:99]
	v_mfma_f32_16x16x32_bf16 v[100:103], v[210:213], v[178:181], v[100:103]
	v_mfma_f32_16x16x32_bf16 v[80:83], v[202:205], v[186:189], v[80:83]
	v_mfma_f32_16x16x32_bf16 v[84:87], v[210:213], v[186:189], v[84:87]
	v_mfma_f32_16x16x32_bf16 v[64:67], v[202:205], v[194:197], v[64:67]
	v_mfma_f32_16x16x32_bf16 v[68:71], v[210:213], v[194:197], v[68:71]
	s_mov_b32 m0, s29
	v_lshl_add_u64 v[218:219], s[36:37], 0, v[130:131]
	s_barrier
	ds_read_b128 v[166:169], v148 offset:16384
	ds_read_b128 v[170:173], v148 offset:17408
	ds_read_b128 v[174:177], v148 offset:18432
	ds_read_b128 v[178:181], v148 offset:19456
	ds_read_b128 v[182:185], v148 offset:20480
	ds_read_b128 v[186:189], v148 offset:21504
	ds_read_b128 v[190:193], v148 offset:22528
	ds_read_b128 v[194:197], v148 offset:23552
	global_load_lds_dwordx4 v[218:219], off
	v_lshl_add_u64 v[220:221], s[36:37], 0, v[132:133]
	s_mov_b32 m0, s43
	s_nop 0
	global_load_lds_dwordx4 v[220:221], off
	s_waitcnt vmcnt(10)
	s_barrier
	s_waitcnt lgkmcnt(0)
	s_waitcnt lgkmcnt(0)
	v_mfma_f32_16x16x32_bf16 v[56:59], v[150:153], v[166:169], v[56:59]
	v_mfma_f32_16x16x32_bf16 v[60:63], v[158:161], v[166:169], v[60:63]
	v_mfma_f32_16x16x32_bf16 v[40:43], v[150:153], v[174:177], v[40:43]
	v_mfma_f32_16x16x32_bf16 v[44:47], v[158:161], v[174:177], v[44:47]
	v_mfma_f32_16x16x32_bf16 v[24:27], v[150:153], v[182:185], v[24:27]
	v_mfma_f32_16x16x32_bf16 v[28:31], v[158:161], v[182:185], v[28:31]
	v_mfma_f32_16x16x32_bf16 v[8:11], v[150:153], v[190:193], v[8:11]
	v_mfma_f32_16x16x32_bf16 v[12:15], v[158:161], v[190:193], v[12:15]
	v_mfma_f32_16x16x32_bf16 v[56:59], v[154:157], v[170:173], v[56:59]
	v_mfma_f32_16x16x32_bf16 v[60:63], v[162:165], v[170:173], v[60:63]
	v_mfma_f32_16x16x32_bf16 v[40:43], v[154:157], v[178:181], v[40:43]
	v_mfma_f32_16x16x32_bf16 v[44:47], v[162:165], v[178:181], v[44:47]
	v_mfma_f32_16x16x32_bf16 v[24:27], v[154:157], v[186:189], v[24:27]
	v_mfma_f32_16x16x32_bf16 v[28:31], v[162:165], v[186:189], v[28:31]
	v_mfma_f32_16x16x32_bf16 v[8:11], v[154:157], v[194:197], v[8:11]
	v_mfma_f32_16x16x32_bf16 v[12:15], v[162:165], v[194:197], v[12:15]
	s_barrier
	s_add_u32 s78, s34, 0x40000
	s_addc_u32 s79, s35, 0
	s_add_i32 s80, s61, s42
	v_lshl_add_u64 v[150:151], s[78:79], 0, v[130:131]
	s_mov_b32 m0, s80
	s_nop 0
	global_load_lds_dwordx4 v[150:151], off
	v_lshl_add_u64 v[150:151], s[78:79], 0, v[132:133]
	s_add_i32 m0, s80, 0x2000
	s_nop 0
	global_load_lds_dwordx4 v[150:151], off
	s_waitcnt vmcnt(10)
	s_barrier
	v_mfma_f32_16x16x32_bf16 v[48:51], v[198:201], v[166:169], v[48:51]
	v_mfma_f32_16x16x32_bf16 v[52:55], v[206:209], v[166:169], v[52:55]
	v_mfma_f32_16x16x32_bf16 v[32:35], v[198:201], v[174:177], v[32:35]
	v_mfma_f32_16x16x32_bf16 v[36:39], v[206:209], v[174:177], v[36:39]
	v_mfma_f32_16x16x32_bf16 v[16:19], v[198:201], v[182:185], v[16:19]
	v_mfma_f32_16x16x32_bf16 v[20:23], v[206:209], v[182:185], v[20:23]
	v_mfma_f32_16x16x32_bf16 v[0:3], v[198:201], v[190:193], v[0:3]
	v_mfma_f32_16x16x32_bf16 v[4:7], v[206:209], v[190:193], v[4:7]
	v_mfma_f32_16x16x32_bf16 v[48:51], v[202:205], v[170:173], v[48:51]
	v_mfma_f32_16x16x32_bf16 v[52:55], v[210:213], v[170:173], v[52:55]
	v_mfma_f32_16x16x32_bf16 v[32:35], v[202:205], v[178:181], v[32:35]
	v_mfma_f32_16x16x32_bf16 v[36:39], v[210:213], v[178:181], v[36:39]
	v_mfma_f32_16x16x32_bf16 v[16:19], v[202:205], v[186:189], v[16:19]
	v_mfma_f32_16x16x32_bf16 v[20:23], v[210:213], v[186:189], v[20:23]
	v_mfma_f32_16x16x32_bf16 v[0:3], v[202:205], v[194:197], v[0:3]
	v_mfma_f32_16x16x32_bf16 v[4:7], v[210:213], v[194:197], v[4:7]
	s_add_i32 s78, 0, 0x18000
	v_add_u32_e32 v162, s78, v143
	s_barrier
	ds_read_b128 v[150:153], v162
	ds_read_b128 v[154:157], v162 offset:1024
	ds_read_b128 v[158:161], v162 offset:2048
	ds_read_b128 v[162:165], v162 offset:3072
	s_add_u32 s36, s36, 0x40000
	s_addc_u32 s37, s37, 0
	s_mov_b32 m0, s52
	v_lshl_add_u64 v[198:199], s[36:37], 0, v[130:131]
	ds_read_b128 v[166:169], v148 offset:32768
	ds_read_b128 v[170:173], v148 offset:33792
	ds_read_b128 v[174:177], v148 offset:34816
	ds_read_b128 v[178:181], v148 offset:35840
	ds_read_b128 v[182:185], v148 offset:36864
	ds_read_b128 v[186:189], v148 offset:37888
	ds_read_b128 v[190:193], v148 offset:38912
	ds_read_b128 v[194:197], v148 offset:39936
	global_load_lds_dwordx4 v[198:199], off
	v_lshl_add_u64 v[198:199], s[36:37], 0, v[132:133]
	s_mov_b32 m0, s53
	s_nop 0
	global_load_lds_dwordx4 v[198:199], off
	s_waitcnt lgkmcnt(8)
	s_waitcnt vmcnt(10)
	s_barrier
	s_waitcnt lgkmcnt(0)
	s_waitcnt lgkmcnt(0)
	v_mfma_f32_16x16x32_bf16 v[120:123], v[150:153], v[166:169], v[120:123]
	v_mfma_f32_16x16x32_bf16 v[124:127], v[158:161], v[166:169], v[124:127]
	v_mfma_f32_16x16x32_bf16 v[104:107], v[150:153], v[174:177], v[104:107]
	v_mfma_f32_16x16x32_bf16 v[108:111], v[158:161], v[174:177], v[108:111]
	v_mfma_f32_16x16x32_bf16 v[88:91], v[150:153], v[182:185], v[88:91]
	v_mfma_f32_16x16x32_bf16 v[92:95], v[158:161], v[182:185], v[92:95]
	v_mfma_f32_16x16x32_bf16 v[72:75], v[150:153], v[190:193], v[72:75]
	v_mfma_f32_16x16x32_bf16 v[76:79], v[158:161], v[190:193], v[76:79]
	v_mfma_f32_16x16x32_bf16 v[120:123], v[154:157], v[170:173], v[120:123]
	v_mfma_f32_16x16x32_bf16 v[124:127], v[162:165], v[170:173], v[124:127]
	v_mfma_f32_16x16x32_bf16 v[104:107], v[154:157], v[178:181], v[104:107]
	v_mfma_f32_16x16x32_bf16 v[108:111], v[162:165], v[178:181], v[108:111]
	v_mfma_f32_16x16x32_bf16 v[88:91], v[154:157], v[186:189], v[88:91]
	v_mfma_f32_16x16x32_bf16 v[92:95], v[162:165], v[186:189], v[92:95]
	v_mfma_f32_16x16x32_bf16 v[72:75], v[154:157], v[194:197], v[72:75]
	v_mfma_f32_16x16x32_bf16 v[76:79], v[162:165], v[194:197], v[76:79]
	s_barrier
	s_add_i32 s36, 0, 0x1c000
	s_add_i32 s37, s78, s42
	v_add_u32_e32 v210, s36, v143
	v_lshl_add_u64 v[214:215], v[214:215], 0, s[8:9]
	s_mov_b32 m0, s37
	ds_read_b128 v[198:201], v210
	ds_read_b128 v[202:205], v210 offset:1024
	ds_read_b128 v[206:209], v210 offset:2048
	ds_read_b128 v[210:213], v210 offset:3072
	global_load_lds_dwordx4 v[214:215], off
	v_lshl_add_u64 v[214:215], v[216:217], 0, s[8:9]
	s_add_i32 m0, s37, 0x2000
	s_nop 0
	global_load_lds_dwordx4 v[214:215], off
	s_waitcnt vmcnt(10)
	s_barrier
	s_waitcnt lgkmcnt(0)
	s_waitcnt lgkmcnt(0)
	v_mfma_f32_16x16x32_bf16 v[112:115], v[198:201], v[166:169], v[112:115]
	v_mfma_f32_16x16x32_bf16 v[116:119], v[206:209], v[166:169], v[116:119]
	v_mfma_f32_16x16x32_bf16 v[96:99], v[198:201], v[174:177], v[96:99]
	v_mfma_f32_16x16x32_bf16 v[100:103], v[206:209], v[174:177], v[100:103]
	v_mfma_f32_16x16x32_bf16 v[80:83], v[198:201], v[182:185], v[80:83]
	v_mfma_f32_16x16x32_bf16 v[84:87], v[206:209], v[182:185], v[84:87]
	v_mfma_f32_16x16x32_bf16 v[64:67], v[198:201], v[190:193], v[64:67]
	v_mfma_f32_16x16x32_bf16 v[68:71], v[206:209], v[190:193], v[68:71]
	v_mfma_f32_16x16x32_bf16 v[112:115], v[202:205], v[170:173], v[112:115]
	v_mfma_f32_16x16x32_bf16 v[116:119], v[210:213], v[170:173], v[116:119]
	v_mfma_f32_16x16x32_bf16 v[96:99], v[202:205], v[178:181], v[96:99]
	v_mfma_f32_16x16x32_bf16 v[100:103], v[210:213], v[178:181], v[100:103]
	v_mfma_f32_16x16x32_bf16 v[80:83], v[202:205], v[186:189], v[80:83]
	v_mfma_f32_16x16x32_bf16 v[84:87], v[210:213], v[186:189], v[84:87]
	v_mfma_f32_16x16x32_bf16 v[64:67], v[202:205], v[194:197], v[64:67]
	v_mfma_f32_16x16x32_bf16 v[68:71], v[210:213], v[194:197], v[68:71]
	s_mov_b32 m0, s55
	v_lshl_add_u64 v[214:215], v[218:219], 0, s[8:9]
	s_barrier
	ds_read_b128 v[166:169], v148 offset:49152
	ds_read_b128 v[170:173], v148 offset:50176
	ds_read_b128 v[174:177], v148 offset:51200
	ds_read_b128 v[178:181], v148 offset:52224
	ds_read_b128 v[182:185], v148 offset:53248
	ds_read_b128 v[186:189], v148 offset:54272
	ds_read_b128 v[190:193], v148 offset:55296
	ds_read_b128 v[194:197], v148 offset:56320
	global_load_lds_dwordx4 v[214:215], off
	v_lshl_add_u64 v[214:215], v[220:221], 0, s[8:9]
	s_mov_b32 m0, s56
	s_nop 0
	global_load_lds_dwordx4 v[214:215], off
	s_waitcnt vmcnt(10)
	s_barrier
	s_waitcnt lgkmcnt(0)
	s_waitcnt lgkmcnt(0)
	v_mfma_f32_16x16x32_bf16 v[56:59], v[150:153], v[166:169], v[56:59]
	v_mfma_f32_16x16x32_bf16 v[60:63], v[158:161], v[166:169], v[60:63]
	v_mfma_f32_16x16x32_bf16 v[40:43], v[150:153], v[174:177], v[40:43]
	v_mfma_f32_16x16x32_bf16 v[44:47], v[158:161], v[174:177], v[44:47]
	v_mfma_f32_16x16x32_bf16 v[24:27], v[150:153], v[182:185], v[24:27]
	v_mfma_f32_16x16x32_bf16 v[28:31], v[158:161], v[182:185], v[28:31]
	v_mfma_f32_16x16x32_bf16 v[8:11], v[150:153], v[190:193], v[8:11]
	v_mfma_f32_16x16x32_bf16 v[12:15], v[158:161], v[190:193], v[12:15]
	v_mfma_f32_16x16x32_bf16 v[56:59], v[154:157], v[170:173], v[56:59]
	v_mfma_f32_16x16x32_bf16 v[60:63], v[162:165], v[170:173], v[60:63]
	v_mfma_f32_16x16x32_bf16 v[40:43], v[154:157], v[178:181], v[40:43]
	v_mfma_f32_16x16x32_bf16 v[44:47], v[162:165], v[178:181], v[44:47]
	v_mfma_f32_16x16x32_bf16 v[24:27], v[154:157], v[186:189], v[24:27]
	v_mfma_f32_16x16x32_bf16 v[28:31], v[162:165], v[186:189], v[28:31]
	v_mfma_f32_16x16x32_bf16 v[8:11], v[154:157], v[194:197], v[8:11]
	v_mfma_f32_16x16x32_bf16 v[12:15], v[162:165], v[194:197], v[12:15]
	s_barrier
	s_add_u32 s34, s34, 0x40080
	s_addc_u32 s35, s35, 0
	s_add_i32 s36, s36, s42
	v_lshl_add_u64 v[150:151], s[34:35], 0, v[130:131]
	s_mov_b32 m0, s36
	s_nop 0
	global_load_lds_dwordx4 v[150:151], off
	v_lshl_add_u64 v[150:151], s[34:35], 0, v[132:133]
	s_add_i32 m0, s36, 0x2000
	s_nop 0
	global_load_lds_dwordx4 v[150:151], off
	s_waitcnt vmcnt(10)
	s_barrier
	v_mfma_f32_16x16x32_bf16 v[48:51], v[198:201], v[166:169], v[48:51]
	v_mfma_f32_16x16x32_bf16 v[52:55], v[206:209], v[166:169], v[52:55]
	v_mfma_f32_16x16x32_bf16 v[32:35], v[198:201], v[174:177], v[32:35]
	v_mfma_f32_16x16x32_bf16 v[36:39], v[206:209], v[174:177], v[36:39]
	v_mfma_f32_16x16x32_bf16 v[16:19], v[198:201], v[182:185], v[16:19]
	v_mfma_f32_16x16x32_bf16 v[20:23], v[206:209], v[182:185], v[20:23]
	v_mfma_f32_16x16x32_bf16 v[0:3], v[198:201], v[190:193], v[0:3]
	v_mfma_f32_16x16x32_bf16 v[4:7], v[206:209], v[190:193], v[4:7]
	v_mfma_f32_16x16x32_bf16 v[48:51], v[202:205], v[170:173], v[48:51]
	v_mfma_f32_16x16x32_bf16 v[52:55], v[210:213], v[170:173], v[52:55]
	v_mfma_f32_16x16x32_bf16 v[32:35], v[202:205], v[178:181], v[32:35]
	v_mfma_f32_16x16x32_bf16 v[36:39], v[210:213], v[178:181], v[36:39]
	v_mfma_f32_16x16x32_bf16 v[16:19], v[202:205], v[186:189], v[16:19]
	v_mfma_f32_16x16x32_bf16 v[20:23], v[210:213], v[186:189], v[20:23]
	v_mfma_f32_16x16x32_bf16 v[0:3], v[202:205], v[194:197], v[0:3]
	v_mfma_f32_16x16x32_bf16 v[4:7], v[210:213], v[194:197], v[4:7]
	s_add_i32 s77, s77, 2
	s_add_u32 s30, s30, 0x100
	s_addc_u32 s31, s31, 0
	s_add_u32 s75, s75, 0x100
	s_addc_u32 s76, s76, 0
	s_cmp_gt_u32 s77, 13
	s_barrier
	s_cbranch_scc0 .LBB0_1141
	v_mul_f32_e32 v124, 0xbfb8aa3b, v124
	v_exp_f32_e32 v150, v124
	v_mul_f32_e32 v124, 0xbfb8aa3b, v125
	v_exp_f32_e32 v151, v124
	v_lshl_add_u32 v124, s28, 8, v142
	v_ashrrev_i32_e32 v125, 31, v124
	v_lshlrev_b64 v[154:155], 11, v[124:125]
	v_pk_add_f32 v[150:151], v[150:151], 1.0 op_sel_hi:[1,0]
	v_mul_f32_e32 v126, 0xbfb8aa3b, v126
	v_div_scale_f32 v153, s[30:31], v151, v151, v121
	v_rcp_f32_e32 v156, v153
	v_mul_f32_e32 v127, 0xbfb8aa3b, v127
	v_exp_f32_e32 v126, v126
	v_exp_f32_e32 v127, v127
	v_fma_f32 v125, -v153, v156, 1.0
	v_fmac_f32_e32 v156, v125, v156
	v_div_scale_f32 v125, vcc, v121, v151, v121
	v_mul_f32_e32 v157, v125, v156
	v_fma_f32 v158, -v153, v157, v125
	v_fmac_f32_e32 v157, v158, v156
	v_fma_f32 v125, -v153, v157, v125
	v_div_scale_f32 v153, s[30:31], v150, v150, v120
	v_rcp_f32_e32 v158, v153
	v_div_fmas_f32 v125, v125, v156, v157
	v_div_fixup_f32 v121, v125, v151, v121
	v_pk_add_f32 v[126:127], v[126:127], 1.0 op_sel_hi:[1,0]
	v_fma_f32 v125, -v153, v158, 1.0
	v_fmac_f32_e32 v158, v125, v158
	v_div_scale_f32 v125, vcc, v120, v150, v120
	v_mul_f32_e32 v151, v125, v158
	v_fma_f32 v156, -v153, v151, v125
	v_fmac_f32_e32 v151, v156, v158
	v_fma_f32 v125, -v153, v151, v125
	v_div_scale_f32 v153, s[30:31], v127, v127, v123
	v_rcp_f32_e32 v156, v153
	v_div_fmas_f32 v125, v125, v158, v151
	v_div_fixup_f32 v120, v125, v150, v120
	v_mul_f32_e32 v116, 0xbfb8aa3b, v116
	v_fma_f32 v125, -v153, v156, 1.0
	v_fmac_f32_e32 v156, v125, v156
	v_div_scale_f32 v125, vcc, v123, v127, v123
	v_mul_f32_e32 v150, v125, v156
	v_fma_f32 v151, -v153, v150, v125
	v_fmac_f32_e32 v150, v151, v156
	v_div_scale_f32 v151, s[30:31], v126, v126, v122
	v_fma_f32 v125, -v153, v150, v125
	v_rcp_f32_e32 v153, v151
	v_div_fmas_f32 v125, v125, v156, v150
	v_div_fixup_f32 v123, v125, v127, v123
	v_mul_f32_e32 v117, 0xbfb8aa3b, v117
	v_fma_f32 v125, -v151, v153, 1.0
	v_fmac_f32_e32 v153, v125, v153
	v_div_scale_f32 v125, vcc, v122, v126, v122
	v_mul_f32_e32 v127, v125, v153
	v_fma_f32 v150, -v151, v127, v125
	v_exp_f32_e32 v116, v116
	v_exp_f32_e32 v117, v117
	v_fmac_f32_e32 v127, v150, v153
	v_fma_f32 v125, -v151, v127, v125
	v_div_fmas_f32 v125, v125, v153, v127
	v_div_fixup_f32 v125, v125, v126, v122
	v_pk_add_f32 v[126:127], v[116:117], 1.0 op_sel_hi:[1,0]
	v_cvt_pk_bf16_f32 v123, v125, v123
	v_div_scale_f32 v125, s[30:31], v127, v127, v113
	v_lshl_or_b32 v152, s72, 7, v144
	v_rcp_f32_e32 v150, v125
	v_ashrrev_i32_e32 v153, 31, v152
	v_lshl_add_u64 v[154:155], s[46:47], 0, v[154:155]
	v_cvt_pk_bf16_f32 v122, v120, v121
	v_lshlrev_b64 v[120:121], 1, v[152:153]
	v_lshl_add_u64 v[116:117], v[154:155], 0, v[120:121]
	global_store_dwordx2 v[116:117], v[122:123], off
	v_fma_f32 v122, -v125, v150, 1.0
	v_fmac_f32_e32 v150, v122, v150
	v_div_scale_f32 v122, vcc, v113, v127, v113
	v_mul_f32_e32 v123, v122, v150
	v_fma_f32 v151, -v125, v123, v122
	v_fmac_f32_e32 v123, v151, v150
	v_fma_f32 v122, -v125, v123, v122
	v_div_scale_f32 v125, s[30:31], v126, v126, v112
	v_rcp_f32_e32 v151, v125
	v_div_fmas_f32 v122, v122, v150, v123
	v_mul_f32_e32 v118, 0xbfb8aa3b, v118
	v_mul_f32_e32 v119, 0xbfb8aa3b, v119
	v_div_fixup_f32 v113, v122, v127, v113
	v_fma_f32 v122, -v125, v151, 1.0
	v_exp_f32_e32 v118, v118
	v_exp_f32_e32 v119, v119
	v_fmac_f32_e32 v151, v122, v151
	v_div_scale_f32 v122, vcc, v112, v126, v112
	v_mul_f32_e32 v123, v122, v151
	v_fma_f32 v127, -v125, v123, v122
	v_fmac_f32_e32 v123, v127, v151
	v_pk_add_f32 v[118:119], v[118:119], 1.0 op_sel_hi:[1,0]
	v_fma_f32 v122, -v125, v123, v122
	v_div_scale_f32 v125, s[30:31], v119, v119, v115
	v_rcp_f32_e32 v127, v125
	v_div_fmas_f32 v122, v122, v151, v123
	v_div_fixup_f32 v112, v122, v126, v112
	v_mul_f32_e32 v108, 0xbfb8aa3b, v108
	v_fma_f32 v122, -v125, v127, 1.0
	v_fmac_f32_e32 v127, v122, v127
	v_div_scale_f32 v122, vcc, v115, v119, v115
	v_mul_f32_e32 v123, v122, v127
	v_fma_f32 v126, -v125, v123, v122
	v_fmac_f32_e32 v123, v126, v127
	v_fma_f32 v122, -v125, v123, v122
	v_div_scale_f32 v125, s[30:31], v118, v118, v114
	v_rcp_f32_e32 v126, v125
	v_div_fmas_f32 v122, v122, v127, v123
	v_div_fixup_f32 v115, v122, v119, v115
	v_mul_f32_e32 v109, 0xbfb8aa3b, v109
	v_fma_f32 v119, -v125, v126, 1.0
	v_fmac_f32_e32 v126, v119, v126
	v_div_scale_f32 v119, vcc, v114, v118, v114
	v_mul_f32_e32 v122, v119, v126
	v_fma_f32 v123, -v125, v122, v119
	v_exp_f32_e32 v108, v108
	v_exp_f32_e32 v109, v109
	v_fmac_f32_e32 v122, v123, v126
	v_fma_f32 v119, -v125, v122, v119
	v_div_fmas_f32 v119, v119, v126, v122
	v_div_fixup_f32 v114, v119, v118, v114
	v_pk_add_f32 v[108:109], v[108:109], 1.0 op_sel_hi:[1,0]
	v_cvt_pk_bf16_f32 v112, v112, v113
	v_cvt_pk_bf16_f32 v113, v114, v115
	v_div_scale_f32 v114, s[30:31], v109, v109, v105
	v_rcp_f32_e32 v115, v114
	v_mul_f32_e32 v110, 0xbfb8aa3b, v110
	v_mul_f32_e32 v111, 0xbfb8aa3b, v111
	v_exp_f32_e32 v110, v110
	v_fma_f32 v118, -v114, v115, 1.0
	v_fmac_f32_e32 v115, v118, v115
	v_div_scale_f32 v118, vcc, v105, v109, v105
	v_mul_f32_e32 v119, v118, v115
	v_fma_f32 v122, -v114, v119, v118
	v_fmac_f32_e32 v119, v122, v115
	v_fma_f32 v114, -v114, v119, v118
	v_div_scale_f32 v118, s[30:31], v108, v108, v104
	v_rcp_f32_e32 v122, v118
	v_div_fmas_f32 v114, v114, v115, v119
	v_exp_f32_e32 v111, v111
	v_div_fixup_f32 v105, v114, v109, v105
	v_fma_f32 v109, -v118, v122, 1.0
	v_fmac_f32_e32 v122, v109, v122
	v_div_scale_f32 v109, vcc, v104, v108, v104
	v_mul_f32_e32 v114, v109, v122
	v_fma_f32 v115, -v118, v114, v109
	v_pk_add_f32 v[110:111], v[110:111], 1.0 op_sel_hi:[1,0]
	v_fmac_f32_e32 v114, v115, v122
	v_div_scale_f32 v115, s[30:31], v111, v111, v107
	v_fma_f32 v109, -v118, v114, v109
	v_rcp_f32_e32 v118, v115
	v_div_fmas_f32 v109, v109, v122, v114
	v_div_fixup_f32 v104, v109, v108, v104
	v_mul_f32_e32 v100, 0xbfb8aa3b, v100
	v_fma_f32 v108, -v115, v118, 1.0
	v_fmac_f32_e32 v118, v108, v118
	v_div_scale_f32 v108, vcc, v107, v111, v107
	v_mul_f32_e32 v109, v108, v118
	v_fma_f32 v114, -v115, v109, v108
	v_fmac_f32_e32 v109, v114, v118
	v_div_scale_f32 v114, s[30:31], v110, v110, v106
	v_fma_f32 v108, -v115, v109, v108
	v_rcp_f32_e32 v115, v114
	v_div_fmas_f32 v108, v108, v118, v109
	v_div_fixup_f32 v107, v108, v111, v107
	v_mul_f32_e32 v101, 0xbfb8aa3b, v101
	v_fma_f32 v108, -v114, v115, 1.0
	v_fmac_f32_e32 v115, v108, v115
	v_div_scale_f32 v108, vcc, v106, v110, v106
	v_mul_f32_e32 v109, v108, v115
	v_exp_f32_e32 v100, v100
	v_exp_f32_e32 v101, v101
	v_fma_f32 v111, -v114, v109, v108
	v_fmac_f32_e32 v109, v111, v115
	v_fma_f32 v108, -v114, v109, v108
	v_div_fmas_f32 v108, v108, v115, v109
	v_pk_add_f32 v[100:101], v[100:101], 1.0 op_sel_hi:[1,0]
	global_store_dwordx2 v[116:117], v[112:113], off offset:128
	v_or_b32_e32 v112, 16, v124
	v_div_fixup_f32 v106, v108, v110, v106
	v_div_scale_f32 v108, s[30:31], v101, v101, v97
	v_ashrrev_i32_e32 v113, 31, v112
	v_rcp_f32_e32 v109, v108
	v_lshlrev_b64 v[112:113], 11, v[112:113]
	v_lshl_add_u64 v[112:113], s[46:47], 0, v[112:113]
	v_cvt_pk_bf16_f32 v104, v104, v105
	v_cvt_pk_bf16_f32 v105, v106, v107
	v_lshl_add_u64 v[106:107], v[112:113], 0, v[120:121]
	global_store_dwordx2 v[106:107], v[104:105], off
	v_fma_f32 v104, -v108, v109, 1.0
	v_fmac_f32_e32 v109, v104, v109
	v_div_scale_f32 v104, vcc, v97, v101, v97
	v_mul_f32_e32 v105, v104, v109
	v_fma_f32 v110, -v108, v105, v104
	v_fmac_f32_e32 v105, v110, v109
	v_fma_f32 v104, -v108, v105, v104
	v_div_scale_f32 v108, s[30:31], v100, v100, v96
	v_rcp_f32_e32 v110, v108
	v_mul_f32_e32 v102, 0xbfb8aa3b, v102
	v_mul_f32_e32 v103, 0xbfb8aa3b, v103
	v_div_fmas_f32 v104, v104, v109, v105
	v_exp_f32_e32 v102, v102
	v_exp_f32_e32 v103, v103
	v_div_fixup_f32 v97, v104, v101, v97
	v_fma_f32 v101, -v108, v110, 1.0
	v_fmac_f32_e32 v110, v101, v110
	v_div_scale_f32 v101, vcc, v96, v100, v96
	v_mul_f32_e32 v104, v101, v110
	v_fma_f32 v105, -v108, v104, v101
	v_pk_add_f32 v[102:103], v[102:103], 1.0 op_sel_hi:[1,0]
	v_fmac_f32_e32 v104, v105, v110
	v_div_scale_f32 v105, s[30:31], v103, v103, v99
	v_fma_f32 v101, -v108, v104, v101
	v_rcp_f32_e32 v108, v105
	v_div_fmas_f32 v101, v101, v110, v104
	v_div_fixup_f32 v96, v101, v100, v96
	v_mul_f32_e32 v92, 0xbfb8aa3b, v92
	v_fma_f32 v100, -v105, v108, 1.0
	v_fmac_f32_e32 v108, v100, v108
	v_div_scale_f32 v100, vcc, v99, v103, v99
	v_mul_f32_e32 v101, v100, v108
	v_fma_f32 v104, -v105, v101, v100
	v_fmac_f32_e32 v101, v104, v108
	v_div_scale_f32 v104, s[30:31], v102, v102, v98
	v_fma_f32 v100, -v105, v101, v100
	v_rcp_f32_e32 v105, v104
	v_div_fmas_f32 v100, v100, v108, v101
	v_div_fixup_f32 v99, v100, v103, v99
	v_mul_f32_e32 v93, 0xbfb8aa3b, v93
	v_fma_f32 v100, -v104, v105, 1.0
	v_fmac_f32_e32 v105, v100, v105
	v_div_scale_f32 v100, vcc, v98, v102, v98
	v_mul_f32_e32 v101, v100, v105
	v_fma_f32 v103, -v104, v101, v100
	v_exp_f32_e32 v92, v92
	v_exp_f32_e32 v93, v93
	v_fmac_f32_e32 v101, v103, v105
	v_fma_f32 v100, -v104, v101, v100
	v_div_fmas_f32 v100, v100, v105, v101
	v_div_fixup_f32 v98, v100, v102, v98
	v_pk_add_f32 v[92:93], v[92:93], 1.0 op_sel_hi:[1,0]
	v_cvt_pk_bf16_f32 v96, v96, v97
	v_cvt_pk_bf16_f32 v97, v98, v99
	v_div_scale_f32 v98, s[30:31], v93, v93, v89
	v_rcp_f32_e32 v99, v98
	v_mul_f32_e32 v94, 0xbfb8aa3b, v94
	v_mul_f32_e32 v95, 0xbfb8aa3b, v95
	v_exp_f32_e32 v94, v94
	v_fma_f32 v100, -v98, v99, 1.0
	v_fmac_f32_e32 v99, v100, v99
	v_div_scale_f32 v100, vcc, v89, v93, v89
	v_mul_f32_e32 v101, v100, v99
	v_fma_f32 v102, -v98, v101, v100
	v_fmac_f32_e32 v101, v102, v99
	v_fma_f32 v98, -v98, v101, v100
	v_div_scale_f32 v100, s[30:31], v92, v92, v88
	v_rcp_f32_e32 v102, v100
	v_div_fmas_f32 v98, v98, v99, v101
	v_exp_f32_e32 v95, v95
	v_div_fixup_f32 v89, v98, v93, v89
	v_fma_f32 v93, -v100, v102, 1.0
	v_fmac_f32_e32 v102, v93, v102
	v_div_scale_f32 v93, vcc, v88, v92, v88
	v_mul_f32_e32 v98, v93, v102
	v_fma_f32 v99, -v100, v98, v93
	v_pk_add_f32 v[94:95], v[94:95], 1.0 op_sel_hi:[1,0]
	v_fmac_f32_e32 v98, v99, v102
	v_div_scale_f32 v99, s[30:31], v95, v95, v91
	v_fma_f32 v93, -v100, v98, v93
	v_rcp_f32_e32 v100, v99
	v_div_fmas_f32 v93, v93, v102, v98
	v_div_fixup_f32 v88, v93, v92, v88
	v_mul_f32_e32 v84, 0xbfb8aa3b, v84
	v_fma_f32 v92, -v99, v100, 1.0
	v_fmac_f32_e32 v100, v92, v100
	v_div_scale_f32 v92, vcc, v91, v95, v91
	v_mul_f32_e32 v93, v92, v100
	v_fma_f32 v98, -v99, v93, v92
	v_fmac_f32_e32 v93, v98, v100
	v_div_scale_f32 v98, s[30:31], v94, v94, v90
	v_fma_f32 v92, -v99, v93, v92
	v_rcp_f32_e32 v99, v98
	v_div_fmas_f32 v92, v92, v100, v93
	v_div_fixup_f32 v91, v92, v95, v91
	v_mul_f32_e32 v85, 0xbfb8aa3b, v85
	v_fma_f32 v92, -v98, v99, 1.0
	v_fmac_f32_e32 v99, v92, v99
	v_div_scale_f32 v92, vcc, v90, v94, v90
	v_mul_f32_e32 v93, v92, v99
	v_exp_f32_e32 v84, v84
	v_exp_f32_e32 v85, v85
	v_fma_f32 v95, -v98, v93, v92
	v_fmac_f32_e32 v93, v95, v99
	v_fma_f32 v92, -v98, v93, v92
	v_div_fmas_f32 v92, v92, v99, v93
	v_pk_add_f32 v[84:85], v[84:85], 1.0 op_sel_hi:[1,0]
	global_store_dwordx2 v[106:107], v[96:97], off offset:128
	v_or_b32_e32 v96, 32, v124
	v_div_fixup_f32 v90, v92, v94, v90
	v_div_scale_f32 v92, s[30:31], v85, v85, v81
	v_ashrrev_i32_e32 v97, 31, v96
	v_rcp_f32_e32 v93, v92
	v_lshlrev_b64 v[96:97], 11, v[96:97]
	v_lshl_add_u64 v[96:97], s[46:47], 0, v[96:97]
	v_cvt_pk_bf16_f32 v88, v88, v89
	v_cvt_pk_bf16_f32 v89, v90, v91
	v_lshl_add_u64 v[90:91], v[96:97], 0, v[120:121]
	global_store_dwordx2 v[90:91], v[88:89], off
	v_fma_f32 v88, -v92, v93, 1.0
	v_fmac_f32_e32 v93, v88, v93
	v_div_scale_f32 v88, vcc, v81, v85, v81
	v_mul_f32_e32 v89, v88, v93
	v_fma_f32 v94, -v92, v89, v88
	v_fmac_f32_e32 v89, v94, v93
	v_fma_f32 v88, -v92, v89, v88
	v_div_scale_f32 v92, s[30:31], v84, v84, v80
	v_rcp_f32_e32 v94, v92
	v_mul_f32_e32 v86, 0xbfb8aa3b, v86
	v_mul_f32_e32 v87, 0xbfb8aa3b, v87
	v_div_fmas_f32 v88, v88, v93, v89
	v_exp_f32_e32 v86, v86
	v_exp_f32_e32 v87, v87
	v_div_fixup_f32 v81, v88, v85, v81
	v_fma_f32 v85, -v92, v94, 1.0
	v_fmac_f32_e32 v94, v85, v94
	v_div_scale_f32 v85, vcc, v80, v84, v80
	v_mul_f32_e32 v88, v85, v94
	v_fma_f32 v89, -v92, v88, v85
	v_pk_add_f32 v[86:87], v[86:87], 1.0 op_sel_hi:[1,0]
	v_fmac_f32_e32 v88, v89, v94
	v_div_scale_f32 v89, s[30:31], v87, v87, v83
	v_fma_f32 v85, -v92, v88, v85
	v_rcp_f32_e32 v92, v89
	v_div_fmas_f32 v85, v85, v94, v88
	v_div_fixup_f32 v80, v85, v84, v80
	v_mul_f32_e32 v76, 0xbfb8aa3b, v76
	v_fma_f32 v84, -v89, v92, 1.0
	v_fmac_f32_e32 v92, v84, v92
	v_div_scale_f32 v84, vcc, v83, v87, v83
	v_mul_f32_e32 v85, v84, v92
	v_fma_f32 v88, -v89, v85, v84
	v_fmac_f32_e32 v85, v88, v92
	v_div_scale_f32 v88, s[30:31], v86, v86, v82
	v_fma_f32 v84, -v89, v85, v84
	v_rcp_f32_e32 v89, v88
	v_div_fmas_f32 v84, v84, v92, v85
	v_div_fixup_f32 v83, v84, v87, v83
	v_mul_f32_e32 v77, 0xbfb8aa3b, v77
	v_fma_f32 v84, -v88, v89, 1.0
	v_fmac_f32_e32 v89, v84, v89
	v_div_scale_f32 v84, vcc, v82, v86, v82
	v_mul_f32_e32 v85, v84, v89
	v_fma_f32 v87, -v88, v85, v84
	v_exp_f32_e32 v76, v76
	v_exp_f32_e32 v77, v77
	v_fmac_f32_e32 v85, v87, v89
	v_fma_f32 v84, -v88, v85, v84
	v_div_fmas_f32 v84, v84, v89, v85
	v_div_fixup_f32 v82, v84, v86, v82
	v_pk_add_f32 v[76:77], v[76:77], 1.0 op_sel_hi:[1,0]
	v_cvt_pk_bf16_f32 v80, v80, v81
	v_cvt_pk_bf16_f32 v81, v82, v83
	v_div_scale_f32 v82, s[30:31], v77, v77, v73
	v_rcp_f32_e32 v83, v82
	v_mul_f32_e32 v78, 0xbfb8aa3b, v78
	v_mul_f32_e32 v79, 0xbfb8aa3b, v79
	v_exp_f32_e32 v78, v78
	v_fma_f32 v84, -v82, v83, 1.0
	v_fmac_f32_e32 v83, v84, v83
	v_div_scale_f32 v84, vcc, v73, v77, v73
	v_mul_f32_e32 v85, v84, v83
	v_fma_f32 v86, -v82, v85, v84
	v_fmac_f32_e32 v85, v86, v83
	v_fma_f32 v82, -v82, v85, v84
	v_div_scale_f32 v84, s[30:31], v76, v76, v72
	v_rcp_f32_e32 v86, v84
	v_div_fmas_f32 v82, v82, v83, v85
	v_exp_f32_e32 v79, v79
	v_div_fixup_f32 v73, v82, v77, v73
	v_fma_f32 v77, -v84, v86, 1.0
	v_fmac_f32_e32 v86, v77, v86
	v_div_scale_f32 v77, vcc, v72, v76, v72
	v_mul_f32_e32 v82, v77, v86
	v_fma_f32 v83, -v84, v82, v77
	v_pk_add_f32 v[78:79], v[78:79], 1.0 op_sel_hi:[1,0]
	v_fmac_f32_e32 v82, v83, v86
	v_div_scale_f32 v83, s[30:31], v79, v79, v75
	v_fma_f32 v77, -v84, v82, v77
	v_rcp_f32_e32 v84, v83
	v_div_fmas_f32 v77, v77, v86, v82
	v_div_fixup_f32 v72, v77, v76, v72
	v_mul_f32_e32 v68, 0xbfb8aa3b, v68
	v_fma_f32 v76, -v83, v84, 1.0
	v_fmac_f32_e32 v84, v76, v84
	v_div_scale_f32 v76, vcc, v75, v79, v75
	v_mul_f32_e32 v77, v76, v84
	v_fma_f32 v82, -v83, v77, v76
	v_fmac_f32_e32 v77, v82, v84
	v_div_scale_f32 v82, s[30:31], v78, v78, v74
	v_fma_f32 v76, -v83, v77, v76
	v_rcp_f32_e32 v83, v82
	v_div_fmas_f32 v76, v76, v84, v77
	v_div_fixup_f32 v75, v76, v79, v75
	v_mul_f32_e32 v69, 0xbfb8aa3b, v69
	v_fma_f32 v76, -v82, v83, 1.0
	v_fmac_f32_e32 v83, v76, v83
	v_div_scale_f32 v76, vcc, v74, v78, v74
	v_mul_f32_e32 v77, v76, v83
	v_exp_f32_e32 v68, v68
	v_exp_f32_e32 v69, v69
	v_fma_f32 v79, -v82, v77, v76
	v_fmac_f32_e32 v77, v79, v83
	v_fma_f32 v76, -v82, v77, v76
	v_div_fmas_f32 v76, v76, v83, v77
	v_pk_add_f32 v[68:69], v[68:69], 1.0 op_sel_hi:[1,0]
	global_store_dwordx2 v[90:91], v[80:81], off offset:128
	v_or_b32_e32 v80, 48, v124
	v_div_fixup_f32 v74, v76, v78, v74
	v_div_scale_f32 v76, s[30:31], v69, v69, v65
	v_ashrrev_i32_e32 v81, 31, v80
	v_rcp_f32_e32 v77, v76
	v_lshlrev_b64 v[80:81], 11, v[80:81]
	v_lshl_add_u64 v[80:81], s[46:47], 0, v[80:81]
	v_cvt_pk_bf16_f32 v72, v72, v73
	v_cvt_pk_bf16_f32 v73, v74, v75
	v_lshl_add_u64 v[74:75], v[80:81], 0, v[120:121]
	global_store_dwordx2 v[74:75], v[72:73], off
	v_fma_f32 v72, -v76, v77, 1.0
	v_fmac_f32_e32 v77, v72, v77
	v_div_scale_f32 v72, vcc, v65, v69, v65
	v_mul_f32_e32 v73, v72, v77
	v_fma_f32 v78, -v76, v73, v72
	v_fmac_f32_e32 v73, v78, v77
	v_fma_f32 v72, -v76, v73, v72
	v_div_scale_f32 v76, s[30:31], v68, v68, v64
	v_rcp_f32_e32 v78, v76
	v_mul_f32_e32 v70, 0xbfb8aa3b, v70
	v_mul_f32_e32 v71, 0xbfb8aa3b, v71
	v_div_fmas_f32 v72, v72, v77, v73
	v_exp_f32_e32 v70, v70
	v_exp_f32_e32 v71, v71
	v_div_fixup_f32 v65, v72, v69, v65
	v_fma_f32 v69, -v76, v78, 1.0
	v_fmac_f32_e32 v78, v69, v78
	v_div_scale_f32 v69, vcc, v64, v68, v64
	v_mul_f32_e32 v72, v69, v78
	v_fma_f32 v73, -v76, v72, v69
	v_pk_add_f32 v[70:71], v[70:71], 1.0 op_sel_hi:[1,0]
	v_fmac_f32_e32 v72, v73, v78
	v_div_scale_f32 v73, s[30:31], v71, v71, v67
	v_fma_f32 v69, -v76, v72, v69
	v_rcp_f32_e32 v76, v73
	v_div_fmas_f32 v69, v69, v78, v72
	v_div_fixup_f32 v64, v69, v68, v64
	v_mul_f32_e32 v60, 0xbfb8aa3b, v60
	v_fma_f32 v68, -v73, v76, 1.0
	v_fmac_f32_e32 v76, v68, v76
	v_div_scale_f32 v68, vcc, v67, v71, v67
	v_mul_f32_e32 v69, v68, v76
	v_fma_f32 v72, -v73, v69, v68
	v_fmac_f32_e32 v69, v72, v76
	v_div_scale_f32 v72, s[30:31], v70, v70, v66
	v_fma_f32 v68, -v73, v69, v68
	v_rcp_f32_e32 v73, v72
	v_div_fmas_f32 v68, v68, v76, v69
	v_div_fixup_f32 v67, v68, v71, v67
	v_mul_f32_e32 v61, 0xbfb8aa3b, v61
	v_fma_f32 v68, -v72, v73, 1.0
	v_fmac_f32_e32 v73, v68, v73
	v_div_scale_f32 v68, vcc, v66, v70, v66
	v_mul_f32_e32 v69, v68, v73
	v_exp_f32_e32 v60, v60
	v_exp_f32_e32 v61, v61
	v_fma_f32 v71, -v72, v69, v68
	v_fmac_f32_e32 v69, v71, v73
	v_fma_f32 v68, -v72, v69, v68
	v_div_fmas_f32 v68, v68, v73, v69
	v_pk_add_f32 v[60:61], v[60:61], 1.0 op_sel_hi:[1,0]
	v_div_fixup_f32 v66, v68, v70, v66
	v_div_scale_f32 v68, s[30:31], v61, v61, v57
	v_rcp_f32_e32 v69, v68
	v_cvt_pk_bf16_f32 v64, v64, v65
	v_cvt_pk_bf16_f32 v65, v66, v67
	global_store_dwordx2 v[74:75], v[64:65], off offset:128
	v_fma_f32 v64, -v68, v69, 1.0
	v_fmac_f32_e32 v69, v64, v69
	v_div_scale_f32 v64, vcc, v57, v61, v57
	v_mul_f32_e32 v65, v64, v69
	v_fma_f32 v66, -v68, v65, v64
	v_fmac_f32_e32 v65, v66, v69
	v_div_scale_f32 v66, s[30:31], v60, v60, v56
	v_rcp_f32_e32 v67, v66
	v_fma_f32 v64, -v68, v65, v64
	v_mul_f32_e32 v62, 0xbfb8aa3b, v62
	v_mul_f32_e32 v63, 0xbfb8aa3b, v63
	v_div_fmas_f32 v64, v64, v69, v65
	v_exp_f32_e32 v62, v62
	v_exp_f32_e32 v63, v63
	v_div_fixup_f32 v57, v64, v61, v57
	v_fma_f32 v61, -v66, v67, 1.0
	v_fmac_f32_e32 v67, v61, v67
	v_div_scale_f32 v61, vcc, v56, v60, v56
	v_mul_f32_e32 v64, v61, v67
	v_fma_f32 v65, -v66, v64, v61
	v_pk_add_f32 v[62:63], v[62:63], 1.0 op_sel_hi:[1,0]
	v_fmac_f32_e32 v64, v65, v67
	v_div_scale_f32 v65, s[30:31], v63, v63, v59
	v_fma_f32 v61, -v66, v64, v61
	v_rcp_f32_e32 v66, v65
	v_div_fmas_f32 v61, v61, v67, v64
	v_div_fixup_f32 v56, v61, v60, v56
	v_mul_f32_e32 v52, 0xbfb8aa3b, v52
	v_fma_f32 v60, -v65, v66, 1.0
	v_fmac_f32_e32 v66, v60, v66
	v_div_scale_f32 v60, vcc, v59, v63, v59
	v_mul_f32_e32 v61, v60, v66
	v_fma_f32 v64, -v65, v61, v60
	v_fmac_f32_e32 v61, v64, v66
	v_div_scale_f32 v64, s[30:31], v62, v62, v58
	v_fma_f32 v60, -v65, v61, v60
	v_rcp_f32_e32 v65, v64
	v_div_fmas_f32 v60, v60, v66, v61
	v_div_fixup_f32 v59, v60, v63, v59
	v_mul_f32_e32 v53, 0xbfb8aa3b, v53
	v_fma_f32 v60, -v64, v65, 1.0
	v_fmac_f32_e32 v65, v60, v65
	v_div_scale_f32 v60, vcc, v58, v62, v58
	v_mul_f32_e32 v61, v60, v65
	v_exp_f32_e32 v52, v52
	v_exp_f32_e32 v53, v53
	v_fma_f32 v63, -v64, v61, v60
	v_fmac_f32_e32 v61, v63, v65
	v_fma_f32 v60, -v64, v61, v60
	v_div_fmas_f32 v60, v60, v65, v61
	v_pk_add_f32 v[52:53], v[52:53], 1.0 op_sel_hi:[1,0]
	v_div_fixup_f32 v58, v60, v62, v58
	v_div_scale_f32 v62, s[30:31], v53, v53, v49
	v_rcp_f32_e32 v63, v62
	v_add_co_u32_e32 v60, vcc, s62, v116
	v_cvt_pk_bf16_f32 v56, v56, v57
	v_cvt_pk_bf16_f32 v57, v58, v59
	v_addc_co_u32_e32 v61, vcc, 0, v117, vcc
	global_store_dwordx2 v[60:61], v[56:57], off
	v_fma_f32 v56, -v62, v63, 1.0
	v_fmac_f32_e32 v63, v56, v63
	v_div_scale_f32 v56, vcc, v49, v53, v49
	v_mul_f32_e32 v57, v56, v63
	v_fma_f32 v60, -v62, v57, v56
	v_fmac_f32_e32 v57, v60, v63
	v_div_scale_f32 v60, s[30:31], v52, v52, v48
	v_rcp_f32_e32 v61, v60
	v_fma_f32 v56, -v62, v57, v56
	v_mul_f32_e32 v54, 0xbfb8aa3b, v54
	v_mul_f32_e32 v55, 0xbfb8aa3b, v55
	v_div_fmas_f32 v56, v56, v63, v57
	v_exp_f32_e32 v54, v54
	v_exp_f32_e32 v55, v55
	v_div_fixup_f32 v49, v56, v53, v49
	v_fma_f32 v53, -v60, v61, 1.0
	v_fmac_f32_e32 v61, v53, v61
	v_div_scale_f32 v53, vcc, v48, v52, v48
	v_mul_f32_e32 v56, v53, v61
	v_fma_f32 v57, -v60, v56, v53
	v_pk_add_f32 v[54:55], v[54:55], 1.0 op_sel_hi:[1,0]
	v_fmac_f32_e32 v56, v57, v61
	v_div_scale_f32 v57, s[30:31], v55, v55, v51
	v_fma_f32 v53, -v60, v56, v53
	v_rcp_f32_e32 v60, v57
	v_div_fmas_f32 v53, v53, v61, v56
	v_div_fixup_f32 v48, v53, v52, v48
	v_mul_f32_e32 v44, 0xbfb8aa3b, v44
	v_fma_f32 v52, -v57, v60, 1.0
	v_fmac_f32_e32 v60, v52, v60
	v_div_scale_f32 v52, vcc, v51, v55, v51
	v_mul_f32_e32 v53, v52, v60
	v_fma_f32 v56, -v57, v53, v52
	v_fmac_f32_e32 v53, v56, v60
	v_div_scale_f32 v56, s[30:31], v54, v54, v50
	v_fma_f32 v52, -v57, v53, v52
	v_rcp_f32_e32 v57, v56
	v_div_fmas_f32 v52, v52, v60, v53
	v_div_fixup_f32 v51, v52, v55, v51
	v_mul_f32_e32 v45, 0xbfb8aa3b, v45
	v_fma_f32 v52, -v56, v57, 1.0
	v_fmac_f32_e32 v57, v52, v57
	v_div_scale_f32 v52, vcc, v50, v54, v50
	v_mul_f32_e32 v53, v52, v57
	v_exp_f32_e32 v44, v44
	v_exp_f32_e32 v45, v45
	v_fma_f32 v55, -v56, v53, v52
	v_fmac_f32_e32 v53, v55, v57
	v_fma_f32 v52, -v56, v53, v52
	v_div_fmas_f32 v52, v52, v57, v53
	v_pk_add_f32 v[44:45], v[44:45], 1.0 op_sel_hi:[1,0]
	v_div_fixup_f32 v50, v52, v54, v50
	v_div_scale_f32 v52, s[30:31], v45, v45, v41
	v_rcp_f32_e32 v53, v52
	v_lshl_add_u64 v[58:59], v[116:117], 0, s[6:7]
	v_cvt_pk_bf16_f32 v48, v48, v49
	v_cvt_pk_bf16_f32 v49, v50, v51
	global_store_dwordx2 v[58:59], v[48:49], off offset:128
	v_fma_f32 v48, -v52, v53, 1.0
	v_fmac_f32_e32 v53, v48, v53
	v_div_scale_f32 v48, vcc, v41, v45, v41
	v_mul_f32_e32 v49, v48, v53
	v_fma_f32 v50, -v52, v49, v48
	v_fmac_f32_e32 v49, v50, v53
	v_div_scale_f32 v50, s[30:31], v44, v44, v40
	v_rcp_f32_e32 v51, v50
	v_fma_f32 v48, -v52, v49, v48
	v_mul_f32_e32 v46, 0xbfb8aa3b, v46
	v_mul_f32_e32 v47, 0xbfb8aa3b, v47
	v_div_fmas_f32 v48, v48, v53, v49
	v_exp_f32_e32 v46, v46
	v_exp_f32_e32 v47, v47
	v_div_fixup_f32 v41, v48, v45, v41
	v_fma_f32 v45, -v50, v51, 1.0
	v_fmac_f32_e32 v51, v45, v51
	v_div_scale_f32 v45, vcc, v40, v44, v40
	v_mul_f32_e32 v48, v45, v51
	v_fma_f32 v49, -v50, v48, v45
	v_pk_add_f32 v[46:47], v[46:47], 1.0 op_sel_hi:[1,0]
	v_fmac_f32_e32 v48, v49, v51
	v_div_scale_f32 v49, s[30:31], v47, v47, v43
	v_fma_f32 v45, -v50, v48, v45
	v_rcp_f32_e32 v50, v49
	v_div_fmas_f32 v45, v45, v51, v48
	v_div_fixup_f32 v40, v45, v44, v40
	v_mul_f32_e32 v36, 0xbfb8aa3b, v36
	v_fma_f32 v44, -v49, v50, 1.0
	v_fmac_f32_e32 v50, v44, v50
	v_div_scale_f32 v44, vcc, v43, v47, v43
	v_mul_f32_e32 v45, v44, v50
	v_fma_f32 v48, -v49, v45, v44
	v_fmac_f32_e32 v45, v48, v50
	v_div_scale_f32 v48, s[30:31], v46, v46, v42
	v_fma_f32 v44, -v49, v45, v44
	v_rcp_f32_e32 v49, v48
	v_div_fmas_f32 v44, v44, v50, v45
	v_div_fixup_f32 v43, v44, v47, v43
	v_mul_f32_e32 v37, 0xbfb8aa3b, v37
	v_fma_f32 v44, -v48, v49, 1.0
	v_fmac_f32_e32 v49, v44, v49
	v_div_scale_f32 v44, vcc, v42, v46, v42
	v_mul_f32_e32 v45, v44, v49
	v_exp_f32_e32 v36, v36
	v_exp_f32_e32 v37, v37
	v_fma_f32 v47, -v48, v45, v44
	v_fmac_f32_e32 v45, v47, v49
	v_fma_f32 v44, -v48, v45, v44
	v_div_fmas_f32 v44, v44, v49, v45
	v_pk_add_f32 v[36:37], v[36:37], 1.0 op_sel_hi:[1,0]
	v_div_fixup_f32 v42, v44, v46, v42
	v_div_scale_f32 v46, s[30:31], v37, v37, v33
	v_rcp_f32_e32 v47, v46
	v_add_co_u32_e32 v44, vcc, s63, v116
	v_cvt_pk_bf16_f32 v40, v40, v41
	v_cvt_pk_bf16_f32 v41, v42, v43
	v_addc_co_u32_e32 v45, vcc, 0, v117, vcc
	global_store_dwordx2 v[44:45], v[40:41], off
	v_fma_f32 v40, -v46, v47, 1.0
	v_fmac_f32_e32 v47, v40, v47
	v_div_scale_f32 v40, vcc, v33, v37, v33
	v_mul_f32_e32 v41, v40, v47
	v_fma_f32 v44, -v46, v41, v40
	v_fmac_f32_e32 v41, v44, v47
	v_div_scale_f32 v44, s[30:31], v36, v36, v32
	v_rcp_f32_e32 v45, v44
	v_fma_f32 v40, -v46, v41, v40
	v_mul_f32_e32 v38, 0xbfb8aa3b, v38
	v_mul_f32_e32 v39, 0xbfb8aa3b, v39
	v_div_fmas_f32 v40, v40, v47, v41
	v_exp_f32_e32 v38, v38
	v_exp_f32_e32 v39, v39
	v_div_fixup_f32 v33, v40, v37, v33
	v_fma_f32 v37, -v44, v45, 1.0
	v_fmac_f32_e32 v45, v37, v45
	v_div_scale_f32 v37, vcc, v32, v36, v32
	v_mul_f32_e32 v40, v37, v45
	v_fma_f32 v41, -v44, v40, v37
	v_pk_add_f32 v[38:39], v[38:39], 1.0 op_sel_hi:[1,0]
	v_fmac_f32_e32 v40, v41, v45
	v_div_scale_f32 v41, s[30:31], v39, v39, v35
	v_fma_f32 v37, -v44, v40, v37
	v_rcp_f32_e32 v44, v41
	v_div_fmas_f32 v37, v37, v45, v40
	v_div_fixup_f32 v32, v37, v36, v32
	v_mul_f32_e32 v28, 0xbfb8aa3b, v28
	v_fma_f32 v36, -v41, v44, 1.0
	v_fmac_f32_e32 v44, v36, v44
	v_div_scale_f32 v36, vcc, v35, v39, v35
	v_mul_f32_e32 v37, v36, v44
	v_fma_f32 v40, -v41, v37, v36
	v_fmac_f32_e32 v37, v40, v44
	v_div_scale_f32 v40, s[30:31], v38, v38, v34
	v_fma_f32 v36, -v41, v37, v36
	v_rcp_f32_e32 v41, v40
	v_div_fmas_f32 v36, v36, v44, v37
	v_div_fixup_f32 v35, v36, v39, v35
	v_mul_f32_e32 v29, 0xbfb8aa3b, v29
	v_fma_f32 v36, -v40, v41, 1.0
	v_fmac_f32_e32 v41, v36, v41
	v_div_scale_f32 v36, vcc, v34, v38, v34
	v_mul_f32_e32 v37, v36, v41
	v_exp_f32_e32 v28, v28
	v_exp_f32_e32 v29, v29
	v_fma_f32 v39, -v40, v37, v36
	v_fmac_f32_e32 v37, v39, v41
	v_fma_f32 v36, -v40, v37, v36
	v_div_fmas_f32 v36, v36, v41, v37
	v_pk_add_f32 v[28:29], v[28:29], 1.0 op_sel_hi:[1,0]
	v_div_fixup_f32 v34, v36, v38, v34
	v_div_scale_f32 v36, s[30:31], v29, v29, v25
	v_rcp_f32_e32 v37, v36
	v_lshl_add_u64 v[42:43], v[116:117], 0, s[10:11]
	v_cvt_pk_bf16_f32 v32, v32, v33
	v_cvt_pk_bf16_f32 v33, v34, v35
	global_store_dwordx2 v[42:43], v[32:33], off offset:128
	v_fma_f32 v32, -v36, v37, 1.0
	v_fmac_f32_e32 v37, v32, v37
	v_div_scale_f32 v32, vcc, v25, v29, v25
	v_mul_f32_e32 v33, v32, v37
	v_fma_f32 v34, -v36, v33, v32
	v_fmac_f32_e32 v33, v34, v37
	v_div_scale_f32 v34, s[30:31], v28, v28, v24
	v_rcp_f32_e32 v35, v34
	v_fma_f32 v32, -v36, v33, v32
	v_mul_f32_e32 v30, 0xbfb8aa3b, v30
	v_mul_f32_e32 v31, 0xbfb8aa3b, v31
	v_div_fmas_f32 v32, v32, v37, v33
	v_exp_f32_e32 v30, v30
	v_exp_f32_e32 v31, v31
	v_div_fixup_f32 v25, v32, v29, v25
	v_fma_f32 v29, -v34, v35, 1.0
	v_fmac_f32_e32 v35, v29, v35
	v_div_scale_f32 v29, vcc, v24, v28, v24
	v_mul_f32_e32 v32, v29, v35
	v_fma_f32 v33, -v34, v32, v29
	v_pk_add_f32 v[30:31], v[30:31], 1.0 op_sel_hi:[1,0]
	v_fmac_f32_e32 v32, v33, v35
	v_div_scale_f32 v33, s[30:31], v31, v31, v27
	v_fma_f32 v29, -v34, v32, v29
	v_rcp_f32_e32 v34, v33
	v_div_fmas_f32 v29, v29, v35, v32
	v_div_fixup_f32 v24, v29, v28, v24
	v_mul_f32_e32 v20, 0xbfb8aa3b, v20
	v_fma_f32 v28, -v33, v34, 1.0
	v_fmac_f32_e32 v34, v28, v34
	v_div_scale_f32 v28, vcc, v27, v31, v27
	v_mul_f32_e32 v29, v28, v34
	v_fma_f32 v32, -v33, v29, v28
	v_fmac_f32_e32 v29, v32, v34
	v_div_scale_f32 v32, s[30:31], v30, v30, v26
	v_fma_f32 v28, -v33, v29, v28
	v_rcp_f32_e32 v33, v32
	v_div_fmas_f32 v28, v28, v34, v29
	v_div_fixup_f32 v27, v28, v31, v27
	v_mul_f32_e32 v21, 0xbfb8aa3b, v21
	v_fma_f32 v28, -v32, v33, 1.0
	v_fmac_f32_e32 v33, v28, v33
	v_div_scale_f32 v28, vcc, v26, v30, v26
	v_mul_f32_e32 v29, v28, v33
	v_exp_f32_e32 v20, v20
	v_exp_f32_e32 v21, v21
	v_fma_f32 v31, -v32, v29, v28
	v_fmac_f32_e32 v29, v31, v33
	v_fma_f32 v28, -v32, v29, v28
	v_div_fmas_f32 v28, v28, v33, v29
	v_pk_add_f32 v[20:21], v[20:21], 1.0 op_sel_hi:[1,0]
	v_div_fixup_f32 v26, v28, v30, v26
	v_div_scale_f32 v30, s[30:31], v21, v21, v17
	v_rcp_f32_e32 v31, v30
	v_add_co_u32_e32 v28, vcc, s70, v116
	v_cvt_pk_bf16_f32 v24, v24, v25
	v_cvt_pk_bf16_f32 v25, v26, v27
	v_addc_co_u32_e32 v29, vcc, 0, v117, vcc
	global_store_dwordx2 v[28:29], v[24:25], off
	v_fma_f32 v24, -v30, v31, 1.0
	v_fmac_f32_e32 v31, v24, v31
	v_div_scale_f32 v24, vcc, v17, v21, v17
	v_mul_f32_e32 v25, v24, v31
	v_fma_f32 v28, -v30, v25, v24
	v_fmac_f32_e32 v25, v28, v31
	v_div_scale_f32 v28, s[30:31], v20, v20, v16
	v_rcp_f32_e32 v29, v28
	v_fma_f32 v24, -v30, v25, v24
	v_mul_f32_e32 v22, 0xbfb8aa3b, v22
	v_mul_f32_e32 v23, 0xbfb8aa3b, v23
	v_div_fmas_f32 v24, v24, v31, v25
	v_exp_f32_e32 v22, v22
	v_exp_f32_e32 v23, v23
	v_div_fixup_f32 v17, v24, v21, v17
	v_fma_f32 v21, -v28, v29, 1.0
	v_fmac_f32_e32 v29, v21, v29
	v_div_scale_f32 v21, vcc, v16, v20, v16
	v_mul_f32_e32 v24, v21, v29
	v_fma_f32 v25, -v28, v24, v21
	v_pk_add_f32 v[22:23], v[22:23], 1.0 op_sel_hi:[1,0]
	v_fmac_f32_e32 v24, v25, v29
	v_div_scale_f32 v25, s[30:31], v23, v23, v19
	v_fma_f32 v21, -v28, v24, v21
	v_rcp_f32_e32 v28, v25
	v_div_fmas_f32 v21, v21, v29, v24
	v_div_fixup_f32 v16, v21, v20, v16
	v_mul_f32_e32 v12, 0xbfb8aa3b, v12
	v_fma_f32 v20, -v25, v28, 1.0
	v_fmac_f32_e32 v28, v20, v28
	v_div_scale_f32 v20, vcc, v19, v23, v19
	v_mul_f32_e32 v21, v20, v28
	v_fma_f32 v24, -v25, v21, v20
	v_fmac_f32_e32 v21, v24, v28
	v_div_scale_f32 v24, s[30:31], v22, v22, v18
	v_fma_f32 v20, -v25, v21, v20
	v_rcp_f32_e32 v25, v24
	v_div_fmas_f32 v20, v20, v28, v21
	v_div_fixup_f32 v19, v20, v23, v19
	v_mul_f32_e32 v13, 0xbfb8aa3b, v13
	v_fma_f32 v20, -v24, v25, 1.0
	v_fmac_f32_e32 v25, v20, v25
	v_div_scale_f32 v20, vcc, v18, v22, v18
	v_mul_f32_e32 v21, v20, v25
	v_exp_f32_e32 v12, v12
	v_exp_f32_e32 v13, v13
	v_fma_f32 v23, -v24, v21, v20
	v_fmac_f32_e32 v21, v23, v25
	v_fma_f32 v20, -v24, v21, v20
	v_div_fmas_f32 v20, v20, v25, v21
	v_pk_add_f32 v[12:13], v[12:13], 1.0 op_sel_hi:[1,0]
	v_div_fixup_f32 v18, v20, v22, v18
	v_div_scale_f32 v20, s[30:31], v13, v13, v9
	v_rcp_f32_e32 v21, v20
	v_lshl_add_u64 v[26:27], v[116:117], 0, s[12:13]
	v_cvt_pk_bf16_f32 v16, v16, v17
	v_cvt_pk_bf16_f32 v17, v18, v19
	global_store_dwordx2 v[26:27], v[16:17], off offset:128
	v_fma_f32 v16, -v20, v21, 1.0
	v_fmac_f32_e32 v21, v16, v21
	v_div_scale_f32 v16, vcc, v9, v13, v9
	v_mul_f32_e32 v17, v16, v21
	v_fma_f32 v18, -v20, v17, v16
	v_fmac_f32_e32 v17, v18, v21
	v_div_scale_f32 v18, s[30:31], v12, v12, v8
	v_rcp_f32_e32 v19, v18
	v_fma_f32 v16, -v20, v17, v16
	v_mul_f32_e32 v14, 0xbfb8aa3b, v14
	v_mul_f32_e32 v15, 0xbfb8aa3b, v15
	v_div_fmas_f32 v16, v16, v21, v17
	v_exp_f32_e32 v14, v14
	v_exp_f32_e32 v15, v15
	v_div_fixup_f32 v9, v16, v13, v9
	v_fma_f32 v13, -v18, v19, 1.0
	v_fmac_f32_e32 v19, v13, v19
	v_div_scale_f32 v13, vcc, v8, v12, v8
	v_mul_f32_e32 v16, v13, v19
	v_fma_f32 v17, -v18, v16, v13
	v_pk_add_f32 v[14:15], v[14:15], 1.0 op_sel_hi:[1,0]
	v_fmac_f32_e32 v16, v17, v19
	v_div_scale_f32 v17, s[30:31], v15, v15, v11
	v_fma_f32 v13, -v18, v16, v13
	v_rcp_f32_e32 v18, v17
	v_div_fmas_f32 v13, v13, v19, v16
	v_div_fixup_f32 v8, v13, v12, v8
	v_mul_f32_e32 v4, 0xbfb8aa3b, v4
	v_fma_f32 v12, -v17, v18, 1.0
	v_fmac_f32_e32 v18, v12, v18
	v_div_scale_f32 v12, vcc, v11, v15, v11
	v_mul_f32_e32 v13, v12, v18
	v_fma_f32 v16, -v17, v13, v12
	v_fmac_f32_e32 v13, v16, v18
	v_div_scale_f32 v16, s[30:31], v14, v14, v10
	v_fma_f32 v12, -v17, v13, v12
	v_rcp_f32_e32 v17, v16
	v_div_fmas_f32 v12, v12, v18, v13
	v_div_fixup_f32 v11, v12, v15, v11
	v_mul_f32_e32 v5, 0xbfb8aa3b, v5
	v_fma_f32 v12, -v16, v17, 1.0
	v_fmac_f32_e32 v17, v12, v17
	v_div_scale_f32 v12, vcc, v10, v14, v10
	v_mul_f32_e32 v13, v12, v17
	v_exp_f32_e32 v4, v4
	v_exp_f32_e32 v5, v5
	v_fma_f32 v15, -v16, v13, v12
	v_fmac_f32_e32 v13, v15, v17
	v_fma_f32 v12, -v16, v13, v12
	v_div_fmas_f32 v12, v12, v17, v13
	v_pk_add_f32 v[4:5], v[4:5], 1.0 op_sel_hi:[1,0]
	v_div_fixup_f32 v10, v12, v14, v10
	v_div_scale_f32 v14, s[30:31], v5, v5, v1
	v_rcp_f32_e32 v15, v14
	v_add_co_u32_e32 v12, vcc, s71, v116
	v_cvt_pk_bf16_f32 v8, v8, v9
	v_cvt_pk_bf16_f32 v9, v10, v11
	v_addc_co_u32_e32 v13, vcc, 0, v117, vcc
	global_store_dwordx2 v[12:13], v[8:9], off
	v_fma_f32 v8, -v14, v15, 1.0
	v_fmac_f32_e32 v15, v8, v15
	v_div_scale_f32 v8, vcc, v1, v5, v1
	v_mul_f32_e32 v9, v8, v15
	v_fma_f32 v12, -v14, v9, v8
	v_fmac_f32_e32 v9, v12, v15
	v_div_scale_f32 v12, s[30:31], v4, v4, v0
	v_rcp_f32_e32 v13, v12
	v_fma_f32 v8, -v14, v9, v8
	v_mul_f32_e32 v6, 0xbfb8aa3b, v6
	v_mul_f32_e32 v7, 0xbfb8aa3b, v7
	v_div_fmas_f32 v8, v8, v15, v9
	v_exp_f32_e32 v6, v6
	v_exp_f32_e32 v7, v7
	v_div_fixup_f32 v1, v8, v5, v1
	v_fma_f32 v5, -v12, v13, 1.0
	v_fmac_f32_e32 v13, v5, v13
	v_div_scale_f32 v5, vcc, v0, v4, v0
	v_mul_f32_e32 v8, v5, v13
	v_fma_f32 v9, -v12, v8, v5
	v_pk_add_f32 v[6:7], v[6:7], 1.0 op_sel_hi:[1,0]
	v_fmac_f32_e32 v8, v9, v13
	v_div_scale_f32 v9, s[30:31], v7, v7, v3
	v_fma_f32 v5, -v12, v8, v5
	v_rcp_f32_e32 v12, v9
	v_div_fmas_f32 v5, v5, v13, v8
	v_div_fixup_f32 v0, v5, v4, v0
	v_lshl_add_u64 v[10:11], v[116:117], 0, s[14:15]
	v_fma_f32 v4, -v9, v12, 1.0
	v_fmac_f32_e32 v12, v4, v12
	v_div_scale_f32 v4, vcc, v3, v7, v3
	v_mul_f32_e32 v5, v4, v12
	v_fma_f32 v8, -v9, v5, v4
	v_fmac_f32_e32 v5, v8, v12
	v_div_scale_f32 v8, s[30:31], v6, v6, v2
	v_fma_f32 v4, -v9, v5, v4
	v_rcp_f32_e32 v9, v8
	v_div_fmas_f32 v4, v4, v12, v5
	v_div_fixup_f32 v3, v4, v7, v3
	v_cvt_pk_bf16_f32 v0, v0, v1
	v_fma_f32 v4, -v8, v9, 1.0
	v_fmac_f32_e32 v9, v4, v9
	v_div_scale_f32 v4, vcc, v2, v6, v2
	v_mul_f32_e32 v5, v4, v9
	v_fma_f32 v7, -v8, v5, v4
	v_fmac_f32_e32 v5, v7, v9
	v_fma_f32 v4, -v8, v5, v4
	v_div_fmas_f32 v4, v4, v9, v5
	v_div_fixup_f32 v2, v4, v6, v2
	v_cvt_pk_bf16_f32 v1, v2, v3
	s_and_b64 vcc, exec, s[4:5]
	s_mov_b32 s72, s16
	s_mov_b32 s28, s18
	s_mov_b64 s[34:35], s[26:27]
	s_mov_b64 s[30:31], s[20:21]
	global_store_dwordx2 v[10:11], v[0:1], off offset:128
	s_cbranch_vccz .LBB0_1134
	s_waitcnt vmcnt(16)
	s_cmpk_gt_u32 s40, 0xff
	s_cbranch_scc1 .LBB0_1145
	s_barrier

.LBB0_1291:
	ds_read_b128 v[154:157], v151
	ds_read_b128 v[158:161], v151 offset:1024
	ds_read_b128 v[162:165], v151 offset:2048
	ds_read_b128 v[166:169], v151 offset:3072
	s_add_u32 s36, s34, 0xfffc0080
	s_addc_u32 s37, s35, -1
	s_cmp_eq_u32 s79, 12
	s_cselect_b32 s39, s21, s37
	s_cselect_b32 s38, s75, s36
	s_cselect_b32 s37, s19, s78
	s_cselect_b32 s36, s76, s77
	v_lshl_add_u64 v[202:203], s[34:35], 0, v[138:139]
	s_add_i32 m0, s31, 0xc000
	ds_read_b128 v[170:173], v152
	ds_read_b128 v[174:177], v152 offset:1024
	ds_read_b128 v[178:181], v152 offset:2048
	ds_read_b128 v[182:185], v152 offset:3072
	ds_read_b128 v[186:189], v152 offset:4096
	ds_read_b128 v[190:193], v152 offset:5120
	ds_read_b128 v[194:197], v152 offset:6144
	ds_read_b128 v[198:201], v152 offset:7168
	global_load_lds_dwordx4 v[202:203], off
	v_lshl_add_u64 v[202:203], s[34:35], 0, v[140:141]
	s_add_i32 m0, s31, 0xe000
	s_nop 0
	global_load_lds_dwordx4 v[202:203], off
	s_waitcnt lgkmcnt(8)
	s_waitcnt vmcnt(10)
	s_barrier
	s_waitcnt lgkmcnt(0)
	s_waitcnt lgkmcnt(0)
	v_mfma_f32_16x16x32_bf16 v[124:127], v[154:157], v[170:173], v[124:127]
	v_mfma_f32_16x16x32_bf16 v[120:123], v[162:165], v[170:173], v[120:123]
	v_mfma_f32_16x16x32_bf16 v[108:111], v[154:157], v[178:181], v[108:111]
	v_mfma_f32_16x16x32_bf16 v[104:107], v[162:165], v[178:181], v[104:107]
	v_mfma_f32_16x16x32_bf16 v[92:95], v[154:157], v[186:189], v[92:95]
	v_mfma_f32_16x16x32_bf16 v[88:91], v[162:165], v[186:189], v[88:91]
	v_mfma_f32_16x16x32_bf16 v[76:79], v[154:157], v[194:197], v[76:79]
	v_mfma_f32_16x16x32_bf16 v[72:75], v[162:165], v[194:197], v[72:75]
	v_mfma_f32_16x16x32_bf16 v[124:127], v[158:161], v[174:177], v[124:127]
	v_mfma_f32_16x16x32_bf16 v[120:123], v[166:169], v[174:177], v[120:123]
	v_mfma_f32_16x16x32_bf16 v[108:111], v[158:161], v[182:185], v[108:111]
	v_mfma_f32_16x16x32_bf16 v[104:107], v[166:169], v[182:185], v[104:107]
	v_mfma_f32_16x16x32_bf16 v[92:95], v[158:161], v[190:193], v[92:95]
	v_mfma_f32_16x16x32_bf16 v[88:91], v[166:169], v[190:193], v[88:91]
	v_mfma_f32_16x16x32_bf16 v[76:79], v[158:161], v[198:201], v[76:79]
	v_mfma_f32_16x16x32_bf16 v[72:75], v[166:169], v[198:201], v[72:75]
	s_barrier
	s_add_i32 s80, s62, s52
	v_lshl_add_u64 v[218:219], s[36:37], 0, v[132:133]
	s_mov_b32 m0, s80
	ds_read_b128 v[202:205], v153
	ds_read_b128 v[206:209], v153 offset:1024
	ds_read_b128 v[210:213], v153 offset:2048
	ds_read_b128 v[214:217], v153 offset:3072
	global_load_lds_dwordx4 v[218:219], off
	v_lshl_add_u64 v[220:221], s[36:37], 0, v[136:137]
	s_add_i32 m0, s80, 0x2000
	s_nop 0
	global_load_lds_dwordx4 v[220:221], off
	s_waitcnt vmcnt(10)
	s_barrier
	s_waitcnt lgkmcnt(0)
	s_waitcnt lgkmcnt(0)
	v_mfma_f32_16x16x32_bf16 v[116:119], v[202:205], v[170:173], v[116:119]
	v_mfma_f32_16x16x32_bf16 v[112:115], v[210:213], v[170:173], v[112:115]
	v_mfma_f32_16x16x32_bf16 v[100:103], v[202:205], v[178:181], v[100:103]
	v_mfma_f32_16x16x32_bf16 v[96:99], v[210:213], v[178:181], v[96:99]
	v_mfma_f32_16x16x32_bf16 v[84:87], v[202:205], v[186:189], v[84:87]
	v_mfma_f32_16x16x32_bf16 v[80:83], v[210:213], v[186:189], v[80:83]
	v_mfma_f32_16x16x32_bf16 v[68:71], v[202:205], v[194:197], v[68:71]
	v_mfma_f32_16x16x32_bf16 v[64:67], v[210:213], v[194:197], v[64:67]
	v_mfma_f32_16x16x32_bf16 v[116:119], v[206:209], v[174:177], v[116:119]
	v_mfma_f32_16x16x32_bf16 v[112:115], v[214:217], v[174:177], v[112:115]
	v_mfma_f32_16x16x32_bf16 v[100:103], v[206:209], v[182:185], v[100:103]
	v_mfma_f32_16x16x32_bf16 v[96:99], v[214:217], v[182:185], v[96:99]
	v_mfma_f32_16x16x32_bf16 v[84:87], v[206:209], v[190:193], v[84:87]
	v_mfma_f32_16x16x32_bf16 v[80:83], v[214:217], v[190:193], v[80:83]
	v_mfma_f32_16x16x32_bf16 v[68:71], v[206:209], v[198:201], v[68:71]
	v_mfma_f32_16x16x32_bf16 v[64:67], v[214:217], v[198:201], v[64:67]
	s_mov_b32 m0, s31
	v_lshl_add_u64 v[222:223], s[38:39], 0, v[130:131]
	s_barrier
	ds_read_b128 v[170:173], v152 offset:16384
	ds_read_b128 v[174:177], v152 offset:17408
	ds_read_b128 v[178:181], v152 offset:18432
	ds_read_b128 v[182:185], v152 offset:19456
	ds_read_b128 v[186:189], v152 offset:20480
	ds_read_b128 v[190:193], v152 offset:21504
	ds_read_b128 v[194:197], v152 offset:22528
	ds_read_b128 v[198:201], v152 offset:23552
	global_load_lds_dwordx4 v[222:223], off
	v_lshl_add_u64 v[224:225], s[38:39], 0, v[134:135]
	s_mov_b32 m0, s53
	s_nop 0
	global_load_lds_dwordx4 v[224:225], off
	s_waitcnt vmcnt(10)
	s_barrier
	s_waitcnt lgkmcnt(0)
	s_waitcnt lgkmcnt(0)
	v_mfma_f32_16x16x32_bf16 v[60:63], v[154:157], v[170:173], v[60:63]
	v_mfma_f32_16x16x32_bf16 v[56:59], v[162:165], v[170:173], v[56:59]
	v_mfma_f32_16x16x32_bf16 v[44:47], v[154:157], v[178:181], v[44:47]
	v_mfma_f32_16x16x32_bf16 v[40:43], v[162:165], v[178:181], v[40:43]
	v_mfma_f32_16x16x32_bf16 v[28:31], v[154:157], v[186:189], v[28:31]
	v_mfma_f32_16x16x32_bf16 v[24:27], v[162:165], v[186:189], v[24:27]
	v_mfma_f32_16x16x32_bf16 v[12:15], v[154:157], v[194:197], v[12:15]
	v_mfma_f32_16x16x32_bf16 v[8:11], v[162:165], v[194:197], v[8:11]
	v_mfma_f32_16x16x32_bf16 v[60:63], v[158:161], v[174:177], v[60:63]
	v_mfma_f32_16x16x32_bf16 v[56:59], v[166:169], v[174:177], v[56:59]
	v_mfma_f32_16x16x32_bf16 v[44:47], v[158:161], v[182:185], v[44:47]
	v_mfma_f32_16x16x32_bf16 v[40:43], v[166:169], v[182:185], v[40:43]
	v_mfma_f32_16x16x32_bf16 v[28:31], v[158:161], v[190:193], v[28:31]
	v_mfma_f32_16x16x32_bf16 v[24:27], v[166:169], v[190:193], v[24:27]
	v_mfma_f32_16x16x32_bf16 v[12:15], v[158:161], v[198:201], v[12:15]
	v_mfma_f32_16x16x32_bf16 v[8:11], v[166:169], v[198:201], v[8:11]
	s_barrier
	s_add_u32 s80, s36, 0x40000
	s_addc_u32 s81, s37, 0
	s_add_i32 s82, s63, s52
	v_lshl_add_u64 v[154:155], s[80:81], 0, v[132:133]
	s_mov_b32 m0, s82
	s_nop 0
	global_load_lds_dwordx4 v[154:155], off
	v_lshl_add_u64 v[154:155], s[80:81], 0, v[136:137]
	s_add_i32 m0, s82, 0x2000
	s_nop 0
	global_load_lds_dwordx4 v[154:155], off
	s_waitcnt vmcnt(10)
	s_barrier
	v_mfma_f32_16x16x32_bf16 v[52:55], v[202:205], v[170:173], v[52:55]
	v_mfma_f32_16x16x32_bf16 v[48:51], v[210:213], v[170:173], v[48:51]
	v_mfma_f32_16x16x32_bf16 v[36:39], v[202:205], v[178:181], v[36:39]
	v_mfma_f32_16x16x32_bf16 v[32:35], v[210:213], v[178:181], v[32:35]
	v_mfma_f32_16x16x32_bf16 v[20:23], v[202:205], v[186:189], v[20:23]
	v_mfma_f32_16x16x32_bf16 v[16:19], v[210:213], v[186:189], v[16:19]
	v_mfma_f32_16x16x32_bf16 v[4:7], v[202:205], v[194:197], v[4:7]
	v_mfma_f32_16x16x32_bf16 v[0:3], v[210:213], v[194:197], v[0:3]
	v_mfma_f32_16x16x32_bf16 v[52:55], v[206:209], v[174:177], v[52:55]
	v_mfma_f32_16x16x32_bf16 v[48:51], v[214:217], v[174:177], v[48:51]
	v_mfma_f32_16x16x32_bf16 v[36:39], v[206:209], v[182:185], v[36:39]
	v_mfma_f32_16x16x32_bf16 v[32:35], v[214:217], v[182:185], v[32:35]
	v_mfma_f32_16x16x32_bf16 v[20:23], v[206:209], v[190:193], v[20:23]
	v_mfma_f32_16x16x32_bf16 v[16:19], v[214:217], v[190:193], v[16:19]
	v_mfma_f32_16x16x32_bf16 v[4:7], v[206:209], v[198:201], v[4:7]
	v_mfma_f32_16x16x32_bf16 v[0:3], v[214:217], v[198:201], v[0:3]
	s_add_i32 s80, 0, 0x18000
	v_add_u32_e32 v166, s80, v149
	s_barrier
	ds_read_b128 v[154:157], v166
	ds_read_b128 v[158:161], v166 offset:1024
	ds_read_b128 v[162:165], v166 offset:2048
	ds_read_b128 v[166:169], v166 offset:3072
	s_add_u32 s38, s38, 0x40000
	s_addc_u32 s39, s39, 0
	s_mov_b32 m0, s54
	v_lshl_add_u64 v[202:203], s[38:39], 0, v[130:131]
	ds_read_b128 v[170:173], v152 offset:32768
	ds_read_b128 v[174:177], v152 offset:33792
	ds_read_b128 v[178:181], v152 offset:34816
	ds_read_b128 v[182:185], v152 offset:35840
	ds_read_b128 v[186:189], v152 offset:36864
	ds_read_b128 v[190:193], v152 offset:37888
	ds_read_b128 v[194:197], v152 offset:38912
	ds_read_b128 v[198:201], v152 offset:39936
	global_load_lds_dwordx4 v[202:203], off
	v_lshl_add_u64 v[202:203], s[38:39], 0, v[134:135]
	s_mov_b32 m0, s55
	s_nop 0
	global_load_lds_dwordx4 v[202:203], off
	s_waitcnt lgkmcnt(8)
	s_waitcnt vmcnt(10)
	s_barrier
	s_waitcnt lgkmcnt(0)
	s_waitcnt lgkmcnt(0)
	v_mfma_f32_16x16x32_bf16 v[124:127], v[154:157], v[170:173], v[124:127]
	v_mfma_f32_16x16x32_bf16 v[120:123], v[162:165], v[170:173], v[120:123]
	v_mfma_f32_16x16x32_bf16 v[108:111], v[154:157], v[178:181], v[108:111]
	v_mfma_f32_16x16x32_bf16 v[104:107], v[162:165], v[178:181], v[104:107]
	v_mfma_f32_16x16x32_bf16 v[92:95], v[154:157], v[186:189], v[92:95]
	v_mfma_f32_16x16x32_bf16 v[88:91], v[162:165], v[186:189], v[88:91]
	v_mfma_f32_16x16x32_bf16 v[76:79], v[154:157], v[194:197], v[76:79]
	v_mfma_f32_16x16x32_bf16 v[72:75], v[162:165], v[194:197], v[72:75]
	v_mfma_f32_16x16x32_bf16 v[124:127], v[158:161], v[174:177], v[124:127]
	v_mfma_f32_16x16x32_bf16 v[120:123], v[166:169], v[174:177], v[120:123]
	v_mfma_f32_16x16x32_bf16 v[108:111], v[158:161], v[182:185], v[108:111]
	v_mfma_f32_16x16x32_bf16 v[104:107], v[166:169], v[182:185], v[104:107]
	v_mfma_f32_16x16x32_bf16 v[92:95], v[158:161], v[190:193], v[92:95]
	v_mfma_f32_16x16x32_bf16 v[88:91], v[166:169], v[190:193], v[88:91]
	v_mfma_f32_16x16x32_bf16 v[76:79], v[158:161], v[198:201], v[76:79]
	v_mfma_f32_16x16x32_bf16 v[72:75], v[166:169], v[198:201], v[72:75]
	s_barrier
	s_add_i32 s38, 0, 0x1c000
	s_add_i32 s39, s80, s52
	v_add_u32_e32 v214, s38, v149
	v_lshl_add_u64 v[218:219], v[218:219], 0, s[8:9]
	s_mov_b32 m0, s39
	ds_read_b128 v[202:205], v214
	ds_read_b128 v[206:209], v214 offset:1024
	ds_read_b128 v[210:213], v214 offset:2048
	ds_read_b128 v[214:217], v214 offset:3072
	global_load_lds_dwordx4 v[218:219], off
	v_lshl_add_u64 v[218:219], v[220:221], 0, s[8:9]
	s_add_i32 m0, s39, 0x2000
	s_nop 0
	global_load_lds_dwordx4 v[218:219], off
	s_waitcnt vmcnt(10)
	s_barrier
	s_waitcnt lgkmcnt(0)
	s_waitcnt lgkmcnt(0)
	v_mfma_f32_16x16x32_bf16 v[116:119], v[202:205], v[170:173], v[116:119]
	v_mfma_f32_16x16x32_bf16 v[112:115], v[210:213], v[170:173], v[112:115]
	v_mfma_f32_16x16x32_bf16 v[100:103], v[202:205], v[178:181], v[100:103]
	v_mfma_f32_16x16x32_bf16 v[96:99], v[210:213], v[178:181], v[96:99]
	v_mfma_f32_16x16x32_bf16 v[84:87], v[202:205], v[186:189], v[84:87]
	v_mfma_f32_16x16x32_bf16 v[80:83], v[210:213], v[186:189], v[80:83]
	v_mfma_f32_16x16x32_bf16 v[68:71], v[202:205], v[194:197], v[68:71]
	v_mfma_f32_16x16x32_bf16 v[64:67], v[210:213], v[194:197], v[64:67]
	v_mfma_f32_16x16x32_bf16 v[116:119], v[206:209], v[174:177], v[116:119]
	v_mfma_f32_16x16x32_bf16 v[112:115], v[214:217], v[174:177], v[112:115]
	v_mfma_f32_16x16x32_bf16 v[100:103], v[206:209], v[182:185], v[100:103]
	v_mfma_f32_16x16x32_bf16 v[96:99], v[214:217], v[182:185], v[96:99]
	v_mfma_f32_16x16x32_bf16 v[84:87], v[206:209], v[190:193], v[84:87]
	v_mfma_f32_16x16x32_bf16 v[80:83], v[214:217], v[190:193], v[80:83]
	v_mfma_f32_16x16x32_bf16 v[68:71], v[206:209], v[198:201], v[68:71]
	v_mfma_f32_16x16x32_bf16 v[64:67], v[214:217], v[198:201], v[64:67]
	s_mov_b32 m0, s57
	v_lshl_add_u64 v[218:219], v[222:223], 0, s[8:9]
	s_barrier
	ds_read_b128 v[170:173], v152 offset:49152
	ds_read_b128 v[174:177], v152 offset:50176
	ds_read_b128 v[178:181], v152 offset:51200
	ds_read_b128 v[182:185], v152 offset:52224
	ds_read_b128 v[186:189], v152 offset:53248
	ds_read_b128 v[190:193], v152 offset:54272
	ds_read_b128 v[194:197], v152 offset:55296
	ds_read_b128 v[198:201], v152 offset:56320
	global_load_lds_dwordx4 v[218:219], off
	v_lshl_add_u64 v[218:219], v[224:225], 0, s[8:9]
	s_mov_b32 m0, s60
	s_nop 0
	global_load_lds_dwordx4 v[218:219], off
	s_waitcnt vmcnt(10)
	s_barrier
	s_waitcnt lgkmcnt(0)
	s_waitcnt lgkmcnt(0)
	v_mfma_f32_16x16x32_bf16 v[60:63], v[154:157], v[170:173], v[60:63]
	v_mfma_f32_16x16x32_bf16 v[56:59], v[162:165], v[170:173], v[56:59]
	v_mfma_f32_16x16x32_bf16 v[44:47], v[154:157], v[178:181], v[44:47]
	v_mfma_f32_16x16x32_bf16 v[40:43], v[162:165], v[178:181], v[40:43]
	v_mfma_f32_16x16x32_bf16 v[28:31], v[154:157], v[186:189], v[28:31]
	v_mfma_f32_16x16x32_bf16 v[24:27], v[162:165], v[186:189], v[24:27]
	v_mfma_f32_16x16x32_bf16 v[12:15], v[154:157], v[194:197], v[12:15]
	v_mfma_f32_16x16x32_bf16 v[8:11], v[162:165], v[194:197], v[8:11]
	v_mfma_f32_16x16x32_bf16 v[60:63], v[158:161], v[174:177], v[60:63]
	v_mfma_f32_16x16x32_bf16 v[56:59], v[166:169], v[174:177], v[56:59]
	v_mfma_f32_16x16x32_bf16 v[44:47], v[158:161], v[182:185], v[44:47]
	v_mfma_f32_16x16x32_bf16 v[40:43], v[166:169], v[182:185], v[40:43]
	v_mfma_f32_16x16x32_bf16 v[28:31], v[158:161], v[190:193], v[28:31]
	v_mfma_f32_16x16x32_bf16 v[24:27], v[166:169], v[190:193], v[24:27]
	v_mfma_f32_16x16x32_bf16 v[12:15], v[158:161], v[198:201], v[12:15]
	v_mfma_f32_16x16x32_bf16 v[8:11], v[166:169], v[198:201], v[8:11]
	s_barrier
	s_add_u32 s36, s36, 0x40080
	s_addc_u32 s37, s37, 0
	s_add_i32 s38, s38, s52
	v_lshl_add_u64 v[154:155], s[36:37], 0, v[132:133]
	s_mov_b32 m0, s38
	s_nop 0
	global_load_lds_dwordx4 v[154:155], off
	v_lshl_add_u64 v[154:155], s[36:37], 0, v[136:137]
	s_add_i32 m0, s38, 0x2000
	s_nop 0
	global_load_lds_dwordx4 v[154:155], off
	s_waitcnt vmcnt(10)
	s_barrier
	v_mfma_f32_16x16x32_bf16 v[52:55], v[202:205], v[170:173], v[52:55]
	v_mfma_f32_16x16x32_bf16 v[48:51], v[210:213], v[170:173], v[48:51]
	v_mfma_f32_16x16x32_bf16 v[36:39], v[202:205], v[178:181], v[36:39]
	v_mfma_f32_16x16x32_bf16 v[32:35], v[210:213], v[178:181], v[32:35]
	v_mfma_f32_16x16x32_bf16 v[20:23], v[202:205], v[186:189], v[20:23]
	v_mfma_f32_16x16x32_bf16 v[16:19], v[210:213], v[186:189], v[16:19]
	v_mfma_f32_16x16x32_bf16 v[4:7], v[202:205], v[194:197], v[4:7]
	v_mfma_f32_16x16x32_bf16 v[0:3], v[210:213], v[194:197], v[0:3]
	v_mfma_f32_16x16x32_bf16 v[52:55], v[206:209], v[174:177], v[52:55]
	v_mfma_f32_16x16x32_bf16 v[48:51], v[214:217], v[174:177], v[48:51]
	v_mfma_f32_16x16x32_bf16 v[36:39], v[206:209], v[182:185], v[36:39]
	v_mfma_f32_16x16x32_bf16 v[32:35], v[214:217], v[182:185], v[32:35]
	v_mfma_f32_16x16x32_bf16 v[20:23], v[206:209], v[190:193], v[20:23]
	v_mfma_f32_16x16x32_bf16 v[16:19], v[214:217], v[190:193], v[16:19]
	v_mfma_f32_16x16x32_bf16 v[4:7], v[206:209], v[198:201], v[4:7]
	v_mfma_f32_16x16x32_bf16 v[0:3], v[214:217], v[198:201], v[0:3]
	s_add_i32 s79, s79, 2
	s_add_u32 s34, s34, 0x100
	s_addc_u32 s35, s35, 0
	s_add_u32 s77, s77, 0x100
	s_addc_u32 s78, s78, 0
	s_cmp_gt_u32 s79, 13
	s_barrier
	s_cbranch_scc0 .LBB0_1291
	v_lshl_add_u32 v154, s30, 8, v148
	v_max_f32_e32 v126, v126, v126
	v_max_f32_e32 v127, v127, v127
	v_lshl_or_b32 v156, s74, 8, v150
	v_ashrrev_i32_e32 v155, 31, v154
	v_max_f32_e32 v124, v124, v124
	v_max_f32_e32 v120, v120, v120
	v_max_f32_e32 v125, v125, v125
	v_max_f32_e32 v121, v121, v121
	v_max_f32_e32 v126, 0, v126
	v_max_f32_e32 v122, v122, v122
	v_max_f32_e32 v127, 0, v127
	v_max_f32_e32 v123, v123, v123
	v_lshlrev_b64 v[158:159], 13, v[154:155]
	v_max_f32_e32 v124, 0, v124
	v_max_f32_e32 v120, 0, v120
	v_max_f32_e32 v125, 0, v125
	v_max_f32_e32 v121, 0, v121
	v_max_f32_e32 v122, 0, v122
	v_max_f32_e32 v123, 0, v123
	v_pk_mul_f32 v[126:127], v[126:127], v[126:127]
	v_ashrrev_i32_e32 v157, 31, v156
	v_lshl_add_u64 v[158:159], s[46:47], 0, v[158:159]
	v_pk_mul_f32 v[124:125], v[124:125], v[124:125]
	v_pk_mul_f32 v[120:121], v[120:121], v[120:121]
	v_pk_mul_f32 v[160:161], v[122:123], v[122:123]
	v_cvt_pk_bf16_f32 v123, v126, v127
	v_lshlrev_b64 v[126:127], 1, v[156:157]
	v_max_f32_e32 v112, v112, v112
	v_max_f32_e32 v113, v113, v113
	v_cvt_pk_bf16_f32 v122, v124, v125
	v_cvt_pk_bf16_f32 v124, v120, v121
	v_cvt_pk_bf16_f32 v125, v160, v161
	v_lshl_add_u64 v[120:121], v[158:159], 0, v[126:127]
	v_max_f32_e32 v112, 0, v112
	v_max_f32_e32 v113, 0, v113
	global_store_dwordx4 v[120:121], v[122:125], off
	v_max_f32_e32 v116, v116, v116
	v_max_f32_e32 v117, v117, v117
	v_pk_mul_f32 v[122:123], v[112:113], v[112:113]
	v_max_f32_e32 v113, v114, v114
	v_max_f32_e32 v112, v118, v118
	v_max_f32_e32 v114, 0, v113
	v_max_f32_e32 v113, v119, v119
	v_max_f32_e32 v115, v115, v115
	v_max_f32_e32 v116, 0, v116
	v_max_f32_e32 v117, 0, v117
	v_max_f32_e32 v112, 0, v112
	v_max_f32_e32 v113, 0, v113
	v_max_f32_e32 v115, 0, v115
	v_pk_mul_f32 v[116:117], v[116:117], v[116:117]
	v_pk_mul_f32 v[118:119], v[112:113], v[112:113]
	v_pk_mul_f32 v[124:125], v[114:115], v[114:115]
	v_max_f32_e32 v104, v104, v104
	v_max_f32_e32 v105, v105, v105
	v_cvt_pk_bf16_f32 v112, v116, v117
	v_cvt_pk_bf16_f32 v113, v118, v119
	v_cvt_pk_bf16_f32 v114, v122, v123
	v_cvt_pk_bf16_f32 v115, v124, v125
	v_max_f32_e32 v104, 0, v104
	v_max_f32_e32 v105, 0, v105
	global_store_dwordx4 v[120:121], v[112:115], off offset:256
	v_max_f32_e32 v108, v108, v108
	v_max_f32_e32 v109, v109, v109
	v_or_b32_e32 v112, 16, v154
	v_pk_mul_f32 v[114:115], v[104:105], v[104:105]
	v_max_f32_e32 v105, v106, v106
	v_ashrrev_i32_e32 v113, 31, v112
	v_max_f32_e32 v104, v110, v110
	v_max_f32_e32 v106, 0, v105
	v_max_f32_e32 v105, v111, v111
	v_max_f32_e32 v107, v107, v107
	v_lshlrev_b64 v[112:113], 13, v[112:113]
	v_max_f32_e32 v108, 0, v108
	v_max_f32_e32 v109, 0, v109
	v_max_f32_e32 v104, 0, v104
	v_max_f32_e32 v105, 0, v105
	v_max_f32_e32 v107, 0, v107
	v_lshl_add_u64 v[112:113], s[46:47], 0, v[112:113]
	v_pk_mul_f32 v[108:109], v[108:109], v[108:109]
	v_pk_mul_f32 v[110:111], v[104:105], v[104:105]
	v_pk_mul_f32 v[116:117], v[106:107], v[106:107]
	v_max_f32_e32 v96, v96, v96
	v_max_f32_e32 v97, v97, v97
	v_cvt_pk_bf16_f32 v104, v108, v109
	v_cvt_pk_bf16_f32 v105, v110, v111
	v_cvt_pk_bf16_f32 v106, v114, v115
	v_cvt_pk_bf16_f32 v107, v116, v117
	v_lshl_add_u64 v[108:109], v[112:113], 0, v[126:127]
	v_max_f32_e32 v96, 0, v96
	v_max_f32_e32 v97, 0, v97
	global_store_dwordx4 v[108:109], v[104:107], off
	v_max_f32_e32 v100, v100, v100
	v_max_f32_e32 v101, v101, v101
	v_pk_mul_f32 v[104:105], v[96:97], v[96:97]
	v_max_f32_e32 v97, v98, v98
	v_max_f32_e32 v96, v102, v102
	v_max_f32_e32 v98, 0, v97
	v_max_f32_e32 v97, v103, v103
	v_max_f32_e32 v99, v99, v99
	v_max_f32_e32 v100, 0, v100
	v_max_f32_e32 v101, 0, v101
	v_max_f32_e32 v96, 0, v96
	v_max_f32_e32 v97, 0, v97
	v_max_f32_e32 v99, 0, v99
	v_pk_mul_f32 v[100:101], v[100:101], v[100:101]
	v_pk_mul_f32 v[102:103], v[96:97], v[96:97]
	v_pk_mul_f32 v[106:107], v[98:99], v[98:99]
	v_max_f32_e32 v88, v88, v88
	v_max_f32_e32 v89, v89, v89
	v_cvt_pk_bf16_f32 v96, v100, v101
	v_cvt_pk_bf16_f32 v97, v102, v103
	v_cvt_pk_bf16_f32 v98, v104, v105
	v_cvt_pk_bf16_f32 v99, v106, v107
	v_max_f32_e32 v88, 0, v88
	v_max_f32_e32 v89, 0, v89
	global_store_dwordx4 v[108:109], v[96:99], off offset:256
	v_max_f32_e32 v92, v92, v92
	v_max_f32_e32 v93, v93, v93
	v_or_b32_e32 v96, 32, v154
	v_pk_mul_f32 v[98:99], v[88:89], v[88:89]
	v_max_f32_e32 v89, v90, v90
	v_ashrrev_i32_e32 v97, 31, v96
	v_max_f32_e32 v88, v94, v94
	v_max_f32_e32 v90, 0, v89
	v_max_f32_e32 v89, v95, v95
	v_max_f32_e32 v91, v91, v91
	v_lshlrev_b64 v[96:97], 13, v[96:97]
	v_max_f32_e32 v92, 0, v92
	v_max_f32_e32 v93, 0, v93
	v_max_f32_e32 v88, 0, v88
	v_max_f32_e32 v89, 0, v89
	v_max_f32_e32 v91, 0, v91
	v_lshl_add_u64 v[96:97], s[46:47], 0, v[96:97]
	v_pk_mul_f32 v[92:93], v[92:93], v[92:93]
	v_pk_mul_f32 v[94:95], v[88:89], v[88:89]
	v_pk_mul_f32 v[100:101], v[90:91], v[90:91]
	v_max_f32_e32 v80, v80, v80
	v_max_f32_e32 v81, v81, v81
	v_cvt_pk_bf16_f32 v88, v92, v93
	v_cvt_pk_bf16_f32 v89, v94, v95
	v_cvt_pk_bf16_f32 v90, v98, v99
	v_cvt_pk_bf16_f32 v91, v100, v101
	v_lshl_add_u64 v[92:93], v[96:97], 0, v[126:127]
	v_max_f32_e32 v80, 0, v80
	v_max_f32_e32 v81, 0, v81
	global_store_dwordx4 v[92:93], v[88:91], off
	v_max_f32_e32 v84, v84, v84
	v_max_f32_e32 v85, v85, v85
	v_pk_mul_f32 v[88:89], v[80:81], v[80:81]
	v_max_f32_e32 v81, v82, v82
	v_max_f32_e32 v80, v86, v86
	v_max_f32_e32 v82, 0, v81
	v_max_f32_e32 v81, v87, v87
	v_max_f32_e32 v83, v83, v83
	v_max_f32_e32 v84, 0, v84
	v_max_f32_e32 v85, 0, v85
	v_max_f32_e32 v80, 0, v80
	v_max_f32_e32 v81, 0, v81
	v_max_f32_e32 v83, 0, v83
	v_pk_mul_f32 v[84:85], v[84:85], v[84:85]
	v_pk_mul_f32 v[86:87], v[80:81], v[80:81]
	v_pk_mul_f32 v[90:91], v[82:83], v[82:83]
	v_max_f32_e32 v72, v72, v72
	v_max_f32_e32 v73, v73, v73
	v_cvt_pk_bf16_f32 v80, v84, v85
	v_cvt_pk_bf16_f32 v81, v86, v87
	v_cvt_pk_bf16_f32 v82, v88, v89
	v_cvt_pk_bf16_f32 v83, v90, v91
	v_max_f32_e32 v72, 0, v72
	v_max_f32_e32 v73, 0, v73
	global_store_dwordx4 v[92:93], v[80:83], off offset:256
	v_max_f32_e32 v76, v76, v76
	v_max_f32_e32 v77, v77, v77
	v_or_b32_e32 v80, 48, v154
	v_pk_mul_f32 v[82:83], v[72:73], v[72:73]
	v_max_f32_e32 v73, v74, v74
	v_ashrrev_i32_e32 v81, 31, v80
	v_max_f32_e32 v72, v78, v78
	v_max_f32_e32 v74, 0, v73
	v_max_f32_e32 v73, v79, v79
	v_max_f32_e32 v75, v75, v75
	v_lshlrev_b64 v[80:81], 13, v[80:81]
	v_max_f32_e32 v76, 0, v76
	v_max_f32_e32 v77, 0, v77
	v_max_f32_e32 v72, 0, v72
	v_max_f32_e32 v73, 0, v73
	v_max_f32_e32 v75, 0, v75
	v_lshl_add_u64 v[80:81], s[46:47], 0, v[80:81]
	v_pk_mul_f32 v[76:77], v[76:77], v[76:77]
	v_pk_mul_f32 v[78:79], v[72:73], v[72:73]
	v_pk_mul_f32 v[84:85], v[74:75], v[74:75]
	v_max_f32_e32 v64, v64, v64
	v_max_f32_e32 v65, v65, v65
	v_cvt_pk_bf16_f32 v72, v76, v77
	v_cvt_pk_bf16_f32 v73, v78, v79
	v_cvt_pk_bf16_f32 v74, v82, v83
	v_cvt_pk_bf16_f32 v75, v84, v85
	v_lshl_add_u64 v[76:77], v[80:81], 0, v[126:127]
	v_max_f32_e32 v64, 0, v64
	v_max_f32_e32 v65, 0, v65
	global_store_dwordx4 v[76:77], v[72:75], off
	v_max_f32_e32 v68, v68, v68
	v_max_f32_e32 v69, v69, v69
	v_pk_mul_f32 v[72:73], v[64:65], v[64:65]
	v_max_f32_e32 v65, v66, v66
	v_max_f32_e32 v64, v70, v70
	v_max_f32_e32 v66, 0, v65
	v_max_f32_e32 v65, v71, v71
	v_max_f32_e32 v67, v67, v67
	v_max_f32_e32 v68, 0, v68
	v_max_f32_e32 v69, 0, v69
	v_max_f32_e32 v64, 0, v64
	v_max_f32_e32 v65, 0, v65
	v_max_f32_e32 v67, 0, v67
	v_pk_mul_f32 v[68:69], v[68:69], v[68:69]
	v_pk_mul_f32 v[70:71], v[64:65], v[64:65]
	v_pk_mul_f32 v[74:75], v[66:67], v[66:67]
	v_max_f32_e32 v56, v56, v56
	v_max_f32_e32 v57, v57, v57
	v_cvt_pk_bf16_f32 v64, v68, v69
	v_cvt_pk_bf16_f32 v65, v70, v71
	v_cvt_pk_bf16_f32 v66, v72, v73
	v_cvt_pk_bf16_f32 v67, v74, v75
	v_max_f32_e32 v56, 0, v56
	v_max_f32_e32 v57, 0, v57
	global_store_dwordx4 v[76:77], v[64:67], off offset:256
	v_max_f32_e32 v60, v60, v60
	v_max_f32_e32 v61, v61, v61
	v_pk_mul_f32 v[64:65], v[56:57], v[56:57]
	v_max_f32_e32 v57, v58, v58
	v_max_f32_e32 v56, v62, v62
	v_max_f32_e32 v58, 0, v57
	v_max_f32_e32 v57, v63, v63
	v_max_f32_e32 v56, 0, v56
	v_max_f32_e32 v57, 0, v57
	v_max_f32_e32 v59, v59, v59
	v_max_f32_e32 v60, 0, v60
	v_max_f32_e32 v61, 0, v61
	v_max_f32_e32 v59, 0, v59
	v_pk_mul_f32 v[62:63], v[56:57], v[56:57]
	v_pk_mul_f32 v[60:61], v[60:61], v[60:61]
	v_pk_mul_f32 v[66:67], v[58:59], v[58:59]
	v_cvt_pk_bf16_f32 v57, v62, v63
	v_add_co_u32_e32 v62, vcc, s70, v120
	v_max_f32_e32 v48, v48, v48
	v_max_f32_e32 v49, v49, v49
	v_cvt_pk_bf16_f32 v56, v60, v61
	v_cvt_pk_bf16_f32 v58, v64, v65
	v_cvt_pk_bf16_f32 v59, v66, v67
	v_addc_co_u32_e32 v63, vcc, 0, v121, vcc
	v_max_f32_e32 v48, 0, v48
	v_max_f32_e32 v49, 0, v49
	global_store_dwordx4 v[62:63], v[56:59], off
	v_max_f32_e32 v52, v52, v52
	v_max_f32_e32 v53, v53, v53
	v_pk_mul_f32 v[56:57], v[48:49], v[48:49]
	v_max_f32_e32 v49, v50, v50
	v_max_f32_e32 v48, v54, v54
	v_max_f32_e32 v50, 0, v49
	v_max_f32_e32 v49, v55, v55
	v_max_f32_e32 v51, v51, v51
	v_max_f32_e32 v52, 0, v52
	v_max_f32_e32 v53, 0, v53
	v_max_f32_e32 v48, 0, v48
	v_max_f32_e32 v49, 0, v49
	v_max_f32_e32 v51, 0, v51
	v_pk_mul_f32 v[52:53], v[52:53], v[52:53]
	v_pk_mul_f32 v[54:55], v[48:49], v[48:49]
	v_pk_mul_f32 v[58:59], v[50:51], v[50:51]
	v_max_f32_e32 v40, v40, v40
	v_max_f32_e32 v41, v41, v41
	v_lshl_add_u64 v[60:61], v[120:121], 0, s[10:11]
	v_cvt_pk_bf16_f32 v48, v52, v53
	v_cvt_pk_bf16_f32 v49, v54, v55
	v_cvt_pk_bf16_f32 v50, v56, v57
	v_cvt_pk_bf16_f32 v51, v58, v59
	v_max_f32_e32 v40, 0, v40
	v_max_f32_e32 v41, 0, v41
	global_store_dwordx4 v[60:61], v[48:51], off offset:256
	v_max_f32_e32 v44, v44, v44
	v_max_f32_e32 v45, v45, v45
	v_pk_mul_f32 v[48:49], v[40:41], v[40:41]
	v_max_f32_e32 v41, v42, v42
	v_max_f32_e32 v40, v46, v46
	v_max_f32_e32 v42, 0, v41
	v_max_f32_e32 v41, v47, v47
	v_max_f32_e32 v40, 0, v40
	v_max_f32_e32 v41, 0, v41
	v_max_f32_e32 v43, v43, v43
	v_max_f32_e32 v44, 0, v44
	v_max_f32_e32 v45, 0, v45
	v_max_f32_e32 v43, 0, v43
	v_pk_mul_f32 v[46:47], v[40:41], v[40:41]
	v_pk_mul_f32 v[44:45], v[44:45], v[44:45]
	v_pk_mul_f32 v[50:51], v[42:43], v[42:43]
	v_cvt_pk_bf16_f32 v41, v46, v47
	v_add_co_u32_e32 v46, vcc, s71, v120
	v_max_f32_e32 v32, v32, v32
	v_max_f32_e32 v33, v33, v33
	v_cvt_pk_bf16_f32 v40, v44, v45
	v_cvt_pk_bf16_f32 v42, v48, v49
	v_cvt_pk_bf16_f32 v43, v50, v51
	v_addc_co_u32_e32 v47, vcc, 0, v121, vcc
	v_max_f32_e32 v32, 0, v32
	v_max_f32_e32 v33, 0, v33
	global_store_dwordx4 v[46:47], v[40:43], off
	v_max_f32_e32 v36, v36, v36
	v_max_f32_e32 v37, v37, v37
	v_pk_mul_f32 v[40:41], v[32:33], v[32:33]
	v_max_f32_e32 v33, v34, v34
	v_max_f32_e32 v32, v38, v38
	v_max_f32_e32 v34, 0, v33
	v_max_f32_e32 v33, v39, v39
	v_max_f32_e32 v35, v35, v35
	v_max_f32_e32 v36, 0, v36
	v_max_f32_e32 v37, 0, v37
	v_max_f32_e32 v32, 0, v32
	v_max_f32_e32 v33, 0, v33
	v_max_f32_e32 v35, 0, v35
	v_pk_mul_f32 v[36:37], v[36:37], v[36:37]
	v_pk_mul_f32 v[38:39], v[32:33], v[32:33]
	v_pk_mul_f32 v[42:43], v[34:35], v[34:35]
	v_max_f32_e32 v24, v24, v24
	v_max_f32_e32 v25, v25, v25
	v_lshl_add_u64 v[44:45], v[120:121], 0, s[12:13]
	v_cvt_pk_bf16_f32 v32, v36, v37
	v_cvt_pk_bf16_f32 v33, v38, v39
	v_cvt_pk_bf16_f32 v34, v40, v41
	v_cvt_pk_bf16_f32 v35, v42, v43
	v_max_f32_e32 v24, 0, v24
	v_max_f32_e32 v25, 0, v25
	global_store_dwordx4 v[44:45], v[32:35], off offset:256
	v_max_f32_e32 v28, v28, v28
	v_max_f32_e32 v29, v29, v29
	v_pk_mul_f32 v[32:33], v[24:25], v[24:25]
	v_max_f32_e32 v25, v26, v26
	v_max_f32_e32 v24, v30, v30
	v_max_f32_e32 v26, 0, v25
	v_max_f32_e32 v25, v31, v31
	v_max_f32_e32 v24, 0, v24
	v_max_f32_e32 v25, 0, v25
	v_max_f32_e32 v27, v27, v27
	v_max_f32_e32 v28, 0, v28
	v_max_f32_e32 v29, 0, v29
	v_max_f32_e32 v27, 0, v27
	v_pk_mul_f32 v[30:31], v[24:25], v[24:25]
	v_pk_mul_f32 v[28:29], v[28:29], v[28:29]
	v_pk_mul_f32 v[34:35], v[26:27], v[26:27]
	v_cvt_pk_bf16_f32 v25, v30, v31
	v_add_co_u32_e32 v30, vcc, s72, v120
	v_max_f32_e32 v16, v16, v16
	v_max_f32_e32 v17, v17, v17
	v_cvt_pk_bf16_f32 v24, v28, v29
	v_cvt_pk_bf16_f32 v26, v32, v33
	v_cvt_pk_bf16_f32 v27, v34, v35
	v_addc_co_u32_e32 v31, vcc, 0, v121, vcc
	v_max_f32_e32 v16, 0, v16
	v_max_f32_e32 v17, 0, v17
	global_store_dwordx4 v[30:31], v[24:27], off
	v_max_f32_e32 v20, v20, v20
	v_max_f32_e32 v21, v21, v21
	v_pk_mul_f32 v[24:25], v[16:17], v[16:17]
	v_max_f32_e32 v17, v18, v18
	v_max_f32_e32 v16, v22, v22
	v_max_f32_e32 v18, 0, v17
	v_max_f32_e32 v17, v23, v23
	v_max_f32_e32 v19, v19, v19
	v_max_f32_e32 v20, 0, v20
	v_max_f32_e32 v21, 0, v21
	v_max_f32_e32 v16, 0, v16
	v_max_f32_e32 v17, 0, v17
	v_max_f32_e32 v19, 0, v19
	v_pk_mul_f32 v[20:21], v[20:21], v[20:21]
	v_pk_mul_f32 v[22:23], v[16:17], v[16:17]
	v_pk_mul_f32 v[26:27], v[18:19], v[18:19]
	v_max_f32_e32 v8, v8, v8
	v_max_f32_e32 v9, v9, v9
	v_lshl_add_u64 v[28:29], v[120:121], 0, s[14:15]
	v_cvt_pk_bf16_f32 v16, v20, v21
	v_cvt_pk_bf16_f32 v17, v22, v23
	v_cvt_pk_bf16_f32 v18, v24, v25
	v_cvt_pk_bf16_f32 v19, v26, v27
	v_max_f32_e32 v8, 0, v8
	v_max_f32_e32 v9, 0, v9
	global_store_dwordx4 v[28:29], v[16:19], off offset:256
	v_max_f32_e32 v12, v12, v12
	v_max_f32_e32 v13, v13, v13
	v_pk_mul_f32 v[16:17], v[8:9], v[8:9]
	v_max_f32_e32 v9, v10, v10
	v_max_f32_e32 v8, v14, v14
	v_max_f32_e32 v10, 0, v9
	v_max_f32_e32 v9, v15, v15
	v_max_f32_e32 v8, 0, v8
	v_max_f32_e32 v9, 0, v9
	v_max_f32_e32 v11, v11, v11
	v_max_f32_e32 v12, 0, v12
	v_max_f32_e32 v13, 0, v13
	v_max_f32_e32 v11, 0, v11
	v_pk_mul_f32 v[14:15], v[8:9], v[8:9]
	v_pk_mul_f32 v[12:13], v[12:13], v[12:13]
	v_pk_mul_f32 v[18:19], v[10:11], v[10:11]
	v_cvt_pk_bf16_f32 v9, v14, v15
	v_add_co_u32_e32 v14, vcc, s73, v120
	v_max_f32_e32 v0, v0, v0
	v_max_f32_e32 v1, v1, v1
	v_cvt_pk_bf16_f32 v8, v12, v13
	v_cvt_pk_bf16_f32 v10, v16, v17
	v_cvt_pk_bf16_f32 v11, v18, v19
	v_addc_co_u32_e32 v15, vcc, 0, v121, vcc
	v_max_f32_e32 v0, 0, v0
	v_max_f32_e32 v1, 0, v1
	global_store_dwordx4 v[14:15], v[8:11], off
	v_max_f32_e32 v4, v4, v4
	v_max_f32_e32 v5, v5, v5
	v_pk_mul_f32 v[8:9], v[0:1], v[0:1]
	v_max_f32_e32 v1, v2, v2
	v_max_f32_e32 v0, v6, v6
	v_max_f32_e32 v2, 0, v1
	v_max_f32_e32 v1, v7, v7
	v_max_f32_e32 v3, v3, v3
	v_max_f32_e32 v4, 0, v4
	v_max_f32_e32 v5, 0, v5
	v_max_f32_e32 v0, 0, v0
	v_max_f32_e32 v1, 0, v1
	v_max_f32_e32 v3, 0, v3
	v_pk_mul_f32 v[4:5], v[4:5], v[4:5]
	v_pk_mul_f32 v[6:7], v[0:1], v[0:1]
	v_pk_mul_f32 v[10:11], v[2:3], v[2:3]
	v_lshl_add_u64 v[12:13], v[120:121], 0, s[16:17]
	v_cvt_pk_bf16_f32 v0, v4, v5
	v_cvt_pk_bf16_f32 v1, v6, v7
	v_cvt_pk_bf16_f32 v2, v8, v9
	v_cvt_pk_bf16_f32 v3, v10, v11
	s_and_b64 vcc, exec, s[4:5]
	s_mov_b32 s74, s18
	s_mov_b32 s30, s20
	s_mov_b64 s[36:37], s[28:29]
	s_mov_b64 s[34:35], s[26:27]
	global_store_dwordx4 v[12:13], v[0:3], off offset:256
	s_cbranch_vccz .LBB0_1284
	s_waitcnt vmcnt(16)
	s_cmpk_gt_u32 s40, 0xff
	s_cbranch_scc1 .LBB0_1295
	s_barrier

.LBB0_1310:
	ds_read_b128 v[154:157], v151
	ds_read_b128 v[158:161], v151 offset:1024
	ds_read_b128 v[162:165], v151 offset:2048
	ds_read_b128 v[166:169], v151 offset:3072
	s_add_u32 s38, s36, 0xfffc0080
	s_addc_u32 s39, s37, -1
	s_cmp_eq_u32 s77, 12
	s_cselect_b32 s41, s27, s39
	s_cselect_b32 s40, s73, s38
	s_cselect_b32 s39, s21, s76
	s_cselect_b32 s38, s74, s75
	v_lshl_add_u64 v[202:203], s[36:37], 0, v[138:139]
	s_add_i32 m0, s35, 0xc000
	ds_read_b128 v[170:173], v152
	ds_read_b128 v[174:177], v152 offset:1024
	ds_read_b128 v[178:181], v152 offset:2048
	ds_read_b128 v[182:185], v152 offset:3072
	ds_read_b128 v[186:189], v152 offset:4096
	ds_read_b128 v[190:193], v152 offset:5120
	ds_read_b128 v[194:197], v152 offset:6144
	ds_read_b128 v[198:201], v152 offset:7168
	global_load_lds_dwordx4 v[202:203], off
	v_lshl_add_u64 v[202:203], s[36:37], 0, v[140:141]
	s_add_i32 m0, s35, 0xe000
	s_nop 0
	global_load_lds_dwordx4 v[202:203], off
	s_waitcnt lgkmcnt(8)
	s_waitcnt vmcnt(10)
	s_barrier
	s_waitcnt lgkmcnt(0)
	s_waitcnt lgkmcnt(0)
	v_mfma_f32_16x16x32_bf16 v[124:127], v[154:157], v[170:173], v[124:127]
	v_mfma_f32_16x16x32_bf16 v[120:123], v[162:165], v[170:173], v[120:123]
	v_mfma_f32_16x16x32_bf16 v[108:111], v[154:157], v[178:181], v[108:111]
	v_mfma_f32_16x16x32_bf16 v[104:107], v[162:165], v[178:181], v[104:107]
	v_mfma_f32_16x16x32_bf16 v[92:95], v[154:157], v[186:189], v[92:95]
	v_mfma_f32_16x16x32_bf16 v[88:91], v[162:165], v[186:189], v[88:91]
	v_mfma_f32_16x16x32_bf16 v[76:79], v[154:157], v[194:197], v[76:79]
	v_mfma_f32_16x16x32_bf16 v[72:75], v[162:165], v[194:197], v[72:75]
	v_mfma_f32_16x16x32_bf16 v[124:127], v[158:161], v[174:177], v[124:127]
	v_mfma_f32_16x16x32_bf16 v[120:123], v[166:169], v[174:177], v[120:123]
	v_mfma_f32_16x16x32_bf16 v[108:111], v[158:161], v[182:185], v[108:111]
	v_mfma_f32_16x16x32_bf16 v[104:107], v[166:169], v[182:185], v[104:107]
	v_mfma_f32_16x16x32_bf16 v[92:95], v[158:161], v[190:193], v[92:95]
	v_mfma_f32_16x16x32_bf16 v[88:91], v[166:169], v[190:193], v[88:91]
	v_mfma_f32_16x16x32_bf16 v[76:79], v[158:161], v[198:201], v[76:79]
	v_mfma_f32_16x16x32_bf16 v[72:75], v[166:169], v[198:201], v[72:75]
	s_barrier
	s_add_i32 s78, s62, s52
	v_lshl_add_u64 v[218:219], s[38:39], 0, v[132:133]
	s_mov_b32 m0, s78
	ds_read_b128 v[202:205], v153
	ds_read_b128 v[206:209], v153 offset:1024
	ds_read_b128 v[210:213], v153 offset:2048
	ds_read_b128 v[214:217], v153 offset:3072
	global_load_lds_dwordx4 v[218:219], off
	v_lshl_add_u64 v[220:221], s[38:39], 0, v[136:137]
	s_add_i32 m0, s78, 0x2000
	s_nop 0
	global_load_lds_dwordx4 v[220:221], off
	s_waitcnt vmcnt(10)
	s_barrier
	s_waitcnt lgkmcnt(0)
	s_waitcnt lgkmcnt(0)
	v_mfma_f32_16x16x32_bf16 v[116:119], v[202:205], v[170:173], v[116:119]
	v_mfma_f32_16x16x32_bf16 v[112:115], v[210:213], v[170:173], v[112:115]
	v_mfma_f32_16x16x32_bf16 v[100:103], v[202:205], v[178:181], v[100:103]
	v_mfma_f32_16x16x32_bf16 v[96:99], v[210:213], v[178:181], v[96:99]
	v_mfma_f32_16x16x32_bf16 v[84:87], v[202:205], v[186:189], v[84:87]
	v_mfma_f32_16x16x32_bf16 v[80:83], v[210:213], v[186:189], v[80:83]
	v_mfma_f32_16x16x32_bf16 v[68:71], v[202:205], v[194:197], v[68:71]
	v_mfma_f32_16x16x32_bf16 v[64:67], v[210:213], v[194:197], v[64:67]
	v_mfma_f32_16x16x32_bf16 v[116:119], v[206:209], v[174:177], v[116:119]
	v_mfma_f32_16x16x32_bf16 v[112:115], v[214:217], v[174:177], v[112:115]
	v_mfma_f32_16x16x32_bf16 v[100:103], v[206:209], v[182:185], v[100:103]
	v_mfma_f32_16x16x32_bf16 v[96:99], v[214:217], v[182:185], v[96:99]
	v_mfma_f32_16x16x32_bf16 v[84:87], v[206:209], v[190:193], v[84:87]
	v_mfma_f32_16x16x32_bf16 v[80:83], v[214:217], v[190:193], v[80:83]
	v_mfma_f32_16x16x32_bf16 v[68:71], v[206:209], v[198:201], v[68:71]
	v_mfma_f32_16x16x32_bf16 v[64:67], v[214:217], v[198:201], v[64:67]
	s_mov_b32 m0, s35
	v_lshl_add_u64 v[222:223], s[40:41], 0, v[130:131]
	s_barrier
	ds_read_b128 v[170:173], v152 offset:16384
	ds_read_b128 v[174:177], v152 offset:17408
	ds_read_b128 v[178:181], v152 offset:18432
	ds_read_b128 v[182:185], v152 offset:19456
	ds_read_b128 v[186:189], v152 offset:20480
	ds_read_b128 v[190:193], v152 offset:21504
	ds_read_b128 v[194:197], v152 offset:22528
	ds_read_b128 v[198:201], v152 offset:23552
	global_load_lds_dwordx4 v[222:223], off
	v_lshl_add_u64 v[224:225], s[40:41], 0, v[134:135]
	s_mov_b32 m0, s53
	s_nop 0
	global_load_lds_dwordx4 v[224:225], off
	s_waitcnt vmcnt(10)
	s_barrier
	s_waitcnt lgkmcnt(0)
	s_waitcnt lgkmcnt(0)
	v_mfma_f32_16x16x32_bf16 v[60:63], v[154:157], v[170:173], v[60:63]
	v_mfma_f32_16x16x32_bf16 v[56:59], v[162:165], v[170:173], v[56:59]
	v_mfma_f32_16x16x32_bf16 v[44:47], v[154:157], v[178:181], v[44:47]
	v_mfma_f32_16x16x32_bf16 v[40:43], v[162:165], v[178:181], v[40:43]
	v_mfma_f32_16x16x32_bf16 v[28:31], v[154:157], v[186:189], v[28:31]
	v_mfma_f32_16x16x32_bf16 v[24:27], v[162:165], v[186:189], v[24:27]
	v_mfma_f32_16x16x32_bf16 v[12:15], v[154:157], v[194:197], v[12:15]
	v_mfma_f32_16x16x32_bf16 v[8:11], v[162:165], v[194:197], v[8:11]
	v_mfma_f32_16x16x32_bf16 v[60:63], v[158:161], v[174:177], v[60:63]
	v_mfma_f32_16x16x32_bf16 v[56:59], v[166:169], v[174:177], v[56:59]
	v_mfma_f32_16x16x32_bf16 v[44:47], v[158:161], v[182:185], v[44:47]
	v_mfma_f32_16x16x32_bf16 v[40:43], v[166:169], v[182:185], v[40:43]
	v_mfma_f32_16x16x32_bf16 v[28:31], v[158:161], v[190:193], v[28:31]
	v_mfma_f32_16x16x32_bf16 v[24:27], v[166:169], v[190:193], v[24:27]
	v_mfma_f32_16x16x32_bf16 v[12:15], v[158:161], v[198:201], v[12:15]
	v_mfma_f32_16x16x32_bf16 v[8:11], v[166:169], v[198:201], v[8:11]
	s_barrier
	s_add_u32 s78, s38, 0x40000
	s_addc_u32 s79, s39, 0
	s_add_i32 s80, s63, s52
	v_lshl_add_u64 v[154:155], s[78:79], 0, v[132:133]
	s_mov_b32 m0, s80
	s_nop 0
	global_load_lds_dwordx4 v[154:155], off
	v_lshl_add_u64 v[154:155], s[78:79], 0, v[136:137]
	s_add_i32 m0, s80, 0x2000
	s_nop 0
	global_load_lds_dwordx4 v[154:155], off
	s_waitcnt vmcnt(10)
	s_barrier
	v_mfma_f32_16x16x32_bf16 v[52:55], v[202:205], v[170:173], v[52:55]
	v_mfma_f32_16x16x32_bf16 v[48:51], v[210:213], v[170:173], v[48:51]
	v_mfma_f32_16x16x32_bf16 v[36:39], v[202:205], v[178:181], v[36:39]
	v_mfma_f32_16x16x32_bf16 v[32:35], v[210:213], v[178:181], v[32:35]
	v_mfma_f32_16x16x32_bf16 v[20:23], v[202:205], v[186:189], v[20:23]
	v_mfma_f32_16x16x32_bf16 v[16:19], v[210:213], v[186:189], v[16:19]
	v_mfma_f32_16x16x32_bf16 v[4:7], v[202:205], v[194:197], v[4:7]
	v_mfma_f32_16x16x32_bf16 v[0:3], v[210:213], v[194:197], v[0:3]
	v_mfma_f32_16x16x32_bf16 v[52:55], v[206:209], v[174:177], v[52:55]
	v_mfma_f32_16x16x32_bf16 v[48:51], v[214:217], v[174:177], v[48:51]
	v_mfma_f32_16x16x32_bf16 v[36:39], v[206:209], v[182:185], v[36:39]
	v_mfma_f32_16x16x32_bf16 v[32:35], v[214:217], v[182:185], v[32:35]
	v_mfma_f32_16x16x32_bf16 v[20:23], v[206:209], v[190:193], v[20:23]
	v_mfma_f32_16x16x32_bf16 v[16:19], v[214:217], v[190:193], v[16:19]
	v_mfma_f32_16x16x32_bf16 v[4:7], v[206:209], v[198:201], v[4:7]
	v_mfma_f32_16x16x32_bf16 v[0:3], v[214:217], v[198:201], v[0:3]
	s_add_i32 s78, 0, 0x18000
	v_add_u32_e32 v166, s78, v149
	s_barrier
	ds_read_b128 v[154:157], v166
	ds_read_b128 v[158:161], v166 offset:1024
	ds_read_b128 v[162:165], v166 offset:2048
	ds_read_b128 v[166:169], v166 offset:3072
	s_add_u32 s40, s40, 0x40000
	s_addc_u32 s41, s41, 0
	s_mov_b32 m0, s54
	v_lshl_add_u64 v[202:203], s[40:41], 0, v[130:131]
	ds_read_b128 v[170:173], v152 offset:32768
	ds_read_b128 v[174:177], v152 offset:33792
	ds_read_b128 v[178:181], v152 offset:34816
	ds_read_b128 v[182:185], v152 offset:35840
	ds_read_b128 v[186:189], v152 offset:36864
	ds_read_b128 v[190:193], v152 offset:37888
	ds_read_b128 v[194:197], v152 offset:38912
	ds_read_b128 v[198:201], v152 offset:39936
	global_load_lds_dwordx4 v[202:203], off
	v_lshl_add_u64 v[202:203], s[40:41], 0, v[134:135]
	s_mov_b32 m0, s55
	s_nop 0
	global_load_lds_dwordx4 v[202:203], off
	s_waitcnt lgkmcnt(8)
	s_waitcnt vmcnt(10)
	s_barrier
	s_waitcnt lgkmcnt(0)
	s_waitcnt lgkmcnt(0)
	v_mfma_f32_16x16x32_bf16 v[124:127], v[154:157], v[170:173], v[124:127]
	v_mfma_f32_16x16x32_bf16 v[120:123], v[162:165], v[170:173], v[120:123]
	v_mfma_f32_16x16x32_bf16 v[108:111], v[154:157], v[178:181], v[108:111]
	v_mfma_f32_16x16x32_bf16 v[104:107], v[162:165], v[178:181], v[104:107]
	v_mfma_f32_16x16x32_bf16 v[92:95], v[154:157], v[186:189], v[92:95]
	v_mfma_f32_16x16x32_bf16 v[88:91], v[162:165], v[186:189], v[88:91]
	v_mfma_f32_16x16x32_bf16 v[76:79], v[154:157], v[194:197], v[76:79]
	v_mfma_f32_16x16x32_bf16 v[72:75], v[162:165], v[194:197], v[72:75]
	v_mfma_f32_16x16x32_bf16 v[124:127], v[158:161], v[174:177], v[124:127]
	v_mfma_f32_16x16x32_bf16 v[120:123], v[166:169], v[174:177], v[120:123]
	v_mfma_f32_16x16x32_bf16 v[108:111], v[158:161], v[182:185], v[108:111]
	v_mfma_f32_16x16x32_bf16 v[104:107], v[166:169], v[182:185], v[104:107]
	v_mfma_f32_16x16x32_bf16 v[92:95], v[158:161], v[190:193], v[92:95]
	v_mfma_f32_16x16x32_bf16 v[88:91], v[166:169], v[190:193], v[88:91]
	v_mfma_f32_16x16x32_bf16 v[76:79], v[158:161], v[198:201], v[76:79]
	v_mfma_f32_16x16x32_bf16 v[72:75], v[166:169], v[198:201], v[72:75]
	s_barrier
	s_add_i32 s40, 0, 0x1c000
	s_add_i32 s41, s78, s52
	v_add_u32_e32 v214, s40, v149
	v_lshl_add_u64 v[218:219], v[218:219], 0, s[10:11]
	s_mov_b32 m0, s41
	ds_read_b128 v[202:205], v214
	ds_read_b128 v[206:209], v214 offset:1024
	ds_read_b128 v[210:213], v214 offset:2048
	ds_read_b128 v[214:217], v214 offset:3072
	global_load_lds_dwordx4 v[218:219], off
	v_lshl_add_u64 v[218:219], v[220:221], 0, s[10:11]
	s_add_i32 m0, s41, 0x2000
	s_nop 0
	global_load_lds_dwordx4 v[218:219], off
	s_waitcnt vmcnt(10)
	s_barrier
	s_waitcnt lgkmcnt(0)
	s_waitcnt lgkmcnt(0)
	v_mfma_f32_16x16x32_bf16 v[116:119], v[202:205], v[170:173], v[116:119]
	v_mfma_f32_16x16x32_bf16 v[112:115], v[210:213], v[170:173], v[112:115]
	v_mfma_f32_16x16x32_bf16 v[100:103], v[202:205], v[178:181], v[100:103]
	v_mfma_f32_16x16x32_bf16 v[96:99], v[210:213], v[178:181], v[96:99]
	v_mfma_f32_16x16x32_bf16 v[84:87], v[202:205], v[186:189], v[84:87]
	v_mfma_f32_16x16x32_bf16 v[80:83], v[210:213], v[186:189], v[80:83]
	v_mfma_f32_16x16x32_bf16 v[68:71], v[202:205], v[194:197], v[68:71]
	v_mfma_f32_16x16x32_bf16 v[64:67], v[210:213], v[194:197], v[64:67]
	v_mfma_f32_16x16x32_bf16 v[116:119], v[206:209], v[174:177], v[116:119]
	v_mfma_f32_16x16x32_bf16 v[112:115], v[214:217], v[174:177], v[112:115]
	v_mfma_f32_16x16x32_bf16 v[100:103], v[206:209], v[182:185], v[100:103]
	v_mfma_f32_16x16x32_bf16 v[96:99], v[214:217], v[182:185], v[96:99]
	v_mfma_f32_16x16x32_bf16 v[84:87], v[206:209], v[190:193], v[84:87]
	v_mfma_f32_16x16x32_bf16 v[80:83], v[214:217], v[190:193], v[80:83]
	v_mfma_f32_16x16x32_bf16 v[68:71], v[206:209], v[198:201], v[68:71]
	v_mfma_f32_16x16x32_bf16 v[64:67], v[214:217], v[198:201], v[64:67]
	s_mov_b32 m0, s57
	v_lshl_add_u64 v[218:219], v[222:223], 0, s[10:11]
	s_barrier
	ds_read_b128 v[170:173], v152 offset:49152
	ds_read_b128 v[174:177], v152 offset:50176
	ds_read_b128 v[178:181], v152 offset:51200
	ds_read_b128 v[182:185], v152 offset:52224
	ds_read_b128 v[186:189], v152 offset:53248
	ds_read_b128 v[190:193], v152 offset:54272
	ds_read_b128 v[194:197], v152 offset:55296
	ds_read_b128 v[198:201], v152 offset:56320
	global_load_lds_dwordx4 v[218:219], off
	v_lshl_add_u64 v[218:219], v[224:225], 0, s[10:11]
	s_mov_b32 m0, s60
	s_nop 0
	global_load_lds_dwordx4 v[218:219], off
	s_waitcnt vmcnt(10)
	s_barrier
	s_waitcnt lgkmcnt(0)
	s_waitcnt lgkmcnt(0)
	v_mfma_f32_16x16x32_bf16 v[60:63], v[154:157], v[170:173], v[60:63]
	v_mfma_f32_16x16x32_bf16 v[56:59], v[162:165], v[170:173], v[56:59]
	v_mfma_f32_16x16x32_bf16 v[44:47], v[154:157], v[178:181], v[44:47]
	v_mfma_f32_16x16x32_bf16 v[40:43], v[162:165], v[178:181], v[40:43]
	v_mfma_f32_16x16x32_bf16 v[28:31], v[154:157], v[186:189], v[28:31]
	v_mfma_f32_16x16x32_bf16 v[24:27], v[162:165], v[186:189], v[24:27]
	v_mfma_f32_16x16x32_bf16 v[12:15], v[154:157], v[194:197], v[12:15]
	v_mfma_f32_16x16x32_bf16 v[8:11], v[162:165], v[194:197], v[8:11]
	v_mfma_f32_16x16x32_bf16 v[60:63], v[158:161], v[174:177], v[60:63]
	v_mfma_f32_16x16x32_bf16 v[56:59], v[166:169], v[174:177], v[56:59]
	v_mfma_f32_16x16x32_bf16 v[44:47], v[158:161], v[182:185], v[44:47]
	v_mfma_f32_16x16x32_bf16 v[40:43], v[166:169], v[182:185], v[40:43]
	v_mfma_f32_16x16x32_bf16 v[28:31], v[158:161], v[190:193], v[28:31]
	v_mfma_f32_16x16x32_bf16 v[24:27], v[166:169], v[190:193], v[24:27]
	v_mfma_f32_16x16x32_bf16 v[12:15], v[158:161], v[198:201], v[12:15]
	v_mfma_f32_16x16x32_bf16 v[8:11], v[166:169], v[198:201], v[8:11]
	s_barrier
	s_add_u32 s38, s38, 0x40080
	s_addc_u32 s39, s39, 0
	s_add_i32 s40, s40, s52
	v_lshl_add_u64 v[154:155], s[38:39], 0, v[132:133]
	s_mov_b32 m0, s40
	s_nop 0
	global_load_lds_dwordx4 v[154:155], off
	v_lshl_add_u64 v[154:155], s[38:39], 0, v[136:137]
	s_add_i32 m0, s40, 0x2000
	s_nop 0
	global_load_lds_dwordx4 v[154:155], off
	s_waitcnt vmcnt(10)
	s_barrier
	v_mfma_f32_16x16x32_bf16 v[52:55], v[202:205], v[170:173], v[52:55]
	v_mfma_f32_16x16x32_bf16 v[48:51], v[210:213], v[170:173], v[48:51]
	v_mfma_f32_16x16x32_bf16 v[36:39], v[202:205], v[178:181], v[36:39]
	v_mfma_f32_16x16x32_bf16 v[32:35], v[210:213], v[178:181], v[32:35]
	v_mfma_f32_16x16x32_bf16 v[20:23], v[202:205], v[186:189], v[20:23]
	v_mfma_f32_16x16x32_bf16 v[16:19], v[210:213], v[186:189], v[16:19]
	v_mfma_f32_16x16x32_bf16 v[4:7], v[202:205], v[194:197], v[4:7]
	v_mfma_f32_16x16x32_bf16 v[0:3], v[210:213], v[194:197], v[0:3]
	v_mfma_f32_16x16x32_bf16 v[52:55], v[206:209], v[174:177], v[52:55]
	v_mfma_f32_16x16x32_bf16 v[48:51], v[214:217], v[174:177], v[48:51]
	v_mfma_f32_16x16x32_bf16 v[36:39], v[206:209], v[182:185], v[36:39]
	v_mfma_f32_16x16x32_bf16 v[32:35], v[214:217], v[182:185], v[32:35]
	v_mfma_f32_16x16x32_bf16 v[20:23], v[206:209], v[190:193], v[20:23]
	v_mfma_f32_16x16x32_bf16 v[16:19], v[214:217], v[190:193], v[16:19]
	v_mfma_f32_16x16x32_bf16 v[4:7], v[206:209], v[198:201], v[4:7]
	v_mfma_f32_16x16x32_bf16 v[0:3], v[214:217], v[198:201], v[0:3]
	s_add_i32 s77, s77, 2
	s_add_u32 s36, s36, 0x100
	s_addc_u32 s37, s37, 0
	s_add_u32 s75, s75, 0x100
	s_addc_u32 s76, s76, 0
	s_cmp_gt_u32 s77, 13
	s_barrier
	s_cbranch_scc0 .LBB0_1310
	v_lshl_add_u32 v154, s34, 8, v148
	v_max_f32_e32 v126, v126, v126
	v_max_f32_e32 v127, v127, v127
	v_lshl_or_b32 v156, s72, 8, v150
	v_ashrrev_i32_e32 v155, 31, v154
	v_max_f32_e32 v124, v124, v124
	v_max_f32_e32 v120, v120, v120
	v_max_f32_e32 v125, v125, v125
	v_max_f32_e32 v121, v121, v121
	v_max_f32_e32 v126, 0, v126
	v_max_f32_e32 v122, v122, v122
	v_max_f32_e32 v127, 0, v127
	v_max_f32_e32 v123, v123, v123
	v_lshlrev_b64 v[158:159], 13, v[154:155]
	v_max_f32_e32 v124, 0, v124
	v_max_f32_e32 v120, 0, v120
	v_max_f32_e32 v125, 0, v125
	v_max_f32_e32 v121, 0, v121
	v_max_f32_e32 v122, 0, v122
	v_max_f32_e32 v123, 0, v123
	v_pk_mul_f32 v[126:127], v[126:127], v[126:127]
	v_ashrrev_i32_e32 v157, 31, v156
	v_lshl_add_u64 v[158:159], s[46:47], 0, v[158:159]
	v_pk_mul_f32 v[124:125], v[124:125], v[124:125]
	v_pk_mul_f32 v[120:121], v[120:121], v[120:121]
	v_pk_mul_f32 v[160:161], v[122:123], v[122:123]
	v_cvt_pk_bf16_f32 v123, v126, v127
	v_lshlrev_b64 v[126:127], 1, v[156:157]
	v_max_f32_e32 v112, v112, v112
	v_max_f32_e32 v113, v113, v113
	v_cvt_pk_bf16_f32 v122, v124, v125
	v_cvt_pk_bf16_f32 v124, v120, v121
	v_cvt_pk_bf16_f32 v125, v160, v161
	v_lshl_add_u64 v[120:121], v[158:159], 0, v[126:127]
	v_max_f32_e32 v112, 0, v112
	v_max_f32_e32 v113, 0, v113
	global_store_dwordx4 v[120:121], v[122:125], off
	v_max_f32_e32 v116, v116, v116
	v_max_f32_e32 v117, v117, v117
	v_pk_mul_f32 v[122:123], v[112:113], v[112:113]
	v_max_f32_e32 v113, v114, v114
	v_max_f32_e32 v112, v118, v118
	v_max_f32_e32 v114, 0, v113
	v_max_f32_e32 v113, v119, v119
	v_max_f32_e32 v115, v115, v115
	v_max_f32_e32 v116, 0, v116
	v_max_f32_e32 v117, 0, v117
	v_max_f32_e32 v112, 0, v112
	v_max_f32_e32 v113, 0, v113
	v_max_f32_e32 v115, 0, v115
	v_pk_mul_f32 v[116:117], v[116:117], v[116:117]
	v_pk_mul_f32 v[118:119], v[112:113], v[112:113]
	v_pk_mul_f32 v[124:125], v[114:115], v[114:115]
	v_max_f32_e32 v104, v104, v104
	v_max_f32_e32 v105, v105, v105
	v_cvt_pk_bf16_f32 v112, v116, v117
	v_cvt_pk_bf16_f32 v113, v118, v119
	v_cvt_pk_bf16_f32 v114, v122, v123
	v_cvt_pk_bf16_f32 v115, v124, v125
	v_max_f32_e32 v104, 0, v104
	v_max_f32_e32 v105, 0, v105
	global_store_dwordx4 v[120:121], v[112:115], off offset:256
	v_max_f32_e32 v108, v108, v108
	v_max_f32_e32 v109, v109, v109
	v_or_b32_e32 v112, 16, v154
	v_pk_mul_f32 v[114:115], v[104:105], v[104:105]
	v_max_f32_e32 v105, v106, v106
	v_ashrrev_i32_e32 v113, 31, v112
	v_max_f32_e32 v104, v110, v110
	v_max_f32_e32 v106, 0, v105
	v_max_f32_e32 v105, v111, v111
	v_max_f32_e32 v107, v107, v107
	v_lshlrev_b64 v[112:113], 13, v[112:113]
	v_max_f32_e32 v108, 0, v108
	v_max_f32_e32 v109, 0, v109
	v_max_f32_e32 v104, 0, v104
	v_max_f32_e32 v105, 0, v105
	v_max_f32_e32 v107, 0, v107
	v_lshl_add_u64 v[112:113], s[46:47], 0, v[112:113]
	v_pk_mul_f32 v[108:109], v[108:109], v[108:109]
	v_pk_mul_f32 v[110:111], v[104:105], v[104:105]
	v_pk_mul_f32 v[116:117], v[106:107], v[106:107]
	v_max_f32_e32 v96, v96, v96
	v_max_f32_e32 v97, v97, v97
	v_cvt_pk_bf16_f32 v104, v108, v109
	v_cvt_pk_bf16_f32 v105, v110, v111
	v_cvt_pk_bf16_f32 v106, v114, v115
	v_cvt_pk_bf16_f32 v107, v116, v117
	v_lshl_add_u64 v[108:109], v[112:113], 0, v[126:127]
	v_max_f32_e32 v96, 0, v96
	v_max_f32_e32 v97, 0, v97
	global_store_dwordx4 v[108:109], v[104:107], off
	v_max_f32_e32 v100, v100, v100
	v_max_f32_e32 v101, v101, v101
	v_pk_mul_f32 v[104:105], v[96:97], v[96:97]
	v_max_f32_e32 v97, v98, v98
	v_max_f32_e32 v96, v102, v102
	v_max_f32_e32 v98, 0, v97
	v_max_f32_e32 v97, v103, v103
	v_max_f32_e32 v99, v99, v99
	v_max_f32_e32 v100, 0, v100
	v_max_f32_e32 v101, 0, v101
	v_max_f32_e32 v96, 0, v96
	v_max_f32_e32 v97, 0, v97
	v_max_f32_e32 v99, 0, v99
	v_pk_mul_f32 v[100:101], v[100:101], v[100:101]
	v_pk_mul_f32 v[102:103], v[96:97], v[96:97]
	v_pk_mul_f32 v[106:107], v[98:99], v[98:99]
	v_max_f32_e32 v88, v88, v88
	v_max_f32_e32 v89, v89, v89
	v_cvt_pk_bf16_f32 v96, v100, v101
	v_cvt_pk_bf16_f32 v97, v102, v103
	v_cvt_pk_bf16_f32 v98, v104, v105
	v_cvt_pk_bf16_f32 v99, v106, v107
	v_max_f32_e32 v88, 0, v88
	v_max_f32_e32 v89, 0, v89
	global_store_dwordx4 v[108:109], v[96:99], off offset:256
	v_max_f32_e32 v92, v92, v92
	v_max_f32_e32 v93, v93, v93
	v_or_b32_e32 v96, 32, v154
	v_pk_mul_f32 v[98:99], v[88:89], v[88:89]
	v_max_f32_e32 v89, v90, v90
	v_ashrrev_i32_e32 v97, 31, v96
	v_max_f32_e32 v88, v94, v94
	v_max_f32_e32 v90, 0, v89
	v_max_f32_e32 v89, v95, v95
	v_max_f32_e32 v91, v91, v91
	v_lshlrev_b64 v[96:97], 13, v[96:97]
	v_max_f32_e32 v92, 0, v92
	v_max_f32_e32 v93, 0, v93
	v_max_f32_e32 v88, 0, v88
	v_max_f32_e32 v89, 0, v89
	v_max_f32_e32 v91, 0, v91
	v_lshl_add_u64 v[96:97], s[46:47], 0, v[96:97]
	v_pk_mul_f32 v[92:93], v[92:93], v[92:93]
	v_pk_mul_f32 v[94:95], v[88:89], v[88:89]
	v_pk_mul_f32 v[100:101], v[90:91], v[90:91]
	v_max_f32_e32 v80, v80, v80
	v_max_f32_e32 v81, v81, v81
	v_cvt_pk_bf16_f32 v88, v92, v93
	v_cvt_pk_bf16_f32 v89, v94, v95
	v_cvt_pk_bf16_f32 v90, v98, v99
	v_cvt_pk_bf16_f32 v91, v100, v101
	v_lshl_add_u64 v[92:93], v[96:97], 0, v[126:127]
	v_max_f32_e32 v80, 0, v80
	v_max_f32_e32 v81, 0, v81
	global_store_dwordx4 v[92:93], v[88:91], off
	v_max_f32_e32 v84, v84, v84
	v_max_f32_e32 v85, v85, v85
	v_pk_mul_f32 v[88:89], v[80:81], v[80:81]
	v_max_f32_e32 v81, v82, v82
	v_max_f32_e32 v80, v86, v86
	v_max_f32_e32 v82, 0, v81
	v_max_f32_e32 v81, v87, v87
	v_max_f32_e32 v83, v83, v83
	v_max_f32_e32 v84, 0, v84
	v_max_f32_e32 v85, 0, v85
	v_max_f32_e32 v80, 0, v80
	v_max_f32_e32 v81, 0, v81
	v_max_f32_e32 v83, 0, v83
	v_pk_mul_f32 v[84:85], v[84:85], v[84:85]
	v_pk_mul_f32 v[86:87], v[80:81], v[80:81]
	v_pk_mul_f32 v[90:91], v[82:83], v[82:83]
	v_max_f32_e32 v72, v72, v72
	v_max_f32_e32 v73, v73, v73
	v_cvt_pk_bf16_f32 v80, v84, v85
	v_cvt_pk_bf16_f32 v81, v86, v87
	v_cvt_pk_bf16_f32 v82, v88, v89
	v_cvt_pk_bf16_f32 v83, v90, v91
	v_max_f32_e32 v72, 0, v72
	v_max_f32_e32 v73, 0, v73
	global_store_dwordx4 v[92:93], v[80:83], off offset:256
	v_max_f32_e32 v76, v76, v76
	v_max_f32_e32 v77, v77, v77
	v_or_b32_e32 v80, 48, v154
	v_pk_mul_f32 v[82:83], v[72:73], v[72:73]
	v_max_f32_e32 v73, v74, v74
	v_ashrrev_i32_e32 v81, 31, v80
	v_max_f32_e32 v72, v78, v78
	v_max_f32_e32 v74, 0, v73
	v_max_f32_e32 v73, v79, v79
	v_max_f32_e32 v75, v75, v75
	v_lshlrev_b64 v[80:81], 13, v[80:81]
	v_max_f32_e32 v76, 0, v76
	v_max_f32_e32 v77, 0, v77
	v_max_f32_e32 v72, 0, v72
	v_max_f32_e32 v73, 0, v73
	v_max_f32_e32 v75, 0, v75
	v_lshl_add_u64 v[80:81], s[46:47], 0, v[80:81]
	v_pk_mul_f32 v[76:77], v[76:77], v[76:77]
	v_pk_mul_f32 v[78:79], v[72:73], v[72:73]
	v_pk_mul_f32 v[84:85], v[74:75], v[74:75]
	v_max_f32_e32 v64, v64, v64
	v_max_f32_e32 v65, v65, v65
	v_cvt_pk_bf16_f32 v72, v76, v77
	v_cvt_pk_bf16_f32 v73, v78, v79
	v_cvt_pk_bf16_f32 v74, v82, v83
	v_cvt_pk_bf16_f32 v75, v84, v85
	v_lshl_add_u64 v[76:77], v[80:81], 0, v[126:127]
	v_max_f32_e32 v64, 0, v64
	v_max_f32_e32 v65, 0, v65
	global_store_dwordx4 v[76:77], v[72:75], off
	v_max_f32_e32 v68, v68, v68
	v_max_f32_e32 v69, v69, v69
	v_pk_mul_f32 v[72:73], v[64:65], v[64:65]
	v_max_f32_e32 v65, v66, v66
	v_max_f32_e32 v64, v70, v70
	v_max_f32_e32 v66, 0, v65
	v_max_f32_e32 v65, v71, v71
	v_max_f32_e32 v67, v67, v67
	v_max_f32_e32 v68, 0, v68
	v_max_f32_e32 v69, 0, v69
	v_max_f32_e32 v64, 0, v64
	v_max_f32_e32 v65, 0, v65
	v_max_f32_e32 v67, 0, v67
	v_pk_mul_f32 v[68:69], v[68:69], v[68:69]
	v_pk_mul_f32 v[70:71], v[64:65], v[64:65]
	v_pk_mul_f32 v[74:75], v[66:67], v[66:67]
	v_max_f32_e32 v56, v56, v56
	v_max_f32_e32 v57, v57, v57
	v_cvt_pk_bf16_f32 v64, v68, v69
	v_cvt_pk_bf16_f32 v65, v70, v71
	v_cvt_pk_bf16_f32 v66, v72, v73
	v_cvt_pk_bf16_f32 v67, v74, v75
	v_max_f32_e32 v56, 0, v56
	v_max_f32_e32 v57, 0, v57
	global_store_dwordx4 v[76:77], v[64:67], off offset:256
	v_max_f32_e32 v60, v60, v60
	v_max_f32_e32 v61, v61, v61
	v_pk_mul_f32 v[64:65], v[56:57], v[56:57]
	v_max_f32_e32 v57, v58, v58
	v_max_f32_e32 v56, v62, v62
	v_max_f32_e32 v58, 0, v57
	v_max_f32_e32 v57, v63, v63
	v_max_f32_e32 v56, 0, v56
	v_max_f32_e32 v57, 0, v57
	v_max_f32_e32 v59, v59, v59
	v_max_f32_e32 v60, 0, v60
	v_max_f32_e32 v61, 0, v61
	v_max_f32_e32 v59, 0, v59
	v_pk_mul_f32 v[62:63], v[56:57], v[56:57]
	v_pk_mul_f32 v[60:61], v[60:61], v[60:61]
	v_pk_mul_f32 v[66:67], v[58:59], v[58:59]
	v_cvt_pk_bf16_f32 v57, v62, v63
	v_add_co_u32_e32 v62, vcc, s64, v120
	v_max_f32_e32 v48, v48, v48
	v_max_f32_e32 v49, v49, v49
	v_cvt_pk_bf16_f32 v56, v60, v61
	v_cvt_pk_bf16_f32 v58, v64, v65
	v_cvt_pk_bf16_f32 v59, v66, v67
	v_addc_co_u32_e32 v63, vcc, 0, v121, vcc
	v_max_f32_e32 v48, 0, v48
	v_max_f32_e32 v49, 0, v49
	global_store_dwordx4 v[62:63], v[56:59], off
	v_max_f32_e32 v52, v52, v52
	v_max_f32_e32 v53, v53, v53
	v_pk_mul_f32 v[56:57], v[48:49], v[48:49]
	v_max_f32_e32 v49, v50, v50
	v_max_f32_e32 v48, v54, v54
	v_max_f32_e32 v50, 0, v49
	v_max_f32_e32 v49, v55, v55
	v_max_f32_e32 v51, v51, v51
	v_max_f32_e32 v52, 0, v52
	v_max_f32_e32 v53, 0, v53
	v_max_f32_e32 v48, 0, v48
	v_max_f32_e32 v49, 0, v49
	v_max_f32_e32 v51, 0, v51
	v_pk_mul_f32 v[52:53], v[52:53], v[52:53]
	v_pk_mul_f32 v[54:55], v[48:49], v[48:49]
	v_pk_mul_f32 v[58:59], v[50:51], v[50:51]
	v_max_f32_e32 v40, v40, v40
	v_max_f32_e32 v41, v41, v41
	v_lshl_add_u64 v[60:61], v[120:121], 0, s[12:13]
	v_cvt_pk_bf16_f32 v48, v52, v53
	v_cvt_pk_bf16_f32 v49, v54, v55
	v_cvt_pk_bf16_f32 v50, v56, v57
	v_cvt_pk_bf16_f32 v51, v58, v59
	v_max_f32_e32 v40, 0, v40
	v_max_f32_e32 v41, 0, v41
	global_store_dwordx4 v[60:61], v[48:51], off offset:256
	v_max_f32_e32 v44, v44, v44
	v_max_f32_e32 v45, v45, v45
	v_pk_mul_f32 v[48:49], v[40:41], v[40:41]
	v_max_f32_e32 v41, v42, v42
	v_max_f32_e32 v40, v46, v46
	v_max_f32_e32 v42, 0, v41
	v_max_f32_e32 v41, v47, v47
	v_max_f32_e32 v40, 0, v40
	v_max_f32_e32 v41, 0, v41
	v_max_f32_e32 v43, v43, v43
	v_max_f32_e32 v44, 0, v44
	v_max_f32_e32 v45, 0, v45
	v_max_f32_e32 v43, 0, v43
	v_pk_mul_f32 v[46:47], v[40:41], v[40:41]
	v_pk_mul_f32 v[44:45], v[44:45], v[44:45]
	v_pk_mul_f32 v[50:51], v[42:43], v[42:43]
	v_cvt_pk_bf16_f32 v41, v46, v47
	v_add_co_u32_e32 v46, vcc, s65, v120
	v_max_f32_e32 v32, v32, v32
	v_max_f32_e32 v33, v33, v33
	v_cvt_pk_bf16_f32 v40, v44, v45
	v_cvt_pk_bf16_f32 v42, v48, v49
	v_cvt_pk_bf16_f32 v43, v50, v51
	v_addc_co_u32_e32 v47, vcc, 0, v121, vcc
	v_max_f32_e32 v32, 0, v32
	v_max_f32_e32 v33, 0, v33
	global_store_dwordx4 v[46:47], v[40:43], off
	v_max_f32_e32 v36, v36, v36
	v_max_f32_e32 v37, v37, v37
	v_pk_mul_f32 v[40:41], v[32:33], v[32:33]
	v_max_f32_e32 v33, v34, v34
	v_max_f32_e32 v32, v38, v38
	v_max_f32_e32 v34, 0, v33
	v_max_f32_e32 v33, v39, v39
	v_max_f32_e32 v35, v35, v35
	v_max_f32_e32 v36, 0, v36
	v_max_f32_e32 v37, 0, v37
	v_max_f32_e32 v32, 0, v32
	v_max_f32_e32 v33, 0, v33
	v_max_f32_e32 v35, 0, v35
	v_pk_mul_f32 v[36:37], v[36:37], v[36:37]
	v_pk_mul_f32 v[38:39], v[32:33], v[32:33]
	v_pk_mul_f32 v[42:43], v[34:35], v[34:35]
	v_max_f32_e32 v24, v24, v24
	v_max_f32_e32 v25, v25, v25
	v_lshl_add_u64 v[44:45], v[120:121], 0, s[14:15]
	v_cvt_pk_bf16_f32 v32, v36, v37
	v_cvt_pk_bf16_f32 v33, v38, v39
	v_cvt_pk_bf16_f32 v34, v40, v41
	v_cvt_pk_bf16_f32 v35, v42, v43
	v_max_f32_e32 v24, 0, v24
	v_max_f32_e32 v25, 0, v25
	global_store_dwordx4 v[44:45], v[32:35], off offset:256
	v_max_f32_e32 v28, v28, v28
	v_max_f32_e32 v29, v29, v29
	v_pk_mul_f32 v[32:33], v[24:25], v[24:25]
	v_max_f32_e32 v25, v26, v26
	v_max_f32_e32 v24, v30, v30
	v_max_f32_e32 v26, 0, v25
	v_max_f32_e32 v25, v31, v31
	v_max_f32_e32 v24, 0, v24
	v_max_f32_e32 v25, 0, v25
	v_max_f32_e32 v27, v27, v27
	v_max_f32_e32 v28, 0, v28
	v_max_f32_e32 v29, 0, v29
	v_max_f32_e32 v27, 0, v27
	v_pk_mul_f32 v[30:31], v[24:25], v[24:25]
	v_pk_mul_f32 v[28:29], v[28:29], v[28:29]
	v_pk_mul_f32 v[34:35], v[26:27], v[26:27]
	v_cvt_pk_bf16_f32 v25, v30, v31
	v_add_co_u32_e32 v30, vcc, s70, v120
	v_max_f32_e32 v16, v16, v16
	v_max_f32_e32 v17, v17, v17
	v_cvt_pk_bf16_f32 v24, v28, v29
	v_cvt_pk_bf16_f32 v26, v32, v33
	v_cvt_pk_bf16_f32 v27, v34, v35
	v_addc_co_u32_e32 v31, vcc, 0, v121, vcc
	v_max_f32_e32 v16, 0, v16
	v_max_f32_e32 v17, 0, v17
	global_store_dwordx4 v[30:31], v[24:27], off
	v_max_f32_e32 v20, v20, v20
	v_max_f32_e32 v21, v21, v21
	v_pk_mul_f32 v[24:25], v[16:17], v[16:17]
	v_max_f32_e32 v17, v18, v18
	v_max_f32_e32 v16, v22, v22
	v_max_f32_e32 v18, 0, v17
	v_max_f32_e32 v17, v23, v23
	v_max_f32_e32 v19, v19, v19
	v_max_f32_e32 v20, 0, v20
	v_max_f32_e32 v21, 0, v21
	v_max_f32_e32 v16, 0, v16
	v_max_f32_e32 v17, 0, v17
	v_max_f32_e32 v19, 0, v19
	v_pk_mul_f32 v[20:21], v[20:21], v[20:21]
	v_pk_mul_f32 v[22:23], v[16:17], v[16:17]
	v_pk_mul_f32 v[26:27], v[18:19], v[18:19]
	v_max_f32_e32 v8, v8, v8
	v_max_f32_e32 v9, v9, v9
	v_lshl_add_u64 v[28:29], v[120:121], 0, s[16:17]
	v_cvt_pk_bf16_f32 v16, v20, v21
	v_cvt_pk_bf16_f32 v17, v22, v23
	v_cvt_pk_bf16_f32 v18, v24, v25
	v_cvt_pk_bf16_f32 v19, v26, v27
	v_max_f32_e32 v8, 0, v8
	v_max_f32_e32 v9, 0, v9
	global_store_dwordx4 v[28:29], v[16:19], off offset:256
	v_max_f32_e32 v12, v12, v12
	v_max_f32_e32 v13, v13, v13
	v_pk_mul_f32 v[16:17], v[8:9], v[8:9]
	v_max_f32_e32 v9, v10, v10
	v_max_f32_e32 v8, v14, v14
	v_max_f32_e32 v10, 0, v9
	v_max_f32_e32 v9, v15, v15
	v_max_f32_e32 v8, 0, v8
	v_max_f32_e32 v9, 0, v9
	v_max_f32_e32 v11, v11, v11
	v_max_f32_e32 v12, 0, v12
	v_max_f32_e32 v13, 0, v13
	v_max_f32_e32 v11, 0, v11
	v_pk_mul_f32 v[14:15], v[8:9], v[8:9]
	v_pk_mul_f32 v[12:13], v[12:13], v[12:13]
	v_pk_mul_f32 v[18:19], v[10:11], v[10:11]
	v_cvt_pk_bf16_f32 v9, v14, v15
	v_add_co_u32_e32 v14, vcc, s71, v120
	v_max_f32_e32 v0, v0, v0
	v_max_f32_e32 v1, v1, v1
	v_cvt_pk_bf16_f32 v8, v12, v13
	v_cvt_pk_bf16_f32 v10, v16, v17
	v_cvt_pk_bf16_f32 v11, v18, v19
	v_addc_co_u32_e32 v15, vcc, 0, v121, vcc
	v_max_f32_e32 v0, 0, v0
	v_max_f32_e32 v1, 0, v1
	global_store_dwordx4 v[14:15], v[8:11], off
	v_max_f32_e32 v4, v4, v4
	v_max_f32_e32 v5, v5, v5
	v_pk_mul_f32 v[8:9], v[0:1], v[0:1]
	v_max_f32_e32 v1, v2, v2
	v_max_f32_e32 v0, v6, v6
	v_max_f32_e32 v2, 0, v1
	v_max_f32_e32 v1, v7, v7
	v_max_f32_e32 v3, v3, v3
	v_max_f32_e32 v4, 0, v4
	v_max_f32_e32 v5, 0, v5
	v_max_f32_e32 v0, 0, v0
	v_max_f32_e32 v1, 0, v1
	v_max_f32_e32 v3, 0, v3
	v_pk_mul_f32 v[4:5], v[4:5], v[4:5]
	v_pk_mul_f32 v[6:7], v[0:1], v[0:1]
	v_pk_mul_f32 v[10:11], v[2:3], v[2:3]
	v_lshl_add_u64 v[12:13], v[120:121], 0, s[18:19]
	v_cvt_pk_bf16_f32 v0, v4, v5
	v_cvt_pk_bf16_f32 v1, v6, v7
	v_cvt_pk_bf16_f32 v2, v8, v9
	v_cvt_pk_bf16_f32 v3, v10, v11
	s_and_b64 vcc, exec, s[4:5]
	s_mov_b32 s72, s20
	s_mov_b32 s34, s26
	s_mov_b64 s[38:39], s[30:31]
	s_mov_b64 s[36:37], s[28:29]
	global_store_dwordx4 v[12:13], v[0:3], off offset:256
	s_cbranch_vccz .LBB0_1303
	s_waitcnt vmcnt(16)
	s_cmpk_gt_u32 s42, 0xff
	s_cbranch_scc1 .LBB0_1314
	s_barrier

.LBB0_1384:
	ds_read_b128 v[156:159], v153
	ds_read_b128 v[160:163], v153 offset:1024
	ds_read_b128 v[164:167], v153 offset:2048
	ds_read_b128 v[168:171], v153 offset:3072
	s_add_u32 s36, s34, 0xfff00080
	s_addc_u32 s37, s35, -1
	s_cmp_eq_u32 s77, 60
	s_cselect_b32 s39, s27, s37
	s_cselect_b32 s38, s73, s36
	s_cselect_b32 s37, s21, s76
	s_cselect_b32 s36, s74, s75
	v_lshl_add_u64 v[204:205], s[34:35], 0, v[138:139]
	s_add_i32 m0, s19, 0xc000
	ds_read_b128 v[172:175], v154
	ds_read_b128 v[176:179], v154 offset:1024
	ds_read_b128 v[180:183], v154 offset:2048
	ds_read_b128 v[184:187], v154 offset:3072
	ds_read_b128 v[188:191], v154 offset:4096
	ds_read_b128 v[192:195], v154 offset:5120
	ds_read_b128 v[196:199], v154 offset:6144
	ds_read_b128 v[200:203], v154 offset:7168
	global_load_lds_dwordx4 v[204:205], off
	v_lshl_add_u64 v[204:205], s[34:35], 0, v[140:141]
	s_add_i32 m0, s19, 0xe000
	s_nop 0
	global_load_lds_dwordx4 v[204:205], off
	s_waitcnt lgkmcnt(8)
	s_waitcnt vmcnt(10)
	s_barrier
	s_waitcnt lgkmcnt(0)
	s_waitcnt lgkmcnt(0)
	v_mfma_f32_16x16x32_bf16 v[124:127], v[156:159], v[172:175], v[124:127]
	v_mfma_f32_16x16x32_bf16 v[120:123], v[164:167], v[172:175], v[120:123]
	v_mfma_f32_16x16x32_bf16 v[116:119], v[156:159], v[180:183], v[116:119]
	v_mfma_f32_16x16x32_bf16 v[112:115], v[164:167], v[180:183], v[112:115]
	v_mfma_f32_16x16x32_bf16 v[100:103], v[156:159], v[188:191], v[100:103]
	v_mfma_f32_16x16x32_bf16 v[96:99], v[164:167], v[188:191], v[96:99]
	v_mfma_f32_16x16x32_bf16 v[84:87], v[156:159], v[196:199], v[84:87]
	v_mfma_f32_16x16x32_bf16 v[80:83], v[164:167], v[196:199], v[80:83]
	v_mfma_f32_16x16x32_bf16 v[124:127], v[160:163], v[176:179], v[124:127]
	v_mfma_f32_16x16x32_bf16 v[120:123], v[168:171], v[176:179], v[120:123]
	v_mfma_f32_16x16x32_bf16 v[116:119], v[160:163], v[184:187], v[116:119]
	v_mfma_f32_16x16x32_bf16 v[112:115], v[168:171], v[184:187], v[112:115]
	v_mfma_f32_16x16x32_bf16 v[100:103], v[160:163], v[192:195], v[100:103]
	v_mfma_f32_16x16x32_bf16 v[96:99], v[168:171], v[192:195], v[96:99]
	v_mfma_f32_16x16x32_bf16 v[84:87], v[160:163], v[200:203], v[84:87]
	v_mfma_f32_16x16x32_bf16 v[80:83], v[168:171], v[200:203], v[80:83]
	s_barrier
	s_add_i32 s78, s62, s43
	v_lshl_add_u64 v[220:221], s[36:37], 0, v[134:135]
	s_mov_b32 m0, s78
	ds_read_b128 v[204:207], v155
	ds_read_b128 v[208:211], v155 offset:1024
	ds_read_b128 v[212:215], v155 offset:2048
	ds_read_b128 v[216:219], v155 offset:3072
	global_load_lds_dwordx4 v[220:221], off
	v_lshl_add_u64 v[222:223], s[36:37], 0, v[130:131]
	s_add_i32 m0, s78, 0x2000
	s_nop 0
	global_load_lds_dwordx4 v[222:223], off
	s_waitcnt vmcnt(10)
	s_barrier
	s_waitcnt lgkmcnt(0)
	s_waitcnt lgkmcnt(0)
	v_mfma_f32_16x16x32_bf16 v[108:111], v[204:207], v[172:175], v[108:111]
	v_mfma_f32_16x16x32_bf16 v[104:107], v[212:215], v[172:175], v[104:107]
	v_mfma_f32_16x16x32_bf16 v[92:95], v[204:207], v[180:183], v[92:95]
	v_mfma_f32_16x16x32_bf16 v[88:91], v[212:215], v[180:183], v[88:91]
	v_mfma_f32_16x16x32_bf16 v[76:79], v[204:207], v[188:191], v[76:79]
	v_mfma_f32_16x16x32_bf16 v[72:75], v[212:215], v[188:191], v[72:75]
	v_mfma_f32_16x16x32_bf16 v[68:71], v[204:207], v[196:199], v[68:71]
	v_mfma_f32_16x16x32_bf16 v[64:67], v[212:215], v[196:199], v[64:67]
	v_mfma_f32_16x16x32_bf16 v[108:111], v[208:211], v[176:179], v[108:111]
	v_mfma_f32_16x16x32_bf16 v[104:107], v[216:219], v[176:179], v[104:107]
	v_mfma_f32_16x16x32_bf16 v[92:95], v[208:211], v[184:187], v[92:95]
	v_mfma_f32_16x16x32_bf16 v[88:91], v[216:219], v[184:187], v[88:91]
	v_mfma_f32_16x16x32_bf16 v[76:79], v[208:211], v[192:195], v[76:79]
	v_mfma_f32_16x16x32_bf16 v[72:75], v[216:219], v[192:195], v[72:75]
	v_mfma_f32_16x16x32_bf16 v[68:71], v[208:211], v[200:203], v[68:71]
	v_mfma_f32_16x16x32_bf16 v[64:67], v[216:219], v[200:203], v[64:67]
	s_mov_b32 m0, s19
	v_lshl_add_u64 v[224:225], s[38:39], 0, v[136:137]
	s_barrier
	ds_read_b128 v[172:175], v154 offset:16384
	ds_read_b128 v[176:179], v154 offset:17408
	ds_read_b128 v[180:183], v154 offset:18432
	ds_read_b128 v[184:187], v154 offset:19456
	ds_read_b128 v[188:191], v154 offset:20480
	ds_read_b128 v[192:195], v154 offset:21504
	ds_read_b128 v[196:199], v154 offset:22528
	ds_read_b128 v[200:203], v154 offset:23552
	global_load_lds_dwordx4 v[224:225], off
	v_lshl_add_u64 v[226:227], s[38:39], 0, v[132:133]
	s_mov_b32 m0, s53
	s_nop 0
	global_load_lds_dwordx4 v[226:227], off
	s_waitcnt vmcnt(10)
	s_barrier
	s_waitcnt lgkmcnt(0)
	s_waitcnt lgkmcnt(0)
	v_mfma_f32_16x16x32_bf16 v[60:63], v[156:159], v[172:175], v[60:63]
	v_mfma_f32_16x16x32_bf16 v[56:59], v[164:167], v[172:175], v[56:59]
	v_mfma_f32_16x16x32_bf16 v[52:55], v[156:159], v[180:183], v[52:55]
	v_mfma_f32_16x16x32_bf16 v[48:51], v[164:167], v[180:183], v[48:51]
	v_mfma_f32_16x16x32_bf16 v[36:39], v[156:159], v[188:191], v[36:39]
	v_mfma_f32_16x16x32_bf16 v[32:35], v[164:167], v[188:191], v[32:35]
	v_mfma_f32_16x16x32_bf16 v[20:23], v[156:159], v[196:199], v[20:23]
	v_mfma_f32_16x16x32_bf16 v[16:19], v[164:167], v[196:199], v[16:19]
	v_mfma_f32_16x16x32_bf16 v[60:63], v[160:163], v[176:179], v[60:63]
	v_mfma_f32_16x16x32_bf16 v[56:59], v[168:171], v[176:179], v[56:59]
	v_mfma_f32_16x16x32_bf16 v[52:55], v[160:163], v[184:187], v[52:55]
	v_mfma_f32_16x16x32_bf16 v[48:51], v[168:171], v[184:187], v[48:51]
	v_mfma_f32_16x16x32_bf16 v[36:39], v[160:163], v[192:195], v[36:39]
	v_mfma_f32_16x16x32_bf16 v[32:35], v[168:171], v[192:195], v[32:35]
	v_mfma_f32_16x16x32_bf16 v[20:23], v[160:163], v[200:203], v[20:23]
	v_mfma_f32_16x16x32_bf16 v[16:19], v[168:171], v[200:203], v[16:19]
	s_barrier
	s_add_u32 s78, s36, 0x100000
	s_addc_u32 s79, s37, 0
	s_add_i32 s80, s63, s43
	v_lshl_add_u64 v[156:157], s[78:79], 0, v[134:135]
	s_mov_b32 m0, s80
	s_nop 0
	global_load_lds_dwordx4 v[156:157], off
	v_lshl_add_u64 v[156:157], s[78:79], 0, v[130:131]
	s_add_i32 m0, s80, 0x2000
	s_nop 0
	global_load_lds_dwordx4 v[156:157], off
	s_waitcnt vmcnt(10)
	s_barrier
	v_mfma_f32_16x16x32_bf16 v[44:47], v[204:207], v[172:175], v[44:47]
	v_mfma_f32_16x16x32_bf16 v[40:43], v[212:215], v[172:175], v[40:43]
	v_mfma_f32_16x16x32_bf16 v[28:31], v[204:207], v[180:183], v[28:31]
	v_mfma_f32_16x16x32_bf16 v[24:27], v[212:215], v[180:183], v[24:27]
	v_mfma_f32_16x16x32_bf16 v[12:15], v[204:207], v[188:191], v[12:15]
	v_mfma_f32_16x16x32_bf16 v[8:11], v[212:215], v[188:191], v[8:11]
	v_mfma_f32_16x16x32_bf16 v[4:7], v[204:207], v[196:199], v[4:7]
	v_mfma_f32_16x16x32_bf16 v[0:3], v[212:215], v[196:199], v[0:3]
	v_mfma_f32_16x16x32_bf16 v[44:47], v[208:211], v[176:179], v[44:47]
	v_mfma_f32_16x16x32_bf16 v[40:43], v[216:219], v[176:179], v[40:43]
	v_mfma_f32_16x16x32_bf16 v[28:31], v[208:211], v[184:187], v[28:31]
	v_mfma_f32_16x16x32_bf16 v[24:27], v[216:219], v[184:187], v[24:27]
	v_mfma_f32_16x16x32_bf16 v[12:15], v[208:211], v[192:195], v[12:15]
	v_mfma_f32_16x16x32_bf16 v[8:11], v[216:219], v[192:195], v[8:11]
	v_mfma_f32_16x16x32_bf16 v[4:7], v[208:211], v[200:203], v[4:7]
	v_mfma_f32_16x16x32_bf16 v[0:3], v[216:219], v[200:203], v[0:3]
	s_add_i32 s78, 0, 0x18000
	v_add_u32_e32 v168, s78, v151
	s_barrier
	ds_read_b128 v[156:159], v168
	ds_read_b128 v[160:163], v168 offset:1024
	ds_read_b128 v[164:167], v168 offset:2048
	ds_read_b128 v[168:171], v168 offset:3072
	s_add_u32 s38, s38, 0x100000
	s_addc_u32 s39, s39, 0
	s_mov_b32 m0, s54
	v_lshl_add_u64 v[204:205], s[38:39], 0, v[136:137]
	ds_read_b128 v[172:175], v154 offset:32768
	ds_read_b128 v[176:179], v154 offset:33792
	ds_read_b128 v[180:183], v154 offset:34816
	ds_read_b128 v[184:187], v154 offset:35840
	ds_read_b128 v[188:191], v154 offset:36864
	ds_read_b128 v[192:195], v154 offset:37888
	ds_read_b128 v[196:199], v154 offset:38912
	ds_read_b128 v[200:203], v154 offset:39936
	global_load_lds_dwordx4 v[204:205], off
	v_lshl_add_u64 v[204:205], s[38:39], 0, v[132:133]
	s_mov_b32 m0, s55
	s_nop 0
	global_load_lds_dwordx4 v[204:205], off
	s_waitcnt lgkmcnt(8)
	s_waitcnt vmcnt(10)
	s_barrier
	s_waitcnt lgkmcnt(0)
	s_waitcnt lgkmcnt(0)
	v_mfma_f32_16x16x32_bf16 v[124:127], v[156:159], v[172:175], v[124:127]
	v_mfma_f32_16x16x32_bf16 v[120:123], v[164:167], v[172:175], v[120:123]
	v_mfma_f32_16x16x32_bf16 v[116:119], v[156:159], v[180:183], v[116:119]
	v_mfma_f32_16x16x32_bf16 v[112:115], v[164:167], v[180:183], v[112:115]
	v_mfma_f32_16x16x32_bf16 v[100:103], v[156:159], v[188:191], v[100:103]
	v_mfma_f32_16x16x32_bf16 v[96:99], v[164:167], v[188:191], v[96:99]
	v_mfma_f32_16x16x32_bf16 v[84:87], v[156:159], v[196:199], v[84:87]
	v_mfma_f32_16x16x32_bf16 v[80:83], v[164:167], v[196:199], v[80:83]
	v_mfma_f32_16x16x32_bf16 v[124:127], v[160:163], v[176:179], v[124:127]
	v_mfma_f32_16x16x32_bf16 v[120:123], v[168:171], v[176:179], v[120:123]
	v_mfma_f32_16x16x32_bf16 v[116:119], v[160:163], v[184:187], v[116:119]
	v_mfma_f32_16x16x32_bf16 v[112:115], v[168:171], v[184:187], v[112:115]
	v_mfma_f32_16x16x32_bf16 v[100:103], v[160:163], v[192:195], v[100:103]
	v_mfma_f32_16x16x32_bf16 v[96:99], v[168:171], v[192:195], v[96:99]
	v_mfma_f32_16x16x32_bf16 v[84:87], v[160:163], v[200:203], v[84:87]
	v_mfma_f32_16x16x32_bf16 v[80:83], v[168:171], v[200:203], v[80:83]
	s_barrier
	s_add_i32 s38, 0, 0x1c000
	s_add_i32 s39, s78, s43
	v_add_u32_e32 v216, s38, v151
	v_lshl_add_u64 v[220:221], v[220:221], 0, s[8:9]
	s_mov_b32 m0, s39
	ds_read_b128 v[204:207], v216
	ds_read_b128 v[208:211], v216 offset:1024
	ds_read_b128 v[212:215], v216 offset:2048
	ds_read_b128 v[216:219], v216 offset:3072
	global_load_lds_dwordx4 v[220:221], off
	v_lshl_add_u64 v[220:221], v[222:223], 0, s[8:9]
	s_add_i32 m0, s39, 0x2000
	s_nop 0
	global_load_lds_dwordx4 v[220:221], off
	s_waitcnt vmcnt(10)
	s_barrier
	s_waitcnt lgkmcnt(0)
	s_waitcnt lgkmcnt(0)
	v_mfma_f32_16x16x32_bf16 v[108:111], v[204:207], v[172:175], v[108:111]
	v_mfma_f32_16x16x32_bf16 v[104:107], v[212:215], v[172:175], v[104:107]
	v_mfma_f32_16x16x32_bf16 v[92:95], v[204:207], v[180:183], v[92:95]
	v_mfma_f32_16x16x32_bf16 v[88:91], v[212:215], v[180:183], v[88:91]
	v_mfma_f32_16x16x32_bf16 v[76:79], v[204:207], v[188:191], v[76:79]
	v_mfma_f32_16x16x32_bf16 v[72:75], v[212:215], v[188:191], v[72:75]
	v_mfma_f32_16x16x32_bf16 v[68:71], v[204:207], v[196:199], v[68:71]
	v_mfma_f32_16x16x32_bf16 v[64:67], v[212:215], v[196:199], v[64:67]
	v_mfma_f32_16x16x32_bf16 v[108:111], v[208:211], v[176:179], v[108:111]
	v_mfma_f32_16x16x32_bf16 v[104:107], v[216:219], v[176:179], v[104:107]
	v_mfma_f32_16x16x32_bf16 v[92:95], v[208:211], v[184:187], v[92:95]
	v_mfma_f32_16x16x32_bf16 v[88:91], v[216:219], v[184:187], v[88:91]
	v_mfma_f32_16x16x32_bf16 v[76:79], v[208:211], v[192:195], v[76:79]
	v_mfma_f32_16x16x32_bf16 v[72:75], v[216:219], v[192:195], v[72:75]
	v_mfma_f32_16x16x32_bf16 v[68:71], v[208:211], v[200:203], v[68:71]
	v_mfma_f32_16x16x32_bf16 v[64:67], v[216:219], v[200:203], v[64:67]
	s_mov_b32 m0, s57
	v_lshl_add_u64 v[220:221], v[224:225], 0, s[8:9]
	s_barrier
	ds_read_b128 v[172:175], v154 offset:49152
	ds_read_b128 v[176:179], v154 offset:50176
	ds_read_b128 v[180:183], v154 offset:51200
	ds_read_b128 v[184:187], v154 offset:52224
	ds_read_b128 v[188:191], v154 offset:53248
	ds_read_b128 v[192:195], v154 offset:54272
	ds_read_b128 v[196:199], v154 offset:55296
	ds_read_b128 v[200:203], v154 offset:56320
	global_load_lds_dwordx4 v[220:221], off
	v_lshl_add_u64 v[220:221], v[226:227], 0, s[8:9]
	s_mov_b32 m0, s60
	s_nop 0
	global_load_lds_dwordx4 v[220:221], off
	s_waitcnt vmcnt(10)
	s_barrier
	s_waitcnt lgkmcnt(0)
	s_waitcnt lgkmcnt(0)
	v_mfma_f32_16x16x32_bf16 v[60:63], v[156:159], v[172:175], v[60:63]
	v_mfma_f32_16x16x32_bf16 v[56:59], v[164:167], v[172:175], v[56:59]
	v_mfma_f32_16x16x32_bf16 v[52:55], v[156:159], v[180:183], v[52:55]
	v_mfma_f32_16x16x32_bf16 v[48:51], v[164:167], v[180:183], v[48:51]
	v_mfma_f32_16x16x32_bf16 v[36:39], v[156:159], v[188:191], v[36:39]
	v_mfma_f32_16x16x32_bf16 v[32:35], v[164:167], v[188:191], v[32:35]
	v_mfma_f32_16x16x32_bf16 v[20:23], v[156:159], v[196:199], v[20:23]
	v_mfma_f32_16x16x32_bf16 v[16:19], v[164:167], v[196:199], v[16:19]
	v_mfma_f32_16x16x32_bf16 v[60:63], v[160:163], v[176:179], v[60:63]
	v_mfma_f32_16x16x32_bf16 v[56:59], v[168:171], v[176:179], v[56:59]
	v_mfma_f32_16x16x32_bf16 v[52:55], v[160:163], v[184:187], v[52:55]
	v_mfma_f32_16x16x32_bf16 v[48:51], v[168:171], v[184:187], v[48:51]
	v_mfma_f32_16x16x32_bf16 v[36:39], v[160:163], v[192:195], v[36:39]
	v_mfma_f32_16x16x32_bf16 v[32:35], v[168:171], v[192:195], v[32:35]
	v_mfma_f32_16x16x32_bf16 v[20:23], v[160:163], v[200:203], v[20:23]
	v_mfma_f32_16x16x32_bf16 v[16:19], v[168:171], v[200:203], v[16:19]
	s_barrier
	s_add_u32 s36, s36, 0x100080
	s_addc_u32 s37, s37, 0
	s_add_i32 s38, s38, s43
	v_lshl_add_u64 v[156:157], s[36:37], 0, v[134:135]
	s_mov_b32 m0, s38
	s_nop 0
	global_load_lds_dwordx4 v[156:157], off
	v_lshl_add_u64 v[156:157], s[36:37], 0, v[130:131]
	s_add_i32 m0, s38, 0x2000
	s_nop 0
	global_load_lds_dwordx4 v[156:157], off
	s_waitcnt vmcnt(10)
	s_barrier
	v_mfma_f32_16x16x32_bf16 v[44:47], v[204:207], v[172:175], v[44:47]
	v_mfma_f32_16x16x32_bf16 v[40:43], v[212:215], v[172:175], v[40:43]
	v_mfma_f32_16x16x32_bf16 v[28:31], v[204:207], v[180:183], v[28:31]
	v_mfma_f32_16x16x32_bf16 v[24:27], v[212:215], v[180:183], v[24:27]
	v_mfma_f32_16x16x32_bf16 v[12:15], v[204:207], v[188:191], v[12:15]
	v_mfma_f32_16x16x32_bf16 v[8:11], v[212:215], v[188:191], v[8:11]
	v_mfma_f32_16x16x32_bf16 v[4:7], v[204:207], v[196:199], v[4:7]
	v_mfma_f32_16x16x32_bf16 v[0:3], v[212:215], v[196:199], v[0:3]
	v_mfma_f32_16x16x32_bf16 v[44:47], v[208:211], v[176:179], v[44:47]
	v_mfma_f32_16x16x32_bf16 v[40:43], v[216:219], v[176:179], v[40:43]
	v_mfma_f32_16x16x32_bf16 v[28:31], v[208:211], v[184:187], v[28:31]
	v_mfma_f32_16x16x32_bf16 v[24:27], v[216:219], v[184:187], v[24:27]
	v_mfma_f32_16x16x32_bf16 v[12:15], v[208:211], v[192:195], v[12:15]
	v_mfma_f32_16x16x32_bf16 v[8:11], v[216:219], v[192:195], v[8:11]
	v_mfma_f32_16x16x32_bf16 v[4:7], v[208:211], v[200:203], v[4:7]
	v_mfma_f32_16x16x32_bf16 v[0:3], v[216:219], v[200:203], v[0:3]
	s_add_i32 s77, s77, 2
	s_add_u32 s34, s34, 0x100
	s_addc_u32 s35, s35, 0
	s_add_u32 s75, s75, 0x100
	s_addc_u32 s76, s76, 0
	s_cmp_gt_u32 s77, 61
	s_barrier
	s_cbranch_scc0 .LBB0_1384
	v_lshl_add_u32 v156, s18, 8, v150
	v_lshl_or_b32 v158, s72, 8, v152
	v_ashrrev_i32_e32 v157, 31, v156
	v_lshlrev_b64 v[160:161], 11, v[156:157]
	v_ashrrev_i32_e32 v159, 31, v158
	v_lshl_add_u64 v[160:161], s[44:45], 0, v[160:161]
	v_cvt_pk_bf16_f32 v124, v124, v125
	v_cvt_pk_bf16_f32 v125, v126, v127
	v_cvt_pk_bf16_f32 v126, v120, v121
	v_lshlrev_b64 v[120:121], 1, v[158:159]
	v_cvt_pk_bf16_f32 v127, v122, v123
	v_lshl_add_u64 v[122:123], v[160:161], 0, v[120:121]
	v_cvt_pk_bf16_f32 v108, v108, v109
	v_cvt_pk_bf16_f32 v109, v110, v111
	v_cvt_pk_bf16_f32 v110, v104, v105
	v_or_b32_e32 v104, 16, v156
	v_cvt_pk_bf16_f32 v60, v60, v61
	v_cvt_pk_bf16_f32 v61, v62, v63
	v_cvt_pk_bf16_f32 v63, v58, v59
	v_add_co_u32_e32 v58, vcc, s64, v122
	v_ashrrev_i32_e32 v105, 31, v104
	v_cvt_pk_bf16_f32 v62, v56, v57
	v_lshl_add_u64 v[56:57], v[122:123], 0, s[10:11]
	v_addc_co_u32_e32 v59, vcc, 0, v123, vcc
	v_cvt_pk_bf16_f32 v44, v44, v45
	v_cvt_pk_bf16_f32 v45, v46, v47
	v_cvt_pk_bf16_f32 v46, v40, v41
	v_cvt_pk_bf16_f32 v47, v42, v43
	v_cvt_pk_bf16_f32 v111, v106, v107
	v_lshlrev_b64 v[104:105], 11, v[104:105]
	v_cvt_pk_bf16_f32 v92, v92, v93
	v_cvt_pk_bf16_f32 v93, v94, v95
	v_cvt_pk_bf16_f32 v94, v88, v89
	v_or_b32_e32 v88, 32, v156
	global_store_dwordx4 v[56:57], v[44:47], off offset:256
	global_store_dwordx4 v[122:123], v[108:111], off offset:256
	v_ashrrev_i32_e32 v89, 31, v88
	v_add_co_u32_e32 v46, vcc, s65, v122
	v_lshl_add_u64 v[108:109], s[44:45], 0, v[104:105]
	v_lshl_add_u64 v[44:45], v[122:123], 0, s[12:13]
	v_addc_co_u32_e32 v47, vcc, 0, v123, vcc
	v_cvt_pk_bf16_f32 v28, v28, v29
	v_cvt_pk_bf16_f32 v29, v30, v31
	v_cvt_pk_bf16_f32 v30, v24, v25
	v_cvt_pk_bf16_f32 v31, v26, v27
	v_lshl_add_u64 v[108:109], v[108:109], 0, v[120:121]
	v_cvt_pk_bf16_f32 v95, v90, v91
	v_lshlrev_b64 v[88:89], 11, v[88:89]
	v_cvt_pk_bf16_f32 v76, v76, v77
	v_cvt_pk_bf16_f32 v77, v78, v79
	v_cvt_pk_bf16_f32 v78, v72, v73
	v_or_b32_e32 v72, 48, v156
	global_store_dwordx4 v[44:45], v[28:31], off offset:256
	global_store_dwordx4 v[108:109], v[92:95], off offset:256
	v_ashrrev_i32_e32 v73, 31, v72
	v_add_co_u32_e32 v30, vcc, s70, v122
	v_lshl_add_u64 v[92:93], s[44:45], 0, v[88:89]
	v_lshl_add_u64 v[28:29], v[122:123], 0, s[14:15]
	v_addc_co_u32_e32 v31, vcc, 0, v123, vcc
	v_cvt_pk_bf16_f32 v12, v12, v13
	v_cvt_pk_bf16_f32 v13, v14, v15
	v_cvt_pk_bf16_f32 v14, v8, v9
	v_cvt_pk_bf16_f32 v15, v10, v11
	v_lshl_add_u64 v[92:93], v[92:93], 0, v[120:121]
	v_cvt_pk_bf16_f32 v79, v74, v75
	v_lshlrev_b64 v[72:73], 11, v[72:73]
	global_store_dwordx4 v[28:29], v[12:15], off offset:256
	global_store_dwordx4 v[92:93], v[76:79], off offset:256
	v_cvt_pk_bf16_f32 v104, v116, v117
	v_add_co_u32_e32 v14, vcc, s71, v122
	v_lshl_add_u64 v[76:77], s[44:45], 0, v[72:73]
	s_nop 0
	v_addc_co_u32_e32 v15, vcc, 0, v123, vcc
	v_cvt_pk_bf16_f32 v105, v118, v119
	v_cvt_pk_bf16_f32 v106, v112, v113
	v_cvt_pk_bf16_f32 v107, v114, v115
	v_cvt_pk_bf16_f32 v88, v100, v101
	v_cvt_pk_bf16_f32 v89, v102, v103
	v_cvt_pk_bf16_f32 v90, v96, v97
	v_cvt_pk_bf16_f32 v91, v98, v99
	v_cvt_pk_bf16_f32 v72, v84, v85
	v_cvt_pk_bf16_f32 v73, v86, v87
	v_cvt_pk_bf16_f32 v74, v80, v81
	v_cvt_pk_bf16_f32 v75, v82, v83
	v_lshl_add_u64 v[76:77], v[76:77], 0, v[120:121]
	v_cvt_pk_bf16_f32 v68, v68, v69
	v_cvt_pk_bf16_f32 v69, v70, v71
	v_cvt_pk_bf16_f32 v70, v64, v65
	v_cvt_pk_bf16_f32 v71, v66, v67
	v_cvt_pk_bf16_f32 v40, v52, v53
	v_cvt_pk_bf16_f32 v41, v54, v55
	v_cvt_pk_bf16_f32 v42, v48, v49
	v_cvt_pk_bf16_f32 v43, v50, v51
	v_cvt_pk_bf16_f32 v24, v36, v37
	v_cvt_pk_bf16_f32 v25, v38, v39
	v_cvt_pk_bf16_f32 v26, v32, v33
	v_cvt_pk_bf16_f32 v27, v34, v35
	v_cvt_pk_bf16_f32 v8, v20, v21
	v_cvt_pk_bf16_f32 v9, v22, v23
	v_cvt_pk_bf16_f32 v10, v16, v17
	v_cvt_pk_bf16_f32 v11, v18, v19
	v_lshl_add_u64 v[12:13], v[122:123], 0, s[16:17]
	v_cvt_pk_bf16_f32 v4, v4, v5
	v_cvt_pk_bf16_f32 v5, v6, v7
	v_cvt_pk_bf16_f32 v6, v0, v1
	v_cvt_pk_bf16_f32 v7, v2, v3
	s_and_b64 vcc, exec, s[4:5]
	s_mov_b32 s72, s20
	s_mov_b32 s18, s26
	s_mov_b64 s[36:37], s[30:31]
	s_mov_b64 s[34:35], s[28:29]
	global_store_dwordx4 v[122:123], v[124:127], off
	global_store_dwordx4 v[108:109], v[104:107], off
	global_store_dwordx4 v[92:93], v[88:91], off
	global_store_dwordx4 v[76:77], v[72:75], off
	global_store_dwordx4 v[76:77], v[68:71], off offset:256
	global_store_dwordx4 v[58:59], v[60:63], off
	global_store_dwordx4 v[46:47], v[40:43], off
	global_store_dwordx4 v[30:31], v[24:27], off
	global_store_dwordx4 v[14:15], v[8:11], off
	global_store_dwordx4 v[12:13], v[4:7], off offset:256
	s_cbranch_vccz .LBB0_1381
	s_waitcnt vmcnt(16)
	s_cmpk_gt_u32 s40, 0xff
	s_cbranch_scc1 .LBB0_1388
	s_barrier
